# GEMM K-loop: pointer/counter SALU moved off the critical load segment (reads first)
# speedup vs baseline: 1.0304x; 1.0010x over previous
; #define PG8_STAGE(bufoff, gbase, voff) do { _Pragma("unroll") for (int _i = 0; _i < 2; ++_i) \
;         __builtin_amdgcn_global_load_lds((const unsigned*)((const char*)(gbase) + (voff)[_i]), (PG8_LAS unsigned*)(lds + (bufoff) + ldsw + _i * 8192), 16, 0, 0); } while (0)
; #define PG8_LDA(dst, b, h) do { _Pragma("unroll") for (int m = 0; m < 4; ++m) _Pragma("unroll") for (int k = 0; k < 2; ++k) dst[m][k] = *(const PG8_LAS bf16x8*)(lds + PG8_SA(b, h) + aoff + m * 2048 + k * 1024); } while (0)
; #define PG8_LDB(dst, b, h) do { _Pragma("unroll") for (int n = 0; n < 2; ++n) _Pragma("unroll") for (int k = 0; k < 2; ++k) dst[n][k] = *(const PG8_LAS bf16x8*)(lds + PG8_SB(b, h) + boff + n * 2048 + k * 1024); } while (0)
; #define PG8_WAIT_V(n) asm volatile("s_waitcnt vmcnt(" #n ")" ::: "memory")
; #define PG8_WAIT_L(n) asm volatile("s_waitcnt lgkmcnt(" #n ")" ::: "memory")
; #define PG8_BAR __builtin_amdgcn_s_barrier()
; #define PG8_SCHED __builtin_amdgcn_sched_barrier(0)
; template <class Epi, class Sched, bool ALIGN_EPI = false, bool SP2 = false>
; __device__ __forceinline__ void gemm_phase(PG8_LAS unsigned char* lds, const Gemm g, const Sched& S, const Epi& E, const int tid) {
;     ...
;         const bool has_next = S.next(ui + 1, nxt);
;         const char* nA = has_next ? (const char*)g.A + (size_t)nxt.pm * tstep : cA; const char* nB = has_next ? (const char*)g.Bt + (size_t)nxt.pn * tstep : cB;
;         for (int t = 0; t < nt; t += 2) {
;             const bool last = (t == nt - 2);
;             const char* a1 = cA + (size_t)(t + 1) * kstep;
;             const char* a2 = last ? nA : cA + (size_t)(t + 2) * kstep; const char* b2 = last ? nB : cB + (size_t)(t + 2) * kstep;
;             const char* a3 = a2 + kstep; const char* b3 = b2 + kstep;
;             if (last && has_next) S.a_ready(nxt);
;             if constexpr (SP2) {
;             PG8_LDB(B0, 0, 0); PG8_LDB(B1, 0, 1); PG8_SCHED; PG8_LDA(At, 0, 0); PG8_STAGE(PG8_SA(1, 1), a1 + hstep, voffA);
;             PG8_WAIT_V(8); PG8_WAIT_L(0); PG8_BAR; PG8_MMA(0, 0, At, B0); PG8_MMA(0, 1, At, B1); PG8_BAR; PG8_SCHED;
;             PG8_LDA(At, 0, 1); PG8_STAGE(PG8_SB(0, 0), b2, voffB); PG8_STAGE(PG8_SB(0, 1), b2 + hstep, voffB); PG8_STAGE(PG8_SA(0, 0), a2, voffA);
;             PG8_WAIT_V(8); PG8_WAIT_L(0); PG8_BAR; PG8_MMA(1, 0, At, B0); PG8_MMA(1, 1, At, B1); PG8_BAR; PG8_SCHED;
.LBB0_318:
	s_ashr_i32 s29, s28, 31
	s_lshl_b64 s[30:31], s[28:29], 20
	s_add_u32 s30, s48, s30
	s_addc_u32 s31, s49, s31
	s_and_b64 s[34:35], s[6:7], exec
	s_cselect_b32 s9, s31, s43
	s_cselect_b32 s29, s30, s42
	s_ashr_i32 s27, s26, 31
	s_lshl_b64 s[34:35], s[26:27], 20
	s_add_u32 s34, s50, s34
	s_addc_u32 s35, s51, s35
	s_and_b64 s[46:47], s[6:7], exec
	s_cselect_b32 s27, s35, s45
	s_cselect_b32 s37, s34, s44
	s_add_u32 s42, s42, 0x80080
	s_addc_u32 s43, s43, 0
	s_add_u32 s69, s44, 0x100
	s_addc_u32 s92, s45, 0
	s_mov_b32 s76, -2
	s_waitcnt vmcnt(0)
	s_add_i32 s77, 0, 0x10000
	v_add_u32_e32 v136, s77, v178
	s_add_i32 s80, 0, 0x14000
	ds_read_b128 v[128:131], v136
	ds_read_b128 v[132:135], v136 offset:1024
	ds_read_b128 v[150:153], v136 offset:2048
	ds_read_b128 v[154:157], v136 offset:3072
	v_add_u32_e32 v136, s80, v178
	ds_read_b128 v[158:161], v136
	ds_read_b128 v[162:165], v136 offset:1024
	ds_read_b128 v[166:169], v136 offset:2048
	ds_read_b128 v[170:173], v136 offset:3072
	v_lshl_add_u64 v[136:137], s[42:43], 0, v[146:147]
	s_add_i32 m0, s53, 0xc000
	ds_read_b128 v[174:177], v179
	ds_read_b128 v[180:183], v179 offset:1024
	ds_read_b128 v[184:187], v179 offset:2048
	ds_read_b128 v[188:191], v179 offset:3072
	ds_read_b128 v[192:195], v179 offset:4096
	ds_read_b128 v[196:199], v179 offset:5120
	ds_read_b128 v[200:203], v179 offset:6144
	ds_read_b128 v[206:209], v179 offset:7168
	s_add_u32 s44, s42, 0xfff80080
	s_addc_u32 s45, s43, -1
	s_cmp_eq_u32 s76, 28
	s_cselect_b32 s47, s9, s45
	s_cselect_b32 s46, s29, s44
	s_cselect_b32 s45, s27, s92
	s_cselect_b32 s44, s37, s69
	global_load_lds_dwordx4 v[136:137], off
	v_lshl_add_u64 v[136:137], s[42:43], 0, v[148:149]
	s_add_i32 m0, s53, 0xe000
	s_nop 0
	global_load_lds_dwordx4 v[136:137], off
	s_waitcnt vmcnt(24)
	s_waitcnt lgkmcnt(0)
	s_setprio 1
	s_barrier
	v_mfma_f32_16x16x32_bf16 v[124:127], v[128:131], v[174:177], 0
	v_mfma_f32_16x16x32_bf16 v[120:123], v[150:153], v[174:177], 0
	v_mfma_f32_16x16x32_bf16 v[108:111], v[128:131], v[184:187], 0
	v_mfma_f32_16x16x32_bf16 v[104:107], v[150:153], v[184:187], 0
	v_mfma_f32_16x16x32_bf16 v[92:95], v[128:131], v[192:195], 0
	v_mfma_f32_16x16x32_bf16 v[88:91], v[150:153], v[192:195], 0
	v_mfma_f32_16x16x32_bf16 v[76:79], v[128:131], v[200:203], 0
	v_mfma_f32_16x16x32_bf16 v[72:75], v[150:153], v[200:203], 0
	v_mfma_f32_16x16x32_bf16 v[124:127], v[132:135], v[180:183], v[124:127]
	v_mfma_f32_16x16x32_bf16 v[120:123], v[154:157], v[180:183], v[120:123]
	v_mfma_f32_16x16x32_bf16 v[108:111], v[132:135], v[188:191], v[108:111]
	v_mfma_f32_16x16x32_bf16 v[104:107], v[154:157], v[188:191], v[104:107]
	v_mfma_f32_16x16x32_bf16 v[92:95], v[132:135], v[196:199], v[92:95]
	v_mfma_f32_16x16x32_bf16 v[88:91], v[154:157], v[196:199], v[88:91]
	v_mfma_f32_16x16x32_bf16 v[76:79], v[132:135], v[206:209], v[76:79]
	v_mfma_f32_16x16x32_bf16 v[72:75], v[154:157], v[206:209], v[72:75]
	s_setprio 0
	s_setprio 1
	v_mfma_f32_16x16x32_bf16 v[116:119], v[158:161], v[174:177], 0
	v_mfma_f32_16x16x32_bf16 v[112:115], v[166:169], v[174:177], 0
	v_mfma_f32_16x16x32_bf16 v[100:103], v[158:161], v[184:187], 0
	v_mfma_f32_16x16x32_bf16 v[96:99], v[166:169], v[184:187], 0
	v_mfma_f32_16x16x32_bf16 v[84:87], v[158:161], v[192:195], 0
	v_mfma_f32_16x16x32_bf16 v[80:83], v[166:169], v[192:195], 0
	v_mfma_f32_16x16x32_bf16 v[68:71], v[158:161], v[200:203], 0
	v_mfma_f32_16x16x32_bf16 v[64:67], v[166:169], v[200:203], 0
	v_mfma_f32_16x16x32_bf16 v[116:119], v[162:165], v[180:183], v[116:119]
	v_mfma_f32_16x16x32_bf16 v[112:115], v[170:173], v[180:183], v[112:115]
	v_mfma_f32_16x16x32_bf16 v[100:103], v[162:165], v[188:191], v[100:103]
	v_mfma_f32_16x16x32_bf16 v[96:99], v[170:173], v[188:191], v[96:99]
	v_mfma_f32_16x16x32_bf16 v[84:87], v[162:165], v[196:199], v[84:87]
	v_mfma_f32_16x16x32_bf16 v[80:83], v[170:173], v[196:199], v[80:83]
	v_mfma_f32_16x16x32_bf16 v[68:71], v[162:165], v[206:209], v[68:71]
	v_mfma_f32_16x16x32_bf16 v[64:67], v[170:173], v[206:209], v[64:67]
	s_barrier
	s_setprio 0
	s_add_i32 s77, s77, s52
	v_lshl_add_u64 v[136:137], s[44:45], 0, v[140:141]
	s_mov_b32 m0, s77
	ds_read_b128 v[174:177], v179 offset:16384
	ds_read_b128 v[180:183], v179 offset:17408
	ds_read_b128 v[184:187], v179 offset:18432
	ds_read_b128 v[188:191], v179 offset:19456
	ds_read_b128 v[192:195], v179 offset:20480
	ds_read_b128 v[196:199], v179 offset:21504
	ds_read_b128 v[200:203], v179 offset:22528
	ds_read_b128 v[206:209], v179 offset:23552
	global_load_lds_dwordx4 v[136:137], off
	s_add_i32 m0, s77, 0x2000
	s_add_u32 s78, s44, 0x80000
	v_lshl_add_u64 v[210:211], s[44:45], 0, v[144:145]
	s_addc_u32 s79, s45, 0
	s_add_i32 s77, s80, s52
	global_load_lds_dwordx4 v[210:211], off
	v_lshl_add_u64 v[212:213], s[78:79], 0, v[140:141]
	s_mov_b32 m0, s77
	v_lshl_add_u64 v[214:215], s[46:47], 0, v[142:143]
	global_load_lds_dwordx4 v[212:213], off
	v_lshl_add_u64 v[212:213], s[78:79], 0, v[144:145]
	s_add_i32 m0, s77, 0x2000
	s_nop 0
	global_load_lds_dwordx4 v[212:213], off
	v_lshl_add_u64 v[212:213], s[46:47], 0, v[138:139]
	s_mov_b32 m0, s53
	s_nop 0
	global_load_lds_dwordx4 v[212:213], off
	s_mov_b32 m0, s54
	s_nop 0
	global_load_lds_dwordx4 v[214:215], off
	s_waitcnt vmcnt(8)
	s_waitcnt lgkmcnt(0)
	s_setprio 1
	s_barrier
; #define PG8_STAGE(bufoff, gbase, voff) do { _Pragma("unroll") for (int _i = 0; _i < 2; ++_i) \
;         __builtin_amdgcn_global_load_lds((const unsigned*)((const char*)(gbase) + (voff)[_i]), (PG8_LAS unsigned*)(lds + (bufoff) + ldsw + _i * 8192), 16, 0, 0); } while (0)
; #define PG8_LDA(dst, b, h) do { _Pragma("unroll") for (int m = 0; m < 4; ++m) _Pragma("unroll") for (int k = 0; k < 2; ++k) dst[m][k] = *(const PG8_LAS bf16x8*)(lds + PG8_SA(b, h) + aoff + m * 2048 + k * 1024); } while (0)
; #define PG8_LDB(dst, b, h) do { _Pragma("unroll") for (int n = 0; n < 2; ++n) _Pragma("unroll") for (int k = 0; k < 2; ++k) dst[n][k] = *(const PG8_LAS bf16x8*)(lds + PG8_SB(b, h) + boff + n * 2048 + k * 1024); } while (0)
; #define PG8_MMA(ai, bj, At, Bt) do { __builtin_amdgcn_s_setprio(1); _Pragma("unroll") for (int m = 0; m < 4; ++m) _Pragma("unroll") for (int n = 0; n < 2; ++n) _Pragma("unroll") for (int k = 0; k < 2; ++k) \
;         acc[ai][bj][m][n] = __builtin_amdgcn_mfma_f32_16x16x32_bf16(Bt[n][k], At[m][k], acc[ai][bj][m][n], 0, 0, 0); __builtin_amdgcn_s_setprio(0); } while (0)
; #define PG8_WAIT_V(n) asm volatile("s_waitcnt vmcnt(" #n ")" ::: "memory")
; #define PG8_WAIT_L(n) asm volatile("s_waitcnt lgkmcnt(" #n ")" ::: "memory")
; #define PG8_BAR __builtin_amdgcn_s_barrier()
; #define PG8_SCHED __builtin_amdgcn_sched_barrier(0)
; template <class Epi, class Sched, bool ALIGN_EPI = false, bool SP2 = false>
; __device__ __forceinline__ void gemm_phase(PG8_LAS unsigned char* lds, const Gemm g, const Sched& S, const Epi& E, const int tid) {
;     ...
;             PG8_WAIT_V(8); PG8_WAIT_L(0); PG8_BAR; PG8_MMA(1, 0, At, B0); PG8_MMA(1, 1, At, B1); PG8_BAR; PG8_SCHED;
;             PG8_LDB(B0, 1, 0); PG8_LDB(B1, 1, 1); PG8_SCHED; PG8_LDA(At, 1, 0); PG8_STAGE(PG8_SA(0, 1), a2 + hstep, voffA);
;             PG8_WAIT_V(8); PG8_WAIT_L(0); PG8_BAR; PG8_MMA(0, 0, At, B0); PG8_MMA(0, 1, At, B1); PG8_BAR; PG8_SCHED;
	v_mfma_f32_16x16x32_bf16 v[60:63], v[128:131], v[174:177], 0
	v_mfma_f32_16x16x32_bf16 v[56:59], v[150:153], v[174:177], 0
	v_mfma_f32_16x16x32_bf16 v[44:47], v[128:131], v[184:187], 0
	v_mfma_f32_16x16x32_bf16 v[40:43], v[150:153], v[184:187], 0
	v_mfma_f32_16x16x32_bf16 v[28:31], v[128:131], v[192:195], 0
	v_mfma_f32_16x16x32_bf16 v[24:27], v[150:153], v[192:195], 0
	v_mfma_f32_16x16x32_bf16 v[12:15], v[128:131], v[200:203], 0
	v_mfma_f32_16x16x32_bf16 v[8:11], v[150:153], v[200:203], 0
	v_mfma_f32_16x16x32_bf16 v[60:63], v[132:135], v[180:183], v[60:63]
	v_mfma_f32_16x16x32_bf16 v[56:59], v[154:157], v[180:183], v[56:59]
	v_mfma_f32_16x16x32_bf16 v[44:47], v[132:135], v[188:191], v[44:47]
	v_mfma_f32_16x16x32_bf16 v[40:43], v[154:157], v[188:191], v[40:43]
	v_mfma_f32_16x16x32_bf16 v[28:31], v[132:135], v[196:199], v[28:31]
	v_mfma_f32_16x16x32_bf16 v[24:27], v[154:157], v[196:199], v[24:27]
	v_mfma_f32_16x16x32_bf16 v[12:15], v[132:135], v[206:209], v[12:15]
	v_mfma_f32_16x16x32_bf16 v[8:11], v[154:157], v[206:209], v[8:11]
	s_setprio 0
	s_setprio 1
	v_mfma_f32_16x16x32_bf16 v[52:55], v[158:161], v[174:177], 0
	v_mfma_f32_16x16x32_bf16 v[48:51], v[166:169], v[174:177], 0
	v_mfma_f32_16x16x32_bf16 v[36:39], v[158:161], v[184:187], 0
	v_mfma_f32_16x16x32_bf16 v[32:35], v[166:169], v[184:187], 0
	v_mfma_f32_16x16x32_bf16 v[20:23], v[158:161], v[192:195], 0
	v_mfma_f32_16x16x32_bf16 v[16:19], v[166:169], v[192:195], 0
	v_mfma_f32_16x16x32_bf16 v[4:7], v[158:161], v[200:203], 0
	v_mfma_f32_16x16x32_bf16 v[0:3], v[166:169], v[200:203], 0
	v_mfma_f32_16x16x32_bf16 v[52:55], v[162:165], v[180:183], v[52:55]
	v_mfma_f32_16x16x32_bf16 v[48:51], v[170:173], v[180:183], v[48:51]
	v_mfma_f32_16x16x32_bf16 v[36:39], v[162:165], v[188:191], v[36:39]
	v_mfma_f32_16x16x32_bf16 v[32:35], v[170:173], v[188:191], v[32:35]
	v_mfma_f32_16x16x32_bf16 v[20:23], v[162:165], v[196:199], v[20:23]
	v_mfma_f32_16x16x32_bf16 v[16:19], v[170:173], v[196:199], v[16:19]
	v_mfma_f32_16x16x32_bf16 v[4:7], v[162:165], v[206:209], v[4:7]
	v_mfma_f32_16x16x32_bf16 v[0:3], v[170:173], v[206:209], v[0:3]
	s_barrier
	s_setprio 0
	s_add_i32 s77, 0, 0x18000
	s_add_i32 s78, 0, 0x1c000
	v_add_u32_e32 v154, s77, v178
	v_add_u32_e32 v170, s78, v178
	ds_read_b128 v[128:131], v154
	ds_read_b128 v[132:135], v154 offset:1024
	ds_read_b128 v[150:153], v154 offset:2048
	ds_read_b128 v[154:157], v154 offset:3072
	ds_read_b128 v[158:161], v170
	ds_read_b128 v[162:165], v170 offset:1024
	ds_read_b128 v[166:169], v170 offset:2048
	ds_read_b128 v[170:173], v170 offset:3072
	s_add_u32 s46, s46, 0x80000
	s_addc_u32 s47, s47, 0
	s_mov_b32 m0, s55
	v_lshl_add_u64 v[216:217], s[46:47], 0, v[138:139]
	ds_read_b128 v[174:177], v179 offset:32768
	ds_read_b128 v[180:183], v179 offset:33792
	ds_read_b128 v[184:187], v179 offset:34816
	ds_read_b128 v[188:191], v179 offset:35840
	ds_read_b128 v[192:195], v179 offset:36864
	ds_read_b128 v[196:199], v179 offset:37888
	ds_read_b128 v[200:203], v179 offset:38912
	ds_read_b128 v[206:209], v179 offset:39936
	global_load_lds_dwordx4 v[216:217], off
	v_lshl_add_u64 v[216:217], s[46:47], 0, v[142:143]
	s_mov_b32 m0, s0
	s_nop 0
	global_load_lds_dwordx4 v[216:217], off
	s_waitcnt vmcnt(8)
	s_waitcnt lgkmcnt(0)
	s_setprio 1
	s_barrier
	v_mfma_f32_16x16x32_bf16 v[124:127], v[128:131], v[174:177], v[124:127]
	v_mfma_f32_16x16x32_bf16 v[120:123], v[150:153], v[174:177], v[120:123]
	v_mfma_f32_16x16x32_bf16 v[108:111], v[128:131], v[184:187], v[108:111]
	v_mfma_f32_16x16x32_bf16 v[104:107], v[150:153], v[184:187], v[104:107]
	v_mfma_f32_16x16x32_bf16 v[92:95], v[128:131], v[192:195], v[92:95]
	v_mfma_f32_16x16x32_bf16 v[88:91], v[150:153], v[192:195], v[88:91]
	v_mfma_f32_16x16x32_bf16 v[76:79], v[128:131], v[200:203], v[76:79]
	v_mfma_f32_16x16x32_bf16 v[72:75], v[150:153], v[200:203], v[72:75]
	v_mfma_f32_16x16x32_bf16 v[124:127], v[132:135], v[180:183], v[124:127]
	v_mfma_f32_16x16x32_bf16 v[120:123], v[154:157], v[180:183], v[120:123]
	v_mfma_f32_16x16x32_bf16 v[108:111], v[132:135], v[188:191], v[108:111]
	v_mfma_f32_16x16x32_bf16 v[104:107], v[154:157], v[188:191], v[104:107]
	v_mfma_f32_16x16x32_bf16 v[92:95], v[132:135], v[196:199], v[92:95]
	v_mfma_f32_16x16x32_bf16 v[88:91], v[154:157], v[196:199], v[88:91]
	v_mfma_f32_16x16x32_bf16 v[76:79], v[132:135], v[206:209], v[76:79]
	v_mfma_f32_16x16x32_bf16 v[72:75], v[154:157], v[206:209], v[72:75]
	s_setprio 0
	s_setprio 1
	v_mfma_f32_16x16x32_bf16 v[116:119], v[158:161], v[174:177], v[116:119]
	v_mfma_f32_16x16x32_bf16 v[112:115], v[166:169], v[174:177], v[112:115]
	v_mfma_f32_16x16x32_bf16 v[100:103], v[158:161], v[184:187], v[100:103]
	v_mfma_f32_16x16x32_bf16 v[96:99], v[166:169], v[184:187], v[96:99]
	v_mfma_f32_16x16x32_bf16 v[84:87], v[158:161], v[192:195], v[84:87]
	v_mfma_f32_16x16x32_bf16 v[80:83], v[166:169], v[192:195], v[80:83]
	v_mfma_f32_16x16x32_bf16 v[68:71], v[158:161], v[200:203], v[68:71]
	v_mfma_f32_16x16x32_bf16 v[64:67], v[166:169], v[200:203], v[64:67]
	v_mfma_f32_16x16x32_bf16 v[116:119], v[162:165], v[180:183], v[116:119]
	v_mfma_f32_16x16x32_bf16 v[112:115], v[170:173], v[180:183], v[112:115]
	v_mfma_f32_16x16x32_bf16 v[100:103], v[162:165], v[188:191], v[100:103]
	v_mfma_f32_16x16x32_bf16 v[96:99], v[170:173], v[188:191], v[96:99]
	v_mfma_f32_16x16x32_bf16 v[84:87], v[162:165], v[196:199], v[84:87]
	v_mfma_f32_16x16x32_bf16 v[80:83], v[170:173], v[196:199], v[80:83]
	v_mfma_f32_16x16x32_bf16 v[68:71], v[162:165], v[206:209], v[68:71]
	v_mfma_f32_16x16x32_bf16 v[64:67], v[170:173], v[206:209], v[64:67]
	s_barrier
; #define PG8_STAGE(bufoff, gbase, voff) do { _Pragma("unroll") for (int _i = 0; _i < 2; ++_i) \
;         __builtin_amdgcn_global_load_lds((const unsigned*)((const char*)(gbase) + (voff)[_i]), (PG8_LAS unsigned*)(lds + (bufoff) + ldsw + _i * 8192), 16, 0, 0); } while (0)
; #define PG8_LDA(dst, b, h) do { _Pragma("unroll") for (int m = 0; m < 4; ++m) _Pragma("unroll") for (int k = 0; k < 2; ++k) dst[m][k] = *(const PG8_LAS bf16x8*)(lds + PG8_SA(b, h) + aoff + m * 2048 + k * 1024); } while (0)
; #define PG8_LDB(dst, b, h) do { _Pragma("unroll") for (int n = 0; n < 2; ++n) _Pragma("unroll") for (int k = 0; k < 2; ++k) dst[n][k] = *(const PG8_LAS bf16x8*)(lds + PG8_SB(b, h) + boff + n * 2048 + k * 1024); } while (0)
; #define PG8_MMA(ai, bj, At, Bt) do { __builtin_amdgcn_s_setprio(1); _Pragma("unroll") for (int m = 0; m < 4; ++m) _Pragma("unroll") for (int n = 0; n < 2; ++n) _Pragma("unroll") for (int k = 0; k < 2; ++k) \
;         acc[ai][bj][m][n] = __builtin_amdgcn_mfma_f32_16x16x32_bf16(Bt[n][k], At[m][k], acc[ai][bj][m][n], 0, 0, 0); __builtin_amdgcn_s_setprio(0); } while (0)
; template <class Epi, class Sched, bool ALIGN_EPI = false, bool SP2 = false>
; __device__ __forceinline__ void gemm_phase(PG8_LAS unsigned char* lds, const Gemm g, const Sched& S, const Epi& E, const int tid) {
;     ...
;     for (;;) {
;         const bool has_next = S.next(ui + 1, nxt);
;         const char* nA = has_next ? (const char*)g.A + (size_t)nxt.pm * tstep : cA; const char* nB = has_next ? (const char*)g.Bt + (size_t)nxt.pn * tstep : cB;
;         for (int t = 0; t < nt; t += 2) {
;             const bool last = (t == nt - 2);
;             const char* a1 = cA + (size_t)(t + 1) * kstep;
;             const char* a2 = last ? nA : cA + (size_t)(t + 2) * kstep; const char* b2 = last ? nB : cB + (size_t)(t + 2) * kstep;
;             const char* a3 = a2 + kstep; const char* b3 = b2 + kstep;
;             if (last && has_next) S.a_ready(nxt);
;             if constexpr (SP2) {
;             PG8_LDB(B0, 0, 0); PG8_LDB(B1, 0, 1); PG8_SCHED; PG8_LDA(At, 0, 0); PG8_STAGE(PG8_SA(1, 1), a1 + hstep, voffA);
;     ...
;             PG8_LDA(At, 1, 1); PG8_STAGE(PG8_SB(1, 0), b3, voffB); PG8_STAGE(PG8_SB(1, 1), b3 + hstep, voffB); PG8_STAGE(PG8_SA(1, 0), a3, voffA);
;             PG8_WAIT_V(8); PG8_WAIT_L(0); PG8_BAR; PG8_MMA(1, 0, At, B0); PG8_MMA(1, 1, At, B1); PG8_BAR; PG8_SCHED;
	s_setprio 0
	s_add_i32 s46, s77, s52
	v_lshl_add_u64 v[136:137], v[136:137], 0, s[70:71]
	s_mov_b32 m0, s46
	ds_read_b128 v[174:177], v179 offset:49152
	ds_read_b128 v[180:183], v179 offset:50176
	ds_read_b128 v[184:187], v179 offset:51200
	ds_read_b128 v[188:191], v179 offset:52224
	ds_read_b128 v[192:195], v179 offset:53248
	ds_read_b128 v[196:199], v179 offset:54272
	ds_read_b128 v[200:203], v179 offset:55296
	ds_read_b128 v[206:209], v179 offset:56320
	global_load_lds_dwordx4 v[136:137], off
	s_add_i32 m0, s46, 0x2000
	s_add_u32 s44, s44, 0x80080
	v_lshl_add_u64 v[136:137], v[210:211], 0, s[70:71]
	s_addc_u32 s45, s45, 0
	s_add_i32 s46, s78, s52
	global_load_lds_dwordx4 v[136:137], off
	v_lshl_add_u64 v[136:137], s[44:45], 0, v[140:141]
	s_mov_b32 m0, s46
	s_nop 0
	global_load_lds_dwordx4 v[136:137], off
	v_lshl_add_u64 v[136:137], s[44:45], 0, v[144:145]
	s_add_i32 m0, s46, 0x2000
	s_nop 0
	global_load_lds_dwordx4 v[136:137], off
	v_lshl_add_u64 v[136:137], v[212:213], 0, s[70:71]
	s_mov_b32 m0, s11
	s_nop 0
	global_load_lds_dwordx4 v[136:137], off
	v_lshl_add_u64 v[136:137], v[214:215], 0, s[70:71]
	s_mov_b32 m0, s64
	s_nop 0
	global_load_lds_dwordx4 v[136:137], off
	s_add_i32 s76, s76, 2
	s_add_u32 s42, s42, 0x100
	s_addc_u32 s43, s43, 0
	s_add_u32 s69, s69, 0x100
	s_addc_u32 s92, s92, 0
	s_waitcnt vmcnt(8)
	s_waitcnt lgkmcnt(0)
	s_setprio 1
	s_barrier
	v_mfma_f32_16x16x32_bf16 v[60:63], v[128:131], v[174:177], v[60:63]
	v_mfma_f32_16x16x32_bf16 v[56:59], v[150:153], v[174:177], v[56:59]
	v_mfma_f32_16x16x32_bf16 v[44:47], v[128:131], v[184:187], v[44:47]
	v_mfma_f32_16x16x32_bf16 v[40:43], v[150:153], v[184:187], v[40:43]
	v_mfma_f32_16x16x32_bf16 v[28:31], v[128:131], v[192:195], v[28:31]
	v_mfma_f32_16x16x32_bf16 v[24:27], v[150:153], v[192:195], v[24:27]
	v_mfma_f32_16x16x32_bf16 v[12:15], v[128:131], v[200:203], v[12:15]
	v_mfma_f32_16x16x32_bf16 v[8:11], v[150:153], v[200:203], v[8:11]
	v_mfma_f32_16x16x32_bf16 v[60:63], v[132:135], v[180:183], v[60:63]
	v_mfma_f32_16x16x32_bf16 v[56:59], v[154:157], v[180:183], v[56:59]
	v_mfma_f32_16x16x32_bf16 v[44:47], v[132:135], v[188:191], v[44:47]
	v_mfma_f32_16x16x32_bf16 v[40:43], v[154:157], v[188:191], v[40:43]
	v_mfma_f32_16x16x32_bf16 v[28:31], v[132:135], v[196:199], v[28:31]
	v_mfma_f32_16x16x32_bf16 v[24:27], v[154:157], v[196:199], v[24:27]
	v_mfma_f32_16x16x32_bf16 v[12:15], v[132:135], v[206:209], v[12:15]
	v_mfma_f32_16x16x32_bf16 v[8:11], v[154:157], v[206:209], v[8:11]
	s_setprio 0
	s_setprio 1
	v_mfma_f32_16x16x32_bf16 v[52:55], v[158:161], v[174:177], v[52:55]
	v_mfma_f32_16x16x32_bf16 v[48:51], v[166:169], v[174:177], v[48:51]
	v_mfma_f32_16x16x32_bf16 v[36:39], v[158:161], v[184:187], v[36:39]
	v_mfma_f32_16x16x32_bf16 v[32:35], v[166:169], v[184:187], v[32:35]
	v_mfma_f32_16x16x32_bf16 v[20:23], v[158:161], v[192:195], v[20:23]
	v_mfma_f32_16x16x32_bf16 v[16:19], v[166:169], v[192:195], v[16:19]
	v_mfma_f32_16x16x32_bf16 v[4:7], v[158:161], v[200:203], v[4:7]
	v_mfma_f32_16x16x32_bf16 v[0:3], v[166:169], v[200:203], v[0:3]
	v_mfma_f32_16x16x32_bf16 v[52:55], v[162:165], v[180:183], v[52:55]
	v_mfma_f32_16x16x32_bf16 v[48:51], v[170:173], v[180:183], v[48:51]
	v_mfma_f32_16x16x32_bf16 v[36:39], v[162:165], v[188:191], v[36:39]
	v_mfma_f32_16x16x32_bf16 v[32:35], v[170:173], v[188:191], v[32:35]
	v_mfma_f32_16x16x32_bf16 v[20:23], v[162:165], v[196:199], v[20:23]
	v_mfma_f32_16x16x32_bf16 v[16:19], v[170:173], v[196:199], v[16:19]
	v_mfma_f32_16x16x32_bf16 v[4:7], v[162:165], v[206:209], v[4:7]
	v_mfma_f32_16x16x32_bf16 v[0:3], v[170:173], v[206:209], v[0:3]
	s_barrier
	s_setprio 0
.LBB0_319:
	s_add_i32 s77, 0, 0x10000
	v_add_u32_e32 v136, s77, v178
	s_add_i32 s80, 0, 0x14000
	ds_read_b128 v[128:131], v136
	ds_read_b128 v[132:135], v136 offset:1024
	ds_read_b128 v[150:153], v136 offset:2048
	ds_read_b128 v[154:157], v136 offset:3072
	v_add_u32_e32 v136, s80, v178
	ds_read_b128 v[158:161], v136
	ds_read_b128 v[162:165], v136 offset:1024
	ds_read_b128 v[166:169], v136 offset:2048
	ds_read_b128 v[170:173], v136 offset:3072
	v_lshl_add_u64 v[136:137], s[42:43], 0, v[146:147]
	s_add_i32 m0, s53, 0xc000
	ds_read_b128 v[174:177], v179
	ds_read_b128 v[180:183], v179 offset:1024
	ds_read_b128 v[184:187], v179 offset:2048
	ds_read_b128 v[188:191], v179 offset:3072
	ds_read_b128 v[192:195], v179 offset:4096
	ds_read_b128 v[196:199], v179 offset:5120
	ds_read_b128 v[200:203], v179 offset:6144
	ds_read_b128 v[206:209], v179 offset:7168
	s_add_u32 s44, s42, 0xfff80080
	s_addc_u32 s45, s43, -1
	s_cmp_eq_u32 s76, 28
	s_cselect_b32 s47, s9, s45
	s_cselect_b32 s46, s29, s44
	s_cselect_b32 s45, s27, s92
	s_cselect_b32 s44, s37, s69
	global_load_lds_dwordx4 v[136:137], off
	v_lshl_add_u64 v[136:137], s[42:43], 0, v[148:149]
	s_add_i32 m0, s53, 0xe000
	s_nop 0
	global_load_lds_dwordx4 v[136:137], off
	s_waitcnt vmcnt(8)
	s_waitcnt lgkmcnt(0)
	s_setprio 1
	s_barrier
; #define PG8_STAGE(bufoff, gbase, voff) do { _Pragma("unroll") for (int _i = 0; _i < 2; ++_i) \
;         __builtin_amdgcn_global_load_lds((const unsigned*)((const char*)(gbase) + (voff)[_i]), (PG8_LAS unsigned*)(lds + (bufoff) + ldsw + _i * 8192), 16, 0, 0); } while (0)
; #define PG8_LDA(dst, b, h) do { _Pragma("unroll") for (int m = 0; m < 4; ++m) _Pragma("unroll") for (int k = 0; k < 2; ++k) dst[m][k] = *(const PG8_LAS bf16x8*)(lds + PG8_SA(b, h) + aoff + m * 2048 + k * 1024); } while (0)
; #define PG8_MMA(ai, bj, At, Bt) do { __builtin_amdgcn_s_setprio(1); _Pragma("unroll") for (int m = 0; m < 4; ++m) _Pragma("unroll") for (int n = 0; n < 2; ++n) _Pragma("unroll") for (int k = 0; k < 2; ++k) \
;         acc[ai][bj][m][n] = __builtin_amdgcn_mfma_f32_16x16x32_bf16(Bt[n][k], At[m][k], acc[ai][bj][m][n], 0, 0, 0); __builtin_amdgcn_s_setprio(0); } while (0)
; #define PG8_WAIT_V(n) asm volatile("s_waitcnt vmcnt(" #n ")" ::: "memory")
; #define PG8_WAIT_L(n) asm volatile("s_waitcnt lgkmcnt(" #n ")" ::: "memory")
; #define PG8_BAR __builtin_amdgcn_s_barrier()
; #define PG8_SCHED __builtin_amdgcn_sched_barrier(0)
; template <class Epi, class Sched, bool ALIGN_EPI = false, bool SP2 = false>
; __device__ __forceinline__ void gemm_phase(PG8_LAS unsigned char* lds, const Gemm g, const Sched& S, const Epi& E, const int tid) {
;     ...
;             PG8_WAIT_V(8); PG8_WAIT_L(0); PG8_BAR; PG8_MMA(0, 0, At, B0); PG8_MMA(0, 1, At, B1); PG8_BAR; PG8_SCHED;
;             PG8_LDA(At, 0, 1); PG8_STAGE(PG8_SB(0, 0), b2, voffB); PG8_STAGE(PG8_SB(0, 1), b2 + hstep, voffB); PG8_STAGE(PG8_SA(0, 0), a2, voffA);
;             PG8_WAIT_V(8); PG8_WAIT_L(0); PG8_BAR; PG8_MMA(1, 0, At, B0); PG8_MMA(1, 1, At, B1); PG8_BAR; PG8_SCHED;
	v_mfma_f32_16x16x32_bf16 v[124:127], v[128:131], v[174:177], v[124:127]
	v_mfma_f32_16x16x32_bf16 v[120:123], v[150:153], v[174:177], v[120:123]
	v_mfma_f32_16x16x32_bf16 v[108:111], v[128:131], v[184:187], v[108:111]
	v_mfma_f32_16x16x32_bf16 v[104:107], v[150:153], v[184:187], v[104:107]
	v_mfma_f32_16x16x32_bf16 v[92:95], v[128:131], v[192:195], v[92:95]
	v_mfma_f32_16x16x32_bf16 v[88:91], v[150:153], v[192:195], v[88:91]
	v_mfma_f32_16x16x32_bf16 v[76:79], v[128:131], v[200:203], v[76:79]
	v_mfma_f32_16x16x32_bf16 v[72:75], v[150:153], v[200:203], v[72:75]
	v_mfma_f32_16x16x32_bf16 v[124:127], v[132:135], v[180:183], v[124:127]
	v_mfma_f32_16x16x32_bf16 v[120:123], v[154:157], v[180:183], v[120:123]
	v_mfma_f32_16x16x32_bf16 v[108:111], v[132:135], v[188:191], v[108:111]
	v_mfma_f32_16x16x32_bf16 v[104:107], v[154:157], v[188:191], v[104:107]
	v_mfma_f32_16x16x32_bf16 v[92:95], v[132:135], v[196:199], v[92:95]
	v_mfma_f32_16x16x32_bf16 v[88:91], v[154:157], v[196:199], v[88:91]
	v_mfma_f32_16x16x32_bf16 v[76:79], v[132:135], v[206:209], v[76:79]
	v_mfma_f32_16x16x32_bf16 v[72:75], v[154:157], v[206:209], v[72:75]
	s_setprio 0
	s_setprio 1
	v_mfma_f32_16x16x32_bf16 v[116:119], v[158:161], v[174:177], v[116:119]
	v_mfma_f32_16x16x32_bf16 v[112:115], v[166:169], v[174:177], v[112:115]
	v_mfma_f32_16x16x32_bf16 v[100:103], v[158:161], v[184:187], v[100:103]
	v_mfma_f32_16x16x32_bf16 v[96:99], v[166:169], v[184:187], v[96:99]
	v_mfma_f32_16x16x32_bf16 v[84:87], v[158:161], v[192:195], v[84:87]
	v_mfma_f32_16x16x32_bf16 v[80:83], v[166:169], v[192:195], v[80:83]
	v_mfma_f32_16x16x32_bf16 v[68:71], v[158:161], v[200:203], v[68:71]
	v_mfma_f32_16x16x32_bf16 v[64:67], v[166:169], v[200:203], v[64:67]
	v_mfma_f32_16x16x32_bf16 v[116:119], v[162:165], v[180:183], v[116:119]
	v_mfma_f32_16x16x32_bf16 v[112:115], v[170:173], v[180:183], v[112:115]
	v_mfma_f32_16x16x32_bf16 v[100:103], v[162:165], v[188:191], v[100:103]
	v_mfma_f32_16x16x32_bf16 v[96:99], v[170:173], v[188:191], v[96:99]
	v_mfma_f32_16x16x32_bf16 v[84:87], v[162:165], v[196:199], v[84:87]
	v_mfma_f32_16x16x32_bf16 v[80:83], v[170:173], v[196:199], v[80:83]
	v_mfma_f32_16x16x32_bf16 v[68:71], v[162:165], v[206:209], v[68:71]
	v_mfma_f32_16x16x32_bf16 v[64:67], v[170:173], v[206:209], v[64:67]
	s_barrier
	s_setprio 0
	s_add_i32 s77, s77, s52
	v_lshl_add_u64 v[136:137], s[44:45], 0, v[140:141]
	s_mov_b32 m0, s77
	ds_read_b128 v[174:177], v179 offset:16384
	ds_read_b128 v[180:183], v179 offset:17408
	ds_read_b128 v[184:187], v179 offset:18432
	ds_read_b128 v[188:191], v179 offset:19456
	ds_read_b128 v[192:195], v179 offset:20480
	ds_read_b128 v[196:199], v179 offset:21504
	ds_read_b128 v[200:203], v179 offset:22528
	ds_read_b128 v[206:209], v179 offset:23552
	global_load_lds_dwordx4 v[136:137], off
	s_add_i32 m0, s77, 0x2000
	s_add_u32 s78, s44, 0x80000
	v_lshl_add_u64 v[210:211], s[44:45], 0, v[144:145]
	s_addc_u32 s79, s45, 0
	s_add_i32 s77, s80, s52
	global_load_lds_dwordx4 v[210:211], off
	v_lshl_add_u64 v[212:213], s[78:79], 0, v[140:141]
	s_mov_b32 m0, s77
	v_lshl_add_u64 v[214:215], s[46:47], 0, v[142:143]
	global_load_lds_dwordx4 v[212:213], off
	v_lshl_add_u64 v[212:213], s[78:79], 0, v[144:145]
	s_add_i32 m0, s77, 0x2000
	s_nop 0
	global_load_lds_dwordx4 v[212:213], off
	v_lshl_add_u64 v[212:213], s[46:47], 0, v[138:139]
	s_mov_b32 m0, s53
	s_nop 0
	global_load_lds_dwordx4 v[212:213], off
	s_mov_b32 m0, s54
	s_nop 0
	global_load_lds_dwordx4 v[214:215], off
	s_waitcnt vmcnt(8)
	s_waitcnt lgkmcnt(0)
	s_setprio 1
	s_barrier
	v_mfma_f32_16x16x32_bf16 v[60:63], v[128:131], v[174:177], v[60:63]
	v_mfma_f32_16x16x32_bf16 v[56:59], v[150:153], v[174:177], v[56:59]
	v_mfma_f32_16x16x32_bf16 v[44:47], v[128:131], v[184:187], v[44:47]
	v_mfma_f32_16x16x32_bf16 v[40:43], v[150:153], v[184:187], v[40:43]
	v_mfma_f32_16x16x32_bf16 v[28:31], v[128:131], v[192:195], v[28:31]
	v_mfma_f32_16x16x32_bf16 v[24:27], v[150:153], v[192:195], v[24:27]
	v_mfma_f32_16x16x32_bf16 v[12:15], v[128:131], v[200:203], v[12:15]
	v_mfma_f32_16x16x32_bf16 v[8:11], v[150:153], v[200:203], v[8:11]
	v_mfma_f32_16x16x32_bf16 v[60:63], v[132:135], v[180:183], v[60:63]
	v_mfma_f32_16x16x32_bf16 v[56:59], v[154:157], v[180:183], v[56:59]
	v_mfma_f32_16x16x32_bf16 v[44:47], v[132:135], v[188:191], v[44:47]
	v_mfma_f32_16x16x32_bf16 v[40:43], v[154:157], v[188:191], v[40:43]
	v_mfma_f32_16x16x32_bf16 v[28:31], v[132:135], v[196:199], v[28:31]
	v_mfma_f32_16x16x32_bf16 v[24:27], v[154:157], v[196:199], v[24:27]
	v_mfma_f32_16x16x32_bf16 v[12:15], v[132:135], v[206:209], v[12:15]
	v_mfma_f32_16x16x32_bf16 v[8:11], v[154:157], v[206:209], v[8:11]
	s_setprio 0
	s_setprio 1
	v_mfma_f32_16x16x32_bf16 v[52:55], v[158:161], v[174:177], v[52:55]
	v_mfma_f32_16x16x32_bf16 v[48:51], v[166:169], v[174:177], v[48:51]
	v_mfma_f32_16x16x32_bf16 v[36:39], v[158:161], v[184:187], v[36:39]
	v_mfma_f32_16x16x32_bf16 v[32:35], v[166:169], v[184:187], v[32:35]
	v_mfma_f32_16x16x32_bf16 v[20:23], v[158:161], v[192:195], v[20:23]
	v_mfma_f32_16x16x32_bf16 v[16:19], v[166:169], v[192:195], v[16:19]
	v_mfma_f32_16x16x32_bf16 v[4:7], v[158:161], v[200:203], v[4:7]
	v_mfma_f32_16x16x32_bf16 v[0:3], v[166:169], v[200:203], v[0:3]
	v_mfma_f32_16x16x32_bf16 v[52:55], v[162:165], v[180:183], v[52:55]
	v_mfma_f32_16x16x32_bf16 v[48:51], v[170:173], v[180:183], v[48:51]
	v_mfma_f32_16x16x32_bf16 v[36:39], v[162:165], v[188:191], v[36:39]
	v_mfma_f32_16x16x32_bf16 v[32:35], v[170:173], v[188:191], v[32:35]
	v_mfma_f32_16x16x32_bf16 v[20:23], v[162:165], v[196:199], v[20:23]
	v_mfma_f32_16x16x32_bf16 v[16:19], v[170:173], v[196:199], v[16:19]
	v_mfma_f32_16x16x32_bf16 v[4:7], v[162:165], v[206:209], v[4:7]
	v_mfma_f32_16x16x32_bf16 v[0:3], v[170:173], v[206:209], v[0:3]
	s_barrier
; #define PG8_STAGE(bufoff, gbase, voff) do { _Pragma("unroll") for (int _i = 0; _i < 2; ++_i) \
;         __builtin_amdgcn_global_load_lds((const unsigned*)((const char*)(gbase) + (voff)[_i]), (PG8_LAS unsigned*)(lds + (bufoff) + ldsw + _i * 8192), 16, 0, 0); } while (0)
; #define PG8_LDA(dst, b, h) do { _Pragma("unroll") for (int m = 0; m < 4; ++m) _Pragma("unroll") for (int k = 0; k < 2; ++k) dst[m][k] = *(const PG8_LAS bf16x8*)(lds + PG8_SA(b, h) + aoff + m * 2048 + k * 1024); } while (0)
; #define PG8_LDB(dst, b, h) do { _Pragma("unroll") for (int n = 0; n < 2; ++n) _Pragma("unroll") for (int k = 0; k < 2; ++k) dst[n][k] = *(const PG8_LAS bf16x8*)(lds + PG8_SB(b, h) + boff + n * 2048 + k * 1024); } while (0)
; #define PG8_MMA(ai, bj, At, Bt) do { __builtin_amdgcn_s_setprio(1); _Pragma("unroll") for (int m = 0; m < 4; ++m) _Pragma("unroll") for (int n = 0; n < 2; ++n) _Pragma("unroll") for (int k = 0; k < 2; ++k) \
;         acc[ai][bj][m][n] = __builtin_amdgcn_mfma_f32_16x16x32_bf16(Bt[n][k], At[m][k], acc[ai][bj][m][n], 0, 0, 0); __builtin_amdgcn_s_setprio(0); } while (0)
; #define PG8_WAIT_V(n) asm volatile("s_waitcnt vmcnt(" #n ")" ::: "memory")
; #define PG8_WAIT_L(n) asm volatile("s_waitcnt lgkmcnt(" #n ")" ::: "memory")
; #define PG8_BAR __builtin_amdgcn_s_barrier()
; #define PG8_SCHED __builtin_amdgcn_sched_barrier(0)
; template <class Epi, class Sched, bool ALIGN_EPI = false, bool SP2 = false>
; __device__ __forceinline__ void gemm_phase(PG8_LAS unsigned char* lds, const Gemm g, const Sched& S, const Epi& E, const int tid) {
;     ...
;             PG8_LDB(B0, 1, 0); PG8_LDB(B1, 1, 1); PG8_SCHED; PG8_LDA(At, 1, 0); PG8_STAGE(PG8_SA(0, 1), a2 + hstep, voffA);
;             PG8_WAIT_V(8); PG8_WAIT_L(0); PG8_BAR; PG8_MMA(0, 0, At, B0); PG8_MMA(0, 1, At, B1); PG8_BAR; PG8_SCHED;
	s_setprio 0
	s_add_i32 s77, 0, 0x18000
	s_add_i32 s78, 0, 0x1c000
	v_add_u32_e32 v154, s77, v178
	v_add_u32_e32 v170, s78, v178
	ds_read_b128 v[128:131], v154
	ds_read_b128 v[132:135], v154 offset:1024
	ds_read_b128 v[150:153], v154 offset:2048
	ds_read_b128 v[154:157], v154 offset:3072
	ds_read_b128 v[158:161], v170
	ds_read_b128 v[162:165], v170 offset:1024
	ds_read_b128 v[166:169], v170 offset:2048
	ds_read_b128 v[170:173], v170 offset:3072
	s_add_u32 s46, s46, 0x80000
	s_addc_u32 s47, s47, 0
	s_mov_b32 m0, s55
	v_lshl_add_u64 v[216:217], s[46:47], 0, v[138:139]
	ds_read_b128 v[174:177], v179 offset:32768
	ds_read_b128 v[180:183], v179 offset:33792
	ds_read_b128 v[184:187], v179 offset:34816
	ds_read_b128 v[188:191], v179 offset:35840
	ds_read_b128 v[192:195], v179 offset:36864
	ds_read_b128 v[196:199], v179 offset:37888
	ds_read_b128 v[200:203], v179 offset:38912
	ds_read_b128 v[206:209], v179 offset:39936
	global_load_lds_dwordx4 v[216:217], off
	v_lshl_add_u64 v[216:217], s[46:47], 0, v[142:143]
	s_mov_b32 m0, s0
	s_nop 0
	global_load_lds_dwordx4 v[216:217], off
	s_waitcnt vmcnt(8)
	s_waitcnt lgkmcnt(0)
	s_setprio 1
	s_barrier
	v_mfma_f32_16x16x32_bf16 v[124:127], v[128:131], v[174:177], v[124:127]
	v_mfma_f32_16x16x32_bf16 v[120:123], v[150:153], v[174:177], v[120:123]
	v_mfma_f32_16x16x32_bf16 v[108:111], v[128:131], v[184:187], v[108:111]
	v_mfma_f32_16x16x32_bf16 v[104:107], v[150:153], v[184:187], v[104:107]
	v_mfma_f32_16x16x32_bf16 v[92:95], v[128:131], v[192:195], v[92:95]
	v_mfma_f32_16x16x32_bf16 v[88:91], v[150:153], v[192:195], v[88:91]
	v_mfma_f32_16x16x32_bf16 v[76:79], v[128:131], v[200:203], v[76:79]
	v_mfma_f32_16x16x32_bf16 v[72:75], v[150:153], v[200:203], v[72:75]
	v_mfma_f32_16x16x32_bf16 v[124:127], v[132:135], v[180:183], v[124:127]
	v_mfma_f32_16x16x32_bf16 v[120:123], v[154:157], v[180:183], v[120:123]
	v_mfma_f32_16x16x32_bf16 v[108:111], v[132:135], v[188:191], v[108:111]
	v_mfma_f32_16x16x32_bf16 v[104:107], v[154:157], v[188:191], v[104:107]
	v_mfma_f32_16x16x32_bf16 v[92:95], v[132:135], v[196:199], v[92:95]
	v_mfma_f32_16x16x32_bf16 v[88:91], v[154:157], v[196:199], v[88:91]
	v_mfma_f32_16x16x32_bf16 v[76:79], v[132:135], v[206:209], v[76:79]
	v_mfma_f32_16x16x32_bf16 v[72:75], v[154:157], v[206:209], v[72:75]
	s_setprio 0
	s_setprio 1
	v_mfma_f32_16x16x32_bf16 v[116:119], v[158:161], v[174:177], v[116:119]
	v_mfma_f32_16x16x32_bf16 v[112:115], v[166:169], v[174:177], v[112:115]
	v_mfma_f32_16x16x32_bf16 v[100:103], v[158:161], v[184:187], v[100:103]
	v_mfma_f32_16x16x32_bf16 v[96:99], v[166:169], v[184:187], v[96:99]
	v_mfma_f32_16x16x32_bf16 v[84:87], v[158:161], v[192:195], v[84:87]
	v_mfma_f32_16x16x32_bf16 v[80:83], v[166:169], v[192:195], v[80:83]
	v_mfma_f32_16x16x32_bf16 v[68:71], v[158:161], v[200:203], v[68:71]
	v_mfma_f32_16x16x32_bf16 v[64:67], v[166:169], v[200:203], v[64:67]
	v_mfma_f32_16x16x32_bf16 v[116:119], v[162:165], v[180:183], v[116:119]
	v_mfma_f32_16x16x32_bf16 v[112:115], v[170:173], v[180:183], v[112:115]
	v_mfma_f32_16x16x32_bf16 v[100:103], v[162:165], v[188:191], v[100:103]
	v_mfma_f32_16x16x32_bf16 v[96:99], v[170:173], v[188:191], v[96:99]
	v_mfma_f32_16x16x32_bf16 v[84:87], v[162:165], v[196:199], v[84:87]
	v_mfma_f32_16x16x32_bf16 v[80:83], v[170:173], v[196:199], v[80:83]
	v_mfma_f32_16x16x32_bf16 v[68:71], v[162:165], v[206:209], v[68:71]
	v_mfma_f32_16x16x32_bf16 v[64:67], v[170:173], v[206:209], v[64:67]
	s_barrier
; #define PG8_STAGE(bufoff, gbase, voff) do { _Pragma("unroll") for (int _i = 0; _i < 2; ++_i) \
;         __builtin_amdgcn_global_load_lds((const unsigned*)((const char*)(gbase) + (voff)[_i]), (PG8_LAS unsigned*)(lds + (bufoff) + ldsw + _i * 8192), 16, 0, 0); } while (0)
; #define PG8_LDA(dst, b, h) do { _Pragma("unroll") for (int m = 0; m < 4; ++m) _Pragma("unroll") for (int k = 0; k < 2; ++k) dst[m][k] = *(const PG8_LAS bf16x8*)(lds + PG8_SA(b, h) + aoff + m * 2048 + k * 1024); } while (0)
; #define PG8_MMA(ai, bj, At, Bt) do { __builtin_amdgcn_s_setprio(1); _Pragma("unroll") for (int m = 0; m < 4; ++m) _Pragma("unroll") for (int n = 0; n < 2; ++n) _Pragma("unroll") for (int k = 0; k < 2; ++k) \
;         acc[ai][bj][m][n] = __builtin_amdgcn_mfma_f32_16x16x32_bf16(Bt[n][k], At[m][k], acc[ai][bj][m][n], 0, 0, 0); __builtin_amdgcn_s_setprio(0); } while (0)
; #define PG8_WAIT_V(n) asm volatile("s_waitcnt vmcnt(" #n ")" ::: "memory")
; #define PG8_WAIT_L(n) asm volatile("s_waitcnt lgkmcnt(" #n ")" ::: "memory")
; #define PG8_BAR __builtin_amdgcn_s_barrier()
; #define PG8_SCHED __builtin_amdgcn_sched_barrier(0)
; template <class Epi, class Sched, bool ALIGN_EPI = false, bool SP2 = false>
; __device__ __forceinline__ void gemm_phase(PG8_LAS unsigned char* lds, const Gemm g, const Sched& S, const Epi& E, const int tid) {
;     ...
;             PG8_LDA(At, 1, 1); PG8_STAGE(PG8_SB(1, 0), b3, voffB); PG8_STAGE(PG8_SB(1, 1), b3 + hstep, voffB); PG8_STAGE(PG8_SA(1, 0), a3, voffA);
;             PG8_WAIT_V(8); PG8_WAIT_L(0); PG8_BAR; PG8_MMA(1, 0, At, B0); PG8_MMA(1, 1, At, B1); PG8_BAR; PG8_SCHED;
;     ...
;         if constexpr (ALIGN_EPI) { if (wr == 0) PG8_BAR; }
	s_setprio 0
	s_add_i32 s46, s77, s52
	v_lshl_add_u64 v[136:137], v[136:137], 0, s[70:71]
	s_mov_b32 m0, s46
	ds_read_b128 v[174:177], v179 offset:49152
	ds_read_b128 v[180:183], v179 offset:50176
	ds_read_b128 v[184:187], v179 offset:51200
	ds_read_b128 v[188:191], v179 offset:52224
	ds_read_b128 v[192:195], v179 offset:53248
	ds_read_b128 v[196:199], v179 offset:54272
	ds_read_b128 v[200:203], v179 offset:55296
	ds_read_b128 v[206:209], v179 offset:56320
	global_load_lds_dwordx4 v[136:137], off
	s_add_i32 m0, s46, 0x2000
	s_add_u32 s44, s44, 0x80080
	v_lshl_add_u64 v[136:137], v[210:211], 0, s[70:71]
	s_addc_u32 s45, s45, 0
	s_add_i32 s46, s78, s52
	global_load_lds_dwordx4 v[136:137], off
	v_lshl_add_u64 v[136:137], s[44:45], 0, v[140:141]
	s_mov_b32 m0, s46
	s_nop 0
	global_load_lds_dwordx4 v[136:137], off
	v_lshl_add_u64 v[136:137], s[44:45], 0, v[144:145]
	s_add_i32 m0, s46, 0x2000
	s_nop 0
	global_load_lds_dwordx4 v[136:137], off
	v_lshl_add_u64 v[136:137], v[212:213], 0, s[70:71]
	s_mov_b32 m0, s11
	s_nop 0
	global_load_lds_dwordx4 v[136:137], off
	v_lshl_add_u64 v[136:137], v[214:215], 0, s[70:71]
	s_mov_b32 m0, s64
	s_nop 0
	global_load_lds_dwordx4 v[136:137], off
	s_add_i32 s76, s76, 2
	s_add_u32 s42, s42, 0x100
	s_addc_u32 s43, s43, 0
	s_add_u32 s69, s69, 0x100
	s_addc_u32 s92, s92, 0
	s_waitcnt vmcnt(8)
	s_waitcnt lgkmcnt(0)
	s_setprio 1
	s_barrier
	v_mfma_f32_16x16x32_bf16 v[60:63], v[128:131], v[174:177], v[60:63]
	v_mfma_f32_16x16x32_bf16 v[56:59], v[150:153], v[174:177], v[56:59]
	v_mfma_f32_16x16x32_bf16 v[44:47], v[128:131], v[184:187], v[44:47]
	v_mfma_f32_16x16x32_bf16 v[40:43], v[150:153], v[184:187], v[40:43]
	v_mfma_f32_16x16x32_bf16 v[28:31], v[128:131], v[192:195], v[28:31]
	v_mfma_f32_16x16x32_bf16 v[24:27], v[150:153], v[192:195], v[24:27]
	v_mfma_f32_16x16x32_bf16 v[12:15], v[128:131], v[200:203], v[12:15]
	v_mfma_f32_16x16x32_bf16 v[8:11], v[150:153], v[200:203], v[8:11]
	v_mfma_f32_16x16x32_bf16 v[60:63], v[132:135], v[180:183], v[60:63]
	v_mfma_f32_16x16x32_bf16 v[56:59], v[154:157], v[180:183], v[56:59]
	v_mfma_f32_16x16x32_bf16 v[44:47], v[132:135], v[188:191], v[44:47]
	v_mfma_f32_16x16x32_bf16 v[40:43], v[154:157], v[188:191], v[40:43]
	v_mfma_f32_16x16x32_bf16 v[28:31], v[132:135], v[196:199], v[28:31]
	v_mfma_f32_16x16x32_bf16 v[24:27], v[154:157], v[196:199], v[24:27]
	v_mfma_f32_16x16x32_bf16 v[12:15], v[132:135], v[206:209], v[12:15]
	v_mfma_f32_16x16x32_bf16 v[8:11], v[154:157], v[206:209], v[8:11]
	s_setprio 0
	s_setprio 1
	v_mfma_f32_16x16x32_bf16 v[52:55], v[158:161], v[174:177], v[52:55]
	v_mfma_f32_16x16x32_bf16 v[48:51], v[166:169], v[174:177], v[48:51]
	v_mfma_f32_16x16x32_bf16 v[36:39], v[158:161], v[184:187], v[36:39]
	v_mfma_f32_16x16x32_bf16 v[32:35], v[166:169], v[184:187], v[32:35]
	v_mfma_f32_16x16x32_bf16 v[20:23], v[158:161], v[192:195], v[20:23]
	v_mfma_f32_16x16x32_bf16 v[16:19], v[166:169], v[192:195], v[16:19]
	v_mfma_f32_16x16x32_bf16 v[4:7], v[158:161], v[200:203], v[4:7]
	v_mfma_f32_16x16x32_bf16 v[0:3], v[166:169], v[200:203], v[0:3]
	v_mfma_f32_16x16x32_bf16 v[52:55], v[162:165], v[180:183], v[52:55]
	v_mfma_f32_16x16x32_bf16 v[48:51], v[170:173], v[180:183], v[48:51]
	v_mfma_f32_16x16x32_bf16 v[36:39], v[162:165], v[188:191], v[36:39]
	v_mfma_f32_16x16x32_bf16 v[32:35], v[170:173], v[188:191], v[32:35]
	v_mfma_f32_16x16x32_bf16 v[20:23], v[162:165], v[196:199], v[20:23]
	v_mfma_f32_16x16x32_bf16 v[16:19], v[170:173], v[196:199], v[16:19]
	v_mfma_f32_16x16x32_bf16 v[4:7], v[162:165], v[206:209], v[4:7]
	v_mfma_f32_16x16x32_bf16 v[0:3], v[170:173], v[206:209], v[0:3]
	s_barrier
	s_setprio 0
	s_cmp_gt_u32 s76, 29
	s_cbranch_scc0 .LBB0_319
	s_and_b64 vcc, exec, s[24:25]
	s_cbranch_vccz .LBB0_322
	s_barrier

; #define PG8_STAGE(bufoff, gbase, voff) do { _Pragma("unroll") for (int _i = 0; _i < 2; ++_i) \
;         __builtin_amdgcn_global_load_lds((const unsigned*)((const char*)(gbase) + (voff)[_i]), (PG8_LAS unsigned*)(lds + (bufoff) + ldsw + _i * 8192), 16, 0, 0); } while (0)
; #define PG8_LDA(dst, b, h) do { _Pragma("unroll") for (int m = 0; m < 4; ++m) _Pragma("unroll") for (int k = 0; k < 2; ++k) dst[m][k] = *(const PG8_LAS bf16x8*)(lds + PG8_SA(b, h) + aoff + m * 2048 + k * 1024); } while (0)
; #define PG8_LDB(dst, b, h) do { _Pragma("unroll") for (int n = 0; n < 2; ++n) _Pragma("unroll") for (int k = 0; k < 2; ++k) dst[n][k] = *(const PG8_LAS bf16x8*)(lds + PG8_SB(b, h) + boff + n * 2048 + k * 1024); } while (0)
; #define PG8_WAIT_V(n) asm volatile("s_waitcnt vmcnt(" #n ")" ::: "memory")
; #define PG8_WAIT_L(n) asm volatile("s_waitcnt lgkmcnt(" #n ")" ::: "memory")
; #define PG8_BAR __builtin_amdgcn_s_barrier()
; #define PG8_SCHED __builtin_amdgcn_sched_barrier(0)
; template <class Epi, class Sched, bool ALIGN_EPI = false, bool SP2 = false>
; __device__ __forceinline__ void gemm_phase(PG8_LAS unsigned char* lds, const Gemm g, const Sched& S, const Epi& E, const int tid) {
;     ...
;     for (;;) {
;         const bool has_next = S.next(ui + 1, nxt);
;         const char* nA = has_next ? (const char*)g.A + (size_t)nxt.pm * tstep : cA; const char* nB = has_next ? (const char*)g.Bt + (size_t)nxt.pn * tstep : cB;
;         for (int t = 0; t < nt; t += 2) {
;             const bool last = (t == nt - 2);
;             const char* a1 = cA + (size_t)(t + 1) * kstep;
;             const char* a2 = last ? nA : cA + (size_t)(t + 2) * kstep; const char* b2 = last ? nB : cB + (size_t)(t + 2) * kstep;
;             const char* a3 = a2 + kstep; const char* b3 = b2 + kstep;
;             if (last && has_next) S.a_ready(nxt);
;             if constexpr (SP2) {
;             PG8_LDB(B0, 0, 0); PG8_LDB(B1, 0, 1); PG8_SCHED; PG8_LDA(At, 0, 0); PG8_STAGE(PG8_SA(1, 1), a1 + hstep, voffA);
;             PG8_WAIT_V(8); PG8_WAIT_L(0); PG8_BAR; PG8_MMA(0, 0, At, B0); PG8_MMA(0, 1, At, B1); PG8_BAR; PG8_SCHED;
;             PG8_LDA(At, 0, 1); PG8_STAGE(PG8_SB(0, 0), b2, voffB); PG8_STAGE(PG8_SB(0, 1), b2 + hstep, voffB); PG8_STAGE(PG8_SA(0, 0), a2, voffA);
;             PG8_WAIT_V(8); PG8_WAIT_L(0); PG8_BAR; PG8_MMA(1, 0, At, B0); PG8_MMA(1, 1, At, B1); PG8_BAR; PG8_SCHED;
.LBB0_583:
	s_add_i32 s69, 0, 0x10000
	s_add_i32 s75, 0, 0x14000
	v_add_u32_e32 v140, s69, v216
	v_add_u32_e32 v156, s75, v216
	ds_read_b128 v[128:131], v140
	ds_read_b128 v[132:135], v140 offset:1024
	ds_read_b128 v[136:139], v140 offset:2048
	ds_read_b128 v[140:143], v140 offset:3072
	ds_read_b128 v[144:147], v156
	ds_read_b128 v[148:151], v156 offset:1024
	ds_read_b128 v[152:155], v156 offset:2048
	ds_read_b128 v[156:159], v156 offset:3072
	v_lshl_add_u64 v[202:203], s[34:35], 0, v[198:199]
	s_add_i32 m0, s46, 0xc000
	ds_read_b128 v[160:163], v217
	ds_read_b128 v[164:167], v217 offset:1024
	ds_read_b128 v[168:171], v217 offset:2048
	ds_read_b128 v[172:175], v217 offset:3072
	ds_read_b128 v[176:179], v217 offset:4096
	ds_read_b128 v[180:183], v217 offset:5120
	ds_read_b128 v[184:187], v217 offset:6144
	ds_read_b128 v[188:191], v217 offset:7168
	s_add_u32 s30, s34, 0xfffc0080
	s_addc_u32 s31, s35, -1
	s_cmp_eq_u32 s68, 12
	s_cselect_b32 s37, s21, s31
	s_cselect_b32 s36, s40, s30
	s_cselect_b32 s31, s19, s65
	s_cselect_b32 s30, s62, s64
	global_load_lds_dwordx4 v[202:203], off
	v_lshl_add_u64 v[202:203], s[34:35], 0, v[200:201]
	s_add_i32 m0, s46, 0xe000
	s_nop 0
	global_load_lds_dwordx4 v[202:203], off
	s_waitcnt vmcnt(8)
	s_waitcnt lgkmcnt(0)
	s_setprio 1
	s_barrier
	v_mfma_f32_16x16x32_bf16 v[120:123], v[128:131], v[160:163], v[120:123]
	v_mfma_f32_16x16x32_bf16 v[124:127], v[136:139], v[160:163], v[124:127]
	v_mfma_f32_16x16x32_bf16 v[104:107], v[128:131], v[168:171], v[104:107]
	v_mfma_f32_16x16x32_bf16 v[108:111], v[136:139], v[168:171], v[108:111]
	v_mfma_f32_16x16x32_bf16 v[88:91], v[128:131], v[176:179], v[88:91]
	v_mfma_f32_16x16x32_bf16 v[92:95], v[136:139], v[176:179], v[92:95]
	v_mfma_f32_16x16x32_bf16 v[72:75], v[128:131], v[184:187], v[72:75]
	v_mfma_f32_16x16x32_bf16 v[76:79], v[136:139], v[184:187], v[76:79]
	v_mfma_f32_16x16x32_bf16 v[120:123], v[132:135], v[164:167], v[120:123]
	v_mfma_f32_16x16x32_bf16 v[124:127], v[140:143], v[164:167], v[124:127]
	v_mfma_f32_16x16x32_bf16 v[104:107], v[132:135], v[172:175], v[104:107]
	v_mfma_f32_16x16x32_bf16 v[108:111], v[140:143], v[172:175], v[108:111]
	v_mfma_f32_16x16x32_bf16 v[88:91], v[132:135], v[180:183], v[88:91]
	v_mfma_f32_16x16x32_bf16 v[92:95], v[140:143], v[180:183], v[92:95]
	v_mfma_f32_16x16x32_bf16 v[72:75], v[132:135], v[188:191], v[72:75]
	v_mfma_f32_16x16x32_bf16 v[76:79], v[140:143], v[188:191], v[76:79]
	s_setprio 0
	s_setprio 1
	v_mfma_f32_16x16x32_bf16 v[112:115], v[144:147], v[160:163], v[112:115]
	v_mfma_f32_16x16x32_bf16 v[116:119], v[152:155], v[160:163], v[116:119]
	v_mfma_f32_16x16x32_bf16 v[96:99], v[144:147], v[168:171], v[96:99]
	v_mfma_f32_16x16x32_bf16 v[100:103], v[152:155], v[168:171], v[100:103]
	v_mfma_f32_16x16x32_bf16 v[80:83], v[144:147], v[176:179], v[80:83]
	v_mfma_f32_16x16x32_bf16 v[84:87], v[152:155], v[176:179], v[84:87]
	v_mfma_f32_16x16x32_bf16 v[60:63], v[144:147], v[184:187], v[60:63]
	v_mfma_f32_16x16x32_bf16 v[68:71], v[152:155], v[184:187], v[68:71]
	v_mfma_f32_16x16x32_bf16 v[112:115], v[148:151], v[164:167], v[112:115]
	v_mfma_f32_16x16x32_bf16 v[116:119], v[156:159], v[164:167], v[116:119]
	v_mfma_f32_16x16x32_bf16 v[96:99], v[148:151], v[172:175], v[96:99]
	v_mfma_f32_16x16x32_bf16 v[100:103], v[156:159], v[172:175], v[100:103]
	v_mfma_f32_16x16x32_bf16 v[80:83], v[148:151], v[180:183], v[80:83]
	v_mfma_f32_16x16x32_bf16 v[84:87], v[156:159], v[180:183], v[84:87]
	v_mfma_f32_16x16x32_bf16 v[60:63], v[148:151], v[188:191], v[60:63]
	v_mfma_f32_16x16x32_bf16 v[68:71], v[156:159], v[188:191], v[68:71]
	s_barrier
	s_setprio 0
	s_add_i32 s69, s69, s43
	v_lshl_add_u64 v[202:203], s[30:31], 0, v[204:205]
	s_mov_b32 m0, s69
	ds_read_b128 v[160:163], v217 offset:16384
	ds_read_b128 v[164:167], v217 offset:17408
	ds_read_b128 v[168:171], v217 offset:18432
	ds_read_b128 v[172:175], v217 offset:19456
	ds_read_b128 v[176:179], v217 offset:20480
	ds_read_b128 v[180:183], v217 offset:21504
	ds_read_b128 v[184:187], v217 offset:22528
	ds_read_b128 v[188:191], v217 offset:23552
	global_load_lds_dwordx4 v[202:203], off
	s_add_i32 m0, s69, 0x2000
	s_add_u32 s76, s30, 0x40000
	v_lshl_add_u64 v[206:207], s[30:31], 0, v[196:197]
	s_addc_u32 s77, s31, 0
	s_add_i32 s69, s75, s43
	global_load_lds_dwordx4 v[206:207], off
	v_lshl_add_u64 v[208:209], s[76:77], 0, v[204:205]
	s_mov_b32 m0, s69
	v_lshl_add_u64 v[210:211], s[36:37], 0, v[194:195]
	global_load_lds_dwordx4 v[208:209], off
	v_lshl_add_u64 v[208:209], s[76:77], 0, v[196:197]
	s_add_i32 m0, s69, 0x2000
	s_nop 0
	global_load_lds_dwordx4 v[208:209], off
	v_lshl_add_u64 v[208:209], s[36:37], 0, v[192:193]
	s_mov_b32 m0, s46
	s_nop 0
	global_load_lds_dwordx4 v[208:209], off
	s_mov_b32 m0, s47
	s_nop 0
	global_load_lds_dwordx4 v[210:211], off
	s_waitcnt vmcnt(8)
	s_waitcnt lgkmcnt(0)
	s_setprio 1
	s_barrier
; #define PG8_STAGE(bufoff, gbase, voff) do { _Pragma("unroll") for (int _i = 0; _i < 2; ++_i) \
;         __builtin_amdgcn_global_load_lds((const unsigned*)((const char*)(gbase) + (voff)[_i]), (PG8_LAS unsigned*)(lds + (bufoff) + ldsw + _i * 8192), 16, 0, 0); } while (0)
; #define PG8_LDA(dst, b, h) do { _Pragma("unroll") for (int m = 0; m < 4; ++m) _Pragma("unroll") for (int k = 0; k < 2; ++k) dst[m][k] = *(const PG8_LAS bf16x8*)(lds + PG8_SA(b, h) + aoff + m * 2048 + k * 1024); } while (0)
; #define PG8_LDB(dst, b, h) do { _Pragma("unroll") for (int n = 0; n < 2; ++n) _Pragma("unroll") for (int k = 0; k < 2; ++k) dst[n][k] = *(const PG8_LAS bf16x8*)(lds + PG8_SB(b, h) + boff + n * 2048 + k * 1024); } while (0)
; #define PG8_MMA(ai, bj, At, Bt) do { __builtin_amdgcn_s_setprio(1); _Pragma("unroll") for (int m = 0; m < 4; ++m) _Pragma("unroll") for (int n = 0; n < 2; ++n) _Pragma("unroll") for (int k = 0; k < 2; ++k) \
;         acc[ai][bj][m][n] = __builtin_amdgcn_mfma_f32_16x16x32_bf16(Bt[n][k], At[m][k], acc[ai][bj][m][n], 0, 0, 0); __builtin_amdgcn_s_setprio(0); } while (0)
; #define PG8_WAIT_V(n) asm volatile("s_waitcnt vmcnt(" #n ")" ::: "memory")
; #define PG8_WAIT_L(n) asm volatile("s_waitcnt lgkmcnt(" #n ")" ::: "memory")
; #define PG8_BAR __builtin_amdgcn_s_barrier()
; #define PG8_SCHED __builtin_amdgcn_sched_barrier(0)
; template <class Epi, class Sched, bool ALIGN_EPI = false, bool SP2 = false>
; __device__ __forceinline__ void gemm_phase(PG8_LAS unsigned char* lds, const Gemm g, const Sched& S, const Epi& E, const int tid) {
;     ...
;             PG8_WAIT_V(8); PG8_WAIT_L(0); PG8_BAR; PG8_MMA(1, 0, At, B0); PG8_MMA(1, 1, At, B1); PG8_BAR; PG8_SCHED;
;             PG8_LDB(B0, 1, 0); PG8_LDB(B1, 1, 1); PG8_SCHED; PG8_LDA(At, 1, 0); PG8_STAGE(PG8_SA(0, 1), a2 + hstep, voffA);
;             PG8_WAIT_V(8); PG8_WAIT_L(0); PG8_BAR; PG8_MMA(0, 0, At, B0); PG8_MMA(0, 1, At, B1); PG8_BAR; PG8_SCHED;
	v_mfma_f32_16x16x32_bf16 v[48:51], v[128:131], v[160:163], v[48:51]
	v_mfma_f32_16x16x32_bf16 v[56:59], v[136:139], v[160:163], v[56:59]
	v_mfma_f32_16x16x32_bf16 v[20:23], v[128:131], v[168:171], v[20:23]
	v_mfma_f32_16x16x32_bf16 v[64:67], v[136:139], v[168:171], v[64:67]
	v_mfma_f32_16x16x32_bf16 v[28:31], v[128:131], v[176:179], v[28:31]
	v_mfma_f32_16x16x32_bf16 v[36:39], v[136:139], v[176:179], v[36:39]
	v_mfma_f32_16x16x32_bf16 v[8:11], v[128:131], v[184:187], v[8:11]
	v_mfma_f32_16x16x32_bf16 v[12:15], v[136:139], v[184:187], v[12:15]
	v_mfma_f32_16x16x32_bf16 v[48:51], v[132:135], v[164:167], v[48:51]
	v_mfma_f32_16x16x32_bf16 v[56:59], v[140:143], v[164:167], v[56:59]
	v_mfma_f32_16x16x32_bf16 v[20:23], v[132:135], v[172:175], v[20:23]
	v_mfma_f32_16x16x32_bf16 v[64:67], v[140:143], v[172:175], v[64:67]
	v_mfma_f32_16x16x32_bf16 v[28:31], v[132:135], v[180:183], v[28:31]
	v_mfma_f32_16x16x32_bf16 v[36:39], v[140:143], v[180:183], v[36:39]
	v_mfma_f32_16x16x32_bf16 v[8:11], v[132:135], v[188:191], v[8:11]
	v_mfma_f32_16x16x32_bf16 v[12:15], v[140:143], v[188:191], v[12:15]
	s_setprio 0
	s_setprio 1
	v_mfma_f32_16x16x32_bf16 v[32:35], v[144:147], v[160:163], v[32:35]
	v_mfma_f32_16x16x32_bf16 v[40:43], v[152:155], v[160:163], v[40:43]
	v_mfma_f32_16x16x32_bf16 v[44:47], v[144:147], v[168:171], v[44:47]
	v_mfma_f32_16x16x32_bf16 v[52:55], v[152:155], v[168:171], v[52:55]
	v_mfma_f32_16x16x32_bf16 v[16:19], v[144:147], v[176:179], v[16:19]
	v_mfma_f32_16x16x32_bf16 v[24:27], v[152:155], v[176:179], v[24:27]
	v_mfma_f32_16x16x32_bf16 v[0:3], v[144:147], v[184:187], v[0:3]
	v_mfma_f32_16x16x32_bf16 v[4:7], v[152:155], v[184:187], v[4:7]
	v_mfma_f32_16x16x32_bf16 v[32:35], v[148:151], v[164:167], v[32:35]
	v_mfma_f32_16x16x32_bf16 v[40:43], v[156:159], v[164:167], v[40:43]
	v_mfma_f32_16x16x32_bf16 v[44:47], v[148:151], v[172:175], v[44:47]
	v_mfma_f32_16x16x32_bf16 v[52:55], v[156:159], v[172:175], v[52:55]
	v_mfma_f32_16x16x32_bf16 v[16:19], v[148:151], v[180:183], v[16:19]
	v_mfma_f32_16x16x32_bf16 v[24:27], v[156:159], v[180:183], v[24:27]
	v_mfma_f32_16x16x32_bf16 v[0:3], v[148:151], v[188:191], v[0:3]
	v_mfma_f32_16x16x32_bf16 v[4:7], v[156:159], v[188:191], v[4:7]
	s_barrier
	s_setprio 0
	s_add_i32 s69, 0, 0x18000
	s_add_i32 s75, 0, 0x1c000
	v_add_u32_e32 v140, s69, v216
	v_add_u32_e32 v156, s75, v216
	ds_read_b128 v[128:131], v140
	ds_read_b128 v[132:135], v140 offset:1024
	ds_read_b128 v[136:139], v140 offset:2048
	ds_read_b128 v[140:143], v140 offset:3072
	ds_read_b128 v[144:147], v156
	ds_read_b128 v[148:151], v156 offset:1024
	ds_read_b128 v[152:155], v156 offset:2048
	ds_read_b128 v[156:159], v156 offset:3072
	s_add_u32 s36, s36, 0x40000
	s_addc_u32 s37, s37, 0
	s_mov_b32 m0, s48
	v_lshl_add_u64 v[212:213], s[36:37], 0, v[192:193]
	ds_read_b128 v[160:163], v217 offset:32768
	ds_read_b128 v[164:167], v217 offset:33792
	ds_read_b128 v[168:171], v217 offset:34816
	ds_read_b128 v[172:175], v217 offset:35840
	ds_read_b128 v[176:179], v217 offset:36864
	ds_read_b128 v[180:183], v217 offset:37888
	ds_read_b128 v[184:187], v217 offset:38912
	ds_read_b128 v[188:191], v217 offset:39936
	global_load_lds_dwordx4 v[212:213], off
	v_lshl_add_u64 v[212:213], s[36:37], 0, v[194:195]
	s_mov_b32 m0, s49
	s_nop 0
	global_load_lds_dwordx4 v[212:213], off
	s_waitcnt vmcnt(8)
	s_waitcnt lgkmcnt(0)
	s_setprio 1
	s_barrier
	v_mfma_f32_16x16x32_bf16 v[120:123], v[128:131], v[160:163], v[120:123]
	v_mfma_f32_16x16x32_bf16 v[124:127], v[136:139], v[160:163], v[124:127]
	v_mfma_f32_16x16x32_bf16 v[104:107], v[128:131], v[168:171], v[104:107]
	v_mfma_f32_16x16x32_bf16 v[108:111], v[136:139], v[168:171], v[108:111]
	v_mfma_f32_16x16x32_bf16 v[88:91], v[128:131], v[176:179], v[88:91]
	v_mfma_f32_16x16x32_bf16 v[92:95], v[136:139], v[176:179], v[92:95]
	v_mfma_f32_16x16x32_bf16 v[72:75], v[128:131], v[184:187], v[72:75]
	v_mfma_f32_16x16x32_bf16 v[76:79], v[136:139], v[184:187], v[76:79]
	v_mfma_f32_16x16x32_bf16 v[120:123], v[132:135], v[164:167], v[120:123]
	v_mfma_f32_16x16x32_bf16 v[124:127], v[140:143], v[164:167], v[124:127]
	v_mfma_f32_16x16x32_bf16 v[104:107], v[132:135], v[172:175], v[104:107]
	v_mfma_f32_16x16x32_bf16 v[108:111], v[140:143], v[172:175], v[108:111]
	v_mfma_f32_16x16x32_bf16 v[88:91], v[132:135], v[180:183], v[88:91]
	v_mfma_f32_16x16x32_bf16 v[92:95], v[140:143], v[180:183], v[92:95]
	v_mfma_f32_16x16x32_bf16 v[72:75], v[132:135], v[188:191], v[72:75]
	v_mfma_f32_16x16x32_bf16 v[76:79], v[140:143], v[188:191], v[76:79]
	s_setprio 0
	s_setprio 1
	v_mfma_f32_16x16x32_bf16 v[112:115], v[144:147], v[160:163], v[112:115]
	v_mfma_f32_16x16x32_bf16 v[116:119], v[152:155], v[160:163], v[116:119]
	v_mfma_f32_16x16x32_bf16 v[96:99], v[144:147], v[168:171], v[96:99]
	v_mfma_f32_16x16x32_bf16 v[100:103], v[152:155], v[168:171], v[100:103]
	v_mfma_f32_16x16x32_bf16 v[80:83], v[144:147], v[176:179], v[80:83]
	v_mfma_f32_16x16x32_bf16 v[84:87], v[152:155], v[176:179], v[84:87]
	v_mfma_f32_16x16x32_bf16 v[60:63], v[144:147], v[184:187], v[60:63]
	v_mfma_f32_16x16x32_bf16 v[68:71], v[152:155], v[184:187], v[68:71]
	v_mfma_f32_16x16x32_bf16 v[112:115], v[148:151], v[164:167], v[112:115]
	v_mfma_f32_16x16x32_bf16 v[116:119], v[156:159], v[164:167], v[116:119]
	v_mfma_f32_16x16x32_bf16 v[96:99], v[148:151], v[172:175], v[96:99]
	v_mfma_f32_16x16x32_bf16 v[100:103], v[156:159], v[172:175], v[100:103]
	v_mfma_f32_16x16x32_bf16 v[80:83], v[148:151], v[180:183], v[80:83]
	v_mfma_f32_16x16x32_bf16 v[84:87], v[156:159], v[180:183], v[84:87]
	v_mfma_f32_16x16x32_bf16 v[60:63], v[148:151], v[188:191], v[60:63]
	v_mfma_f32_16x16x32_bf16 v[68:71], v[156:159], v[188:191], v[68:71]
	s_barrier
; #define PG8_STAGE(bufoff, gbase, voff) do { _Pragma("unroll") for (int _i = 0; _i < 2; ++_i) \
;         __builtin_amdgcn_global_load_lds((const unsigned*)((const char*)(gbase) + (voff)[_i]), (PG8_LAS unsigned*)(lds + (bufoff) + ldsw + _i * 8192), 16, 0, 0); } while (0)
; #define PG8_LDA(dst, b, h) do { _Pragma("unroll") for (int m = 0; m < 4; ++m) _Pragma("unroll") for (int k = 0; k < 2; ++k) dst[m][k] = *(const PG8_LAS bf16x8*)(lds + PG8_SA(b, h) + aoff + m * 2048 + k * 1024); } while (0)
; #define PG8_MMA(ai, bj, At, Bt) do { __builtin_amdgcn_s_setprio(1); _Pragma("unroll") for (int m = 0; m < 4; ++m) _Pragma("unroll") for (int n = 0; n < 2; ++n) _Pragma("unroll") for (int k = 0; k < 2; ++k) \
;         acc[ai][bj][m][n] = __builtin_amdgcn_mfma_f32_16x16x32_bf16(Bt[n][k], At[m][k], acc[ai][bj][m][n], 0, 0, 0); __builtin_amdgcn_s_setprio(0); } while (0)
; #define PG8_WAIT_V(n) asm volatile("s_waitcnt vmcnt(" #n ")" ::: "memory")
; #define PG8_WAIT_L(n) asm volatile("s_waitcnt lgkmcnt(" #n ")" ::: "memory")
; #define PG8_BAR __builtin_amdgcn_s_barrier()
; #define PG8_SCHED __builtin_amdgcn_sched_barrier(0)
; template <class Epi, class Sched, bool ALIGN_EPI = false, bool SP2 = false>
; __device__ __forceinline__ void gemm_phase(PG8_LAS unsigned char* lds, const Gemm g, const Sched& S, const Epi& E, const int tid) {
;     ...
;         for (int t = 0; t < nt; t += 2) {
;             const bool last = (t == nt - 2);
;             const char* a1 = cA + (size_t)(t + 1) * kstep;
;             const char* a2 = last ? nA : cA + (size_t)(t + 2) * kstep; const char* b2 = last ? nB : cB + (size_t)(t + 2) * kstep;
;     ...
;             PG8_LDA(At, 1, 1); PG8_STAGE(PG8_SB(1, 0), b3, voffB); PG8_STAGE(PG8_SB(1, 1), b3 + hstep, voffB); PG8_STAGE(PG8_SA(1, 0), a3, voffA);
;             PG8_WAIT_V(8); PG8_WAIT_L(0); PG8_BAR; PG8_MMA(1, 0, At, B0); PG8_MMA(1, 1, At, B1); PG8_BAR; PG8_SCHED;
	s_setprio 0
	s_add_i32 s36, s69, s43
	v_lshl_add_u64 v[202:203], v[202:203], 0, s[70:71]
	s_mov_b32 m0, s36
	ds_read_b128 v[160:163], v217 offset:49152
	ds_read_b128 v[164:167], v217 offset:50176
	ds_read_b128 v[168:171], v217 offset:51200
	ds_read_b128 v[172:175], v217 offset:52224
	ds_read_b128 v[176:179], v217 offset:53248
	ds_read_b128 v[180:183], v217 offset:54272
	ds_read_b128 v[184:187], v217 offset:55296
	ds_read_b128 v[188:191], v217 offset:56320
	global_load_lds_dwordx4 v[202:203], off
	s_add_i32 m0, s36, 0x2000
	s_add_u32 s30, s30, 0x40080
	v_lshl_add_u64 v[202:203], v[206:207], 0, s[70:71]
	s_addc_u32 s31, s31, 0
	s_add_i32 s36, s75, s43
	global_load_lds_dwordx4 v[202:203], off
	v_lshl_add_u64 v[202:203], s[30:31], 0, v[204:205]
	s_mov_b32 m0, s36
	s_nop 0
	global_load_lds_dwordx4 v[202:203], off
	v_lshl_add_u64 v[202:203], s[30:31], 0, v[196:197]
	s_add_i32 m0, s36, 0x2000
	s_nop 0
	global_load_lds_dwordx4 v[202:203], off
	v_lshl_add_u64 v[202:203], v[208:209], 0, s[70:71]
	s_mov_b32 m0, s51
	s_nop 0
	global_load_lds_dwordx4 v[202:203], off
	v_lshl_add_u64 v[202:203], v[210:211], 0, s[70:71]
	s_mov_b32 m0, s52
	s_nop 0
	global_load_lds_dwordx4 v[202:203], off
	s_add_i32 s68, s68, 2
	s_add_u32 s34, s34, 0x100
	s_addc_u32 s35, s35, 0
	s_add_u32 s64, s64, 0x100
	s_addc_u32 s65, s65, 0
	s_waitcnt vmcnt(8)
	s_waitcnt lgkmcnt(0)
	s_setprio 1
	s_barrier
	v_mfma_f32_16x16x32_bf16 v[48:51], v[128:131], v[160:163], v[48:51]
	v_mfma_f32_16x16x32_bf16 v[56:59], v[136:139], v[160:163], v[56:59]
	v_mfma_f32_16x16x32_bf16 v[20:23], v[128:131], v[168:171], v[20:23]
	v_mfma_f32_16x16x32_bf16 v[64:67], v[136:139], v[168:171], v[64:67]
	v_mfma_f32_16x16x32_bf16 v[28:31], v[128:131], v[176:179], v[28:31]
	v_mfma_f32_16x16x32_bf16 v[36:39], v[136:139], v[176:179], v[36:39]
	v_mfma_f32_16x16x32_bf16 v[8:11], v[128:131], v[184:187], v[8:11]
	v_mfma_f32_16x16x32_bf16 v[12:15], v[136:139], v[184:187], v[12:15]
	v_mfma_f32_16x16x32_bf16 v[48:51], v[132:135], v[164:167], v[48:51]
	v_mfma_f32_16x16x32_bf16 v[56:59], v[140:143], v[164:167], v[56:59]
	v_mfma_f32_16x16x32_bf16 v[20:23], v[132:135], v[172:175], v[20:23]
	v_mfma_f32_16x16x32_bf16 v[64:67], v[140:143], v[172:175], v[64:67]
	v_mfma_f32_16x16x32_bf16 v[28:31], v[132:135], v[180:183], v[28:31]
	v_mfma_f32_16x16x32_bf16 v[36:39], v[140:143], v[180:183], v[36:39]
	v_mfma_f32_16x16x32_bf16 v[8:11], v[132:135], v[188:191], v[8:11]
	v_mfma_f32_16x16x32_bf16 v[12:15], v[140:143], v[188:191], v[12:15]
	s_setprio 0
	s_setprio 1
	v_mfma_f32_16x16x32_bf16 v[32:35], v[144:147], v[160:163], v[32:35]
	v_mfma_f32_16x16x32_bf16 v[40:43], v[152:155], v[160:163], v[40:43]
	v_mfma_f32_16x16x32_bf16 v[44:47], v[144:147], v[168:171], v[44:47]
	v_mfma_f32_16x16x32_bf16 v[52:55], v[152:155], v[168:171], v[52:55]
	v_mfma_f32_16x16x32_bf16 v[16:19], v[144:147], v[176:179], v[16:19]
	v_mfma_f32_16x16x32_bf16 v[24:27], v[152:155], v[176:179], v[24:27]
	v_mfma_f32_16x16x32_bf16 v[0:3], v[144:147], v[184:187], v[0:3]
	v_mfma_f32_16x16x32_bf16 v[4:7], v[152:155], v[184:187], v[4:7]
	v_mfma_f32_16x16x32_bf16 v[32:35], v[148:151], v[164:167], v[32:35]
	v_mfma_f32_16x16x32_bf16 v[40:43], v[156:159], v[164:167], v[40:43]
	v_mfma_f32_16x16x32_bf16 v[44:47], v[148:151], v[172:175], v[44:47]
	v_mfma_f32_16x16x32_bf16 v[52:55], v[156:159], v[172:175], v[52:55]
	v_mfma_f32_16x16x32_bf16 v[16:19], v[148:151], v[180:183], v[16:19]
	v_mfma_f32_16x16x32_bf16 v[24:27], v[156:159], v[180:183], v[24:27]
	v_mfma_f32_16x16x32_bf16 v[0:3], v[148:151], v[188:191], v[0:3]
	v_mfma_f32_16x16x32_bf16 v[4:7], v[156:159], v[188:191], v[4:7]
	s_barrier
	s_setprio 0
	s_cmp_gt_u32 s68, 13
	s_cbranch_scc0 .LBB0_583
	s_and_b64 vcc, exec, s[16:17]
	s_cbranch_vccz .LBB0_586
	s_barrier

; #define PG8_STAGE(bufoff, gbase, voff) do { _Pragma("unroll") for (int _i = 0; _i < 2; ++_i) \
;         __builtin_amdgcn_global_load_lds((const unsigned*)((const char*)(gbase) + (voff)[_i]), (PG8_LAS unsigned*)(lds + (bufoff) + ldsw + _i * 8192), 16, 0, 0); } while (0)
; #define PG8_LDA(dst, b, h) do { _Pragma("unroll") for (int m = 0; m < 4; ++m) _Pragma("unroll") for (int k = 0; k < 2; ++k) dst[m][k] = *(const PG8_LAS bf16x8*)(lds + PG8_SA(b, h) + aoff + m * 2048 + k * 1024); } while (0)
; #define PG8_LDB(dst, b, h) do { _Pragma("unroll") for (int n = 0; n < 2; ++n) _Pragma("unroll") for (int k = 0; k < 2; ++k) dst[n][k] = *(const PG8_LAS bf16x8*)(lds + PG8_SB(b, h) + boff + n * 2048 + k * 1024); } while (0)
; #define PG8_WAIT_V(n) asm volatile("s_waitcnt vmcnt(" #n ")" ::: "memory")
; #define PG8_WAIT_L(n) asm volatile("s_waitcnt lgkmcnt(" #n ")" ::: "memory")
; #define PG8_BAR __builtin_amdgcn_s_barrier()
; #define PG8_SCHED __builtin_amdgcn_sched_barrier(0)
; template <class Epi, class Sched, bool ALIGN_EPI = false, bool SP2 = false>
; __device__ __forceinline__ void gemm_phase(PG8_LAS unsigned char* lds, const Gemm g, const Sched& S, const Epi& E, const int tid) {
;     ...
;         const bool has_next = S.next(ui + 1, nxt);
;         const char* nA = has_next ? (const char*)g.A + (size_t)nxt.pm * tstep : cA; const char* nB = has_next ? (const char*)g.Bt + (size_t)nxt.pn * tstep : cB;
;         for (int t = 0; t < nt; t += 2) {
;             const bool last = (t == nt - 2);
;             const char* a1 = cA + (size_t)(t + 1) * kstep;
;             const char* a2 = last ? nA : cA + (size_t)(t + 2) * kstep; const char* b2 = last ? nB : cB + (size_t)(t + 2) * kstep;
;             const char* a3 = a2 + kstep; const char* b3 = b2 + kstep;
;             if (last && has_next) S.a_ready(nxt);
;             if constexpr (SP2) {
;             PG8_LDB(B0, 0, 0); PG8_LDB(B1, 0, 1); PG8_SCHED; PG8_LDA(At, 0, 0); PG8_STAGE(PG8_SA(1, 1), a1 + hstep, voffA);
;             PG8_WAIT_V(8); PG8_WAIT_L(0); PG8_BAR; PG8_MMA(0, 0, At, B0); PG8_MMA(0, 1, At, B1); PG8_BAR; PG8_SCHED;
;             PG8_LDA(At, 0, 1); PG8_STAGE(PG8_SB(0, 0), b2, voffB); PG8_STAGE(PG8_SB(0, 1), b2 + hstep, voffB); PG8_STAGE(PG8_SA(0, 0), a2, voffA);
;             PG8_WAIT_V(8); PG8_WAIT_L(0); PG8_BAR; PG8_MMA(1, 0, At, B0); PG8_MMA(1, 1, At, B1); PG8_BAR; PG8_SCHED;
.LBB0_660:
	s_ashr_i32 s19, s18, 31
	s_lshl_b64 s[20:21], s[18:19], 20
	s_add_u32 s20, s10, s20
	s_addc_u32 s21, s11, s21
	s_and_b64 s[22:23], s[4:5], exec
	s_cselect_b32 s19, s21, s27
	s_cselect_b32 s50, s20, s26
	s_ashr_i32 s17, s16, 31
	s_lshl_b64 s[22:23], s[16:17], 20
	s_add_u32 s22, s33, s22
	s_addc_u32 s23, s34, s23
	s_and_b64 s[30:31], s[4:5], exec
	s_cselect_b32 s17, s23, s29
	s_cselect_b32 s51, s22, s28
	s_add_u32 s26, s26, 0x80080
	s_addc_u32 s27, s27, 0
	s_add_u32 s52, s28, 0x100
	s_addc_u32 s53, s29, 0
	s_mov_b32 s54, -2
	s_add_i32 s55, 0, 0x10000
	v_add_u32_e32 v138, s55, v139
	s_add_i32 s62, 0, 0x14000
	ds_read_b128 v[144:147], v138
	ds_read_b128 v[148:151], v138 offset:1024
	ds_read_b128 v[152:155], v138 offset:2048
	ds_read_b128 v[156:159], v138 offset:3072
	v_add_u32_e32 v138, s62, v139
	ds_read_b128 v[160:163], v138
	ds_read_b128 v[164:167], v138 offset:1024
	ds_read_b128 v[168:171], v138 offset:2048
	ds_read_b128 v[172:175], v138 offset:3072
	v_lshl_add_u64 v[140:141], s[26:27], 0, v[134:135]
	s_add_i32 m0, s37, 0xc000
	ds_read_b128 v[176:179], v143
	ds_read_b128 v[180:183], v143 offset:1024
	ds_read_b128 v[184:187], v143 offset:2048
	ds_read_b128 v[188:191], v143 offset:3072
	ds_read_b128 v[192:195], v143 offset:4096
	ds_read_b128 v[196:199], v143 offset:5120
	ds_read_b128 v[200:203], v143 offset:6144
	ds_read_b128 v[206:209], v143 offset:7168
	s_add_u32 s28, s26, 0xfff80080
	s_addc_u32 s29, s27, -1
	s_cmp_eq_u32 s54, 28
	s_cselect_b32 s31, s19, s29
	s_cselect_b32 s30, s50, s28
	s_cselect_b32 s29, s17, s53
	s_cselect_b32 s28, s51, s52
	global_load_lds_dwordx4 v[140:141], off
	v_lshl_add_u64 v[140:141], s[26:27], 0, v[136:137]
	s_add_i32 m0, s37, 0xe000
	s_nop 0
	global_load_lds_dwordx4 v[140:141], off
	s_waitcnt vmcnt(24)
	s_waitcnt lgkmcnt(0)
	s_setprio 1
	s_barrier
	v_mfma_f32_16x16x32_bf16 v[124:127], v[144:147], v[176:179], 0
	v_mfma_f32_16x16x32_bf16 v[120:123], v[152:155], v[176:179], 0
	v_mfma_f32_16x16x32_bf16 v[108:111], v[144:147], v[184:187], 0
	v_mfma_f32_16x16x32_bf16 v[104:107], v[152:155], v[184:187], 0
	v_mfma_f32_16x16x32_bf16 v[92:95], v[144:147], v[192:195], 0
	v_mfma_f32_16x16x32_bf16 v[88:91], v[152:155], v[192:195], 0
	v_mfma_f32_16x16x32_bf16 v[76:79], v[144:147], v[200:203], 0
	v_mfma_f32_16x16x32_bf16 v[72:75], v[152:155], v[200:203], 0
	v_mfma_f32_16x16x32_bf16 v[124:127], v[148:151], v[180:183], v[124:127]
	v_mfma_f32_16x16x32_bf16 v[120:123], v[156:159], v[180:183], v[120:123]
	v_mfma_f32_16x16x32_bf16 v[108:111], v[148:151], v[188:191], v[108:111]
	v_mfma_f32_16x16x32_bf16 v[104:107], v[156:159], v[188:191], v[104:107]
	v_mfma_f32_16x16x32_bf16 v[92:95], v[148:151], v[196:199], v[92:95]
	v_mfma_f32_16x16x32_bf16 v[88:91], v[156:159], v[196:199], v[88:91]
	v_mfma_f32_16x16x32_bf16 v[76:79], v[148:151], v[206:209], v[76:79]
	v_mfma_f32_16x16x32_bf16 v[72:75], v[156:159], v[206:209], v[72:75]
	s_setprio 0
	s_setprio 1
	v_mfma_f32_16x16x32_bf16 v[116:119], v[160:163], v[176:179], 0
	v_mfma_f32_16x16x32_bf16 v[112:115], v[168:171], v[176:179], 0
	v_mfma_f32_16x16x32_bf16 v[100:103], v[160:163], v[184:187], 0
	v_mfma_f32_16x16x32_bf16 v[96:99], v[168:171], v[184:187], 0
	v_mfma_f32_16x16x32_bf16 v[84:87], v[160:163], v[192:195], 0
	v_mfma_f32_16x16x32_bf16 v[80:83], v[168:171], v[192:195], 0
	v_mfma_f32_16x16x32_bf16 v[68:71], v[160:163], v[200:203], 0
	v_mfma_f32_16x16x32_bf16 v[64:67], v[168:171], v[200:203], 0
	v_mfma_f32_16x16x32_bf16 v[116:119], v[164:167], v[180:183], v[116:119]
	v_mfma_f32_16x16x32_bf16 v[112:115], v[172:175], v[180:183], v[112:115]
	v_mfma_f32_16x16x32_bf16 v[100:103], v[164:167], v[188:191], v[100:103]
	v_mfma_f32_16x16x32_bf16 v[96:99], v[172:175], v[188:191], v[96:99]
	v_mfma_f32_16x16x32_bf16 v[84:87], v[164:167], v[196:199], v[84:87]
	v_mfma_f32_16x16x32_bf16 v[80:83], v[172:175], v[196:199], v[80:83]
	v_mfma_f32_16x16x32_bf16 v[68:71], v[164:167], v[206:209], v[68:71]
	v_mfma_f32_16x16x32_bf16 v[64:67], v[172:175], v[206:209], v[64:67]
	s_barrier
	s_setprio 0
	s_add_i32 s55, s55, s35
	v_lshl_add_u64 v[140:141], s[28:29], 0, v[204:205]
	s_mov_b32 m0, s55
	ds_read_b128 v[176:179], v143 offset:16384
	ds_read_b128 v[180:183], v143 offset:17408
	ds_read_b128 v[184:187], v143 offset:18432
	ds_read_b128 v[188:191], v143 offset:19456
	ds_read_b128 v[192:195], v143 offset:20480
	ds_read_b128 v[196:199], v143 offset:21504
	ds_read_b128 v[200:203], v143 offset:22528
	ds_read_b128 v[206:209], v143 offset:23552
	global_load_lds_dwordx4 v[140:141], off
	s_add_i32 m0, s55, 0x2000
	s_add_u32 s64, s28, 0x80000
	v_lshl_add_u64 v[210:211], s[28:29], 0, v[128:129]
	s_addc_u32 s65, s29, 0
	s_add_i32 s55, s62, s35
	global_load_lds_dwordx4 v[210:211], off
	v_lshl_add_u64 v[212:213], s[64:65], 0, v[204:205]
	s_mov_b32 m0, s55
	v_lshl_add_u64 v[214:215], s[30:31], 0, v[130:131]
	global_load_lds_dwordx4 v[212:213], off
	v_lshl_add_u64 v[212:213], s[64:65], 0, v[128:129]
	s_add_i32 m0, s55, 0x2000
	s_nop 0
	global_load_lds_dwordx4 v[212:213], off
	v_lshl_add_u64 v[212:213], s[30:31], 0, v[132:133]
	s_mov_b32 m0, s37
	s_nop 0
	global_load_lds_dwordx4 v[212:213], off
	s_mov_b32 m0, s38
	s_nop 0
	global_load_lds_dwordx4 v[214:215], off
	s_waitcnt vmcnt(8)
	s_waitcnt lgkmcnt(0)
	s_setprio 1
	s_barrier
; #define PG8_STAGE(bufoff, gbase, voff) do { _Pragma("unroll") for (int _i = 0; _i < 2; ++_i) \
;         __builtin_amdgcn_global_load_lds((const unsigned*)((const char*)(gbase) + (voff)[_i]), (PG8_LAS unsigned*)(lds + (bufoff) + ldsw + _i * 8192), 16, 0, 0); } while (0)
; #define PG8_LDA(dst, b, h) do { _Pragma("unroll") for (int m = 0; m < 4; ++m) _Pragma("unroll") for (int k = 0; k < 2; ++k) dst[m][k] = *(const PG8_LAS bf16x8*)(lds + PG8_SA(b, h) + aoff + m * 2048 + k * 1024); } while (0)
; #define PG8_LDB(dst, b, h) do { _Pragma("unroll") for (int n = 0; n < 2; ++n) _Pragma("unroll") for (int k = 0; k < 2; ++k) dst[n][k] = *(const PG8_LAS bf16x8*)(lds + PG8_SB(b, h) + boff + n * 2048 + k * 1024); } while (0)
; #define PG8_MMA(ai, bj, At, Bt) do { __builtin_amdgcn_s_setprio(1); _Pragma("unroll") for (int m = 0; m < 4; ++m) _Pragma("unroll") for (int n = 0; n < 2; ++n) _Pragma("unroll") for (int k = 0; k < 2; ++k) \
;         acc[ai][bj][m][n] = __builtin_amdgcn_mfma_f32_16x16x32_bf16(Bt[n][k], At[m][k], acc[ai][bj][m][n], 0, 0, 0); __builtin_amdgcn_s_setprio(0); } while (0)
; #define PG8_WAIT_V(n) asm volatile("s_waitcnt vmcnt(" #n ")" ::: "memory")
; #define PG8_WAIT_L(n) asm volatile("s_waitcnt lgkmcnt(" #n ")" ::: "memory")
; #define PG8_BAR __builtin_amdgcn_s_barrier()
; #define PG8_SCHED __builtin_amdgcn_sched_barrier(0)
; template <class Epi, class Sched, bool ALIGN_EPI = false, bool SP2 = false>
; __device__ __forceinline__ void gemm_phase(PG8_LAS unsigned char* lds, const Gemm g, const Sched& S, const Epi& E, const int tid) {
;     ...
;             PG8_WAIT_V(8); PG8_WAIT_L(0); PG8_BAR; PG8_MMA(1, 0, At, B0); PG8_MMA(1, 1, At, B1); PG8_BAR; PG8_SCHED;
;             PG8_LDB(B0, 1, 0); PG8_LDB(B1, 1, 1); PG8_SCHED; PG8_LDA(At, 1, 0); PG8_STAGE(PG8_SA(0, 1), a2 + hstep, voffA);
;             PG8_WAIT_V(8); PG8_WAIT_L(0); PG8_BAR; PG8_MMA(0, 0, At, B0); PG8_MMA(0, 1, At, B1); PG8_BAR; PG8_SCHED;
	v_mfma_f32_16x16x32_bf16 v[60:63], v[144:147], v[176:179], 0
	v_mfma_f32_16x16x32_bf16 v[56:59], v[152:155], v[176:179], 0
	v_mfma_f32_16x16x32_bf16 v[48:51], v[144:147], v[184:187], 0
	v_mfma_f32_16x16x32_bf16 v[40:43], v[152:155], v[184:187], 0
	v_mfma_f32_16x16x32_bf16 v[32:35], v[144:147], v[192:195], 0
	v_mfma_f32_16x16x32_bf16 v[24:27], v[152:155], v[192:195], 0
	v_mfma_f32_16x16x32_bf16 v[16:19], v[144:147], v[200:203], 0
	v_mfma_f32_16x16x32_bf16 v[8:11], v[152:155], v[200:203], 0
	v_mfma_f32_16x16x32_bf16 v[60:63], v[148:151], v[180:183], v[60:63]
	v_mfma_f32_16x16x32_bf16 v[56:59], v[156:159], v[180:183], v[56:59]
	v_mfma_f32_16x16x32_bf16 v[48:51], v[148:151], v[188:191], v[48:51]
	v_mfma_f32_16x16x32_bf16 v[40:43], v[156:159], v[188:191], v[40:43]
	v_mfma_f32_16x16x32_bf16 v[32:35], v[148:151], v[196:199], v[32:35]
	v_mfma_f32_16x16x32_bf16 v[24:27], v[156:159], v[196:199], v[24:27]
	v_mfma_f32_16x16x32_bf16 v[16:19], v[148:151], v[206:209], v[16:19]
	v_mfma_f32_16x16x32_bf16 v[8:11], v[156:159], v[206:209], v[8:11]
	s_setprio 0
	s_setprio 1
	v_mfma_f32_16x16x32_bf16 v[52:55], v[160:163], v[176:179], 0
	v_mfma_f32_16x16x32_bf16 v[44:47], v[168:171], v[176:179], 0
	v_mfma_f32_16x16x32_bf16 v[36:39], v[160:163], v[184:187], 0
	v_mfma_f32_16x16x32_bf16 v[28:31], v[168:171], v[184:187], 0
	v_mfma_f32_16x16x32_bf16 v[20:23], v[160:163], v[192:195], 0
	v_mfma_f32_16x16x32_bf16 v[12:15], v[168:171], v[192:195], 0
	v_mfma_f32_16x16x32_bf16 v[4:7], v[160:163], v[200:203], 0
	v_mfma_f32_16x16x32_bf16 v[0:3], v[168:171], v[200:203], 0
	v_mfma_f32_16x16x32_bf16 v[52:55], v[164:167], v[180:183], v[52:55]
	v_mfma_f32_16x16x32_bf16 v[44:47], v[172:175], v[180:183], v[44:47]
	v_mfma_f32_16x16x32_bf16 v[36:39], v[164:167], v[188:191], v[36:39]
	v_mfma_f32_16x16x32_bf16 v[28:31], v[172:175], v[188:191], v[28:31]
	v_mfma_f32_16x16x32_bf16 v[20:23], v[164:167], v[196:199], v[20:23]
	v_mfma_f32_16x16x32_bf16 v[12:15], v[172:175], v[196:199], v[12:15]
	v_mfma_f32_16x16x32_bf16 v[4:7], v[164:167], v[206:209], v[4:7]
	v_mfma_f32_16x16x32_bf16 v[0:3], v[172:175], v[206:209], v[0:3]
	s_barrier
	s_setprio 0
	s_add_i32 s55, 0, 0x18000
	v_add_u32_e32 v138, s55, v139
	s_add_i32 s62, 0, 0x1c000
	ds_read_b128 v[144:147], v138
	ds_read_b128 v[148:151], v138 offset:1024
	ds_read_b128 v[152:155], v138 offset:2048
	ds_read_b128 v[156:159], v138 offset:3072
	v_add_u32_e32 v138, s62, v139
	ds_read_b128 v[160:163], v138
	ds_read_b128 v[164:167], v138 offset:1024
	ds_read_b128 v[168:171], v138 offset:2048
	ds_read_b128 v[172:175], v138 offset:3072
	s_add_u32 s30, s30, 0x80000
	s_addc_u32 s31, s31, 0
	s_mov_b32 m0, s40
	v_lshl_add_u64 v[216:217], s[30:31], 0, v[132:133]
	ds_read_b128 v[176:179], v143 offset:32768
	ds_read_b128 v[180:183], v143 offset:33792
	ds_read_b128 v[184:187], v143 offset:34816
	ds_read_b128 v[188:191], v143 offset:35840
	ds_read_b128 v[192:195], v143 offset:36864
	ds_read_b128 v[196:199], v143 offset:37888
	ds_read_b128 v[200:203], v143 offset:38912
	ds_read_b128 v[206:209], v143 offset:39936
	global_load_lds_dwordx4 v[216:217], off
	v_lshl_add_u64 v[216:217], s[30:31], 0, v[130:131]
	s_mov_b32 m0, s42
	s_nop 0
	global_load_lds_dwordx4 v[216:217], off
	s_waitcnt vmcnt(8)
	s_waitcnt lgkmcnt(0)
	s_setprio 1
	s_barrier
	v_mfma_f32_16x16x32_bf16 v[124:127], v[144:147], v[176:179], v[124:127]
	v_mfma_f32_16x16x32_bf16 v[120:123], v[152:155], v[176:179], v[120:123]
	v_mfma_f32_16x16x32_bf16 v[108:111], v[144:147], v[184:187], v[108:111]
	v_mfma_f32_16x16x32_bf16 v[104:107], v[152:155], v[184:187], v[104:107]
	v_mfma_f32_16x16x32_bf16 v[92:95], v[144:147], v[192:195], v[92:95]
	v_mfma_f32_16x16x32_bf16 v[88:91], v[152:155], v[192:195], v[88:91]
	v_mfma_f32_16x16x32_bf16 v[76:79], v[144:147], v[200:203], v[76:79]
	v_mfma_f32_16x16x32_bf16 v[72:75], v[152:155], v[200:203], v[72:75]
	v_mfma_f32_16x16x32_bf16 v[124:127], v[148:151], v[180:183], v[124:127]
	v_mfma_f32_16x16x32_bf16 v[120:123], v[156:159], v[180:183], v[120:123]
	v_mfma_f32_16x16x32_bf16 v[108:111], v[148:151], v[188:191], v[108:111]
	v_mfma_f32_16x16x32_bf16 v[104:107], v[156:159], v[188:191], v[104:107]
	v_mfma_f32_16x16x32_bf16 v[92:95], v[148:151], v[196:199], v[92:95]
	v_mfma_f32_16x16x32_bf16 v[88:91], v[156:159], v[196:199], v[88:91]
	v_mfma_f32_16x16x32_bf16 v[76:79], v[148:151], v[206:209], v[76:79]
	v_mfma_f32_16x16x32_bf16 v[72:75], v[156:159], v[206:209], v[72:75]
	s_setprio 0
	s_setprio 1
	v_mfma_f32_16x16x32_bf16 v[116:119], v[160:163], v[176:179], v[116:119]
	v_mfma_f32_16x16x32_bf16 v[112:115], v[168:171], v[176:179], v[112:115]
	v_mfma_f32_16x16x32_bf16 v[100:103], v[160:163], v[184:187], v[100:103]
	v_mfma_f32_16x16x32_bf16 v[96:99], v[168:171], v[184:187], v[96:99]
	v_mfma_f32_16x16x32_bf16 v[84:87], v[160:163], v[192:195], v[84:87]
	v_mfma_f32_16x16x32_bf16 v[80:83], v[168:171], v[192:195], v[80:83]
	v_mfma_f32_16x16x32_bf16 v[68:71], v[160:163], v[200:203], v[68:71]
	v_mfma_f32_16x16x32_bf16 v[64:67], v[168:171], v[200:203], v[64:67]
	v_mfma_f32_16x16x32_bf16 v[116:119], v[164:167], v[180:183], v[116:119]
	v_mfma_f32_16x16x32_bf16 v[112:115], v[172:175], v[180:183], v[112:115]
	v_mfma_f32_16x16x32_bf16 v[100:103], v[164:167], v[188:191], v[100:103]
	v_mfma_f32_16x16x32_bf16 v[96:99], v[172:175], v[188:191], v[96:99]
	v_mfma_f32_16x16x32_bf16 v[84:87], v[164:167], v[196:199], v[84:87]
	v_mfma_f32_16x16x32_bf16 v[80:83], v[172:175], v[196:199], v[80:83]
	v_mfma_f32_16x16x32_bf16 v[68:71], v[164:167], v[206:209], v[68:71]
	v_mfma_f32_16x16x32_bf16 v[64:67], v[172:175], v[206:209], v[64:67]
	s_barrier
; #define PG8_STAGE(bufoff, gbase, voff) do { _Pragma("unroll") for (int _i = 0; _i < 2; ++_i) \
;         __builtin_amdgcn_global_load_lds((const unsigned*)((const char*)(gbase) + (voff)[_i]), (PG8_LAS unsigned*)(lds + (bufoff) + ldsw + _i * 8192), 16, 0, 0); } while (0)
; #define PG8_LDA(dst, b, h) do { _Pragma("unroll") for (int m = 0; m < 4; ++m) _Pragma("unroll") for (int k = 0; k < 2; ++k) dst[m][k] = *(const PG8_LAS bf16x8*)(lds + PG8_SA(b, h) + aoff + m * 2048 + k * 1024); } while (0)
; #define PG8_LDB(dst, b, h) do { _Pragma("unroll") for (int n = 0; n < 2; ++n) _Pragma("unroll") for (int k = 0; k < 2; ++k) dst[n][k] = *(const PG8_LAS bf16x8*)(lds + PG8_SB(b, h) + boff + n * 2048 + k * 1024); } while (0)
; #define PG8_MMA(ai, bj, At, Bt) do { __builtin_amdgcn_s_setprio(1); _Pragma("unroll") for (int m = 0; m < 4; ++m) _Pragma("unroll") for (int n = 0; n < 2; ++n) _Pragma("unroll") for (int k = 0; k < 2; ++k) \
;         acc[ai][bj][m][n] = __builtin_amdgcn_mfma_f32_16x16x32_bf16(Bt[n][k], At[m][k], acc[ai][bj][m][n], 0, 0, 0); __builtin_amdgcn_s_setprio(0); } while (0)
; #define PG8_WAIT_V(n) asm volatile("s_waitcnt vmcnt(" #n ")" ::: "memory")
; #define PG8_WAIT_L(n) asm volatile("s_waitcnt lgkmcnt(" #n ")" ::: "memory")
; #define PG8_BAR __builtin_amdgcn_s_barrier()
; template <class Epi, class Sched, bool ALIGN_EPI = false, bool SP2 = false>
; __device__ __forceinline__ void gemm_phase(PG8_LAS unsigned char* lds, const Gemm g, const Sched& S, const Epi& E, const int tid) {
;     ...
;         for (int t = 0; t < nt; t += 2) {
;             const bool last = (t == nt - 2);
;             const char* a1 = cA + (size_t)(t + 1) * kstep;
;             const char* a2 = last ? nA : cA + (size_t)(t + 2) * kstep; const char* b2 = last ? nB : cB + (size_t)(t + 2) * kstep;
;             const char* a3 = a2 + kstep; const char* b3 = b2 + kstep;
;             if (last && has_next) S.a_ready(nxt);
;             if constexpr (SP2) {
;             PG8_LDB(B0, 0, 0); PG8_LDB(B1, 0, 1); PG8_SCHED; PG8_LDA(At, 0, 0); PG8_STAGE(PG8_SA(1, 1), a1 + hstep, voffA);
;     ...
;             PG8_LDA(At, 1, 1); PG8_STAGE(PG8_SB(1, 0), b3, voffB); PG8_STAGE(PG8_SB(1, 1), b3 + hstep, voffB); PG8_STAGE(PG8_SA(1, 0), a3, voffA);
;             PG8_WAIT_V(8); PG8_WAIT_L(0); PG8_BAR; PG8_MMA(1, 0, At, B0); PG8_MMA(1, 1, At, B1); PG8_BAR; PG8_SCHED;
	s_setprio 0
	s_add_i32 s30, s55, s35
	v_lshl_add_u64 v[140:141], v[140:141], 0, s[70:71]
	s_mov_b32 m0, s30
	ds_read_b128 v[176:179], v143 offset:49152
	ds_read_b128 v[180:183], v143 offset:50176
	ds_read_b128 v[184:187], v143 offset:51200
	ds_read_b128 v[188:191], v143 offset:52224
	ds_read_b128 v[192:195], v143 offset:53248
	ds_read_b128 v[196:199], v143 offset:54272
	ds_read_b128 v[200:203], v143 offset:55296
	ds_read_b128 v[206:209], v143 offset:56320
	global_load_lds_dwordx4 v[140:141], off
	s_add_i32 m0, s30, 0x2000
	s_add_u32 s28, s28, 0x80080
	v_lshl_add_u64 v[140:141], v[210:211], 0, s[70:71]
	s_addc_u32 s29, s29, 0
	s_add_i32 s30, s62, s35
	global_load_lds_dwordx4 v[140:141], off
	v_lshl_add_u64 v[140:141], s[28:29], 0, v[204:205]
	s_mov_b32 m0, s30
	s_nop 0
	global_load_lds_dwordx4 v[140:141], off
	v_lshl_add_u64 v[140:141], s[28:29], 0, v[128:129]
	s_add_i32 m0, s30, 0x2000
	s_nop 0
	global_load_lds_dwordx4 v[140:141], off
	v_lshl_add_u64 v[140:141], v[212:213], 0, s[70:71]
	s_mov_b32 m0, s46
	s_nop 0
	global_load_lds_dwordx4 v[140:141], off
	v_lshl_add_u64 v[140:141], v[214:215], 0, s[70:71]
	s_mov_b32 m0, s47
	s_nop 0
	global_load_lds_dwordx4 v[140:141], off
	s_add_i32 s54, s54, 2
	s_add_u32 s26, s26, 0x100
	s_addc_u32 s27, s27, 0
	s_add_u32 s52, s52, 0x100
	s_addc_u32 s53, s53, 0
	s_waitcnt vmcnt(8)
	s_waitcnt lgkmcnt(0)
	s_setprio 1
	s_barrier
	v_mfma_f32_16x16x32_bf16 v[60:63], v[144:147], v[176:179], v[60:63]
	v_mfma_f32_16x16x32_bf16 v[56:59], v[152:155], v[176:179], v[56:59]
	v_mfma_f32_16x16x32_bf16 v[48:51], v[144:147], v[184:187], v[48:51]
	v_mfma_f32_16x16x32_bf16 v[40:43], v[152:155], v[184:187], v[40:43]
	v_mfma_f32_16x16x32_bf16 v[32:35], v[144:147], v[192:195], v[32:35]
	v_mfma_f32_16x16x32_bf16 v[24:27], v[152:155], v[192:195], v[24:27]
	v_mfma_f32_16x16x32_bf16 v[16:19], v[144:147], v[200:203], v[16:19]
	v_mfma_f32_16x16x32_bf16 v[8:11], v[152:155], v[200:203], v[8:11]
	v_mfma_f32_16x16x32_bf16 v[60:63], v[148:151], v[180:183], v[60:63]
	v_mfma_f32_16x16x32_bf16 v[56:59], v[156:159], v[180:183], v[56:59]
	v_mfma_f32_16x16x32_bf16 v[48:51], v[148:151], v[188:191], v[48:51]
	v_mfma_f32_16x16x32_bf16 v[40:43], v[156:159], v[188:191], v[40:43]
	v_mfma_f32_16x16x32_bf16 v[32:35], v[148:151], v[196:199], v[32:35]
	v_mfma_f32_16x16x32_bf16 v[24:27], v[156:159], v[196:199], v[24:27]
	v_mfma_f32_16x16x32_bf16 v[16:19], v[148:151], v[206:209], v[16:19]
	v_mfma_f32_16x16x32_bf16 v[8:11], v[156:159], v[206:209], v[8:11]
	s_setprio 0
	s_setprio 1
	v_mfma_f32_16x16x32_bf16 v[52:55], v[160:163], v[176:179], v[52:55]
	v_mfma_f32_16x16x32_bf16 v[44:47], v[168:171], v[176:179], v[44:47]
	v_mfma_f32_16x16x32_bf16 v[36:39], v[160:163], v[184:187], v[36:39]
	v_mfma_f32_16x16x32_bf16 v[28:31], v[168:171], v[184:187], v[28:31]
	v_mfma_f32_16x16x32_bf16 v[20:23], v[160:163], v[192:195], v[20:23]
	v_mfma_f32_16x16x32_bf16 v[12:15], v[168:171], v[192:195], v[12:15]
	v_mfma_f32_16x16x32_bf16 v[4:7], v[160:163], v[200:203], v[4:7]
	v_mfma_f32_16x16x32_bf16 v[0:3], v[168:171], v[200:203], v[0:3]
	v_mfma_f32_16x16x32_bf16 v[52:55], v[164:167], v[180:183], v[52:55]
	v_mfma_f32_16x16x32_bf16 v[44:47], v[172:175], v[180:183], v[44:47]
	v_mfma_f32_16x16x32_bf16 v[36:39], v[164:167], v[188:191], v[36:39]
	v_mfma_f32_16x16x32_bf16 v[28:31], v[172:175], v[188:191], v[28:31]
	v_mfma_f32_16x16x32_bf16 v[20:23], v[164:167], v[196:199], v[20:23]
	v_mfma_f32_16x16x32_bf16 v[12:15], v[172:175], v[196:199], v[12:15]
	v_mfma_f32_16x16x32_bf16 v[4:7], v[164:167], v[206:209], v[4:7]
	v_mfma_f32_16x16x32_bf16 v[0:3], v[172:175], v[206:209], v[0:3]
	s_barrier
	s_setprio 0
.LBB0_661:
	s_add_i32 s55, 0, 0x10000
	v_add_u32_e32 v138, s55, v139
	s_add_i32 s62, 0, 0x14000
	ds_read_b128 v[144:147], v138
	ds_read_b128 v[148:151], v138 offset:1024
	ds_read_b128 v[152:155], v138 offset:2048
	ds_read_b128 v[156:159], v138 offset:3072
	v_add_u32_e32 v138, s62, v139
	ds_read_b128 v[160:163], v138
	ds_read_b128 v[164:167], v138 offset:1024
	ds_read_b128 v[168:171], v138 offset:2048
	ds_read_b128 v[172:175], v138 offset:3072
	v_lshl_add_u64 v[140:141], s[26:27], 0, v[134:135]
	s_add_i32 m0, s37, 0xc000
	ds_read_b128 v[176:179], v143
	ds_read_b128 v[180:183], v143 offset:1024
	ds_read_b128 v[184:187], v143 offset:2048
	ds_read_b128 v[188:191], v143 offset:3072
	ds_read_b128 v[192:195], v143 offset:4096
	ds_read_b128 v[196:199], v143 offset:5120
	ds_read_b128 v[200:203], v143 offset:6144
	ds_read_b128 v[206:209], v143 offset:7168
	s_add_u32 s28, s26, 0xfff80080
	s_addc_u32 s29, s27, -1
	s_cmp_eq_u32 s54, 28
	s_cselect_b32 s31, s19, s29
	s_cselect_b32 s30, s50, s28
	s_cselect_b32 s29, s17, s53
	s_cselect_b32 s28, s51, s52
	global_load_lds_dwordx4 v[140:141], off
	v_lshl_add_u64 v[140:141], s[26:27], 0, v[136:137]
	s_add_i32 m0, s37, 0xe000
	s_nop 0
	global_load_lds_dwordx4 v[140:141], off
	s_waitcnt vmcnt(8)
	s_waitcnt lgkmcnt(0)
	s_setprio 1
	s_barrier
; #define PG8_STAGE(bufoff, gbase, voff) do { _Pragma("unroll") for (int _i = 0; _i < 2; ++_i) \
;         __builtin_amdgcn_global_load_lds((const unsigned*)((const char*)(gbase) + (voff)[_i]), (PG8_LAS unsigned*)(lds + (bufoff) + ldsw + _i * 8192), 16, 0, 0); } while (0)
; #define PG8_LDA(dst, b, h) do { _Pragma("unroll") for (int m = 0; m < 4; ++m) _Pragma("unroll") for (int k = 0; k < 2; ++k) dst[m][k] = *(const PG8_LAS bf16x8*)(lds + PG8_SA(b, h) + aoff + m * 2048 + k * 1024); } while (0)
; #define PG8_MMA(ai, bj, At, Bt) do { __builtin_amdgcn_s_setprio(1); _Pragma("unroll") for (int m = 0; m < 4; ++m) _Pragma("unroll") for (int n = 0; n < 2; ++n) _Pragma("unroll") for (int k = 0; k < 2; ++k) \
;         acc[ai][bj][m][n] = __builtin_amdgcn_mfma_f32_16x16x32_bf16(Bt[n][k], At[m][k], acc[ai][bj][m][n], 0, 0, 0); __builtin_amdgcn_s_setprio(0); } while (0)
; #define PG8_WAIT_V(n) asm volatile("s_waitcnt vmcnt(" #n ")" ::: "memory")
; #define PG8_WAIT_L(n) asm volatile("s_waitcnt lgkmcnt(" #n ")" ::: "memory")
; #define PG8_BAR __builtin_amdgcn_s_barrier()
; #define PG8_SCHED __builtin_amdgcn_sched_barrier(0)
; template <class Epi, class Sched, bool ALIGN_EPI = false, bool SP2 = false>
; __device__ __forceinline__ void gemm_phase(PG8_LAS unsigned char* lds, const Gemm g, const Sched& S, const Epi& E, const int tid) {
;     ...
;             PG8_WAIT_V(8); PG8_WAIT_L(0); PG8_BAR; PG8_MMA(0, 0, At, B0); PG8_MMA(0, 1, At, B1); PG8_BAR; PG8_SCHED;
;             PG8_LDA(At, 0, 1); PG8_STAGE(PG8_SB(0, 0), b2, voffB); PG8_STAGE(PG8_SB(0, 1), b2 + hstep, voffB); PG8_STAGE(PG8_SA(0, 0), a2, voffA);
;             PG8_WAIT_V(8); PG8_WAIT_L(0); PG8_BAR; PG8_MMA(1, 0, At, B0); PG8_MMA(1, 1, At, B1); PG8_BAR; PG8_SCHED;
	v_mfma_f32_16x16x32_bf16 v[124:127], v[144:147], v[176:179], v[124:127]
	v_mfma_f32_16x16x32_bf16 v[120:123], v[152:155], v[176:179], v[120:123]
	v_mfma_f32_16x16x32_bf16 v[108:111], v[144:147], v[184:187], v[108:111]
	v_mfma_f32_16x16x32_bf16 v[104:107], v[152:155], v[184:187], v[104:107]
	v_mfma_f32_16x16x32_bf16 v[92:95], v[144:147], v[192:195], v[92:95]
	v_mfma_f32_16x16x32_bf16 v[88:91], v[152:155], v[192:195], v[88:91]
	v_mfma_f32_16x16x32_bf16 v[76:79], v[144:147], v[200:203], v[76:79]
	v_mfma_f32_16x16x32_bf16 v[72:75], v[152:155], v[200:203], v[72:75]
	v_mfma_f32_16x16x32_bf16 v[124:127], v[148:151], v[180:183], v[124:127]
	v_mfma_f32_16x16x32_bf16 v[120:123], v[156:159], v[180:183], v[120:123]
	v_mfma_f32_16x16x32_bf16 v[108:111], v[148:151], v[188:191], v[108:111]
	v_mfma_f32_16x16x32_bf16 v[104:107], v[156:159], v[188:191], v[104:107]
	v_mfma_f32_16x16x32_bf16 v[92:95], v[148:151], v[196:199], v[92:95]
	v_mfma_f32_16x16x32_bf16 v[88:91], v[156:159], v[196:199], v[88:91]
	v_mfma_f32_16x16x32_bf16 v[76:79], v[148:151], v[206:209], v[76:79]
	v_mfma_f32_16x16x32_bf16 v[72:75], v[156:159], v[206:209], v[72:75]
	s_setprio 0
	s_setprio 1
	v_mfma_f32_16x16x32_bf16 v[116:119], v[160:163], v[176:179], v[116:119]
	v_mfma_f32_16x16x32_bf16 v[112:115], v[168:171], v[176:179], v[112:115]
	v_mfma_f32_16x16x32_bf16 v[100:103], v[160:163], v[184:187], v[100:103]
	v_mfma_f32_16x16x32_bf16 v[96:99], v[168:171], v[184:187], v[96:99]
	v_mfma_f32_16x16x32_bf16 v[84:87], v[160:163], v[192:195], v[84:87]
	v_mfma_f32_16x16x32_bf16 v[80:83], v[168:171], v[192:195], v[80:83]
	v_mfma_f32_16x16x32_bf16 v[68:71], v[160:163], v[200:203], v[68:71]
	v_mfma_f32_16x16x32_bf16 v[64:67], v[168:171], v[200:203], v[64:67]
	v_mfma_f32_16x16x32_bf16 v[116:119], v[164:167], v[180:183], v[116:119]
	v_mfma_f32_16x16x32_bf16 v[112:115], v[172:175], v[180:183], v[112:115]
	v_mfma_f32_16x16x32_bf16 v[100:103], v[164:167], v[188:191], v[100:103]
	v_mfma_f32_16x16x32_bf16 v[96:99], v[172:175], v[188:191], v[96:99]
	v_mfma_f32_16x16x32_bf16 v[84:87], v[164:167], v[196:199], v[84:87]
	v_mfma_f32_16x16x32_bf16 v[80:83], v[172:175], v[196:199], v[80:83]
	v_mfma_f32_16x16x32_bf16 v[68:71], v[164:167], v[206:209], v[68:71]
	v_mfma_f32_16x16x32_bf16 v[64:67], v[172:175], v[206:209], v[64:67]
	s_barrier
	s_setprio 0
	s_add_i32 s55, s55, s35
	v_lshl_add_u64 v[140:141], s[28:29], 0, v[204:205]
	s_mov_b32 m0, s55
	ds_read_b128 v[176:179], v143 offset:16384
	ds_read_b128 v[180:183], v143 offset:17408
	ds_read_b128 v[184:187], v143 offset:18432
	ds_read_b128 v[188:191], v143 offset:19456
	ds_read_b128 v[192:195], v143 offset:20480
	ds_read_b128 v[196:199], v143 offset:21504
	ds_read_b128 v[200:203], v143 offset:22528
	ds_read_b128 v[206:209], v143 offset:23552
	global_load_lds_dwordx4 v[140:141], off
	s_add_i32 m0, s55, 0x2000
	s_add_u32 s64, s28, 0x80000
	v_lshl_add_u64 v[210:211], s[28:29], 0, v[128:129]
	s_addc_u32 s65, s29, 0
	s_add_i32 s55, s62, s35
	global_load_lds_dwordx4 v[210:211], off
	v_lshl_add_u64 v[212:213], s[64:65], 0, v[204:205]
	s_mov_b32 m0, s55
	v_lshl_add_u64 v[214:215], s[30:31], 0, v[130:131]
	global_load_lds_dwordx4 v[212:213], off
	v_lshl_add_u64 v[212:213], s[64:65], 0, v[128:129]
	s_add_i32 m0, s55, 0x2000
	s_nop 0
	global_load_lds_dwordx4 v[212:213], off
	v_lshl_add_u64 v[212:213], s[30:31], 0, v[132:133]
	s_mov_b32 m0, s37
	s_nop 0
	global_load_lds_dwordx4 v[212:213], off
	s_mov_b32 m0, s38
	s_nop 0
	global_load_lds_dwordx4 v[214:215], off
	s_waitcnt vmcnt(8)
	s_waitcnt lgkmcnt(0)
	s_setprio 1
	s_barrier
	v_mfma_f32_16x16x32_bf16 v[60:63], v[144:147], v[176:179], v[60:63]
	v_mfma_f32_16x16x32_bf16 v[56:59], v[152:155], v[176:179], v[56:59]
	v_mfma_f32_16x16x32_bf16 v[48:51], v[144:147], v[184:187], v[48:51]
	v_mfma_f32_16x16x32_bf16 v[40:43], v[152:155], v[184:187], v[40:43]
	v_mfma_f32_16x16x32_bf16 v[32:35], v[144:147], v[192:195], v[32:35]
	v_mfma_f32_16x16x32_bf16 v[24:27], v[152:155], v[192:195], v[24:27]
	v_mfma_f32_16x16x32_bf16 v[16:19], v[144:147], v[200:203], v[16:19]
	v_mfma_f32_16x16x32_bf16 v[8:11], v[152:155], v[200:203], v[8:11]
	v_mfma_f32_16x16x32_bf16 v[60:63], v[148:151], v[180:183], v[60:63]
	v_mfma_f32_16x16x32_bf16 v[56:59], v[156:159], v[180:183], v[56:59]
	v_mfma_f32_16x16x32_bf16 v[48:51], v[148:151], v[188:191], v[48:51]
	v_mfma_f32_16x16x32_bf16 v[40:43], v[156:159], v[188:191], v[40:43]
	v_mfma_f32_16x16x32_bf16 v[32:35], v[148:151], v[196:199], v[32:35]
	v_mfma_f32_16x16x32_bf16 v[24:27], v[156:159], v[196:199], v[24:27]
	v_mfma_f32_16x16x32_bf16 v[16:19], v[148:151], v[206:209], v[16:19]
	v_mfma_f32_16x16x32_bf16 v[8:11], v[156:159], v[206:209], v[8:11]
	s_setprio 0
	s_setprio 1
	v_mfma_f32_16x16x32_bf16 v[52:55], v[160:163], v[176:179], v[52:55]
	v_mfma_f32_16x16x32_bf16 v[44:47], v[168:171], v[176:179], v[44:47]
	v_mfma_f32_16x16x32_bf16 v[36:39], v[160:163], v[184:187], v[36:39]
	v_mfma_f32_16x16x32_bf16 v[28:31], v[168:171], v[184:187], v[28:31]
	v_mfma_f32_16x16x32_bf16 v[20:23], v[160:163], v[192:195], v[20:23]
	v_mfma_f32_16x16x32_bf16 v[12:15], v[168:171], v[192:195], v[12:15]
	v_mfma_f32_16x16x32_bf16 v[4:7], v[160:163], v[200:203], v[4:7]
	v_mfma_f32_16x16x32_bf16 v[0:3], v[168:171], v[200:203], v[0:3]
	v_mfma_f32_16x16x32_bf16 v[52:55], v[164:167], v[180:183], v[52:55]
	v_mfma_f32_16x16x32_bf16 v[44:47], v[172:175], v[180:183], v[44:47]
	v_mfma_f32_16x16x32_bf16 v[36:39], v[164:167], v[188:191], v[36:39]
	v_mfma_f32_16x16x32_bf16 v[28:31], v[172:175], v[188:191], v[28:31]
	v_mfma_f32_16x16x32_bf16 v[20:23], v[164:167], v[196:199], v[20:23]
	v_mfma_f32_16x16x32_bf16 v[12:15], v[172:175], v[196:199], v[12:15]
	v_mfma_f32_16x16x32_bf16 v[4:7], v[164:167], v[206:209], v[4:7]
	v_mfma_f32_16x16x32_bf16 v[0:3], v[172:175], v[206:209], v[0:3]
	s_barrier
; #define PG8_STAGE(bufoff, gbase, voff) do { _Pragma("unroll") for (int _i = 0; _i < 2; ++_i) \
;         __builtin_amdgcn_global_load_lds((const unsigned*)((const char*)(gbase) + (voff)[_i]), (PG8_LAS unsigned*)(lds + (bufoff) + ldsw + _i * 8192), 16, 0, 0); } while (0)
; #define PG8_LDA(dst, b, h) do { _Pragma("unroll") for (int m = 0; m < 4; ++m) _Pragma("unroll") for (int k = 0; k < 2; ++k) dst[m][k] = *(const PG8_LAS bf16x8*)(lds + PG8_SA(b, h) + aoff + m * 2048 + k * 1024); } while (0)
; #define PG8_LDB(dst, b, h) do { _Pragma("unroll") for (int n = 0; n < 2; ++n) _Pragma("unroll") for (int k = 0; k < 2; ++k) dst[n][k] = *(const PG8_LAS bf16x8*)(lds + PG8_SB(b, h) + boff + n * 2048 + k * 1024); } while (0)
; #define PG8_MMA(ai, bj, At, Bt) do { __builtin_amdgcn_s_setprio(1); _Pragma("unroll") for (int m = 0; m < 4; ++m) _Pragma("unroll") for (int n = 0; n < 2; ++n) _Pragma("unroll") for (int k = 0; k < 2; ++k) \
;         acc[ai][bj][m][n] = __builtin_amdgcn_mfma_f32_16x16x32_bf16(Bt[n][k], At[m][k], acc[ai][bj][m][n], 0, 0, 0); __builtin_amdgcn_s_setprio(0); } while (0)
; #define PG8_WAIT_V(n) asm volatile("s_waitcnt vmcnt(" #n ")" ::: "memory")
; #define PG8_WAIT_L(n) asm volatile("s_waitcnt lgkmcnt(" #n ")" ::: "memory")
; #define PG8_BAR __builtin_amdgcn_s_barrier()
; #define PG8_SCHED __builtin_amdgcn_sched_barrier(0)
; template <class Epi, class Sched, bool ALIGN_EPI = false, bool SP2 = false>
; __device__ __forceinline__ void gemm_phase(PG8_LAS unsigned char* lds, const Gemm g, const Sched& S, const Epi& E, const int tid) {
;     ...
;             PG8_LDB(B0, 1, 0); PG8_LDB(B1, 1, 1); PG8_SCHED; PG8_LDA(At, 1, 0); PG8_STAGE(PG8_SA(0, 1), a2 + hstep, voffA);
;             PG8_WAIT_V(8); PG8_WAIT_L(0); PG8_BAR; PG8_MMA(0, 0, At, B0); PG8_MMA(0, 1, At, B1); PG8_BAR; PG8_SCHED;
	s_setprio 0
	s_add_i32 s55, 0, 0x18000
	v_add_u32_e32 v138, s55, v139
	s_add_i32 s62, 0, 0x1c000
	ds_read_b128 v[144:147], v138
	ds_read_b128 v[148:151], v138 offset:1024
	ds_read_b128 v[152:155], v138 offset:2048
	ds_read_b128 v[156:159], v138 offset:3072
	v_add_u32_e32 v138, s62, v139
	ds_read_b128 v[160:163], v138
	ds_read_b128 v[164:167], v138 offset:1024
	ds_read_b128 v[168:171], v138 offset:2048
	ds_read_b128 v[172:175], v138 offset:3072
	s_add_u32 s30, s30, 0x80000
	s_addc_u32 s31, s31, 0
	s_mov_b32 m0, s40
	v_lshl_add_u64 v[216:217], s[30:31], 0, v[132:133]
	ds_read_b128 v[176:179], v143 offset:32768
	ds_read_b128 v[180:183], v143 offset:33792
	ds_read_b128 v[184:187], v143 offset:34816
	ds_read_b128 v[188:191], v143 offset:35840
	ds_read_b128 v[192:195], v143 offset:36864
	ds_read_b128 v[196:199], v143 offset:37888
	ds_read_b128 v[200:203], v143 offset:38912
	ds_read_b128 v[206:209], v143 offset:39936
	global_load_lds_dwordx4 v[216:217], off
	v_lshl_add_u64 v[216:217], s[30:31], 0, v[130:131]
	s_mov_b32 m0, s42
	s_nop 0
	global_load_lds_dwordx4 v[216:217], off
	s_waitcnt vmcnt(8)
	s_waitcnt lgkmcnt(0)
	s_setprio 1
	s_barrier
	v_mfma_f32_16x16x32_bf16 v[124:127], v[144:147], v[176:179], v[124:127]
	v_mfma_f32_16x16x32_bf16 v[120:123], v[152:155], v[176:179], v[120:123]
	v_mfma_f32_16x16x32_bf16 v[108:111], v[144:147], v[184:187], v[108:111]
	v_mfma_f32_16x16x32_bf16 v[104:107], v[152:155], v[184:187], v[104:107]
	v_mfma_f32_16x16x32_bf16 v[92:95], v[144:147], v[192:195], v[92:95]
	v_mfma_f32_16x16x32_bf16 v[88:91], v[152:155], v[192:195], v[88:91]
	v_mfma_f32_16x16x32_bf16 v[76:79], v[144:147], v[200:203], v[76:79]
	v_mfma_f32_16x16x32_bf16 v[72:75], v[152:155], v[200:203], v[72:75]
	v_mfma_f32_16x16x32_bf16 v[124:127], v[148:151], v[180:183], v[124:127]
	v_mfma_f32_16x16x32_bf16 v[120:123], v[156:159], v[180:183], v[120:123]
	v_mfma_f32_16x16x32_bf16 v[108:111], v[148:151], v[188:191], v[108:111]
	v_mfma_f32_16x16x32_bf16 v[104:107], v[156:159], v[188:191], v[104:107]
	v_mfma_f32_16x16x32_bf16 v[92:95], v[148:151], v[196:199], v[92:95]
	v_mfma_f32_16x16x32_bf16 v[88:91], v[156:159], v[196:199], v[88:91]
	v_mfma_f32_16x16x32_bf16 v[76:79], v[148:151], v[206:209], v[76:79]
	v_mfma_f32_16x16x32_bf16 v[72:75], v[156:159], v[206:209], v[72:75]
	s_setprio 0
	s_setprio 1
	v_mfma_f32_16x16x32_bf16 v[116:119], v[160:163], v[176:179], v[116:119]
	v_mfma_f32_16x16x32_bf16 v[112:115], v[168:171], v[176:179], v[112:115]
	v_mfma_f32_16x16x32_bf16 v[100:103], v[160:163], v[184:187], v[100:103]
	v_mfma_f32_16x16x32_bf16 v[96:99], v[168:171], v[184:187], v[96:99]
	v_mfma_f32_16x16x32_bf16 v[84:87], v[160:163], v[192:195], v[84:87]
	v_mfma_f32_16x16x32_bf16 v[80:83], v[168:171], v[192:195], v[80:83]
	v_mfma_f32_16x16x32_bf16 v[68:71], v[160:163], v[200:203], v[68:71]
	v_mfma_f32_16x16x32_bf16 v[64:67], v[168:171], v[200:203], v[64:67]
	v_mfma_f32_16x16x32_bf16 v[116:119], v[164:167], v[180:183], v[116:119]
	v_mfma_f32_16x16x32_bf16 v[112:115], v[172:175], v[180:183], v[112:115]
	v_mfma_f32_16x16x32_bf16 v[100:103], v[164:167], v[188:191], v[100:103]
	v_mfma_f32_16x16x32_bf16 v[96:99], v[172:175], v[188:191], v[96:99]
	v_mfma_f32_16x16x32_bf16 v[84:87], v[164:167], v[196:199], v[84:87]
	v_mfma_f32_16x16x32_bf16 v[80:83], v[172:175], v[196:199], v[80:83]
	v_mfma_f32_16x16x32_bf16 v[68:71], v[164:167], v[206:209], v[68:71]
	v_mfma_f32_16x16x32_bf16 v[64:67], v[172:175], v[206:209], v[64:67]
	s_barrier
; #define PG8_STAGE(bufoff, gbase, voff) do { _Pragma("unroll") for (int _i = 0; _i < 2; ++_i) \
;         __builtin_amdgcn_global_load_lds((const unsigned*)((const char*)(gbase) + (voff)[_i]), (PG8_LAS unsigned*)(lds + (bufoff) + ldsw + _i * 8192), 16, 0, 0); } while (0)
; #define PG8_LDA(dst, b, h) do { _Pragma("unroll") for (int m = 0; m < 4; ++m) _Pragma("unroll") for (int k = 0; k < 2; ++k) dst[m][k] = *(const PG8_LAS bf16x8*)(lds + PG8_SA(b, h) + aoff + m * 2048 + k * 1024); } while (0)
; #define PG8_MMA(ai, bj, At, Bt) do { __builtin_amdgcn_s_setprio(1); _Pragma("unroll") for (int m = 0; m < 4; ++m) _Pragma("unroll") for (int n = 0; n < 2; ++n) _Pragma("unroll") for (int k = 0; k < 2; ++k) \
;         acc[ai][bj][m][n] = __builtin_amdgcn_mfma_f32_16x16x32_bf16(Bt[n][k], At[m][k], acc[ai][bj][m][n], 0, 0, 0); __builtin_amdgcn_s_setprio(0); } while (0)
; #define PG8_WAIT_V(n) asm volatile("s_waitcnt vmcnt(" #n ")" ::: "memory")
; #define PG8_WAIT_L(n) asm volatile("s_waitcnt lgkmcnt(" #n ")" ::: "memory")
; #define PG8_BAR __builtin_amdgcn_s_barrier()
; #define PG8_SCHED __builtin_amdgcn_sched_barrier(0)
; template <class Epi, class Sched, bool ALIGN_EPI = false, bool SP2 = false>
; __device__ __forceinline__ void gemm_phase(PG8_LAS unsigned char* lds, const Gemm g, const Sched& S, const Epi& E, const int tid) {
;     ...
;         for (int t = 0; t < nt; t += 2) {
;             const bool last = (t == nt - 2);
;             const char* a1 = cA + (size_t)(t + 1) * kstep;
;             const char* a2 = last ? nA : cA + (size_t)(t + 2) * kstep; const char* b2 = last ? nB : cB + (size_t)(t + 2) * kstep;
;     ...
;             PG8_LDA(At, 1, 1); PG8_STAGE(PG8_SB(1, 0), b3, voffB); PG8_STAGE(PG8_SB(1, 1), b3 + hstep, voffB); PG8_STAGE(PG8_SA(1, 0), a3, voffA);
;             PG8_WAIT_V(8); PG8_WAIT_L(0); PG8_BAR; PG8_MMA(1, 0, At, B0); PG8_MMA(1, 1, At, B1); PG8_BAR; PG8_SCHED;
	s_setprio 0
	s_add_i32 s30, s55, s35
	v_lshl_add_u64 v[140:141], v[140:141], 0, s[70:71]
	s_mov_b32 m0, s30
	ds_read_b128 v[176:179], v143 offset:49152
	ds_read_b128 v[180:183], v143 offset:50176
	ds_read_b128 v[184:187], v143 offset:51200
	ds_read_b128 v[188:191], v143 offset:52224
	ds_read_b128 v[192:195], v143 offset:53248
	ds_read_b128 v[196:199], v143 offset:54272
	ds_read_b128 v[200:203], v143 offset:55296
	ds_read_b128 v[206:209], v143 offset:56320
	global_load_lds_dwordx4 v[140:141], off
	s_add_i32 m0, s30, 0x2000
	s_add_u32 s28, s28, 0x80080
	v_lshl_add_u64 v[140:141], v[210:211], 0, s[70:71]
	s_addc_u32 s29, s29, 0
	s_add_i32 s30, s62, s35
	global_load_lds_dwordx4 v[140:141], off
	v_lshl_add_u64 v[140:141], s[28:29], 0, v[204:205]
	s_mov_b32 m0, s30
	s_nop 0
	global_load_lds_dwordx4 v[140:141], off
	v_lshl_add_u64 v[140:141], s[28:29], 0, v[128:129]
	s_add_i32 m0, s30, 0x2000
	s_nop 0
	global_load_lds_dwordx4 v[140:141], off
	v_lshl_add_u64 v[140:141], v[212:213], 0, s[70:71]
	s_mov_b32 m0, s46
	s_nop 0
	global_load_lds_dwordx4 v[140:141], off
	v_lshl_add_u64 v[140:141], v[214:215], 0, s[70:71]
	s_mov_b32 m0, s47
	s_nop 0
	global_load_lds_dwordx4 v[140:141], off
	s_add_i32 s54, s54, 2
	s_add_u32 s26, s26, 0x100
	s_addc_u32 s27, s27, 0
	s_add_u32 s52, s52, 0x100
	s_addc_u32 s53, s53, 0
	s_waitcnt vmcnt(8)
	s_waitcnt lgkmcnt(0)
	s_setprio 1
	s_barrier
	v_mfma_f32_16x16x32_bf16 v[60:63], v[144:147], v[176:179], v[60:63]
	v_mfma_f32_16x16x32_bf16 v[56:59], v[152:155], v[176:179], v[56:59]
	v_mfma_f32_16x16x32_bf16 v[48:51], v[144:147], v[184:187], v[48:51]
	v_mfma_f32_16x16x32_bf16 v[40:43], v[152:155], v[184:187], v[40:43]
	v_mfma_f32_16x16x32_bf16 v[32:35], v[144:147], v[192:195], v[32:35]
	v_mfma_f32_16x16x32_bf16 v[24:27], v[152:155], v[192:195], v[24:27]
	v_mfma_f32_16x16x32_bf16 v[16:19], v[144:147], v[200:203], v[16:19]
	v_mfma_f32_16x16x32_bf16 v[8:11], v[152:155], v[200:203], v[8:11]
	v_mfma_f32_16x16x32_bf16 v[60:63], v[148:151], v[180:183], v[60:63]
	v_mfma_f32_16x16x32_bf16 v[56:59], v[156:159], v[180:183], v[56:59]
	v_mfma_f32_16x16x32_bf16 v[48:51], v[148:151], v[188:191], v[48:51]
	v_mfma_f32_16x16x32_bf16 v[40:43], v[156:159], v[188:191], v[40:43]
	v_mfma_f32_16x16x32_bf16 v[32:35], v[148:151], v[196:199], v[32:35]
	v_mfma_f32_16x16x32_bf16 v[24:27], v[156:159], v[196:199], v[24:27]
	v_mfma_f32_16x16x32_bf16 v[16:19], v[148:151], v[206:209], v[16:19]
	v_mfma_f32_16x16x32_bf16 v[8:11], v[156:159], v[206:209], v[8:11]
	s_setprio 0
	s_setprio 1
	v_mfma_f32_16x16x32_bf16 v[52:55], v[160:163], v[176:179], v[52:55]
	v_mfma_f32_16x16x32_bf16 v[44:47], v[168:171], v[176:179], v[44:47]
	v_mfma_f32_16x16x32_bf16 v[36:39], v[160:163], v[184:187], v[36:39]
	v_mfma_f32_16x16x32_bf16 v[28:31], v[168:171], v[184:187], v[28:31]
	v_mfma_f32_16x16x32_bf16 v[20:23], v[160:163], v[192:195], v[20:23]
	v_mfma_f32_16x16x32_bf16 v[12:15], v[168:171], v[192:195], v[12:15]
	v_mfma_f32_16x16x32_bf16 v[4:7], v[160:163], v[200:203], v[4:7]
	v_mfma_f32_16x16x32_bf16 v[0:3], v[168:171], v[200:203], v[0:3]
	v_mfma_f32_16x16x32_bf16 v[52:55], v[164:167], v[180:183], v[52:55]
	v_mfma_f32_16x16x32_bf16 v[44:47], v[172:175], v[180:183], v[44:47]
	v_mfma_f32_16x16x32_bf16 v[36:39], v[164:167], v[188:191], v[36:39]
	v_mfma_f32_16x16x32_bf16 v[28:31], v[172:175], v[188:191], v[28:31]
	v_mfma_f32_16x16x32_bf16 v[20:23], v[164:167], v[196:199], v[20:23]
	v_mfma_f32_16x16x32_bf16 v[12:15], v[172:175], v[196:199], v[12:15]
	v_mfma_f32_16x16x32_bf16 v[4:7], v[164:167], v[206:209], v[4:7]
	v_mfma_f32_16x16x32_bf16 v[0:3], v[172:175], v[206:209], v[0:3]
	s_barrier
	s_setprio 0
	s_cmp_gt_u32 s54, 29
	s_cbranch_scc0 .LBB0_661
	s_and_b64 vcc, exec, s[14:15]
	s_cbranch_vccz .LBB0_664
	s_barrier

; #define PG8_STAGE(bufoff, gbase, voff) do { _Pragma("unroll") for (int _i = 0; _i < 2; ++_i) \
;         __builtin_amdgcn_global_load_lds((const unsigned*)((const char*)(gbase) + (voff)[_i]), (PG8_LAS unsigned*)(lds + (bufoff) + ldsw + _i * 8192), 16, 0, 0); } while (0)
; #define PG8_LDA(dst, b, h) do { _Pragma("unroll") for (int m = 0; m < 4; ++m) _Pragma("unroll") for (int k = 0; k < 2; ++k) dst[m][k] = *(const PG8_LAS bf16x8*)(lds + PG8_SA(b, h) + aoff + m * 2048 + k * 1024); } while (0)
; #define PG8_LDB(dst, b, h) do { _Pragma("unroll") for (int n = 0; n < 2; ++n) _Pragma("unroll") for (int k = 0; k < 2; ++k) dst[n][k] = *(const PG8_LAS bf16x8*)(lds + PG8_SB(b, h) + boff + n * 2048 + k * 1024); } while (0)
; #define PG8_WAIT_V(n) asm volatile("s_waitcnt vmcnt(" #n ")" ::: "memory")
; #define PG8_WAIT_L(n) asm volatile("s_waitcnt lgkmcnt(" #n ")" ::: "memory")
; #define PG8_BAR __builtin_amdgcn_s_barrier()
; #define PG8_SCHED __builtin_amdgcn_sched_barrier(0)
; template <class Epi, class Sched, bool ALIGN_EPI = false, bool SP2 = false>
; __device__ __forceinline__ void gemm_phase(PG8_LAS unsigned char* lds, const Gemm g, const Sched& S, const Epi& E, const int tid) {
;     ...
;         const bool has_next = S.next(ui + 1, nxt);
;         const char* nA = has_next ? (const char*)g.A + (size_t)nxt.pm * tstep : cA; const char* nB = has_next ? (const char*)g.Bt + (size_t)nxt.pn * tstep : cB;
;         for (int t = 0; t < nt; t += 2) {
;             const bool last = (t == nt - 2);
;             const char* a1 = cA + (size_t)(t + 1) * kstep;
;             const char* a2 = last ? nA : cA + (size_t)(t + 2) * kstep; const char* b2 = last ? nB : cB + (size_t)(t + 2) * kstep;
;             const char* a3 = a2 + kstep; const char* b3 = b2 + kstep;
;             if (last && has_next) S.a_ready(nxt);
;             if constexpr (SP2) {
;             PG8_LDB(B0, 0, 0); PG8_LDB(B1, 0, 1); PG8_SCHED; PG8_LDA(At, 0, 0); PG8_STAGE(PG8_SA(1, 1), a1 + hstep, voffA);
;             PG8_WAIT_V(8); PG8_WAIT_L(0); PG8_BAR; PG8_MMA(0, 0, At, B0); PG8_MMA(0, 1, At, B1); PG8_BAR; PG8_SCHED;
;             PG8_LDA(At, 0, 1); PG8_STAGE(PG8_SB(0, 0), b2, voffB); PG8_STAGE(PG8_SB(0, 1), b2 + hstep, voffB); PG8_STAGE(PG8_SA(0, 0), a2, voffA);
;             PG8_WAIT_V(8); PG8_WAIT_L(0); PG8_BAR; PG8_MMA(1, 0, At, B0); PG8_MMA(1, 1, At, B1); PG8_BAR; PG8_SCHED;
.LBB0_679:
	s_ashr_i32 s29, s28, 31
	s_lshl_b64 s[30:31], s[28:29], 20
	s_add_u32 s30, s50, s30
	s_addc_u32 s31, s51, s31
	s_and_b64 s[34:35], s[6:7], exec
	s_cselect_b32 s29, s31, s45
	s_cselect_b32 s43, s30, s44
	s_ashr_i32 s27, s26, 31
	s_lshl_b64 s[34:35], s[26:27], 20
	s_add_u32 s34, s52, s34
	s_addc_u32 s35, s53, s35
	s_and_b64 s[48:49], s[6:7], exec
	s_cselect_b32 s27, s35, s47
	s_cselect_b32 s69, s34, s46
	s_add_u32 s44, s44, 0x80080
	s_addc_u32 s45, s45, 0
	s_add_u32 vcc_lo, s46, 0x100
	s_addc_u32 vcc_hi, s47, 0
	s_mov_b32 s76, -2
	s_waitcnt vmcnt(0)
	s_add_i32 s77, 0, 0x10000
	s_add_i32 s80, 0, 0x14000
	v_add_u32_e32 v152, s77, v166
	v_add_u32_e32 v164, s80, v166
	ds_read_b128 v[128:131], v152
	ds_read_b128 v[144:147], v152 offset:1024
	ds_read_b128 v[148:151], v152 offset:2048
	ds_read_b128 v[152:155], v152 offset:3072
	ds_read_b128 v[156:159], v164
	ds_read_b128 v[160:163], v164 offset:1024
	ds_read_b128 v[168:171], v164 offset:2048
	ds_read_b128 v[172:175], v164 offset:3072
	v_lshl_add_u64 v[164:165], s[44:45], 0, v[140:141]
	s_add_i32 m0, s37, 0xc000
	ds_read_b128 v[176:179], v167
	ds_read_b128 v[180:183], v167 offset:1024
	ds_read_b128 v[184:187], v167 offset:2048
	ds_read_b128 v[188:191], v167 offset:3072
	ds_read_b128 v[192:195], v167 offset:4096
	ds_read_b128 v[196:199], v167 offset:5120
	ds_read_b128 v[200:203], v167 offset:6144
	ds_read_b128 v[214:217], v167 offset:7168
	s_add_u32 s46, s44, 0xfff80080
	s_addc_u32 s47, s45, -1
	s_cmp_eq_u32 s76, 28
	s_cselect_b32 s49, s29, s47
	s_cselect_b32 s48, s43, s46
	s_cselect_b32 s47, s27, vcc_hi
	s_cselect_b32 s46, s69, vcc_lo
	global_load_lds_dwordx4 v[164:165], off
	v_lshl_add_u64 v[164:165], s[44:45], 0, v[142:143]
	s_add_i32 m0, s37, 0xe000
	s_nop 0
	global_load_lds_dwordx4 v[164:165], off
	s_waitcnt vmcnt(24)
	s_waitcnt lgkmcnt(0)
	s_setprio 1
	s_barrier
	v_mfma_f32_16x16x32_bf16 v[124:127], v[128:131], v[176:179], 0
	v_mfma_f32_16x16x32_bf16 v[120:123], v[148:151], v[176:179], 0
	v_mfma_f32_16x16x32_bf16 v[108:111], v[128:131], v[184:187], 0
	v_mfma_f32_16x16x32_bf16 v[104:107], v[148:151], v[184:187], 0
	v_mfma_f32_16x16x32_bf16 v[92:95], v[128:131], v[192:195], 0
	v_mfma_f32_16x16x32_bf16 v[88:91], v[148:151], v[192:195], 0
	v_mfma_f32_16x16x32_bf16 v[76:79], v[128:131], v[200:203], 0
	v_mfma_f32_16x16x32_bf16 v[72:75], v[148:151], v[200:203], 0
	v_mfma_f32_16x16x32_bf16 v[124:127], v[144:147], v[180:183], v[124:127]
	v_mfma_f32_16x16x32_bf16 v[120:123], v[152:155], v[180:183], v[120:123]
	v_mfma_f32_16x16x32_bf16 v[108:111], v[144:147], v[188:191], v[108:111]
	v_mfma_f32_16x16x32_bf16 v[104:107], v[152:155], v[188:191], v[104:107]
	v_mfma_f32_16x16x32_bf16 v[92:95], v[144:147], v[196:199], v[92:95]
	v_mfma_f32_16x16x32_bf16 v[88:91], v[152:155], v[196:199], v[88:91]
	v_mfma_f32_16x16x32_bf16 v[76:79], v[144:147], v[214:217], v[76:79]
	v_mfma_f32_16x16x32_bf16 v[72:75], v[152:155], v[214:217], v[72:75]
	s_setprio 0
	s_setprio 1
	v_mfma_f32_16x16x32_bf16 v[116:119], v[156:159], v[176:179], 0
	v_mfma_f32_16x16x32_bf16 v[112:115], v[168:171], v[176:179], 0
	v_mfma_f32_16x16x32_bf16 v[100:103], v[156:159], v[184:187], 0
	v_mfma_f32_16x16x32_bf16 v[96:99], v[168:171], v[184:187], 0
	v_mfma_f32_16x16x32_bf16 v[84:87], v[156:159], v[192:195], 0
	v_mfma_f32_16x16x32_bf16 v[80:83], v[168:171], v[192:195], 0
	v_mfma_f32_16x16x32_bf16 v[68:71], v[156:159], v[200:203], 0
	v_mfma_f32_16x16x32_bf16 v[64:67], v[168:171], v[200:203], 0
	v_mfma_f32_16x16x32_bf16 v[116:119], v[160:163], v[180:183], v[116:119]
	v_mfma_f32_16x16x32_bf16 v[112:115], v[172:175], v[180:183], v[112:115]
	v_mfma_f32_16x16x32_bf16 v[100:103], v[160:163], v[188:191], v[100:103]
	v_mfma_f32_16x16x32_bf16 v[96:99], v[172:175], v[188:191], v[96:99]
	v_mfma_f32_16x16x32_bf16 v[84:87], v[160:163], v[196:199], v[84:87]
	v_mfma_f32_16x16x32_bf16 v[80:83], v[172:175], v[196:199], v[80:83]
	v_mfma_f32_16x16x32_bf16 v[68:71], v[160:163], v[214:217], v[68:71]
	v_mfma_f32_16x16x32_bf16 v[64:67], v[172:175], v[214:217], v[64:67]
	s_barrier
	s_setprio 0
	s_add_i32 s77, s77, s54
	v_lshl_add_u64 v[164:165], s[46:47], 0, v[134:135]
	s_mov_b32 m0, s77
	ds_read_b128 v[176:179], v167 offset:16384
	ds_read_b128 v[180:183], v167 offset:17408
	ds_read_b128 v[184:187], v167 offset:18432
	ds_read_b128 v[188:191], v167 offset:19456
	ds_read_b128 v[192:195], v167 offset:20480
	ds_read_b128 v[196:199], v167 offset:21504
	ds_read_b128 v[200:203], v167 offset:22528
	ds_read_b128 v[214:217], v167 offset:23552
	global_load_lds_dwordx4 v[164:165], off
	s_add_i32 m0, s77, 0x2000
	s_add_u32 s78, s46, 0x80000
	v_lshl_add_u64 v[206:207], s[46:47], 0, v[138:139]
	s_addc_u32 s79, s47, 0
	s_add_i32 s77, s80, s54
	global_load_lds_dwordx4 v[206:207], off
	v_lshl_add_u64 v[208:209], s[78:79], 0, v[134:135]
	s_mov_b32 m0, s77
	v_lshl_add_u64 v[210:211], s[48:49], 0, v[136:137]
	global_load_lds_dwordx4 v[208:209], off
	v_lshl_add_u64 v[208:209], s[78:79], 0, v[138:139]
	s_add_i32 m0, s77, 0x2000
	s_nop 0
	global_load_lds_dwordx4 v[208:209], off
	v_lshl_add_u64 v[208:209], s[48:49], 0, v[132:133]
	s_mov_b32 m0, s37
	s_nop 0
	global_load_lds_dwordx4 v[208:209], off
	s_mov_b32 m0, s55
	s_nop 0
	global_load_lds_dwordx4 v[210:211], off
	s_waitcnt vmcnt(8)
	s_waitcnt lgkmcnt(0)
	s_setprio 1
	s_barrier
; #define PG8_STAGE(bufoff, gbase, voff) do { _Pragma("unroll") for (int _i = 0; _i < 2; ++_i) \
;         __builtin_amdgcn_global_load_lds((const unsigned*)((const char*)(gbase) + (voff)[_i]), (PG8_LAS unsigned*)(lds + (bufoff) + ldsw + _i * 8192), 16, 0, 0); } while (0)
; #define PG8_LDA(dst, b, h) do { _Pragma("unroll") for (int m = 0; m < 4; ++m) _Pragma("unroll") for (int k = 0; k < 2; ++k) dst[m][k] = *(const PG8_LAS bf16x8*)(lds + PG8_SA(b, h) + aoff + m * 2048 + k * 1024); } while (0)
; #define PG8_LDB(dst, b, h) do { _Pragma("unroll") for (int n = 0; n < 2; ++n) _Pragma("unroll") for (int k = 0; k < 2; ++k) dst[n][k] = *(const PG8_LAS bf16x8*)(lds + PG8_SB(b, h) + boff + n * 2048 + k * 1024); } while (0)
; #define PG8_MMA(ai, bj, At, Bt) do { __builtin_amdgcn_s_setprio(1); _Pragma("unroll") for (int m = 0; m < 4; ++m) _Pragma("unroll") for (int n = 0; n < 2; ++n) _Pragma("unroll") for (int k = 0; k < 2; ++k) \
;         acc[ai][bj][m][n] = __builtin_amdgcn_mfma_f32_16x16x32_bf16(Bt[n][k], At[m][k], acc[ai][bj][m][n], 0, 0, 0); __builtin_amdgcn_s_setprio(0); } while (0)
; #define PG8_WAIT_V(n) asm volatile("s_waitcnt vmcnt(" #n ")" ::: "memory")
; #define PG8_WAIT_L(n) asm volatile("s_waitcnt lgkmcnt(" #n ")" ::: "memory")
; #define PG8_BAR __builtin_amdgcn_s_barrier()
; #define PG8_SCHED __builtin_amdgcn_sched_barrier(0)
; template <class Epi, class Sched, bool ALIGN_EPI = false, bool SP2 = false>
; __device__ __forceinline__ void gemm_phase(PG8_LAS unsigned char* lds, const Gemm g, const Sched& S, const Epi& E, const int tid) {
;     ...
;             PG8_WAIT_V(8); PG8_WAIT_L(0); PG8_BAR; PG8_MMA(1, 0, At, B0); PG8_MMA(1, 1, At, B1); PG8_BAR; PG8_SCHED;
;             PG8_LDB(B0, 1, 0); PG8_LDB(B1, 1, 1); PG8_SCHED; PG8_LDA(At, 1, 0); PG8_STAGE(PG8_SA(0, 1), a2 + hstep, voffA);
;             PG8_WAIT_V(8); PG8_WAIT_L(0); PG8_BAR; PG8_MMA(0, 0, At, B0); PG8_MMA(0, 1, At, B1); PG8_BAR; PG8_SCHED;
	v_mfma_f32_16x16x32_bf16 v[60:63], v[128:131], v[176:179], 0
	v_mfma_f32_16x16x32_bf16 v[56:59], v[148:151], v[176:179], 0
	v_mfma_f32_16x16x32_bf16 v[44:47], v[128:131], v[184:187], 0
	v_mfma_f32_16x16x32_bf16 v[40:43], v[148:151], v[184:187], 0
	v_mfma_f32_16x16x32_bf16 v[28:31], v[128:131], v[192:195], 0
	v_mfma_f32_16x16x32_bf16 v[24:27], v[148:151], v[192:195], 0
	v_mfma_f32_16x16x32_bf16 v[12:15], v[128:131], v[200:203], 0
	v_mfma_f32_16x16x32_bf16 v[8:11], v[148:151], v[200:203], 0
	v_mfma_f32_16x16x32_bf16 v[60:63], v[144:147], v[180:183], v[60:63]
	v_mfma_f32_16x16x32_bf16 v[56:59], v[152:155], v[180:183], v[56:59]
	v_mfma_f32_16x16x32_bf16 v[44:47], v[144:147], v[188:191], v[44:47]
	v_mfma_f32_16x16x32_bf16 v[40:43], v[152:155], v[188:191], v[40:43]
	v_mfma_f32_16x16x32_bf16 v[28:31], v[144:147], v[196:199], v[28:31]
	v_mfma_f32_16x16x32_bf16 v[24:27], v[152:155], v[196:199], v[24:27]
	v_mfma_f32_16x16x32_bf16 v[12:15], v[144:147], v[214:217], v[12:15]
	v_mfma_f32_16x16x32_bf16 v[8:11], v[152:155], v[214:217], v[8:11]
	s_setprio 0
	s_setprio 1
	v_mfma_f32_16x16x32_bf16 v[52:55], v[156:159], v[176:179], 0
	v_mfma_f32_16x16x32_bf16 v[48:51], v[168:171], v[176:179], 0
	v_mfma_f32_16x16x32_bf16 v[36:39], v[156:159], v[184:187], 0
	v_mfma_f32_16x16x32_bf16 v[32:35], v[168:171], v[184:187], 0
	v_mfma_f32_16x16x32_bf16 v[20:23], v[156:159], v[192:195], 0
	v_mfma_f32_16x16x32_bf16 v[16:19], v[168:171], v[192:195], 0
	v_mfma_f32_16x16x32_bf16 v[4:7], v[156:159], v[200:203], 0
	v_mfma_f32_16x16x32_bf16 v[0:3], v[168:171], v[200:203], 0
	v_mfma_f32_16x16x32_bf16 v[52:55], v[160:163], v[180:183], v[52:55]
	v_mfma_f32_16x16x32_bf16 v[48:51], v[172:175], v[180:183], v[48:51]
	v_mfma_f32_16x16x32_bf16 v[36:39], v[160:163], v[188:191], v[36:39]
	v_mfma_f32_16x16x32_bf16 v[32:35], v[172:175], v[188:191], v[32:35]
	v_mfma_f32_16x16x32_bf16 v[20:23], v[160:163], v[196:199], v[20:23]
	v_mfma_f32_16x16x32_bf16 v[16:19], v[172:175], v[196:199], v[16:19]
	v_mfma_f32_16x16x32_bf16 v[4:7], v[160:163], v[214:217], v[4:7]
	v_mfma_f32_16x16x32_bf16 v[0:3], v[172:175], v[214:217], v[0:3]
	s_barrier
	s_setprio 0
	s_add_i32 s77, 0, 0x18000
	s_add_i32 s78, 0, 0x1c000
	v_add_u32_e32 v152, s77, v166
	v_add_u32_e32 v172, s78, v166
	ds_read_b128 v[128:131], v152
	ds_read_b128 v[144:147], v152 offset:1024
	ds_read_b128 v[148:151], v152 offset:2048
	ds_read_b128 v[152:155], v152 offset:3072
	ds_read_b128 v[156:159], v172
	ds_read_b128 v[160:163], v172 offset:1024
	ds_read_b128 v[168:171], v172 offset:2048
	ds_read_b128 v[172:175], v172 offset:3072
	s_add_u32 s48, s48, 0x80000
	s_addc_u32 s49, s49, 0
	s_mov_b32 m0, s0
	v_lshl_add_u64 v[212:213], s[48:49], 0, v[132:133]
	ds_read_b128 v[176:179], v167 offset:32768
	ds_read_b128 v[180:183], v167 offset:33792
	ds_read_b128 v[184:187], v167 offset:34816
	ds_read_b128 v[188:191], v167 offset:35840
	ds_read_b128 v[192:195], v167 offset:36864
	ds_read_b128 v[196:199], v167 offset:37888
	ds_read_b128 v[200:203], v167 offset:38912
	ds_read_b128 v[214:217], v167 offset:39936
	global_load_lds_dwordx4 v[212:213], off
	v_lshl_add_u64 v[212:213], s[48:49], 0, v[136:137]
	s_mov_b32 m0, s33
	s_nop 0
	global_load_lds_dwordx4 v[212:213], off
	s_waitcnt vmcnt(8)
	s_waitcnt lgkmcnt(0)
	s_setprio 1
	s_barrier
	v_mfma_f32_16x16x32_bf16 v[124:127], v[128:131], v[176:179], v[124:127]
	v_mfma_f32_16x16x32_bf16 v[120:123], v[148:151], v[176:179], v[120:123]
	v_mfma_f32_16x16x32_bf16 v[108:111], v[128:131], v[184:187], v[108:111]
	v_mfma_f32_16x16x32_bf16 v[104:107], v[148:151], v[184:187], v[104:107]
	v_mfma_f32_16x16x32_bf16 v[92:95], v[128:131], v[192:195], v[92:95]
	v_mfma_f32_16x16x32_bf16 v[88:91], v[148:151], v[192:195], v[88:91]
	v_mfma_f32_16x16x32_bf16 v[76:79], v[128:131], v[200:203], v[76:79]
	v_mfma_f32_16x16x32_bf16 v[72:75], v[148:151], v[200:203], v[72:75]
	v_mfma_f32_16x16x32_bf16 v[124:127], v[144:147], v[180:183], v[124:127]
	v_mfma_f32_16x16x32_bf16 v[120:123], v[152:155], v[180:183], v[120:123]
	v_mfma_f32_16x16x32_bf16 v[108:111], v[144:147], v[188:191], v[108:111]
	v_mfma_f32_16x16x32_bf16 v[104:107], v[152:155], v[188:191], v[104:107]
	v_mfma_f32_16x16x32_bf16 v[92:95], v[144:147], v[196:199], v[92:95]
	v_mfma_f32_16x16x32_bf16 v[88:91], v[152:155], v[196:199], v[88:91]
	v_mfma_f32_16x16x32_bf16 v[76:79], v[144:147], v[214:217], v[76:79]
	v_mfma_f32_16x16x32_bf16 v[72:75], v[152:155], v[214:217], v[72:75]
	s_setprio 0
	s_setprio 1
	v_mfma_f32_16x16x32_bf16 v[116:119], v[156:159], v[176:179], v[116:119]
	v_mfma_f32_16x16x32_bf16 v[112:115], v[168:171], v[176:179], v[112:115]
	v_mfma_f32_16x16x32_bf16 v[100:103], v[156:159], v[184:187], v[100:103]
	v_mfma_f32_16x16x32_bf16 v[96:99], v[168:171], v[184:187], v[96:99]
	v_mfma_f32_16x16x32_bf16 v[84:87], v[156:159], v[192:195], v[84:87]
	v_mfma_f32_16x16x32_bf16 v[80:83], v[168:171], v[192:195], v[80:83]
	v_mfma_f32_16x16x32_bf16 v[68:71], v[156:159], v[200:203], v[68:71]
	v_mfma_f32_16x16x32_bf16 v[64:67], v[168:171], v[200:203], v[64:67]
	v_mfma_f32_16x16x32_bf16 v[116:119], v[160:163], v[180:183], v[116:119]
	v_mfma_f32_16x16x32_bf16 v[112:115], v[172:175], v[180:183], v[112:115]
	v_mfma_f32_16x16x32_bf16 v[100:103], v[160:163], v[188:191], v[100:103]
	v_mfma_f32_16x16x32_bf16 v[96:99], v[172:175], v[188:191], v[96:99]
	v_mfma_f32_16x16x32_bf16 v[84:87], v[160:163], v[196:199], v[84:87]
	v_mfma_f32_16x16x32_bf16 v[80:83], v[172:175], v[196:199], v[80:83]
	v_mfma_f32_16x16x32_bf16 v[68:71], v[160:163], v[214:217], v[68:71]
	v_mfma_f32_16x16x32_bf16 v[64:67], v[172:175], v[214:217], v[64:67]
	s_barrier
; #define PG8_STAGE(bufoff, gbase, voff) do { _Pragma("unroll") for (int _i = 0; _i < 2; ++_i) \
;         __builtin_amdgcn_global_load_lds((const unsigned*)((const char*)(gbase) + (voff)[_i]), (PG8_LAS unsigned*)(lds + (bufoff) + ldsw + _i * 8192), 16, 0, 0); } while (0)
; #define PG8_LDA(dst, b, h) do { _Pragma("unroll") for (int m = 0; m < 4; ++m) _Pragma("unroll") for (int k = 0; k < 2; ++k) dst[m][k] = *(const PG8_LAS bf16x8*)(lds + PG8_SA(b, h) + aoff + m * 2048 + k * 1024); } while (0)
; #define PG8_LDB(dst, b, h) do { _Pragma("unroll") for (int n = 0; n < 2; ++n) _Pragma("unroll") for (int k = 0; k < 2; ++k) dst[n][k] = *(const PG8_LAS bf16x8*)(lds + PG8_SB(b, h) + boff + n * 2048 + k * 1024); } while (0)
; #define PG8_MMA(ai, bj, At, Bt) do { __builtin_amdgcn_s_setprio(1); _Pragma("unroll") for (int m = 0; m < 4; ++m) _Pragma("unroll") for (int n = 0; n < 2; ++n) _Pragma("unroll") for (int k = 0; k < 2; ++k) \
;         acc[ai][bj][m][n] = __builtin_amdgcn_mfma_f32_16x16x32_bf16(Bt[n][k], At[m][k], acc[ai][bj][m][n], 0, 0, 0); __builtin_amdgcn_s_setprio(0); } while (0)
; #define PG8_WAIT_V(n) asm volatile("s_waitcnt vmcnt(" #n ")" ::: "memory")
; #define PG8_WAIT_L(n) asm volatile("s_waitcnt lgkmcnt(" #n ")" ::: "memory")
; #define PG8_BAR __builtin_amdgcn_s_barrier()
; template <class Epi, class Sched, bool ALIGN_EPI = false, bool SP2 = false>
; __device__ __forceinline__ void gemm_phase(PG8_LAS unsigned char* lds, const Gemm g, const Sched& S, const Epi& E, const int tid) {
;     ...
;         for (int t = 0; t < nt; t += 2) {
;             const bool last = (t == nt - 2);
;             const char* a1 = cA + (size_t)(t + 1) * kstep;
;             const char* a2 = last ? nA : cA + (size_t)(t + 2) * kstep; const char* b2 = last ? nB : cB + (size_t)(t + 2) * kstep;
;             const char* a3 = a2 + kstep; const char* b3 = b2 + kstep;
;             if (last && has_next) S.a_ready(nxt);
;             if constexpr (SP2) {
;             PG8_LDB(B0, 0, 0); PG8_LDB(B1, 0, 1); PG8_SCHED; PG8_LDA(At, 0, 0); PG8_STAGE(PG8_SA(1, 1), a1 + hstep, voffA);
;     ...
;             PG8_LDA(At, 1, 1); PG8_STAGE(PG8_SB(1, 0), b3, voffB); PG8_STAGE(PG8_SB(1, 1), b3 + hstep, voffB); PG8_STAGE(PG8_SA(1, 0), a3, voffA);
;             PG8_WAIT_V(8); PG8_WAIT_L(0); PG8_BAR; PG8_MMA(1, 0, At, B0); PG8_MMA(1, 1, At, B1); PG8_BAR; PG8_SCHED;
	s_setprio 0
	s_add_i32 s48, s77, s54
	v_lshl_add_u64 v[164:165], v[164:165], 0, s[70:71]
	s_mov_b32 m0, s48
	ds_read_b128 v[176:179], v167 offset:49152
	ds_read_b128 v[180:183], v167 offset:50176
	ds_read_b128 v[184:187], v167 offset:51200
	ds_read_b128 v[188:191], v167 offset:52224
	ds_read_b128 v[192:195], v167 offset:53248
	ds_read_b128 v[196:199], v167 offset:54272
	ds_read_b128 v[200:203], v167 offset:55296
	ds_read_b128 v[214:217], v167 offset:56320
	global_load_lds_dwordx4 v[164:165], off
	s_add_i32 m0, s48, 0x2000
	s_add_u32 s46, s46, 0x80080
	v_lshl_add_u64 v[164:165], v[206:207], 0, s[70:71]
	s_addc_u32 s47, s47, 0
	s_add_i32 s48, s78, s54
	global_load_lds_dwordx4 v[164:165], off
	v_lshl_add_u64 v[164:165], s[46:47], 0, v[134:135]
	s_mov_b32 m0, s48
	s_nop 0
	global_load_lds_dwordx4 v[164:165], off
	v_lshl_add_u64 v[164:165], s[46:47], 0, v[138:139]
	s_add_i32 m0, s48, 0x2000
	s_nop 0
	global_load_lds_dwordx4 v[164:165], off
	v_lshl_add_u64 v[164:165], v[208:209], 0, s[70:71]
	s_mov_b32 m0, s10
	s_nop 0
	global_load_lds_dwordx4 v[164:165], off
	v_lshl_add_u64 v[164:165], v[210:211], 0, s[70:71]
	s_mov_b32 m0, s11
	s_nop 0
	global_load_lds_dwordx4 v[164:165], off
	s_add_i32 s76, s76, 2
	s_add_u32 s44, s44, 0x100
	s_addc_u32 s45, s45, 0
	s_add_u32 vcc_lo, vcc_lo, 0x100
	s_addc_u32 vcc_hi, vcc_hi, 0
	s_waitcnt vmcnt(8)
	s_waitcnt lgkmcnt(0)
	s_setprio 1
	s_barrier
	v_mfma_f32_16x16x32_bf16 v[60:63], v[128:131], v[176:179], v[60:63]
	v_mfma_f32_16x16x32_bf16 v[56:59], v[148:151], v[176:179], v[56:59]
	v_mfma_f32_16x16x32_bf16 v[44:47], v[128:131], v[184:187], v[44:47]
	v_mfma_f32_16x16x32_bf16 v[40:43], v[148:151], v[184:187], v[40:43]
	v_mfma_f32_16x16x32_bf16 v[28:31], v[128:131], v[192:195], v[28:31]
	v_mfma_f32_16x16x32_bf16 v[24:27], v[148:151], v[192:195], v[24:27]
	v_mfma_f32_16x16x32_bf16 v[12:15], v[128:131], v[200:203], v[12:15]
	v_mfma_f32_16x16x32_bf16 v[8:11], v[148:151], v[200:203], v[8:11]
	v_mfma_f32_16x16x32_bf16 v[60:63], v[144:147], v[180:183], v[60:63]
	v_mfma_f32_16x16x32_bf16 v[56:59], v[152:155], v[180:183], v[56:59]
	v_mfma_f32_16x16x32_bf16 v[44:47], v[144:147], v[188:191], v[44:47]
	v_mfma_f32_16x16x32_bf16 v[40:43], v[152:155], v[188:191], v[40:43]
	v_mfma_f32_16x16x32_bf16 v[28:31], v[144:147], v[196:199], v[28:31]
	v_mfma_f32_16x16x32_bf16 v[24:27], v[152:155], v[196:199], v[24:27]
	v_mfma_f32_16x16x32_bf16 v[12:15], v[144:147], v[214:217], v[12:15]
	v_mfma_f32_16x16x32_bf16 v[8:11], v[152:155], v[214:217], v[8:11]
	s_setprio 0
	s_setprio 1
	v_mfma_f32_16x16x32_bf16 v[52:55], v[156:159], v[176:179], v[52:55]
	v_mfma_f32_16x16x32_bf16 v[48:51], v[168:171], v[176:179], v[48:51]
	v_mfma_f32_16x16x32_bf16 v[36:39], v[156:159], v[184:187], v[36:39]
	v_mfma_f32_16x16x32_bf16 v[32:35], v[168:171], v[184:187], v[32:35]
	v_mfma_f32_16x16x32_bf16 v[20:23], v[156:159], v[192:195], v[20:23]
	v_mfma_f32_16x16x32_bf16 v[16:19], v[168:171], v[192:195], v[16:19]
	v_mfma_f32_16x16x32_bf16 v[4:7], v[156:159], v[200:203], v[4:7]
	v_mfma_f32_16x16x32_bf16 v[0:3], v[168:171], v[200:203], v[0:3]
	v_mfma_f32_16x16x32_bf16 v[52:55], v[160:163], v[180:183], v[52:55]
	v_mfma_f32_16x16x32_bf16 v[48:51], v[172:175], v[180:183], v[48:51]
	v_mfma_f32_16x16x32_bf16 v[36:39], v[160:163], v[188:191], v[36:39]
	v_mfma_f32_16x16x32_bf16 v[32:35], v[172:175], v[188:191], v[32:35]
	v_mfma_f32_16x16x32_bf16 v[20:23], v[160:163], v[196:199], v[20:23]
	v_mfma_f32_16x16x32_bf16 v[16:19], v[172:175], v[196:199], v[16:19]
	v_mfma_f32_16x16x32_bf16 v[4:7], v[160:163], v[214:217], v[4:7]
	v_mfma_f32_16x16x32_bf16 v[0:3], v[172:175], v[214:217], v[0:3]
	s_barrier
	s_setprio 0
.LBB0_680:
	s_add_i32 s77, 0, 0x10000
	s_add_i32 s80, 0, 0x14000
	v_add_u32_e32 v152, s77, v166
	v_add_u32_e32 v164, s80, v166
	ds_read_b128 v[128:131], v152
	ds_read_b128 v[144:147], v152 offset:1024
	ds_read_b128 v[148:151], v152 offset:2048
	ds_read_b128 v[152:155], v152 offset:3072
	ds_read_b128 v[156:159], v164
	ds_read_b128 v[160:163], v164 offset:1024
	ds_read_b128 v[168:171], v164 offset:2048
	ds_read_b128 v[172:175], v164 offset:3072
	v_lshl_add_u64 v[164:165], s[44:45], 0, v[140:141]
	s_add_i32 m0, s37, 0xc000
	ds_read_b128 v[176:179], v167
	ds_read_b128 v[180:183], v167 offset:1024
	ds_read_b128 v[184:187], v167 offset:2048
	ds_read_b128 v[188:191], v167 offset:3072
	ds_read_b128 v[192:195], v167 offset:4096
	ds_read_b128 v[196:199], v167 offset:5120
	ds_read_b128 v[200:203], v167 offset:6144
	ds_read_b128 v[214:217], v167 offset:7168
	s_add_u32 s46, s44, 0xfff80080
	s_addc_u32 s47, s45, -1
	s_cmp_eq_u32 s76, 28
	s_cselect_b32 s49, s29, s47
	s_cselect_b32 s48, s43, s46
	s_cselect_b32 s47, s27, vcc_hi
	s_cselect_b32 s46, s69, vcc_lo
	global_load_lds_dwordx4 v[164:165], off
	v_lshl_add_u64 v[164:165], s[44:45], 0, v[142:143]
	s_add_i32 m0, s37, 0xe000
	s_nop 0
	global_load_lds_dwordx4 v[164:165], off
	s_waitcnt vmcnt(8)
	s_waitcnt lgkmcnt(0)
	s_setprio 1
	s_barrier
; #define PG8_STAGE(bufoff, gbase, voff) do { _Pragma("unroll") for (int _i = 0; _i < 2; ++_i) \
;         __builtin_amdgcn_global_load_lds((const unsigned*)((const char*)(gbase) + (voff)[_i]), (PG8_LAS unsigned*)(lds + (bufoff) + ldsw + _i * 8192), 16, 0, 0); } while (0)
; #define PG8_LDA(dst, b, h) do { _Pragma("unroll") for (int m = 0; m < 4; ++m) _Pragma("unroll") for (int k = 0; k < 2; ++k) dst[m][k] = *(const PG8_LAS bf16x8*)(lds + PG8_SA(b, h) + aoff + m * 2048 + k * 1024); } while (0)
; #define PG8_MMA(ai, bj, At, Bt) do { __builtin_amdgcn_s_setprio(1); _Pragma("unroll") for (int m = 0; m < 4; ++m) _Pragma("unroll") for (int n = 0; n < 2; ++n) _Pragma("unroll") for (int k = 0; k < 2; ++k) \
;         acc[ai][bj][m][n] = __builtin_amdgcn_mfma_f32_16x16x32_bf16(Bt[n][k], At[m][k], acc[ai][bj][m][n], 0, 0, 0); __builtin_amdgcn_s_setprio(0); } while (0)
; #define PG8_WAIT_V(n) asm volatile("s_waitcnt vmcnt(" #n ")" ::: "memory")
; #define PG8_WAIT_L(n) asm volatile("s_waitcnt lgkmcnt(" #n ")" ::: "memory")
; #define PG8_BAR __builtin_amdgcn_s_barrier()
; #define PG8_SCHED __builtin_amdgcn_sched_barrier(0)
; template <class Epi, class Sched, bool ALIGN_EPI = false, bool SP2 = false>
; __device__ __forceinline__ void gemm_phase(PG8_LAS unsigned char* lds, const Gemm g, const Sched& S, const Epi& E, const int tid) {
;     ...
;             PG8_WAIT_V(8); PG8_WAIT_L(0); PG8_BAR; PG8_MMA(0, 0, At, B0); PG8_MMA(0, 1, At, B1); PG8_BAR; PG8_SCHED;
;             PG8_LDA(At, 0, 1); PG8_STAGE(PG8_SB(0, 0), b2, voffB); PG8_STAGE(PG8_SB(0, 1), b2 + hstep, voffB); PG8_STAGE(PG8_SA(0, 0), a2, voffA);
;             PG8_WAIT_V(8); PG8_WAIT_L(0); PG8_BAR; PG8_MMA(1, 0, At, B0); PG8_MMA(1, 1, At, B1); PG8_BAR; PG8_SCHED;
	v_mfma_f32_16x16x32_bf16 v[124:127], v[128:131], v[176:179], v[124:127]
	v_mfma_f32_16x16x32_bf16 v[120:123], v[148:151], v[176:179], v[120:123]
	v_mfma_f32_16x16x32_bf16 v[108:111], v[128:131], v[184:187], v[108:111]
	v_mfma_f32_16x16x32_bf16 v[104:107], v[148:151], v[184:187], v[104:107]
	v_mfma_f32_16x16x32_bf16 v[92:95], v[128:131], v[192:195], v[92:95]
	v_mfma_f32_16x16x32_bf16 v[88:91], v[148:151], v[192:195], v[88:91]
	v_mfma_f32_16x16x32_bf16 v[76:79], v[128:131], v[200:203], v[76:79]
	v_mfma_f32_16x16x32_bf16 v[72:75], v[148:151], v[200:203], v[72:75]
	v_mfma_f32_16x16x32_bf16 v[124:127], v[144:147], v[180:183], v[124:127]
	v_mfma_f32_16x16x32_bf16 v[120:123], v[152:155], v[180:183], v[120:123]
	v_mfma_f32_16x16x32_bf16 v[108:111], v[144:147], v[188:191], v[108:111]
	v_mfma_f32_16x16x32_bf16 v[104:107], v[152:155], v[188:191], v[104:107]
	v_mfma_f32_16x16x32_bf16 v[92:95], v[144:147], v[196:199], v[92:95]
	v_mfma_f32_16x16x32_bf16 v[88:91], v[152:155], v[196:199], v[88:91]
	v_mfma_f32_16x16x32_bf16 v[76:79], v[144:147], v[214:217], v[76:79]
	v_mfma_f32_16x16x32_bf16 v[72:75], v[152:155], v[214:217], v[72:75]
	s_setprio 0
	s_setprio 1
	v_mfma_f32_16x16x32_bf16 v[116:119], v[156:159], v[176:179], v[116:119]
	v_mfma_f32_16x16x32_bf16 v[112:115], v[168:171], v[176:179], v[112:115]
	v_mfma_f32_16x16x32_bf16 v[100:103], v[156:159], v[184:187], v[100:103]
	v_mfma_f32_16x16x32_bf16 v[96:99], v[168:171], v[184:187], v[96:99]
	v_mfma_f32_16x16x32_bf16 v[84:87], v[156:159], v[192:195], v[84:87]
	v_mfma_f32_16x16x32_bf16 v[80:83], v[168:171], v[192:195], v[80:83]
	v_mfma_f32_16x16x32_bf16 v[68:71], v[156:159], v[200:203], v[68:71]
	v_mfma_f32_16x16x32_bf16 v[64:67], v[168:171], v[200:203], v[64:67]
	v_mfma_f32_16x16x32_bf16 v[116:119], v[160:163], v[180:183], v[116:119]
	v_mfma_f32_16x16x32_bf16 v[112:115], v[172:175], v[180:183], v[112:115]
	v_mfma_f32_16x16x32_bf16 v[100:103], v[160:163], v[188:191], v[100:103]
	v_mfma_f32_16x16x32_bf16 v[96:99], v[172:175], v[188:191], v[96:99]
	v_mfma_f32_16x16x32_bf16 v[84:87], v[160:163], v[196:199], v[84:87]
	v_mfma_f32_16x16x32_bf16 v[80:83], v[172:175], v[196:199], v[80:83]
	v_mfma_f32_16x16x32_bf16 v[68:71], v[160:163], v[214:217], v[68:71]
	v_mfma_f32_16x16x32_bf16 v[64:67], v[172:175], v[214:217], v[64:67]
	s_barrier
	s_setprio 0
	s_add_i32 s77, s77, s54
	v_lshl_add_u64 v[164:165], s[46:47], 0, v[134:135]
	s_mov_b32 m0, s77
	ds_read_b128 v[176:179], v167 offset:16384
	ds_read_b128 v[180:183], v167 offset:17408
	ds_read_b128 v[184:187], v167 offset:18432
	ds_read_b128 v[188:191], v167 offset:19456
	ds_read_b128 v[192:195], v167 offset:20480
	ds_read_b128 v[196:199], v167 offset:21504
	ds_read_b128 v[200:203], v167 offset:22528
	ds_read_b128 v[214:217], v167 offset:23552
	global_load_lds_dwordx4 v[164:165], off
	s_add_i32 m0, s77, 0x2000
	s_add_u32 s78, s46, 0x80000
	v_lshl_add_u64 v[206:207], s[46:47], 0, v[138:139]
	s_addc_u32 s79, s47, 0
	s_add_i32 s77, s80, s54
	global_load_lds_dwordx4 v[206:207], off
	v_lshl_add_u64 v[208:209], s[78:79], 0, v[134:135]
	s_mov_b32 m0, s77
	v_lshl_add_u64 v[210:211], s[48:49], 0, v[136:137]
	global_load_lds_dwordx4 v[208:209], off
	v_lshl_add_u64 v[208:209], s[78:79], 0, v[138:139]
	s_add_i32 m0, s77, 0x2000
	s_nop 0
	global_load_lds_dwordx4 v[208:209], off
	v_lshl_add_u64 v[208:209], s[48:49], 0, v[132:133]
	s_mov_b32 m0, s37
	s_nop 0
	global_load_lds_dwordx4 v[208:209], off
	s_mov_b32 m0, s55
	s_nop 0
	global_load_lds_dwordx4 v[210:211], off
	s_waitcnt vmcnt(8)
	s_waitcnt lgkmcnt(0)
	s_setprio 1
	s_barrier
	v_mfma_f32_16x16x32_bf16 v[60:63], v[128:131], v[176:179], v[60:63]
	v_mfma_f32_16x16x32_bf16 v[56:59], v[148:151], v[176:179], v[56:59]
	v_mfma_f32_16x16x32_bf16 v[44:47], v[128:131], v[184:187], v[44:47]
	v_mfma_f32_16x16x32_bf16 v[40:43], v[148:151], v[184:187], v[40:43]
	v_mfma_f32_16x16x32_bf16 v[28:31], v[128:131], v[192:195], v[28:31]
	v_mfma_f32_16x16x32_bf16 v[24:27], v[148:151], v[192:195], v[24:27]
	v_mfma_f32_16x16x32_bf16 v[12:15], v[128:131], v[200:203], v[12:15]
	v_mfma_f32_16x16x32_bf16 v[8:11], v[148:151], v[200:203], v[8:11]
	v_mfma_f32_16x16x32_bf16 v[60:63], v[144:147], v[180:183], v[60:63]
	v_mfma_f32_16x16x32_bf16 v[56:59], v[152:155], v[180:183], v[56:59]
	v_mfma_f32_16x16x32_bf16 v[44:47], v[144:147], v[188:191], v[44:47]
	v_mfma_f32_16x16x32_bf16 v[40:43], v[152:155], v[188:191], v[40:43]
	v_mfma_f32_16x16x32_bf16 v[28:31], v[144:147], v[196:199], v[28:31]
	v_mfma_f32_16x16x32_bf16 v[24:27], v[152:155], v[196:199], v[24:27]
	v_mfma_f32_16x16x32_bf16 v[12:15], v[144:147], v[214:217], v[12:15]
	v_mfma_f32_16x16x32_bf16 v[8:11], v[152:155], v[214:217], v[8:11]
	s_setprio 0
	s_setprio 1
	v_mfma_f32_16x16x32_bf16 v[52:55], v[156:159], v[176:179], v[52:55]
	v_mfma_f32_16x16x32_bf16 v[48:51], v[168:171], v[176:179], v[48:51]
	v_mfma_f32_16x16x32_bf16 v[36:39], v[156:159], v[184:187], v[36:39]
	v_mfma_f32_16x16x32_bf16 v[32:35], v[168:171], v[184:187], v[32:35]
	v_mfma_f32_16x16x32_bf16 v[20:23], v[156:159], v[192:195], v[20:23]
	v_mfma_f32_16x16x32_bf16 v[16:19], v[168:171], v[192:195], v[16:19]
	v_mfma_f32_16x16x32_bf16 v[4:7], v[156:159], v[200:203], v[4:7]
	v_mfma_f32_16x16x32_bf16 v[0:3], v[168:171], v[200:203], v[0:3]
	v_mfma_f32_16x16x32_bf16 v[52:55], v[160:163], v[180:183], v[52:55]
	v_mfma_f32_16x16x32_bf16 v[48:51], v[172:175], v[180:183], v[48:51]
	v_mfma_f32_16x16x32_bf16 v[36:39], v[160:163], v[188:191], v[36:39]
	v_mfma_f32_16x16x32_bf16 v[32:35], v[172:175], v[188:191], v[32:35]
	v_mfma_f32_16x16x32_bf16 v[20:23], v[160:163], v[196:199], v[20:23]
	v_mfma_f32_16x16x32_bf16 v[16:19], v[172:175], v[196:199], v[16:19]
	v_mfma_f32_16x16x32_bf16 v[4:7], v[160:163], v[214:217], v[4:7]
	v_mfma_f32_16x16x32_bf16 v[0:3], v[172:175], v[214:217], v[0:3]
	s_barrier
; #define PG8_STAGE(bufoff, gbase, voff) do { _Pragma("unroll") for (int _i = 0; _i < 2; ++_i) \
;         __builtin_amdgcn_global_load_lds((const unsigned*)((const char*)(gbase) + (voff)[_i]), (PG8_LAS unsigned*)(lds + (bufoff) + ldsw + _i * 8192), 16, 0, 0); } while (0)
; #define PG8_LDA(dst, b, h) do { _Pragma("unroll") for (int m = 0; m < 4; ++m) _Pragma("unroll") for (int k = 0; k < 2; ++k) dst[m][k] = *(const PG8_LAS bf16x8*)(lds + PG8_SA(b, h) + aoff + m * 2048 + k * 1024); } while (0)
; #define PG8_LDB(dst, b, h) do { _Pragma("unroll") for (int n = 0; n < 2; ++n) _Pragma("unroll") for (int k = 0; k < 2; ++k) dst[n][k] = *(const PG8_LAS bf16x8*)(lds + PG8_SB(b, h) + boff + n * 2048 + k * 1024); } while (0)
; #define PG8_MMA(ai, bj, At, Bt) do { __builtin_amdgcn_s_setprio(1); _Pragma("unroll") for (int m = 0; m < 4; ++m) _Pragma("unroll") for (int n = 0; n < 2; ++n) _Pragma("unroll") for (int k = 0; k < 2; ++k) \
;         acc[ai][bj][m][n] = __builtin_amdgcn_mfma_f32_16x16x32_bf16(Bt[n][k], At[m][k], acc[ai][bj][m][n], 0, 0, 0); __builtin_amdgcn_s_setprio(0); } while (0)
; #define PG8_WAIT_V(n) asm volatile("s_waitcnt vmcnt(" #n ")" ::: "memory")
; #define PG8_WAIT_L(n) asm volatile("s_waitcnt lgkmcnt(" #n ")" ::: "memory")
; #define PG8_BAR __builtin_amdgcn_s_barrier()
; #define PG8_SCHED __builtin_amdgcn_sched_barrier(0)
; template <class Epi, class Sched, bool ALIGN_EPI = false, bool SP2 = false>
; __device__ __forceinline__ void gemm_phase(PG8_LAS unsigned char* lds, const Gemm g, const Sched& S, const Epi& E, const int tid) {
;     ...
;             PG8_LDB(B0, 1, 0); PG8_LDB(B1, 1, 1); PG8_SCHED; PG8_LDA(At, 1, 0); PG8_STAGE(PG8_SA(0, 1), a2 + hstep, voffA);
;             PG8_WAIT_V(8); PG8_WAIT_L(0); PG8_BAR; PG8_MMA(0, 0, At, B0); PG8_MMA(0, 1, At, B1); PG8_BAR; PG8_SCHED;
	s_setprio 0
	s_add_i32 s77, 0, 0x18000
	s_add_i32 s78, 0, 0x1c000
	v_add_u32_e32 v152, s77, v166
	v_add_u32_e32 v172, s78, v166
	ds_read_b128 v[128:131], v152
	ds_read_b128 v[144:147], v152 offset:1024
	ds_read_b128 v[148:151], v152 offset:2048
	ds_read_b128 v[152:155], v152 offset:3072
	ds_read_b128 v[156:159], v172
	ds_read_b128 v[160:163], v172 offset:1024
	ds_read_b128 v[168:171], v172 offset:2048
	ds_read_b128 v[172:175], v172 offset:3072
	s_add_u32 s48, s48, 0x80000
	s_addc_u32 s49, s49, 0
	s_mov_b32 m0, s0
	v_lshl_add_u64 v[212:213], s[48:49], 0, v[132:133]
	ds_read_b128 v[176:179], v167 offset:32768
	ds_read_b128 v[180:183], v167 offset:33792
	ds_read_b128 v[184:187], v167 offset:34816
	ds_read_b128 v[188:191], v167 offset:35840
	ds_read_b128 v[192:195], v167 offset:36864
	ds_read_b128 v[196:199], v167 offset:37888
	ds_read_b128 v[200:203], v167 offset:38912
	ds_read_b128 v[214:217], v167 offset:39936
	global_load_lds_dwordx4 v[212:213], off
	v_lshl_add_u64 v[212:213], s[48:49], 0, v[136:137]
	s_mov_b32 m0, s33
	s_nop 0
	global_load_lds_dwordx4 v[212:213], off
	s_waitcnt vmcnt(8)
	s_waitcnt lgkmcnt(0)
	s_setprio 1
	s_barrier
	v_mfma_f32_16x16x32_bf16 v[124:127], v[128:131], v[176:179], v[124:127]
	v_mfma_f32_16x16x32_bf16 v[120:123], v[148:151], v[176:179], v[120:123]
	v_mfma_f32_16x16x32_bf16 v[108:111], v[128:131], v[184:187], v[108:111]
	v_mfma_f32_16x16x32_bf16 v[104:107], v[148:151], v[184:187], v[104:107]
	v_mfma_f32_16x16x32_bf16 v[92:95], v[128:131], v[192:195], v[92:95]
	v_mfma_f32_16x16x32_bf16 v[88:91], v[148:151], v[192:195], v[88:91]
	v_mfma_f32_16x16x32_bf16 v[76:79], v[128:131], v[200:203], v[76:79]
	v_mfma_f32_16x16x32_bf16 v[72:75], v[148:151], v[200:203], v[72:75]
	v_mfma_f32_16x16x32_bf16 v[124:127], v[144:147], v[180:183], v[124:127]
	v_mfma_f32_16x16x32_bf16 v[120:123], v[152:155], v[180:183], v[120:123]
	v_mfma_f32_16x16x32_bf16 v[108:111], v[144:147], v[188:191], v[108:111]
	v_mfma_f32_16x16x32_bf16 v[104:107], v[152:155], v[188:191], v[104:107]
	v_mfma_f32_16x16x32_bf16 v[92:95], v[144:147], v[196:199], v[92:95]
	v_mfma_f32_16x16x32_bf16 v[88:91], v[152:155], v[196:199], v[88:91]
	v_mfma_f32_16x16x32_bf16 v[76:79], v[144:147], v[214:217], v[76:79]
	v_mfma_f32_16x16x32_bf16 v[72:75], v[152:155], v[214:217], v[72:75]
	s_setprio 0
	s_setprio 1
	v_mfma_f32_16x16x32_bf16 v[116:119], v[156:159], v[176:179], v[116:119]
	v_mfma_f32_16x16x32_bf16 v[112:115], v[168:171], v[176:179], v[112:115]
	v_mfma_f32_16x16x32_bf16 v[100:103], v[156:159], v[184:187], v[100:103]
	v_mfma_f32_16x16x32_bf16 v[96:99], v[168:171], v[184:187], v[96:99]
	v_mfma_f32_16x16x32_bf16 v[84:87], v[156:159], v[192:195], v[84:87]
	v_mfma_f32_16x16x32_bf16 v[80:83], v[168:171], v[192:195], v[80:83]
	v_mfma_f32_16x16x32_bf16 v[68:71], v[156:159], v[200:203], v[68:71]
	v_mfma_f32_16x16x32_bf16 v[64:67], v[168:171], v[200:203], v[64:67]
	v_mfma_f32_16x16x32_bf16 v[116:119], v[160:163], v[180:183], v[116:119]
	v_mfma_f32_16x16x32_bf16 v[112:115], v[172:175], v[180:183], v[112:115]
	v_mfma_f32_16x16x32_bf16 v[100:103], v[160:163], v[188:191], v[100:103]
	v_mfma_f32_16x16x32_bf16 v[96:99], v[172:175], v[188:191], v[96:99]
	v_mfma_f32_16x16x32_bf16 v[84:87], v[160:163], v[196:199], v[84:87]
	v_mfma_f32_16x16x32_bf16 v[80:83], v[172:175], v[196:199], v[80:83]
	v_mfma_f32_16x16x32_bf16 v[68:71], v[160:163], v[214:217], v[68:71]
	v_mfma_f32_16x16x32_bf16 v[64:67], v[172:175], v[214:217], v[64:67]
	s_barrier
; #define PG8_STAGE(bufoff, gbase, voff) do { _Pragma("unroll") for (int _i = 0; _i < 2; ++_i) \
;         __builtin_amdgcn_global_load_lds((const unsigned*)((const char*)(gbase) + (voff)[_i]), (PG8_LAS unsigned*)(lds + (bufoff) + ldsw + _i * 8192), 16, 0, 0); } while (0)
; #define PG8_LDA(dst, b, h) do { _Pragma("unroll") for (int m = 0; m < 4; ++m) _Pragma("unroll") for (int k = 0; k < 2; ++k) dst[m][k] = *(const PG8_LAS bf16x8*)(lds + PG8_SA(b, h) + aoff + m * 2048 + k * 1024); } while (0)
; #define PG8_MMA(ai, bj, At, Bt) do { __builtin_amdgcn_s_setprio(1); _Pragma("unroll") for (int m = 0; m < 4; ++m) _Pragma("unroll") for (int n = 0; n < 2; ++n) _Pragma("unroll") for (int k = 0; k < 2; ++k) \
;         acc[ai][bj][m][n] = __builtin_amdgcn_mfma_f32_16x16x32_bf16(Bt[n][k], At[m][k], acc[ai][bj][m][n], 0, 0, 0); __builtin_amdgcn_s_setprio(0); } while (0)
; #define PG8_WAIT_V(n) asm volatile("s_waitcnt vmcnt(" #n ")" ::: "memory")
; #define PG8_WAIT_L(n) asm volatile("s_waitcnt lgkmcnt(" #n ")" ::: "memory")
; #define PG8_BAR __builtin_amdgcn_s_barrier()
; #define PG8_SCHED __builtin_amdgcn_sched_barrier(0)
; template <class Epi, class Sched, bool ALIGN_EPI = false, bool SP2 = false>
; __device__ __forceinline__ void gemm_phase(PG8_LAS unsigned char* lds, const Gemm g, const Sched& S, const Epi& E, const int tid) {
;     ...
;         for (int t = 0; t < nt; t += 2) {
;             const bool last = (t == nt - 2);
;             const char* a1 = cA + (size_t)(t + 1) * kstep;
;             const char* a2 = last ? nA : cA + (size_t)(t + 2) * kstep; const char* b2 = last ? nB : cB + (size_t)(t + 2) * kstep;
;     ...
;             PG8_LDA(At, 1, 1); PG8_STAGE(PG8_SB(1, 0), b3, voffB); PG8_STAGE(PG8_SB(1, 1), b3 + hstep, voffB); PG8_STAGE(PG8_SA(1, 0), a3, voffA);
;             PG8_WAIT_V(8); PG8_WAIT_L(0); PG8_BAR; PG8_MMA(1, 0, At, B0); PG8_MMA(1, 1, At, B1); PG8_BAR; PG8_SCHED;
	s_setprio 0
	s_add_i32 s48, s77, s54
	v_lshl_add_u64 v[164:165], v[164:165], 0, s[70:71]
	s_mov_b32 m0, s48
	ds_read_b128 v[176:179], v167 offset:49152
	ds_read_b128 v[180:183], v167 offset:50176
	ds_read_b128 v[184:187], v167 offset:51200
	ds_read_b128 v[188:191], v167 offset:52224
	ds_read_b128 v[192:195], v167 offset:53248
	ds_read_b128 v[196:199], v167 offset:54272
	ds_read_b128 v[200:203], v167 offset:55296
	ds_read_b128 v[214:217], v167 offset:56320
	global_load_lds_dwordx4 v[164:165], off
	s_add_i32 m0, s48, 0x2000
	s_add_u32 s46, s46, 0x80080
	v_lshl_add_u64 v[164:165], v[206:207], 0, s[70:71]
	s_addc_u32 s47, s47, 0
	s_add_i32 s48, s78, s54
	global_load_lds_dwordx4 v[164:165], off
	v_lshl_add_u64 v[164:165], s[46:47], 0, v[134:135]
	s_mov_b32 m0, s48
	s_nop 0
	global_load_lds_dwordx4 v[164:165], off
	v_lshl_add_u64 v[164:165], s[46:47], 0, v[138:139]
	s_add_i32 m0, s48, 0x2000
	s_nop 0
	global_load_lds_dwordx4 v[164:165], off
	v_lshl_add_u64 v[164:165], v[208:209], 0, s[70:71]
	s_mov_b32 m0, s10
	s_nop 0
	global_load_lds_dwordx4 v[164:165], off
	v_lshl_add_u64 v[164:165], v[210:211], 0, s[70:71]
	s_mov_b32 m0, s11
	s_nop 0
	global_load_lds_dwordx4 v[164:165], off
	s_add_i32 s76, s76, 2
	s_add_u32 s44, s44, 0x100
	s_addc_u32 s45, s45, 0
	s_add_u32 vcc_lo, vcc_lo, 0x100
	s_addc_u32 vcc_hi, vcc_hi, 0
	s_waitcnt vmcnt(8)
	s_waitcnt lgkmcnt(0)
	s_setprio 1
	s_barrier
	v_mfma_f32_16x16x32_bf16 v[60:63], v[128:131], v[176:179], v[60:63]
	v_mfma_f32_16x16x32_bf16 v[56:59], v[148:151], v[176:179], v[56:59]
	v_mfma_f32_16x16x32_bf16 v[44:47], v[128:131], v[184:187], v[44:47]
	v_mfma_f32_16x16x32_bf16 v[40:43], v[148:151], v[184:187], v[40:43]
	v_mfma_f32_16x16x32_bf16 v[28:31], v[128:131], v[192:195], v[28:31]
	v_mfma_f32_16x16x32_bf16 v[24:27], v[148:151], v[192:195], v[24:27]
	v_mfma_f32_16x16x32_bf16 v[12:15], v[128:131], v[200:203], v[12:15]
	v_mfma_f32_16x16x32_bf16 v[8:11], v[148:151], v[200:203], v[8:11]
	v_mfma_f32_16x16x32_bf16 v[60:63], v[144:147], v[180:183], v[60:63]
	v_mfma_f32_16x16x32_bf16 v[56:59], v[152:155], v[180:183], v[56:59]
	v_mfma_f32_16x16x32_bf16 v[44:47], v[144:147], v[188:191], v[44:47]
	v_mfma_f32_16x16x32_bf16 v[40:43], v[152:155], v[188:191], v[40:43]
	v_mfma_f32_16x16x32_bf16 v[28:31], v[144:147], v[196:199], v[28:31]
	v_mfma_f32_16x16x32_bf16 v[24:27], v[152:155], v[196:199], v[24:27]
	v_mfma_f32_16x16x32_bf16 v[12:15], v[144:147], v[214:217], v[12:15]
	v_mfma_f32_16x16x32_bf16 v[8:11], v[152:155], v[214:217], v[8:11]
	s_setprio 0
	s_setprio 1
	v_mfma_f32_16x16x32_bf16 v[52:55], v[156:159], v[176:179], v[52:55]
	v_mfma_f32_16x16x32_bf16 v[48:51], v[168:171], v[176:179], v[48:51]
	v_mfma_f32_16x16x32_bf16 v[36:39], v[156:159], v[184:187], v[36:39]
	v_mfma_f32_16x16x32_bf16 v[32:35], v[168:171], v[184:187], v[32:35]
	v_mfma_f32_16x16x32_bf16 v[20:23], v[156:159], v[192:195], v[20:23]
	v_mfma_f32_16x16x32_bf16 v[16:19], v[168:171], v[192:195], v[16:19]
	v_mfma_f32_16x16x32_bf16 v[4:7], v[156:159], v[200:203], v[4:7]
	v_mfma_f32_16x16x32_bf16 v[0:3], v[168:171], v[200:203], v[0:3]
	v_mfma_f32_16x16x32_bf16 v[52:55], v[160:163], v[180:183], v[52:55]
	v_mfma_f32_16x16x32_bf16 v[48:51], v[172:175], v[180:183], v[48:51]
	v_mfma_f32_16x16x32_bf16 v[36:39], v[160:163], v[188:191], v[36:39]
	v_mfma_f32_16x16x32_bf16 v[32:35], v[172:175], v[188:191], v[32:35]
	v_mfma_f32_16x16x32_bf16 v[20:23], v[160:163], v[196:199], v[20:23]
	v_mfma_f32_16x16x32_bf16 v[16:19], v[172:175], v[196:199], v[16:19]
	v_mfma_f32_16x16x32_bf16 v[4:7], v[160:163], v[214:217], v[4:7]
	v_mfma_f32_16x16x32_bf16 v[0:3], v[172:175], v[214:217], v[0:3]
	s_barrier
	s_setprio 0
	s_cmp_gt_u32 s76, 29
	s_cbranch_scc0 .LBB0_680
	s_and_b64 vcc, exec, s[22:23]
	s_cbranch_vccz .LBB0_683
	s_barrier

; #define PG8_STAGE(bufoff, gbase, voff) do { _Pragma("unroll") for (int _i = 0; _i < 2; ++_i) \
;         __builtin_amdgcn_global_load_lds((const unsigned*)((const char*)(gbase) + (voff)[_i]), (PG8_LAS unsigned*)(lds + (bufoff) + ldsw + _i * 8192), 16, 0, 0); } while (0)
; #define PG8_LDA(dst, b, h) do { _Pragma("unroll") for (int m = 0; m < 4; ++m) _Pragma("unroll") for (int k = 0; k < 2; ++k) dst[m][k] = *(const PG8_LAS bf16x8*)(lds + PG8_SA(b, h) + aoff + m * 2048 + k * 1024); } while (0)
; #define PG8_LDB(dst, b, h) do { _Pragma("unroll") for (int n = 0; n < 2; ++n) _Pragma("unroll") for (int k = 0; k < 2; ++k) dst[n][k] = *(const PG8_LAS bf16x8*)(lds + PG8_SB(b, h) + boff + n * 2048 + k * 1024); } while (0)
; #define PG8_MMA(ai, bj, At, Bt) do { __builtin_amdgcn_s_setprio(1); _Pragma("unroll") for (int m = 0; m < 4; ++m) _Pragma("unroll") for (int n = 0; n < 2; ++n) _Pragma("unroll") for (int k = 0; k < 2; ++k) \
;         acc[ai][bj][m][n] = __builtin_amdgcn_mfma_f32_16x16x32_bf16(Bt[n][k], At[m][k], acc[ai][bj][m][n], 0, 0, 0); __builtin_amdgcn_s_setprio(0); } while (0)
; #define PG8_WAIT_V(n) asm volatile("s_waitcnt vmcnt(" #n ")" ::: "memory")
; #define PG8_BAR __builtin_amdgcn_s_barrier()
; template <class Epi, class Sched, bool ALIGN_EPI = false, bool SP2 = false>
; __device__ __forceinline__ void gemm_phase(PG8_LAS unsigned char* lds, const Gemm g, const Sched& S, const Epi& E, const int tid) {
;     ...
;         for (int t = 0; t < nt; t += 2) {
;             const bool last = (t == nt - 2);
;             const char* a1 = cA + (size_t)(t + 1) * kstep;
;             const char* a2 = last ? nA : cA + (size_t)(t + 2) * kstep; const char* b2 = last ? nB : cB + (size_t)(t + 2) * kstep;
;             const char* a3 = a2 + kstep; const char* b3 = b2 + kstep;
;             if (last && has_next) S.a_ready(nxt);
;             if constexpr (SP2) {
;             PG8_LDB(B0, 0, 0); PG8_LDB(B1, 0, 1); PG8_SCHED; PG8_LDA(At, 0, 0); PG8_STAGE(PG8_SA(1, 1), a1 + hstep, voffA);
;             PG8_WAIT_V(8); PG8_WAIT_L(0); PG8_BAR; PG8_MMA(0, 0, At, B0); PG8_MMA(0, 1, At, B1); PG8_BAR; PG8_SCHED;
;             PG8_LDA(At, 0, 1); PG8_STAGE(PG8_SB(0, 0), b2, voffB); PG8_STAGE(PG8_SB(0, 1), b2 + hstep, voffB); PG8_STAGE(PG8_SA(0, 0), a2, voffA);
;             PG8_WAIT_V(8); PG8_WAIT_L(0); PG8_BAR; PG8_MMA(1, 0, At, B0); PG8_MMA(1, 1, At, B1); PG8_BAR; PG8_SCHED;
.LBB0_897:
	s_add_i32 s69, 0, 0x10000
	s_add_i32 s75, 0, 0x14000
	v_add_u32_e32 v140, s69, v216
	v_add_u32_e32 v156, s75, v216
	ds_read_b128 v[128:131], v140
	ds_read_b128 v[132:135], v140 offset:1024
	ds_read_b128 v[136:139], v140 offset:2048
	ds_read_b128 v[140:143], v140 offset:3072
	ds_read_b128 v[144:147], v156
	ds_read_b128 v[148:151], v156 offset:1024
	ds_read_b128 v[152:155], v156 offset:2048
	ds_read_b128 v[156:159], v156 offset:3072
	v_lshl_add_u64 v[202:203], s[34:35], 0, v[198:199]
	s_add_i32 m0, s46, 0xc000
	ds_read_b128 v[160:163], v217
	ds_read_b128 v[164:167], v217 offset:1024
	ds_read_b128 v[168:171], v217 offset:2048
	ds_read_b128 v[172:175], v217 offset:3072
	ds_read_b128 v[176:179], v217 offset:4096
	ds_read_b128 v[180:183], v217 offset:5120
	ds_read_b128 v[184:187], v217 offset:6144
	ds_read_b128 v[188:191], v217 offset:7168
	s_add_u32 s30, s34, 0xfff80080
	s_addc_u32 s31, s35, -1
	s_cmp_eq_u32 s68, 28
	s_cselect_b32 s37, s21, s31
	s_cselect_b32 s36, s40, s30
	s_cselect_b32 s31, s19, s65
	s_cselect_b32 s30, s62, s64
	global_load_lds_dwordx4 v[202:203], off
	v_lshl_add_u64 v[202:203], s[34:35], 0, v[200:201]
	s_add_i32 m0, s46, 0xe000
	s_nop 0
	global_load_lds_dwordx4 v[202:203], off
	s_waitcnt vmcnt(8)
	s_waitcnt lgkmcnt(0)
	s_setprio 1
	s_barrier
	v_mfma_f32_16x16x32_bf16 v[120:123], v[128:131], v[160:163], v[120:123]
	v_mfma_f32_16x16x32_bf16 v[124:127], v[136:139], v[160:163], v[124:127]
	v_mfma_f32_16x16x32_bf16 v[104:107], v[128:131], v[168:171], v[104:107]
	v_mfma_f32_16x16x32_bf16 v[108:111], v[136:139], v[168:171], v[108:111]
	v_mfma_f32_16x16x32_bf16 v[88:91], v[128:131], v[176:179], v[88:91]
	v_mfma_f32_16x16x32_bf16 v[92:95], v[136:139], v[176:179], v[92:95]
	v_mfma_f32_16x16x32_bf16 v[72:75], v[128:131], v[184:187], v[72:75]
	v_mfma_f32_16x16x32_bf16 v[76:79], v[136:139], v[184:187], v[76:79]
	v_mfma_f32_16x16x32_bf16 v[120:123], v[132:135], v[164:167], v[120:123]
	v_mfma_f32_16x16x32_bf16 v[124:127], v[140:143], v[164:167], v[124:127]
	v_mfma_f32_16x16x32_bf16 v[104:107], v[132:135], v[172:175], v[104:107]
	v_mfma_f32_16x16x32_bf16 v[108:111], v[140:143], v[172:175], v[108:111]
	v_mfma_f32_16x16x32_bf16 v[88:91], v[132:135], v[180:183], v[88:91]
	v_mfma_f32_16x16x32_bf16 v[92:95], v[140:143], v[180:183], v[92:95]
	v_mfma_f32_16x16x32_bf16 v[72:75], v[132:135], v[188:191], v[72:75]
	v_mfma_f32_16x16x32_bf16 v[76:79], v[140:143], v[188:191], v[76:79]
	s_setprio 0
	s_setprio 1
	v_mfma_f32_16x16x32_bf16 v[112:115], v[144:147], v[160:163], v[112:115]
	v_mfma_f32_16x16x32_bf16 v[116:119], v[152:155], v[160:163], v[116:119]
	v_mfma_f32_16x16x32_bf16 v[96:99], v[144:147], v[168:171], v[96:99]
	v_mfma_f32_16x16x32_bf16 v[100:103], v[152:155], v[168:171], v[100:103]
	v_mfma_f32_16x16x32_bf16 v[80:83], v[144:147], v[176:179], v[80:83]
	v_mfma_f32_16x16x32_bf16 v[84:87], v[152:155], v[176:179], v[84:87]
	v_mfma_f32_16x16x32_bf16 v[60:63], v[144:147], v[184:187], v[60:63]
	v_mfma_f32_16x16x32_bf16 v[68:71], v[152:155], v[184:187], v[68:71]
	v_mfma_f32_16x16x32_bf16 v[112:115], v[148:151], v[164:167], v[112:115]
	v_mfma_f32_16x16x32_bf16 v[116:119], v[156:159], v[164:167], v[116:119]
	v_mfma_f32_16x16x32_bf16 v[96:99], v[148:151], v[172:175], v[96:99]
	v_mfma_f32_16x16x32_bf16 v[100:103], v[156:159], v[172:175], v[100:103]
	v_mfma_f32_16x16x32_bf16 v[80:83], v[148:151], v[180:183], v[80:83]
	v_mfma_f32_16x16x32_bf16 v[84:87], v[156:159], v[180:183], v[84:87]
	v_mfma_f32_16x16x32_bf16 v[60:63], v[148:151], v[188:191], v[60:63]
	v_mfma_f32_16x16x32_bf16 v[68:71], v[156:159], v[188:191], v[68:71]
	s_barrier
	s_setprio 0
	s_add_i32 s69, s69, s43
	v_lshl_add_u64 v[202:203], s[30:31], 0, v[204:205]
	s_mov_b32 m0, s69
	ds_read_b128 v[160:163], v217 offset:16384
	ds_read_b128 v[164:167], v217 offset:17408
	ds_read_b128 v[168:171], v217 offset:18432
	ds_read_b128 v[172:175], v217 offset:19456
	ds_read_b128 v[176:179], v217 offset:20480
	ds_read_b128 v[180:183], v217 offset:21504
	ds_read_b128 v[184:187], v217 offset:22528
	ds_read_b128 v[188:191], v217 offset:23552
	global_load_lds_dwordx4 v[202:203], off
	s_add_i32 m0, s69, 0x2000
	s_add_u32 s76, s30, 0x80000
	v_lshl_add_u64 v[206:207], s[30:31], 0, v[196:197]
	s_addc_u32 s77, s31, 0
	s_add_i32 s69, s75, s43
	global_load_lds_dwordx4 v[206:207], off
	v_lshl_add_u64 v[208:209], s[76:77], 0, v[204:205]
	s_mov_b32 m0, s69
	v_lshl_add_u64 v[210:211], s[36:37], 0, v[194:195]
	global_load_lds_dwordx4 v[208:209], off
	v_lshl_add_u64 v[208:209], s[76:77], 0, v[196:197]
	s_add_i32 m0, s69, 0x2000
	s_nop 0
	global_load_lds_dwordx4 v[208:209], off
	v_lshl_add_u64 v[208:209], s[36:37], 0, v[192:193]
	s_mov_b32 m0, s46
	s_nop 0
	global_load_lds_dwordx4 v[208:209], off
	s_mov_b32 m0, s47
	s_nop 0
	global_load_lds_dwordx4 v[210:211], off
	s_waitcnt vmcnt(8)
	s_waitcnt lgkmcnt(0)
	s_setprio 1
	s_barrier
; #define PG8_STAGE(bufoff, gbase, voff) do { _Pragma("unroll") for (int _i = 0; _i < 2; ++_i) \
;         __builtin_amdgcn_global_load_lds((const unsigned*)((const char*)(gbase) + (voff)[_i]), (PG8_LAS unsigned*)(lds + (bufoff) + ldsw + _i * 8192), 16, 0, 0); } while (0)
; #define PG8_LDA(dst, b, h) do { _Pragma("unroll") for (int m = 0; m < 4; ++m) _Pragma("unroll") for (int k = 0; k < 2; ++k) dst[m][k] = *(const PG8_LAS bf16x8*)(lds + PG8_SA(b, h) + aoff + m * 2048 + k * 1024); } while (0)
; #define PG8_LDB(dst, b, h) do { _Pragma("unroll") for (int n = 0; n < 2; ++n) _Pragma("unroll") for (int k = 0; k < 2; ++k) dst[n][k] = *(const PG8_LAS bf16x8*)(lds + PG8_SB(b, h) + boff + n * 2048 + k * 1024); } while (0)
; #define PG8_MMA(ai, bj, At, Bt) do { __builtin_amdgcn_s_setprio(1); _Pragma("unroll") for (int m = 0; m < 4; ++m) _Pragma("unroll") for (int n = 0; n < 2; ++n) _Pragma("unroll") for (int k = 0; k < 2; ++k) \
;         acc[ai][bj][m][n] = __builtin_amdgcn_mfma_f32_16x16x32_bf16(Bt[n][k], At[m][k], acc[ai][bj][m][n], 0, 0, 0); __builtin_amdgcn_s_setprio(0); } while (0)
; #define PG8_WAIT_V(n) asm volatile("s_waitcnt vmcnt(" #n ")" ::: "memory")
; #define PG8_WAIT_L(n) asm volatile("s_waitcnt lgkmcnt(" #n ")" ::: "memory")
; #define PG8_BAR __builtin_amdgcn_s_barrier()
; #define PG8_SCHED __builtin_amdgcn_sched_barrier(0)
; template <class Epi, class Sched, bool ALIGN_EPI = false, bool SP2 = false>
; __device__ __forceinline__ void gemm_phase(PG8_LAS unsigned char* lds, const Gemm g, const Sched& S, const Epi& E, const int tid) {
;     ...
;             PG8_WAIT_V(8); PG8_WAIT_L(0); PG8_BAR; PG8_MMA(1, 0, At, B0); PG8_MMA(1, 1, At, B1); PG8_BAR; PG8_SCHED;
;             PG8_LDB(B0, 1, 0); PG8_LDB(B1, 1, 1); PG8_SCHED; PG8_LDA(At, 1, 0); PG8_STAGE(PG8_SA(0, 1), a2 + hstep, voffA);
;             PG8_WAIT_V(8); PG8_WAIT_L(0); PG8_BAR; PG8_MMA(0, 0, At, B0); PG8_MMA(0, 1, At, B1); PG8_BAR; PG8_SCHED;
	v_mfma_f32_16x16x32_bf16 v[48:51], v[128:131], v[160:163], v[48:51]
	v_mfma_f32_16x16x32_bf16 v[56:59], v[136:139], v[160:163], v[56:59]
	v_mfma_f32_16x16x32_bf16 v[20:23], v[128:131], v[168:171], v[20:23]
	v_mfma_f32_16x16x32_bf16 v[64:67], v[136:139], v[168:171], v[64:67]
	v_mfma_f32_16x16x32_bf16 v[28:31], v[128:131], v[176:179], v[28:31]
	v_mfma_f32_16x16x32_bf16 v[36:39], v[136:139], v[176:179], v[36:39]
	v_mfma_f32_16x16x32_bf16 v[8:11], v[128:131], v[184:187], v[8:11]
	v_mfma_f32_16x16x32_bf16 v[12:15], v[136:139], v[184:187], v[12:15]
	v_mfma_f32_16x16x32_bf16 v[48:51], v[132:135], v[164:167], v[48:51]
	v_mfma_f32_16x16x32_bf16 v[56:59], v[140:143], v[164:167], v[56:59]
	v_mfma_f32_16x16x32_bf16 v[20:23], v[132:135], v[172:175], v[20:23]
	v_mfma_f32_16x16x32_bf16 v[64:67], v[140:143], v[172:175], v[64:67]
	v_mfma_f32_16x16x32_bf16 v[28:31], v[132:135], v[180:183], v[28:31]
	v_mfma_f32_16x16x32_bf16 v[36:39], v[140:143], v[180:183], v[36:39]
	v_mfma_f32_16x16x32_bf16 v[8:11], v[132:135], v[188:191], v[8:11]
	v_mfma_f32_16x16x32_bf16 v[12:15], v[140:143], v[188:191], v[12:15]
	s_setprio 0
	s_setprio 1
	v_mfma_f32_16x16x32_bf16 v[32:35], v[144:147], v[160:163], v[32:35]
	v_mfma_f32_16x16x32_bf16 v[40:43], v[152:155], v[160:163], v[40:43]
	v_mfma_f32_16x16x32_bf16 v[44:47], v[144:147], v[168:171], v[44:47]
	v_mfma_f32_16x16x32_bf16 v[52:55], v[152:155], v[168:171], v[52:55]
	v_mfma_f32_16x16x32_bf16 v[16:19], v[144:147], v[176:179], v[16:19]
	v_mfma_f32_16x16x32_bf16 v[24:27], v[152:155], v[176:179], v[24:27]
	v_mfma_f32_16x16x32_bf16 v[0:3], v[144:147], v[184:187], v[0:3]
	v_mfma_f32_16x16x32_bf16 v[4:7], v[152:155], v[184:187], v[4:7]
	v_mfma_f32_16x16x32_bf16 v[32:35], v[148:151], v[164:167], v[32:35]
	v_mfma_f32_16x16x32_bf16 v[40:43], v[156:159], v[164:167], v[40:43]
	v_mfma_f32_16x16x32_bf16 v[44:47], v[148:151], v[172:175], v[44:47]
	v_mfma_f32_16x16x32_bf16 v[52:55], v[156:159], v[172:175], v[52:55]
	v_mfma_f32_16x16x32_bf16 v[16:19], v[148:151], v[180:183], v[16:19]
	v_mfma_f32_16x16x32_bf16 v[24:27], v[156:159], v[180:183], v[24:27]
	v_mfma_f32_16x16x32_bf16 v[0:3], v[148:151], v[188:191], v[0:3]
	v_mfma_f32_16x16x32_bf16 v[4:7], v[156:159], v[188:191], v[4:7]
	s_barrier
	s_setprio 0
	s_add_i32 s69, 0, 0x18000
	s_add_i32 s75, 0, 0x1c000
	v_add_u32_e32 v140, s69, v216
	v_add_u32_e32 v156, s75, v216
	ds_read_b128 v[128:131], v140
	ds_read_b128 v[132:135], v140 offset:1024
	ds_read_b128 v[136:139], v140 offset:2048
	ds_read_b128 v[140:143], v140 offset:3072
	ds_read_b128 v[144:147], v156
	ds_read_b128 v[148:151], v156 offset:1024
	ds_read_b128 v[152:155], v156 offset:2048
	ds_read_b128 v[156:159], v156 offset:3072
	s_add_u32 s36, s36, 0x80000
	s_addc_u32 s37, s37, 0
	s_mov_b32 m0, s48
	v_lshl_add_u64 v[212:213], s[36:37], 0, v[192:193]
	ds_read_b128 v[160:163], v217 offset:32768
	ds_read_b128 v[164:167], v217 offset:33792
	ds_read_b128 v[168:171], v217 offset:34816
	ds_read_b128 v[172:175], v217 offset:35840
	ds_read_b128 v[176:179], v217 offset:36864
	ds_read_b128 v[180:183], v217 offset:37888
	ds_read_b128 v[184:187], v217 offset:38912
	ds_read_b128 v[188:191], v217 offset:39936
	global_load_lds_dwordx4 v[212:213], off
	v_lshl_add_u64 v[212:213], s[36:37], 0, v[194:195]
	s_mov_b32 m0, s49
	s_nop 0
	global_load_lds_dwordx4 v[212:213], off
	s_waitcnt vmcnt(8)
	s_waitcnt lgkmcnt(0)
	s_setprio 1
	s_barrier
	v_mfma_f32_16x16x32_bf16 v[120:123], v[128:131], v[160:163], v[120:123]
	v_mfma_f32_16x16x32_bf16 v[124:127], v[136:139], v[160:163], v[124:127]
	v_mfma_f32_16x16x32_bf16 v[104:107], v[128:131], v[168:171], v[104:107]
	v_mfma_f32_16x16x32_bf16 v[108:111], v[136:139], v[168:171], v[108:111]
	v_mfma_f32_16x16x32_bf16 v[88:91], v[128:131], v[176:179], v[88:91]
	v_mfma_f32_16x16x32_bf16 v[92:95], v[136:139], v[176:179], v[92:95]
	v_mfma_f32_16x16x32_bf16 v[72:75], v[128:131], v[184:187], v[72:75]
	v_mfma_f32_16x16x32_bf16 v[76:79], v[136:139], v[184:187], v[76:79]
	v_mfma_f32_16x16x32_bf16 v[120:123], v[132:135], v[164:167], v[120:123]
	v_mfma_f32_16x16x32_bf16 v[124:127], v[140:143], v[164:167], v[124:127]
	v_mfma_f32_16x16x32_bf16 v[104:107], v[132:135], v[172:175], v[104:107]
	v_mfma_f32_16x16x32_bf16 v[108:111], v[140:143], v[172:175], v[108:111]
	v_mfma_f32_16x16x32_bf16 v[88:91], v[132:135], v[180:183], v[88:91]
	v_mfma_f32_16x16x32_bf16 v[92:95], v[140:143], v[180:183], v[92:95]
	v_mfma_f32_16x16x32_bf16 v[72:75], v[132:135], v[188:191], v[72:75]
	v_mfma_f32_16x16x32_bf16 v[76:79], v[140:143], v[188:191], v[76:79]
	s_setprio 0
	s_setprio 1
	v_mfma_f32_16x16x32_bf16 v[112:115], v[144:147], v[160:163], v[112:115]
	v_mfma_f32_16x16x32_bf16 v[116:119], v[152:155], v[160:163], v[116:119]
	v_mfma_f32_16x16x32_bf16 v[96:99], v[144:147], v[168:171], v[96:99]
	v_mfma_f32_16x16x32_bf16 v[100:103], v[152:155], v[168:171], v[100:103]
	v_mfma_f32_16x16x32_bf16 v[80:83], v[144:147], v[176:179], v[80:83]
	v_mfma_f32_16x16x32_bf16 v[84:87], v[152:155], v[176:179], v[84:87]
	v_mfma_f32_16x16x32_bf16 v[60:63], v[144:147], v[184:187], v[60:63]
	v_mfma_f32_16x16x32_bf16 v[68:71], v[152:155], v[184:187], v[68:71]
	v_mfma_f32_16x16x32_bf16 v[112:115], v[148:151], v[164:167], v[112:115]
	v_mfma_f32_16x16x32_bf16 v[116:119], v[156:159], v[164:167], v[116:119]
	v_mfma_f32_16x16x32_bf16 v[96:99], v[148:151], v[172:175], v[96:99]
	v_mfma_f32_16x16x32_bf16 v[100:103], v[156:159], v[172:175], v[100:103]
	v_mfma_f32_16x16x32_bf16 v[80:83], v[148:151], v[180:183], v[80:83]
	v_mfma_f32_16x16x32_bf16 v[84:87], v[156:159], v[180:183], v[84:87]
	v_mfma_f32_16x16x32_bf16 v[60:63], v[148:151], v[188:191], v[60:63]
	v_mfma_f32_16x16x32_bf16 v[68:71], v[156:159], v[188:191], v[68:71]
	s_barrier
; #define PG8_STAGE(bufoff, gbase, voff) do { _Pragma("unroll") for (int _i = 0; _i < 2; ++_i) \
;         __builtin_amdgcn_global_load_lds((const unsigned*)((const char*)(gbase) + (voff)[_i]), (PG8_LAS unsigned*)(lds + (bufoff) + ldsw + _i * 8192), 16, 0, 0); } while (0)
; #define PG8_LDA(dst, b, h) do { _Pragma("unroll") for (int m = 0; m < 4; ++m) _Pragma("unroll") for (int k = 0; k < 2; ++k) dst[m][k] = *(const PG8_LAS bf16x8*)(lds + PG8_SA(b, h) + aoff + m * 2048 + k * 1024); } while (0)
; #define PG8_MMA(ai, bj, At, Bt) do { __builtin_amdgcn_s_setprio(1); _Pragma("unroll") for (int m = 0; m < 4; ++m) _Pragma("unroll") for (int n = 0; n < 2; ++n) _Pragma("unroll") for (int k = 0; k < 2; ++k) \
;         acc[ai][bj][m][n] = __builtin_amdgcn_mfma_f32_16x16x32_bf16(Bt[n][k], At[m][k], acc[ai][bj][m][n], 0, 0, 0); __builtin_amdgcn_s_setprio(0); } while (0)
; #define PG8_WAIT_V(n) asm volatile("s_waitcnt vmcnt(" #n ")" ::: "memory")
; #define PG8_WAIT_L(n) asm volatile("s_waitcnt lgkmcnt(" #n ")" ::: "memory")
; #define PG8_BAR __builtin_amdgcn_s_barrier()
; #define PG8_SCHED __builtin_amdgcn_sched_barrier(0)
; template <class Epi, class Sched, bool ALIGN_EPI = false, bool SP2 = false>
; __device__ __forceinline__ void gemm_phase(PG8_LAS unsigned char* lds, const Gemm g, const Sched& S, const Epi& E, const int tid) {
;     ...
;         for (int t = 0; t < nt; t += 2) {
;             const bool last = (t == nt - 2);
;             const char* a1 = cA + (size_t)(t + 1) * kstep;
;             const char* a2 = last ? nA : cA + (size_t)(t + 2) * kstep; const char* b2 = last ? nB : cB + (size_t)(t + 2) * kstep;
;     ...
;             PG8_LDA(At, 1, 1); PG8_STAGE(PG8_SB(1, 0), b3, voffB); PG8_STAGE(PG8_SB(1, 1), b3 + hstep, voffB); PG8_STAGE(PG8_SA(1, 0), a3, voffA);
;             PG8_WAIT_V(8); PG8_WAIT_L(0); PG8_BAR; PG8_MMA(1, 0, At, B0); PG8_MMA(1, 1, At, B1); PG8_BAR; PG8_SCHED;
	s_setprio 0
	s_add_i32 s36, s69, s43
	v_lshl_add_u64 v[202:203], v[202:203], 0, s[70:71]
	s_mov_b32 m0, s36
	ds_read_b128 v[160:163], v217 offset:49152
	ds_read_b128 v[164:167], v217 offset:50176
	ds_read_b128 v[168:171], v217 offset:51200
	ds_read_b128 v[172:175], v217 offset:52224
	ds_read_b128 v[176:179], v217 offset:53248
	ds_read_b128 v[180:183], v217 offset:54272
	ds_read_b128 v[184:187], v217 offset:55296
	ds_read_b128 v[188:191], v217 offset:56320
	global_load_lds_dwordx4 v[202:203], off
	s_add_i32 m0, s36, 0x2000
	s_add_u32 s30, s30, 0x80080
	v_lshl_add_u64 v[202:203], v[206:207], 0, s[70:71]
	s_addc_u32 s31, s31, 0
	s_add_i32 s36, s75, s43
	global_load_lds_dwordx4 v[202:203], off
	v_lshl_add_u64 v[202:203], s[30:31], 0, v[204:205]
	s_mov_b32 m0, s36
	s_nop 0
	global_load_lds_dwordx4 v[202:203], off
	v_lshl_add_u64 v[202:203], s[30:31], 0, v[196:197]
	s_add_i32 m0, s36, 0x2000
	s_nop 0
	global_load_lds_dwordx4 v[202:203], off
	v_lshl_add_u64 v[202:203], v[208:209], 0, s[70:71]
	s_mov_b32 m0, s51
	s_nop 0
	global_load_lds_dwordx4 v[202:203], off
	v_lshl_add_u64 v[202:203], v[210:211], 0, s[70:71]
	s_mov_b32 m0, s52
	s_nop 0
	global_load_lds_dwordx4 v[202:203], off
	s_add_i32 s68, s68, 2
	s_add_u32 s34, s34, 0x100
	s_addc_u32 s35, s35, 0
	s_add_u32 s64, s64, 0x100
	s_addc_u32 s65, s65, 0
	s_waitcnt vmcnt(8)
	s_waitcnt lgkmcnt(0)
	s_setprio 1
	s_barrier
	v_mfma_f32_16x16x32_bf16 v[48:51], v[128:131], v[160:163], v[48:51]
	v_mfma_f32_16x16x32_bf16 v[56:59], v[136:139], v[160:163], v[56:59]
	v_mfma_f32_16x16x32_bf16 v[20:23], v[128:131], v[168:171], v[20:23]
	v_mfma_f32_16x16x32_bf16 v[64:67], v[136:139], v[168:171], v[64:67]
	v_mfma_f32_16x16x32_bf16 v[28:31], v[128:131], v[176:179], v[28:31]
	v_mfma_f32_16x16x32_bf16 v[36:39], v[136:139], v[176:179], v[36:39]
	v_mfma_f32_16x16x32_bf16 v[8:11], v[128:131], v[184:187], v[8:11]
	v_mfma_f32_16x16x32_bf16 v[12:15], v[136:139], v[184:187], v[12:15]
	v_mfma_f32_16x16x32_bf16 v[48:51], v[132:135], v[164:167], v[48:51]
	v_mfma_f32_16x16x32_bf16 v[56:59], v[140:143], v[164:167], v[56:59]
	v_mfma_f32_16x16x32_bf16 v[20:23], v[132:135], v[172:175], v[20:23]
	v_mfma_f32_16x16x32_bf16 v[64:67], v[140:143], v[172:175], v[64:67]
	v_mfma_f32_16x16x32_bf16 v[28:31], v[132:135], v[180:183], v[28:31]
	v_mfma_f32_16x16x32_bf16 v[36:39], v[140:143], v[180:183], v[36:39]
	v_mfma_f32_16x16x32_bf16 v[8:11], v[132:135], v[188:191], v[8:11]
	v_mfma_f32_16x16x32_bf16 v[12:15], v[140:143], v[188:191], v[12:15]
	s_setprio 0
	s_setprio 1
	v_mfma_f32_16x16x32_bf16 v[32:35], v[144:147], v[160:163], v[32:35]
	v_mfma_f32_16x16x32_bf16 v[40:43], v[152:155], v[160:163], v[40:43]
	v_mfma_f32_16x16x32_bf16 v[44:47], v[144:147], v[168:171], v[44:47]
	v_mfma_f32_16x16x32_bf16 v[52:55], v[152:155], v[168:171], v[52:55]
	v_mfma_f32_16x16x32_bf16 v[16:19], v[144:147], v[176:179], v[16:19]
	v_mfma_f32_16x16x32_bf16 v[24:27], v[152:155], v[176:179], v[24:27]
	v_mfma_f32_16x16x32_bf16 v[0:3], v[144:147], v[184:187], v[0:3]
	v_mfma_f32_16x16x32_bf16 v[4:7], v[152:155], v[184:187], v[4:7]
	v_mfma_f32_16x16x32_bf16 v[32:35], v[148:151], v[164:167], v[32:35]
	v_mfma_f32_16x16x32_bf16 v[40:43], v[156:159], v[164:167], v[40:43]
	v_mfma_f32_16x16x32_bf16 v[44:47], v[148:151], v[172:175], v[44:47]
	v_mfma_f32_16x16x32_bf16 v[52:55], v[156:159], v[172:175], v[52:55]
	v_mfma_f32_16x16x32_bf16 v[16:19], v[148:151], v[180:183], v[16:19]
	v_mfma_f32_16x16x32_bf16 v[24:27], v[156:159], v[180:183], v[24:27]
	v_mfma_f32_16x16x32_bf16 v[0:3], v[148:151], v[188:191], v[0:3]
	v_mfma_f32_16x16x32_bf16 v[4:7], v[156:159], v[188:191], v[4:7]
	s_barrier
	s_setprio 0
	s_cmp_gt_u32 s68, 29
	s_cbranch_scc0 .LBB0_897
	s_and_b64 vcc, exec, s[16:17]
	s_cbranch_vccz .LBB0_900
	s_barrier

; #define PG8_STAGE(bufoff, gbase, voff) do { _Pragma("unroll") for (int _i = 0; _i < 2; ++_i) \
;         __builtin_amdgcn_global_load_lds((const unsigned*)((const char*)(gbase) + (voff)[_i]), (PG8_LAS unsigned*)(lds + (bufoff) + ldsw + _i * 8192), 16, 0, 0); } while (0)
; #define PG8_LDA(dst, b, h) do { _Pragma("unroll") for (int m = 0; m < 4; ++m) _Pragma("unroll") for (int k = 0; k < 2; ++k) dst[m][k] = *(const PG8_LAS bf16x8*)(lds + PG8_SA(b, h) + aoff + m * 2048 + k * 1024); } while (0)
; #define PG8_LDB(dst, b, h) do { _Pragma("unroll") for (int n = 0; n < 2; ++n) _Pragma("unroll") for (int k = 0; k < 2; ++k) dst[n][k] = *(const PG8_LAS bf16x8*)(lds + PG8_SB(b, h) + boff + n * 2048 + k * 1024); } while (0)
; #define PG8_WAIT_V(n) asm volatile("s_waitcnt vmcnt(" #n ")" ::: "memory")
; #define PG8_WAIT_L(n) asm volatile("s_waitcnt lgkmcnt(" #n ")" ::: "memory")
; #define PG8_BAR __builtin_amdgcn_s_barrier()
; #define PG8_SCHED __builtin_amdgcn_sched_barrier(0)
; template <class Epi, class Sched, bool ALIGN_EPI = false, bool SP2 = false>
; __device__ __forceinline__ void gemm_phase(PG8_LAS unsigned char* lds, const Gemm g, const Sched& S, const Epi& E, const int tid) {
;     ...
;         const bool has_next = S.next(ui + 1, nxt);
;         const char* nA = has_next ? (const char*)g.A + (size_t)nxt.pm * tstep : cA; const char* nB = has_next ? (const char*)g.Bt + (size_t)nxt.pn * tstep : cB;
;         for (int t = 0; t < nt; t += 2) {
;             const bool last = (t == nt - 2);
;             const char* a1 = cA + (size_t)(t + 1) * kstep;
;             const char* a2 = last ? nA : cA + (size_t)(t + 2) * kstep; const char* b2 = last ? nB : cB + (size_t)(t + 2) * kstep;
;             const char* a3 = a2 + kstep; const char* b3 = b2 + kstep;
;             if (last && has_next) S.a_ready(nxt);
;             if constexpr (SP2) {
;             PG8_LDB(B0, 0, 0); PG8_LDB(B1, 0, 1); PG8_SCHED; PG8_LDA(At, 0, 0); PG8_STAGE(PG8_SA(1, 1), a1 + hstep, voffA);
;             PG8_WAIT_V(8); PG8_WAIT_L(0); PG8_BAR; PG8_MMA(0, 0, At, B0); PG8_MMA(0, 1, At, B1); PG8_BAR; PG8_SCHED;
;             PG8_LDA(At, 0, 1); PG8_STAGE(PG8_SB(0, 0), b2, voffB); PG8_STAGE(PG8_SB(0, 1), b2 + hstep, voffB); PG8_STAGE(PG8_SA(0, 0), a2, voffA);
;             PG8_WAIT_V(8); PG8_WAIT_L(0); PG8_BAR; PG8_MMA(1, 0, At, B0); PG8_MMA(1, 1, At, B1); PG8_BAR; PG8_SCHED;
.LBB0_1087:
	s_ashr_i32 s19, s18, 31
	s_lshl_b64 s[20:21], s[18:19], 20
	s_add_u32 s20, s11, s20
	s_addc_u32 s21, s33, s21
	s_and_b64 s[22:23], s[4:5], exec
	s_cselect_b32 s19, s21, s27
	s_cselect_b32 s50, s20, s26
	s_ashr_i32 s17, s16, 31
	s_lshl_b64 s[22:23], s[16:17], 20
	s_add_u32 s22, s34, s22
	s_addc_u32 s23, s35, s23
	s_and_b64 s[30:31], s[4:5], exec
	s_cselect_b32 s17, s23, s29
	s_cselect_b32 s51, s22, s28
	s_add_u32 s26, s26, 0x80080
	s_addc_u32 s27, s27, 0
	s_add_u32 s52, s28, 0x100
	s_addc_u32 s53, s29, 0
	s_mov_b32 s54, -2
	s_add_i32 s55, 0, 0x10000
	v_add_u32_e32 v138, s55, v139
	s_add_i32 s62, 0, 0x14000
	ds_read_b128 v[144:147], v138
	ds_read_b128 v[148:151], v138 offset:1024
	ds_read_b128 v[152:155], v138 offset:2048
	ds_read_b128 v[156:159], v138 offset:3072
	v_add_u32_e32 v138, s62, v139
	ds_read_b128 v[160:163], v138
	ds_read_b128 v[164:167], v138 offset:1024
	ds_read_b128 v[168:171], v138 offset:2048
	ds_read_b128 v[172:175], v138 offset:3072
	v_lshl_add_u64 v[140:141], s[26:27], 0, v[134:135]
	s_add_i32 m0, s37, 0xc000
	ds_read_b128 v[176:179], v143
	ds_read_b128 v[180:183], v143 offset:1024
	ds_read_b128 v[184:187], v143 offset:2048
	ds_read_b128 v[188:191], v143 offset:3072
	ds_read_b128 v[192:195], v143 offset:4096
	ds_read_b128 v[196:199], v143 offset:5120
	ds_read_b128 v[200:203], v143 offset:6144
	ds_read_b128 v[206:209], v143 offset:7168
	s_add_u32 s28, s26, 0xfff80080
	s_addc_u32 s29, s27, -1
	s_cmp_eq_u32 s54, 28
	s_cselect_b32 s31, s19, s29
	s_cselect_b32 s30, s50, s28
	s_cselect_b32 s29, s17, s53
	s_cselect_b32 s28, s51, s52
	global_load_lds_dwordx4 v[140:141], off
	v_lshl_add_u64 v[140:141], s[26:27], 0, v[136:137]
	s_add_i32 m0, s37, 0xe000
	s_nop 0
	global_load_lds_dwordx4 v[140:141], off
	s_waitcnt vmcnt(24)
	s_waitcnt lgkmcnt(0)
	s_setprio 1
	s_barrier
	v_mfma_f32_16x16x32_bf16 v[124:127], v[144:147], v[176:179], 0
	v_mfma_f32_16x16x32_bf16 v[120:123], v[152:155], v[176:179], 0
	v_mfma_f32_16x16x32_bf16 v[108:111], v[144:147], v[184:187], 0
	v_mfma_f32_16x16x32_bf16 v[104:107], v[152:155], v[184:187], 0
	v_mfma_f32_16x16x32_bf16 v[92:95], v[144:147], v[192:195], 0
	v_mfma_f32_16x16x32_bf16 v[88:91], v[152:155], v[192:195], 0
	v_mfma_f32_16x16x32_bf16 v[76:79], v[144:147], v[200:203], 0
	v_mfma_f32_16x16x32_bf16 v[72:75], v[152:155], v[200:203], 0
	v_mfma_f32_16x16x32_bf16 v[124:127], v[148:151], v[180:183], v[124:127]
	v_mfma_f32_16x16x32_bf16 v[120:123], v[156:159], v[180:183], v[120:123]
	v_mfma_f32_16x16x32_bf16 v[108:111], v[148:151], v[188:191], v[108:111]
	v_mfma_f32_16x16x32_bf16 v[104:107], v[156:159], v[188:191], v[104:107]
	v_mfma_f32_16x16x32_bf16 v[92:95], v[148:151], v[196:199], v[92:95]
	v_mfma_f32_16x16x32_bf16 v[88:91], v[156:159], v[196:199], v[88:91]
	v_mfma_f32_16x16x32_bf16 v[76:79], v[148:151], v[206:209], v[76:79]
	v_mfma_f32_16x16x32_bf16 v[72:75], v[156:159], v[206:209], v[72:75]
	s_setprio 0
	s_setprio 1
	v_mfma_f32_16x16x32_bf16 v[116:119], v[160:163], v[176:179], 0
	v_mfma_f32_16x16x32_bf16 v[112:115], v[168:171], v[176:179], 0
	v_mfma_f32_16x16x32_bf16 v[100:103], v[160:163], v[184:187], 0
	v_mfma_f32_16x16x32_bf16 v[96:99], v[168:171], v[184:187], 0
	v_mfma_f32_16x16x32_bf16 v[84:87], v[160:163], v[192:195], 0
	v_mfma_f32_16x16x32_bf16 v[80:83], v[168:171], v[192:195], 0
	v_mfma_f32_16x16x32_bf16 v[68:71], v[160:163], v[200:203], 0
	v_mfma_f32_16x16x32_bf16 v[64:67], v[168:171], v[200:203], 0
	v_mfma_f32_16x16x32_bf16 v[116:119], v[164:167], v[180:183], v[116:119]
	v_mfma_f32_16x16x32_bf16 v[112:115], v[172:175], v[180:183], v[112:115]
	v_mfma_f32_16x16x32_bf16 v[100:103], v[164:167], v[188:191], v[100:103]
	v_mfma_f32_16x16x32_bf16 v[96:99], v[172:175], v[188:191], v[96:99]
	v_mfma_f32_16x16x32_bf16 v[84:87], v[164:167], v[196:199], v[84:87]
	v_mfma_f32_16x16x32_bf16 v[80:83], v[172:175], v[196:199], v[80:83]
	v_mfma_f32_16x16x32_bf16 v[68:71], v[164:167], v[206:209], v[68:71]
	v_mfma_f32_16x16x32_bf16 v[64:67], v[172:175], v[206:209], v[64:67]
	s_barrier
	s_setprio 0
	s_add_i32 s55, s55, s36
	v_lshl_add_u64 v[140:141], s[28:29], 0, v[204:205]
	s_mov_b32 m0, s55
	ds_read_b128 v[176:179], v143 offset:16384
	ds_read_b128 v[180:183], v143 offset:17408
	ds_read_b128 v[184:187], v143 offset:18432
	ds_read_b128 v[188:191], v143 offset:19456
	ds_read_b128 v[192:195], v143 offset:20480
	ds_read_b128 v[196:199], v143 offset:21504
	ds_read_b128 v[200:203], v143 offset:22528
	ds_read_b128 v[206:209], v143 offset:23552
	global_load_lds_dwordx4 v[140:141], off
	s_add_i32 m0, s55, 0x2000
	s_add_u32 s64, s28, 0x80000
	v_lshl_add_u64 v[210:211], s[28:29], 0, v[132:133]
	s_addc_u32 s65, s29, 0
	s_add_i32 s55, s62, s36
	global_load_lds_dwordx4 v[210:211], off
	v_lshl_add_u64 v[212:213], s[64:65], 0, v[204:205]
	s_mov_b32 m0, s55
	v_lshl_add_u64 v[214:215], s[30:31], 0, v[130:131]
	global_load_lds_dwordx4 v[212:213], off
	v_lshl_add_u64 v[212:213], s[64:65], 0, v[132:133]
	s_add_i32 m0, s55, 0x2000
	s_nop 0
	global_load_lds_dwordx4 v[212:213], off
	v_lshl_add_u64 v[212:213], s[30:31], 0, v[128:129]
	s_mov_b32 m0, s37
	s_nop 0
	global_load_lds_dwordx4 v[212:213], off
	s_mov_b32 m0, s38
	s_nop 0
	global_load_lds_dwordx4 v[214:215], off
	s_waitcnt vmcnt(8)
	s_waitcnt lgkmcnt(0)
	s_setprio 1
	s_barrier
; #define PG8_STAGE(bufoff, gbase, voff) do { _Pragma("unroll") for (int _i = 0; _i < 2; ++_i) \
;         __builtin_amdgcn_global_load_lds((const unsigned*)((const char*)(gbase) + (voff)[_i]), (PG8_LAS unsigned*)(lds + (bufoff) + ldsw + _i * 8192), 16, 0, 0); } while (0)
; #define PG8_LDA(dst, b, h) do { _Pragma("unroll") for (int m = 0; m < 4; ++m) _Pragma("unroll") for (int k = 0; k < 2; ++k) dst[m][k] = *(const PG8_LAS bf16x8*)(lds + PG8_SA(b, h) + aoff + m * 2048 + k * 1024); } while (0)
; #define PG8_LDB(dst, b, h) do { _Pragma("unroll") for (int n = 0; n < 2; ++n) _Pragma("unroll") for (int k = 0; k < 2; ++k) dst[n][k] = *(const PG8_LAS bf16x8*)(lds + PG8_SB(b, h) + boff + n * 2048 + k * 1024); } while (0)
; #define PG8_MMA(ai, bj, At, Bt) do { __builtin_amdgcn_s_setprio(1); _Pragma("unroll") for (int m = 0; m < 4; ++m) _Pragma("unroll") for (int n = 0; n < 2; ++n) _Pragma("unroll") for (int k = 0; k < 2; ++k) \
;         acc[ai][bj][m][n] = __builtin_amdgcn_mfma_f32_16x16x32_bf16(Bt[n][k], At[m][k], acc[ai][bj][m][n], 0, 0, 0); __builtin_amdgcn_s_setprio(0); } while (0)
; #define PG8_WAIT_V(n) asm volatile("s_waitcnt vmcnt(" #n ")" ::: "memory")
; #define PG8_WAIT_L(n) asm volatile("s_waitcnt lgkmcnt(" #n ")" ::: "memory")
; #define PG8_BAR __builtin_amdgcn_s_barrier()
; #define PG8_SCHED __builtin_amdgcn_sched_barrier(0)
; template <class Epi, class Sched, bool ALIGN_EPI = false, bool SP2 = false>
; __device__ __forceinline__ void gemm_phase(PG8_LAS unsigned char* lds, const Gemm g, const Sched& S, const Epi& E, const int tid) {
;     ...
;             PG8_WAIT_V(8); PG8_WAIT_L(0); PG8_BAR; PG8_MMA(1, 0, At, B0); PG8_MMA(1, 1, At, B1); PG8_BAR; PG8_SCHED;
;             PG8_LDB(B0, 1, 0); PG8_LDB(B1, 1, 1); PG8_SCHED; PG8_LDA(At, 1, 0); PG8_STAGE(PG8_SA(0, 1), a2 + hstep, voffA);
;             PG8_WAIT_V(8); PG8_WAIT_L(0); PG8_BAR; PG8_MMA(0, 0, At, B0); PG8_MMA(0, 1, At, B1); PG8_BAR; PG8_SCHED;
	v_mfma_f32_16x16x32_bf16 v[60:63], v[144:147], v[176:179], 0
	v_mfma_f32_16x16x32_bf16 v[56:59], v[152:155], v[176:179], 0
	v_mfma_f32_16x16x32_bf16 v[44:47], v[144:147], v[184:187], 0
	v_mfma_f32_16x16x32_bf16 v[40:43], v[152:155], v[184:187], 0
	v_mfma_f32_16x16x32_bf16 v[28:31], v[144:147], v[192:195], 0
	v_mfma_f32_16x16x32_bf16 v[24:27], v[152:155], v[192:195], 0
	v_mfma_f32_16x16x32_bf16 v[12:15], v[144:147], v[200:203], 0
	v_mfma_f32_16x16x32_bf16 v[8:11], v[152:155], v[200:203], 0
	v_mfma_f32_16x16x32_bf16 v[60:63], v[148:151], v[180:183], v[60:63]
	v_mfma_f32_16x16x32_bf16 v[56:59], v[156:159], v[180:183], v[56:59]
	v_mfma_f32_16x16x32_bf16 v[44:47], v[148:151], v[188:191], v[44:47]
	v_mfma_f32_16x16x32_bf16 v[40:43], v[156:159], v[188:191], v[40:43]
	v_mfma_f32_16x16x32_bf16 v[28:31], v[148:151], v[196:199], v[28:31]
	v_mfma_f32_16x16x32_bf16 v[24:27], v[156:159], v[196:199], v[24:27]
	v_mfma_f32_16x16x32_bf16 v[12:15], v[148:151], v[206:209], v[12:15]
	v_mfma_f32_16x16x32_bf16 v[8:11], v[156:159], v[206:209], v[8:11]
	s_setprio 0
	s_setprio 1
	v_mfma_f32_16x16x32_bf16 v[52:55], v[160:163], v[176:179], 0
	v_mfma_f32_16x16x32_bf16 v[48:51], v[168:171], v[176:179], 0
	v_mfma_f32_16x16x32_bf16 v[36:39], v[160:163], v[184:187], 0
	v_mfma_f32_16x16x32_bf16 v[32:35], v[168:171], v[184:187], 0
	v_mfma_f32_16x16x32_bf16 v[20:23], v[160:163], v[192:195], 0
	v_mfma_f32_16x16x32_bf16 v[16:19], v[168:171], v[192:195], 0
	v_mfma_f32_16x16x32_bf16 v[4:7], v[160:163], v[200:203], 0
	v_mfma_f32_16x16x32_bf16 v[0:3], v[168:171], v[200:203], 0
	v_mfma_f32_16x16x32_bf16 v[52:55], v[164:167], v[180:183], v[52:55]
	v_mfma_f32_16x16x32_bf16 v[48:51], v[172:175], v[180:183], v[48:51]
	v_mfma_f32_16x16x32_bf16 v[36:39], v[164:167], v[188:191], v[36:39]
	v_mfma_f32_16x16x32_bf16 v[32:35], v[172:175], v[188:191], v[32:35]
	v_mfma_f32_16x16x32_bf16 v[20:23], v[164:167], v[196:199], v[20:23]
	v_mfma_f32_16x16x32_bf16 v[16:19], v[172:175], v[196:199], v[16:19]
	v_mfma_f32_16x16x32_bf16 v[4:7], v[164:167], v[206:209], v[4:7]
	v_mfma_f32_16x16x32_bf16 v[0:3], v[172:175], v[206:209], v[0:3]
	s_barrier
	s_setprio 0
	s_add_i32 s55, 0, 0x18000
	v_add_u32_e32 v138, s55, v139
	s_add_i32 s62, 0, 0x1c000
	ds_read_b128 v[144:147], v138
	ds_read_b128 v[148:151], v138 offset:1024
	ds_read_b128 v[152:155], v138 offset:2048
	ds_read_b128 v[156:159], v138 offset:3072
	v_add_u32_e32 v138, s62, v139
	ds_read_b128 v[160:163], v138
	ds_read_b128 v[164:167], v138 offset:1024
	ds_read_b128 v[168:171], v138 offset:2048
	ds_read_b128 v[172:175], v138 offset:3072
	s_add_u32 s30, s30, 0x80000
	s_addc_u32 s31, s31, 0
	s_mov_b32 m0, s40
	v_lshl_add_u64 v[216:217], s[30:31], 0, v[128:129]
	ds_read_b128 v[176:179], v143 offset:32768
	ds_read_b128 v[180:183], v143 offset:33792
	ds_read_b128 v[184:187], v143 offset:34816
	ds_read_b128 v[188:191], v143 offset:35840
	ds_read_b128 v[192:195], v143 offset:36864
	ds_read_b128 v[196:199], v143 offset:37888
	ds_read_b128 v[200:203], v143 offset:38912
	ds_read_b128 v[206:209], v143 offset:39936
	global_load_lds_dwordx4 v[216:217], off
	v_lshl_add_u64 v[216:217], s[30:31], 0, v[130:131]
	s_mov_b32 m0, s42
	s_nop 0
	global_load_lds_dwordx4 v[216:217], off
	s_waitcnt vmcnt(8)
	s_waitcnt lgkmcnt(0)
	s_setprio 1
	s_barrier
	v_mfma_f32_16x16x32_bf16 v[124:127], v[144:147], v[176:179], v[124:127]
	v_mfma_f32_16x16x32_bf16 v[120:123], v[152:155], v[176:179], v[120:123]
	v_mfma_f32_16x16x32_bf16 v[108:111], v[144:147], v[184:187], v[108:111]
	v_mfma_f32_16x16x32_bf16 v[104:107], v[152:155], v[184:187], v[104:107]
	v_mfma_f32_16x16x32_bf16 v[92:95], v[144:147], v[192:195], v[92:95]
	v_mfma_f32_16x16x32_bf16 v[88:91], v[152:155], v[192:195], v[88:91]
	v_mfma_f32_16x16x32_bf16 v[76:79], v[144:147], v[200:203], v[76:79]
	v_mfma_f32_16x16x32_bf16 v[72:75], v[152:155], v[200:203], v[72:75]
	v_mfma_f32_16x16x32_bf16 v[124:127], v[148:151], v[180:183], v[124:127]
	v_mfma_f32_16x16x32_bf16 v[120:123], v[156:159], v[180:183], v[120:123]
	v_mfma_f32_16x16x32_bf16 v[108:111], v[148:151], v[188:191], v[108:111]
	v_mfma_f32_16x16x32_bf16 v[104:107], v[156:159], v[188:191], v[104:107]
	v_mfma_f32_16x16x32_bf16 v[92:95], v[148:151], v[196:199], v[92:95]
	v_mfma_f32_16x16x32_bf16 v[88:91], v[156:159], v[196:199], v[88:91]
	v_mfma_f32_16x16x32_bf16 v[76:79], v[148:151], v[206:209], v[76:79]
	v_mfma_f32_16x16x32_bf16 v[72:75], v[156:159], v[206:209], v[72:75]
	s_setprio 0
	s_setprio 1
	v_mfma_f32_16x16x32_bf16 v[116:119], v[160:163], v[176:179], v[116:119]
	v_mfma_f32_16x16x32_bf16 v[112:115], v[168:171], v[176:179], v[112:115]
	v_mfma_f32_16x16x32_bf16 v[100:103], v[160:163], v[184:187], v[100:103]
	v_mfma_f32_16x16x32_bf16 v[96:99], v[168:171], v[184:187], v[96:99]
	v_mfma_f32_16x16x32_bf16 v[84:87], v[160:163], v[192:195], v[84:87]
	v_mfma_f32_16x16x32_bf16 v[80:83], v[168:171], v[192:195], v[80:83]
	v_mfma_f32_16x16x32_bf16 v[68:71], v[160:163], v[200:203], v[68:71]
	v_mfma_f32_16x16x32_bf16 v[64:67], v[168:171], v[200:203], v[64:67]
	v_mfma_f32_16x16x32_bf16 v[116:119], v[164:167], v[180:183], v[116:119]
	v_mfma_f32_16x16x32_bf16 v[112:115], v[172:175], v[180:183], v[112:115]
	v_mfma_f32_16x16x32_bf16 v[100:103], v[164:167], v[188:191], v[100:103]
	v_mfma_f32_16x16x32_bf16 v[96:99], v[172:175], v[188:191], v[96:99]
	v_mfma_f32_16x16x32_bf16 v[84:87], v[164:167], v[196:199], v[84:87]
	v_mfma_f32_16x16x32_bf16 v[80:83], v[172:175], v[196:199], v[80:83]
	v_mfma_f32_16x16x32_bf16 v[68:71], v[164:167], v[206:209], v[68:71]
	v_mfma_f32_16x16x32_bf16 v[64:67], v[172:175], v[206:209], v[64:67]
	s_barrier
; #define PG8_STAGE(bufoff, gbase, voff) do { _Pragma("unroll") for (int _i = 0; _i < 2; ++_i) \
;         __builtin_amdgcn_global_load_lds((const unsigned*)((const char*)(gbase) + (voff)[_i]), (PG8_LAS unsigned*)(lds + (bufoff) + ldsw + _i * 8192), 16, 0, 0); } while (0)
; #define PG8_LDA(dst, b, h) do { _Pragma("unroll") for (int m = 0; m < 4; ++m) _Pragma("unroll") for (int k = 0; k < 2; ++k) dst[m][k] = *(const PG8_LAS bf16x8*)(lds + PG8_SA(b, h) + aoff + m * 2048 + k * 1024); } while (0)
; #define PG8_LDB(dst, b, h) do { _Pragma("unroll") for (int n = 0; n < 2; ++n) _Pragma("unroll") for (int k = 0; k < 2; ++k) dst[n][k] = *(const PG8_LAS bf16x8*)(lds + PG8_SB(b, h) + boff + n * 2048 + k * 1024); } while (0)
; #define PG8_MMA(ai, bj, At, Bt) do { __builtin_amdgcn_s_setprio(1); _Pragma("unroll") for (int m = 0; m < 4; ++m) _Pragma("unroll") for (int n = 0; n < 2; ++n) _Pragma("unroll") for (int k = 0; k < 2; ++k) \
;         acc[ai][bj][m][n] = __builtin_amdgcn_mfma_f32_16x16x32_bf16(Bt[n][k], At[m][k], acc[ai][bj][m][n], 0, 0, 0); __builtin_amdgcn_s_setprio(0); } while (0)
; #define PG8_WAIT_V(n) asm volatile("s_waitcnt vmcnt(" #n ")" ::: "memory")
; #define PG8_WAIT_L(n) asm volatile("s_waitcnt lgkmcnt(" #n ")" ::: "memory")
; #define PG8_BAR __builtin_amdgcn_s_barrier()
; template <class Epi, class Sched, bool ALIGN_EPI = false, bool SP2 = false>
; __device__ __forceinline__ void gemm_phase(PG8_LAS unsigned char* lds, const Gemm g, const Sched& S, const Epi& E, const int tid) {
;     ...
;         for (int t = 0; t < nt; t += 2) {
;             const bool last = (t == nt - 2);
;             const char* a1 = cA + (size_t)(t + 1) * kstep;
;             const char* a2 = last ? nA : cA + (size_t)(t + 2) * kstep; const char* b2 = last ? nB : cB + (size_t)(t + 2) * kstep;
;             const char* a3 = a2 + kstep; const char* b3 = b2 + kstep;
;             if (last && has_next) S.a_ready(nxt);
;             if constexpr (SP2) {
;             PG8_LDB(B0, 0, 0); PG8_LDB(B1, 0, 1); PG8_SCHED; PG8_LDA(At, 0, 0); PG8_STAGE(PG8_SA(1, 1), a1 + hstep, voffA);
;     ...
;             PG8_LDA(At, 1, 1); PG8_STAGE(PG8_SB(1, 0), b3, voffB); PG8_STAGE(PG8_SB(1, 1), b3 + hstep, voffB); PG8_STAGE(PG8_SA(1, 0), a3, voffA);
;             PG8_WAIT_V(8); PG8_WAIT_L(0); PG8_BAR; PG8_MMA(1, 0, At, B0); PG8_MMA(1, 1, At, B1); PG8_BAR; PG8_SCHED;
	s_setprio 0
	s_add_i32 s30, s55, s36
	v_lshl_add_u64 v[140:141], v[140:141], 0, s[70:71]
	s_mov_b32 m0, s30
	ds_read_b128 v[176:179], v143 offset:49152
	ds_read_b128 v[180:183], v143 offset:50176
	ds_read_b128 v[184:187], v143 offset:51200
	ds_read_b128 v[188:191], v143 offset:52224
	ds_read_b128 v[192:195], v143 offset:53248
	ds_read_b128 v[196:199], v143 offset:54272
	ds_read_b128 v[200:203], v143 offset:55296
	ds_read_b128 v[206:209], v143 offset:56320
	global_load_lds_dwordx4 v[140:141], off
	s_add_i32 m0, s30, 0x2000
	s_add_u32 s28, s28, 0x80080
	v_lshl_add_u64 v[140:141], v[210:211], 0, s[70:71]
	s_addc_u32 s29, s29, 0
	s_add_i32 s30, s62, s36
	global_load_lds_dwordx4 v[140:141], off
	v_lshl_add_u64 v[140:141], s[28:29], 0, v[204:205]
	s_mov_b32 m0, s30
	s_nop 0
	global_load_lds_dwordx4 v[140:141], off
	v_lshl_add_u64 v[140:141], s[28:29], 0, v[132:133]
	s_add_i32 m0, s30, 0x2000
	s_nop 0
	global_load_lds_dwordx4 v[140:141], off
	v_lshl_add_u64 v[140:141], v[212:213], 0, s[70:71]
	s_mov_b32 m0, s46
	s_nop 0
	global_load_lds_dwordx4 v[140:141], off
	v_lshl_add_u64 v[140:141], v[214:215], 0, s[70:71]
	s_mov_b32 m0, s47
	s_nop 0
	global_load_lds_dwordx4 v[140:141], off
	s_add_i32 s54, s54, 2
	s_add_u32 s26, s26, 0x100
	s_addc_u32 s27, s27, 0
	s_add_u32 s52, s52, 0x100
	s_addc_u32 s53, s53, 0
	s_waitcnt vmcnt(8)
	s_waitcnt lgkmcnt(0)
	s_setprio 1
	s_barrier
	v_mfma_f32_16x16x32_bf16 v[60:63], v[144:147], v[176:179], v[60:63]
	v_mfma_f32_16x16x32_bf16 v[56:59], v[152:155], v[176:179], v[56:59]
	v_mfma_f32_16x16x32_bf16 v[44:47], v[144:147], v[184:187], v[44:47]
	v_mfma_f32_16x16x32_bf16 v[40:43], v[152:155], v[184:187], v[40:43]
	v_mfma_f32_16x16x32_bf16 v[28:31], v[144:147], v[192:195], v[28:31]
	v_mfma_f32_16x16x32_bf16 v[24:27], v[152:155], v[192:195], v[24:27]
	v_mfma_f32_16x16x32_bf16 v[12:15], v[144:147], v[200:203], v[12:15]
	v_mfma_f32_16x16x32_bf16 v[8:11], v[152:155], v[200:203], v[8:11]
	v_mfma_f32_16x16x32_bf16 v[60:63], v[148:151], v[180:183], v[60:63]
	v_mfma_f32_16x16x32_bf16 v[56:59], v[156:159], v[180:183], v[56:59]
	v_mfma_f32_16x16x32_bf16 v[44:47], v[148:151], v[188:191], v[44:47]
	v_mfma_f32_16x16x32_bf16 v[40:43], v[156:159], v[188:191], v[40:43]
	v_mfma_f32_16x16x32_bf16 v[28:31], v[148:151], v[196:199], v[28:31]
	v_mfma_f32_16x16x32_bf16 v[24:27], v[156:159], v[196:199], v[24:27]
	v_mfma_f32_16x16x32_bf16 v[12:15], v[148:151], v[206:209], v[12:15]
	v_mfma_f32_16x16x32_bf16 v[8:11], v[156:159], v[206:209], v[8:11]
	s_setprio 0
	s_setprio 1
	v_mfma_f32_16x16x32_bf16 v[52:55], v[160:163], v[176:179], v[52:55]
	v_mfma_f32_16x16x32_bf16 v[48:51], v[168:171], v[176:179], v[48:51]
	v_mfma_f32_16x16x32_bf16 v[36:39], v[160:163], v[184:187], v[36:39]
	v_mfma_f32_16x16x32_bf16 v[32:35], v[168:171], v[184:187], v[32:35]
	v_mfma_f32_16x16x32_bf16 v[20:23], v[160:163], v[192:195], v[20:23]
	v_mfma_f32_16x16x32_bf16 v[16:19], v[168:171], v[192:195], v[16:19]
	v_mfma_f32_16x16x32_bf16 v[4:7], v[160:163], v[200:203], v[4:7]
	v_mfma_f32_16x16x32_bf16 v[0:3], v[168:171], v[200:203], v[0:3]
	v_mfma_f32_16x16x32_bf16 v[52:55], v[164:167], v[180:183], v[52:55]
	v_mfma_f32_16x16x32_bf16 v[48:51], v[172:175], v[180:183], v[48:51]
	v_mfma_f32_16x16x32_bf16 v[36:39], v[164:167], v[188:191], v[36:39]
	v_mfma_f32_16x16x32_bf16 v[32:35], v[172:175], v[188:191], v[32:35]
	v_mfma_f32_16x16x32_bf16 v[20:23], v[164:167], v[196:199], v[20:23]
	v_mfma_f32_16x16x32_bf16 v[16:19], v[172:175], v[196:199], v[16:19]
	v_mfma_f32_16x16x32_bf16 v[4:7], v[164:167], v[206:209], v[4:7]
	v_mfma_f32_16x16x32_bf16 v[0:3], v[172:175], v[206:209], v[0:3]
	s_barrier
	s_setprio 0
.LBB0_1088:
	s_add_i32 s55, 0, 0x10000
	v_add_u32_e32 v138, s55, v139
	s_add_i32 s62, 0, 0x14000
	ds_read_b128 v[144:147], v138
	ds_read_b128 v[148:151], v138 offset:1024
	ds_read_b128 v[152:155], v138 offset:2048
	ds_read_b128 v[156:159], v138 offset:3072
	v_add_u32_e32 v138, s62, v139
	ds_read_b128 v[160:163], v138
	ds_read_b128 v[164:167], v138 offset:1024
	ds_read_b128 v[168:171], v138 offset:2048
	ds_read_b128 v[172:175], v138 offset:3072
	v_lshl_add_u64 v[140:141], s[26:27], 0, v[134:135]
	s_add_i32 m0, s37, 0xc000
	ds_read_b128 v[176:179], v143
	ds_read_b128 v[180:183], v143 offset:1024
	ds_read_b128 v[184:187], v143 offset:2048
	ds_read_b128 v[188:191], v143 offset:3072
	ds_read_b128 v[192:195], v143 offset:4096
	ds_read_b128 v[196:199], v143 offset:5120
	ds_read_b128 v[200:203], v143 offset:6144
	ds_read_b128 v[206:209], v143 offset:7168
	s_add_u32 s28, s26, 0xfff80080
	s_addc_u32 s29, s27, -1
	s_cmp_eq_u32 s54, 28
	s_cselect_b32 s31, s19, s29
	s_cselect_b32 s30, s50, s28
	s_cselect_b32 s29, s17, s53
	s_cselect_b32 s28, s51, s52
	global_load_lds_dwordx4 v[140:141], off
	v_lshl_add_u64 v[140:141], s[26:27], 0, v[136:137]
	s_add_i32 m0, s37, 0xe000
	s_nop 0
	global_load_lds_dwordx4 v[140:141], off
	s_waitcnt vmcnt(8)
	s_waitcnt lgkmcnt(0)
	s_setprio 1
	s_barrier
; #define PG8_STAGE(bufoff, gbase, voff) do { _Pragma("unroll") for (int _i = 0; _i < 2; ++_i) \
;         __builtin_amdgcn_global_load_lds((const unsigned*)((const char*)(gbase) + (voff)[_i]), (PG8_LAS unsigned*)(lds + (bufoff) + ldsw + _i * 8192), 16, 0, 0); } while (0)
; #define PG8_LDA(dst, b, h) do { _Pragma("unroll") for (int m = 0; m < 4; ++m) _Pragma("unroll") for (int k = 0; k < 2; ++k) dst[m][k] = *(const PG8_LAS bf16x8*)(lds + PG8_SA(b, h) + aoff + m * 2048 + k * 1024); } while (0)
; #define PG8_MMA(ai, bj, At, Bt) do { __builtin_amdgcn_s_setprio(1); _Pragma("unroll") for (int m = 0; m < 4; ++m) _Pragma("unroll") for (int n = 0; n < 2; ++n) _Pragma("unroll") for (int k = 0; k < 2; ++k) \
;         acc[ai][bj][m][n] = __builtin_amdgcn_mfma_f32_16x16x32_bf16(Bt[n][k], At[m][k], acc[ai][bj][m][n], 0, 0, 0); __builtin_amdgcn_s_setprio(0); } while (0)
; #define PG8_WAIT_V(n) asm volatile("s_waitcnt vmcnt(" #n ")" ::: "memory")
; #define PG8_WAIT_L(n) asm volatile("s_waitcnt lgkmcnt(" #n ")" ::: "memory")
; #define PG8_BAR __builtin_amdgcn_s_barrier()
; #define PG8_SCHED __builtin_amdgcn_sched_barrier(0)
; template <class Epi, class Sched, bool ALIGN_EPI = false, bool SP2 = false>
; __device__ __forceinline__ void gemm_phase(PG8_LAS unsigned char* lds, const Gemm g, const Sched& S, const Epi& E, const int tid) {
;     ...
;             PG8_WAIT_V(8); PG8_WAIT_L(0); PG8_BAR; PG8_MMA(0, 0, At, B0); PG8_MMA(0, 1, At, B1); PG8_BAR; PG8_SCHED;
;             PG8_LDA(At, 0, 1); PG8_STAGE(PG8_SB(0, 0), b2, voffB); PG8_STAGE(PG8_SB(0, 1), b2 + hstep, voffB); PG8_STAGE(PG8_SA(0, 0), a2, voffA);
;             PG8_WAIT_V(8); PG8_WAIT_L(0); PG8_BAR; PG8_MMA(1, 0, At, B0); PG8_MMA(1, 1, At, B1); PG8_BAR; PG8_SCHED;
	v_mfma_f32_16x16x32_bf16 v[124:127], v[144:147], v[176:179], v[124:127]
	v_mfma_f32_16x16x32_bf16 v[120:123], v[152:155], v[176:179], v[120:123]
	v_mfma_f32_16x16x32_bf16 v[108:111], v[144:147], v[184:187], v[108:111]
	v_mfma_f32_16x16x32_bf16 v[104:107], v[152:155], v[184:187], v[104:107]
	v_mfma_f32_16x16x32_bf16 v[92:95], v[144:147], v[192:195], v[92:95]
	v_mfma_f32_16x16x32_bf16 v[88:91], v[152:155], v[192:195], v[88:91]
	v_mfma_f32_16x16x32_bf16 v[76:79], v[144:147], v[200:203], v[76:79]
	v_mfma_f32_16x16x32_bf16 v[72:75], v[152:155], v[200:203], v[72:75]
	v_mfma_f32_16x16x32_bf16 v[124:127], v[148:151], v[180:183], v[124:127]
	v_mfma_f32_16x16x32_bf16 v[120:123], v[156:159], v[180:183], v[120:123]
	v_mfma_f32_16x16x32_bf16 v[108:111], v[148:151], v[188:191], v[108:111]
	v_mfma_f32_16x16x32_bf16 v[104:107], v[156:159], v[188:191], v[104:107]
	v_mfma_f32_16x16x32_bf16 v[92:95], v[148:151], v[196:199], v[92:95]
	v_mfma_f32_16x16x32_bf16 v[88:91], v[156:159], v[196:199], v[88:91]
	v_mfma_f32_16x16x32_bf16 v[76:79], v[148:151], v[206:209], v[76:79]
	v_mfma_f32_16x16x32_bf16 v[72:75], v[156:159], v[206:209], v[72:75]
	s_setprio 0
	s_setprio 1
	v_mfma_f32_16x16x32_bf16 v[116:119], v[160:163], v[176:179], v[116:119]
	v_mfma_f32_16x16x32_bf16 v[112:115], v[168:171], v[176:179], v[112:115]
	v_mfma_f32_16x16x32_bf16 v[100:103], v[160:163], v[184:187], v[100:103]
	v_mfma_f32_16x16x32_bf16 v[96:99], v[168:171], v[184:187], v[96:99]
	v_mfma_f32_16x16x32_bf16 v[84:87], v[160:163], v[192:195], v[84:87]
	v_mfma_f32_16x16x32_bf16 v[80:83], v[168:171], v[192:195], v[80:83]
	v_mfma_f32_16x16x32_bf16 v[68:71], v[160:163], v[200:203], v[68:71]
	v_mfma_f32_16x16x32_bf16 v[64:67], v[168:171], v[200:203], v[64:67]
	v_mfma_f32_16x16x32_bf16 v[116:119], v[164:167], v[180:183], v[116:119]
	v_mfma_f32_16x16x32_bf16 v[112:115], v[172:175], v[180:183], v[112:115]
	v_mfma_f32_16x16x32_bf16 v[100:103], v[164:167], v[188:191], v[100:103]
	v_mfma_f32_16x16x32_bf16 v[96:99], v[172:175], v[188:191], v[96:99]
	v_mfma_f32_16x16x32_bf16 v[84:87], v[164:167], v[196:199], v[84:87]
	v_mfma_f32_16x16x32_bf16 v[80:83], v[172:175], v[196:199], v[80:83]
	v_mfma_f32_16x16x32_bf16 v[68:71], v[164:167], v[206:209], v[68:71]
	v_mfma_f32_16x16x32_bf16 v[64:67], v[172:175], v[206:209], v[64:67]
	s_barrier
	s_setprio 0
	s_add_i32 s55, s55, s36
	v_lshl_add_u64 v[140:141], s[28:29], 0, v[204:205]
	s_mov_b32 m0, s55
	ds_read_b128 v[176:179], v143 offset:16384
	ds_read_b128 v[180:183], v143 offset:17408
	ds_read_b128 v[184:187], v143 offset:18432
	ds_read_b128 v[188:191], v143 offset:19456
	ds_read_b128 v[192:195], v143 offset:20480
	ds_read_b128 v[196:199], v143 offset:21504
	ds_read_b128 v[200:203], v143 offset:22528
	ds_read_b128 v[206:209], v143 offset:23552
	global_load_lds_dwordx4 v[140:141], off
	s_add_i32 m0, s55, 0x2000
	s_add_u32 s64, s28, 0x80000
	v_lshl_add_u64 v[210:211], s[28:29], 0, v[132:133]
	s_addc_u32 s65, s29, 0
	s_add_i32 s55, s62, s36
	global_load_lds_dwordx4 v[210:211], off
	v_lshl_add_u64 v[212:213], s[64:65], 0, v[204:205]
	s_mov_b32 m0, s55
	v_lshl_add_u64 v[214:215], s[30:31], 0, v[130:131]
	global_load_lds_dwordx4 v[212:213], off
	v_lshl_add_u64 v[212:213], s[64:65], 0, v[132:133]
	s_add_i32 m0, s55, 0x2000
	s_nop 0
	global_load_lds_dwordx4 v[212:213], off
	v_lshl_add_u64 v[212:213], s[30:31], 0, v[128:129]
	s_mov_b32 m0, s37
	s_nop 0
	global_load_lds_dwordx4 v[212:213], off
	s_mov_b32 m0, s38
	s_nop 0
	global_load_lds_dwordx4 v[214:215], off
	s_waitcnt vmcnt(8)
	s_waitcnt lgkmcnt(0)
	s_setprio 1
	s_barrier
	v_mfma_f32_16x16x32_bf16 v[60:63], v[144:147], v[176:179], v[60:63]
	v_mfma_f32_16x16x32_bf16 v[56:59], v[152:155], v[176:179], v[56:59]
	v_mfma_f32_16x16x32_bf16 v[44:47], v[144:147], v[184:187], v[44:47]
	v_mfma_f32_16x16x32_bf16 v[40:43], v[152:155], v[184:187], v[40:43]
	v_mfma_f32_16x16x32_bf16 v[28:31], v[144:147], v[192:195], v[28:31]
	v_mfma_f32_16x16x32_bf16 v[24:27], v[152:155], v[192:195], v[24:27]
	v_mfma_f32_16x16x32_bf16 v[12:15], v[144:147], v[200:203], v[12:15]
	v_mfma_f32_16x16x32_bf16 v[8:11], v[152:155], v[200:203], v[8:11]
	v_mfma_f32_16x16x32_bf16 v[60:63], v[148:151], v[180:183], v[60:63]
	v_mfma_f32_16x16x32_bf16 v[56:59], v[156:159], v[180:183], v[56:59]
	v_mfma_f32_16x16x32_bf16 v[44:47], v[148:151], v[188:191], v[44:47]
	v_mfma_f32_16x16x32_bf16 v[40:43], v[156:159], v[188:191], v[40:43]
	v_mfma_f32_16x16x32_bf16 v[28:31], v[148:151], v[196:199], v[28:31]
	v_mfma_f32_16x16x32_bf16 v[24:27], v[156:159], v[196:199], v[24:27]
	v_mfma_f32_16x16x32_bf16 v[12:15], v[148:151], v[206:209], v[12:15]
	v_mfma_f32_16x16x32_bf16 v[8:11], v[156:159], v[206:209], v[8:11]
	s_setprio 0
	s_setprio 1
	v_mfma_f32_16x16x32_bf16 v[52:55], v[160:163], v[176:179], v[52:55]
	v_mfma_f32_16x16x32_bf16 v[48:51], v[168:171], v[176:179], v[48:51]
	v_mfma_f32_16x16x32_bf16 v[36:39], v[160:163], v[184:187], v[36:39]
	v_mfma_f32_16x16x32_bf16 v[32:35], v[168:171], v[184:187], v[32:35]
	v_mfma_f32_16x16x32_bf16 v[20:23], v[160:163], v[192:195], v[20:23]
	v_mfma_f32_16x16x32_bf16 v[16:19], v[168:171], v[192:195], v[16:19]
	v_mfma_f32_16x16x32_bf16 v[4:7], v[160:163], v[200:203], v[4:7]
	v_mfma_f32_16x16x32_bf16 v[0:3], v[168:171], v[200:203], v[0:3]
	v_mfma_f32_16x16x32_bf16 v[52:55], v[164:167], v[180:183], v[52:55]
	v_mfma_f32_16x16x32_bf16 v[48:51], v[172:175], v[180:183], v[48:51]
	v_mfma_f32_16x16x32_bf16 v[36:39], v[164:167], v[188:191], v[36:39]
	v_mfma_f32_16x16x32_bf16 v[32:35], v[172:175], v[188:191], v[32:35]
	v_mfma_f32_16x16x32_bf16 v[20:23], v[164:167], v[196:199], v[20:23]
	v_mfma_f32_16x16x32_bf16 v[16:19], v[172:175], v[196:199], v[16:19]
	v_mfma_f32_16x16x32_bf16 v[4:7], v[164:167], v[206:209], v[4:7]
	v_mfma_f32_16x16x32_bf16 v[0:3], v[172:175], v[206:209], v[0:3]
	s_barrier
; #define PG8_STAGE(bufoff, gbase, voff) do { _Pragma("unroll") for (int _i = 0; _i < 2; ++_i) \
;         __builtin_amdgcn_global_load_lds((const unsigned*)((const char*)(gbase) + (voff)[_i]), (PG8_LAS unsigned*)(lds + (bufoff) + ldsw + _i * 8192), 16, 0, 0); } while (0)
; #define PG8_LDA(dst, b, h) do { _Pragma("unroll") for (int m = 0; m < 4; ++m) _Pragma("unroll") for (int k = 0; k < 2; ++k) dst[m][k] = *(const PG8_LAS bf16x8*)(lds + PG8_SA(b, h) + aoff + m * 2048 + k * 1024); } while (0)
; #define PG8_LDB(dst, b, h) do { _Pragma("unroll") for (int n = 0; n < 2; ++n) _Pragma("unroll") for (int k = 0; k < 2; ++k) dst[n][k] = *(const PG8_LAS bf16x8*)(lds + PG8_SB(b, h) + boff + n * 2048 + k * 1024); } while (0)
; #define PG8_MMA(ai, bj, At, Bt) do { __builtin_amdgcn_s_setprio(1); _Pragma("unroll") for (int m = 0; m < 4; ++m) _Pragma("unroll") for (int n = 0; n < 2; ++n) _Pragma("unroll") for (int k = 0; k < 2; ++k) \
;         acc[ai][bj][m][n] = __builtin_amdgcn_mfma_f32_16x16x32_bf16(Bt[n][k], At[m][k], acc[ai][bj][m][n], 0, 0, 0); __builtin_amdgcn_s_setprio(0); } while (0)
; #define PG8_WAIT_V(n) asm volatile("s_waitcnt vmcnt(" #n ")" ::: "memory")
; #define PG8_WAIT_L(n) asm volatile("s_waitcnt lgkmcnt(" #n ")" ::: "memory")
; #define PG8_BAR __builtin_amdgcn_s_barrier()
; #define PG8_SCHED __builtin_amdgcn_sched_barrier(0)
; template <class Epi, class Sched, bool ALIGN_EPI = false, bool SP2 = false>
; __device__ __forceinline__ void gemm_phase(PG8_LAS unsigned char* lds, const Gemm g, const Sched& S, const Epi& E, const int tid) {
;     ...
;             PG8_LDB(B0, 1, 0); PG8_LDB(B1, 1, 1); PG8_SCHED; PG8_LDA(At, 1, 0); PG8_STAGE(PG8_SA(0, 1), a2 + hstep, voffA);
;             PG8_WAIT_V(8); PG8_WAIT_L(0); PG8_BAR; PG8_MMA(0, 0, At, B0); PG8_MMA(0, 1, At, B1); PG8_BAR; PG8_SCHED;
	s_setprio 0
	s_add_i32 s55, 0, 0x18000
	v_add_u32_e32 v138, s55, v139
	s_add_i32 s62, 0, 0x1c000
	ds_read_b128 v[144:147], v138
	ds_read_b128 v[148:151], v138 offset:1024
	ds_read_b128 v[152:155], v138 offset:2048
	ds_read_b128 v[156:159], v138 offset:3072
	v_add_u32_e32 v138, s62, v139
	ds_read_b128 v[160:163], v138
	ds_read_b128 v[164:167], v138 offset:1024
	ds_read_b128 v[168:171], v138 offset:2048
	ds_read_b128 v[172:175], v138 offset:3072
	s_add_u32 s30, s30, 0x80000
	s_addc_u32 s31, s31, 0
	s_mov_b32 m0, s40
	v_lshl_add_u64 v[216:217], s[30:31], 0, v[128:129]
	ds_read_b128 v[176:179], v143 offset:32768
	ds_read_b128 v[180:183], v143 offset:33792
	ds_read_b128 v[184:187], v143 offset:34816
	ds_read_b128 v[188:191], v143 offset:35840
	ds_read_b128 v[192:195], v143 offset:36864
	ds_read_b128 v[196:199], v143 offset:37888
	ds_read_b128 v[200:203], v143 offset:38912
	ds_read_b128 v[206:209], v143 offset:39936
	global_load_lds_dwordx4 v[216:217], off
	v_lshl_add_u64 v[216:217], s[30:31], 0, v[130:131]
	s_mov_b32 m0, s42
	s_nop 0
	global_load_lds_dwordx4 v[216:217], off
	s_waitcnt vmcnt(8)
	s_waitcnt lgkmcnt(0)
	s_setprio 1
	s_barrier
	v_mfma_f32_16x16x32_bf16 v[124:127], v[144:147], v[176:179], v[124:127]
	v_mfma_f32_16x16x32_bf16 v[120:123], v[152:155], v[176:179], v[120:123]
	v_mfma_f32_16x16x32_bf16 v[108:111], v[144:147], v[184:187], v[108:111]
	v_mfma_f32_16x16x32_bf16 v[104:107], v[152:155], v[184:187], v[104:107]
	v_mfma_f32_16x16x32_bf16 v[92:95], v[144:147], v[192:195], v[92:95]
	v_mfma_f32_16x16x32_bf16 v[88:91], v[152:155], v[192:195], v[88:91]
	v_mfma_f32_16x16x32_bf16 v[76:79], v[144:147], v[200:203], v[76:79]
	v_mfma_f32_16x16x32_bf16 v[72:75], v[152:155], v[200:203], v[72:75]
	v_mfma_f32_16x16x32_bf16 v[124:127], v[148:151], v[180:183], v[124:127]
	v_mfma_f32_16x16x32_bf16 v[120:123], v[156:159], v[180:183], v[120:123]
	v_mfma_f32_16x16x32_bf16 v[108:111], v[148:151], v[188:191], v[108:111]
	v_mfma_f32_16x16x32_bf16 v[104:107], v[156:159], v[188:191], v[104:107]
	v_mfma_f32_16x16x32_bf16 v[92:95], v[148:151], v[196:199], v[92:95]
	v_mfma_f32_16x16x32_bf16 v[88:91], v[156:159], v[196:199], v[88:91]
	v_mfma_f32_16x16x32_bf16 v[76:79], v[148:151], v[206:209], v[76:79]
	v_mfma_f32_16x16x32_bf16 v[72:75], v[156:159], v[206:209], v[72:75]
	s_setprio 0
	s_setprio 1
	v_mfma_f32_16x16x32_bf16 v[116:119], v[160:163], v[176:179], v[116:119]
	v_mfma_f32_16x16x32_bf16 v[112:115], v[168:171], v[176:179], v[112:115]
	v_mfma_f32_16x16x32_bf16 v[100:103], v[160:163], v[184:187], v[100:103]
	v_mfma_f32_16x16x32_bf16 v[96:99], v[168:171], v[184:187], v[96:99]
	v_mfma_f32_16x16x32_bf16 v[84:87], v[160:163], v[192:195], v[84:87]
	v_mfma_f32_16x16x32_bf16 v[80:83], v[168:171], v[192:195], v[80:83]
	v_mfma_f32_16x16x32_bf16 v[68:71], v[160:163], v[200:203], v[68:71]
	v_mfma_f32_16x16x32_bf16 v[64:67], v[168:171], v[200:203], v[64:67]
	v_mfma_f32_16x16x32_bf16 v[116:119], v[164:167], v[180:183], v[116:119]
	v_mfma_f32_16x16x32_bf16 v[112:115], v[172:175], v[180:183], v[112:115]
	v_mfma_f32_16x16x32_bf16 v[100:103], v[164:167], v[188:191], v[100:103]
	v_mfma_f32_16x16x32_bf16 v[96:99], v[172:175], v[188:191], v[96:99]
	v_mfma_f32_16x16x32_bf16 v[84:87], v[164:167], v[196:199], v[84:87]
	v_mfma_f32_16x16x32_bf16 v[80:83], v[172:175], v[196:199], v[80:83]
	v_mfma_f32_16x16x32_bf16 v[68:71], v[164:167], v[206:209], v[68:71]
	v_mfma_f32_16x16x32_bf16 v[64:67], v[172:175], v[206:209], v[64:67]
	s_barrier
; #define PG8_STAGE(bufoff, gbase, voff) do { _Pragma("unroll") for (int _i = 0; _i < 2; ++_i) \
;         __builtin_amdgcn_global_load_lds((const unsigned*)((const char*)(gbase) + (voff)[_i]), (PG8_LAS unsigned*)(lds + (bufoff) + ldsw + _i * 8192), 16, 0, 0); } while (0)
; #define PG8_LDA(dst, b, h) do { _Pragma("unroll") for (int m = 0; m < 4; ++m) _Pragma("unroll") for (int k = 0; k < 2; ++k) dst[m][k] = *(const PG8_LAS bf16x8*)(lds + PG8_SA(b, h) + aoff + m * 2048 + k * 1024); } while (0)
; #define PG8_MMA(ai, bj, At, Bt) do { __builtin_amdgcn_s_setprio(1); _Pragma("unroll") for (int m = 0; m < 4; ++m) _Pragma("unroll") for (int n = 0; n < 2; ++n) _Pragma("unroll") for (int k = 0; k < 2; ++k) \
;         acc[ai][bj][m][n] = __builtin_amdgcn_mfma_f32_16x16x32_bf16(Bt[n][k], At[m][k], acc[ai][bj][m][n], 0, 0, 0); __builtin_amdgcn_s_setprio(0); } while (0)
; #define PG8_WAIT_V(n) asm volatile("s_waitcnt vmcnt(" #n ")" ::: "memory")
; #define PG8_WAIT_L(n) asm volatile("s_waitcnt lgkmcnt(" #n ")" ::: "memory")
; #define PG8_BAR __builtin_amdgcn_s_barrier()
; #define PG8_SCHED __builtin_amdgcn_sched_barrier(0)
; template <class Epi, class Sched, bool ALIGN_EPI = false, bool SP2 = false>
; __device__ __forceinline__ void gemm_phase(PG8_LAS unsigned char* lds, const Gemm g, const Sched& S, const Epi& E, const int tid) {
;     ...
;         for (int t = 0; t < nt; t += 2) {
;             const bool last = (t == nt - 2);
;             const char* a1 = cA + (size_t)(t + 1) * kstep;
;             const char* a2 = last ? nA : cA + (size_t)(t + 2) * kstep; const char* b2 = last ? nB : cB + (size_t)(t + 2) * kstep;
;     ...
;             PG8_LDA(At, 1, 1); PG8_STAGE(PG8_SB(1, 0), b3, voffB); PG8_STAGE(PG8_SB(1, 1), b3 + hstep, voffB); PG8_STAGE(PG8_SA(1, 0), a3, voffA);
;             PG8_WAIT_V(8); PG8_WAIT_L(0); PG8_BAR; PG8_MMA(1, 0, At, B0); PG8_MMA(1, 1, At, B1); PG8_BAR; PG8_SCHED;
	s_setprio 0
	s_add_i32 s30, s55, s36
	v_lshl_add_u64 v[140:141], v[140:141], 0, s[70:71]
	s_mov_b32 m0, s30
	ds_read_b128 v[176:179], v143 offset:49152
	ds_read_b128 v[180:183], v143 offset:50176
	ds_read_b128 v[184:187], v143 offset:51200
	ds_read_b128 v[188:191], v143 offset:52224
	ds_read_b128 v[192:195], v143 offset:53248
	ds_read_b128 v[196:199], v143 offset:54272
	ds_read_b128 v[200:203], v143 offset:55296
	ds_read_b128 v[206:209], v143 offset:56320
	global_load_lds_dwordx4 v[140:141], off
	s_add_i32 m0, s30, 0x2000
	s_add_u32 s28, s28, 0x80080
	v_lshl_add_u64 v[140:141], v[210:211], 0, s[70:71]
	s_addc_u32 s29, s29, 0
	s_add_i32 s30, s62, s36
	global_load_lds_dwordx4 v[140:141], off
	v_lshl_add_u64 v[140:141], s[28:29], 0, v[204:205]
	s_mov_b32 m0, s30
	s_nop 0
	global_load_lds_dwordx4 v[140:141], off
	v_lshl_add_u64 v[140:141], s[28:29], 0, v[132:133]
	s_add_i32 m0, s30, 0x2000
	s_nop 0
	global_load_lds_dwordx4 v[140:141], off
	v_lshl_add_u64 v[140:141], v[212:213], 0, s[70:71]
	s_mov_b32 m0, s46
	s_nop 0
	global_load_lds_dwordx4 v[140:141], off
	v_lshl_add_u64 v[140:141], v[214:215], 0, s[70:71]
	s_mov_b32 m0, s47
	s_nop 0
	global_load_lds_dwordx4 v[140:141], off
	s_add_i32 s54, s54, 2
	s_add_u32 s26, s26, 0x100
	s_addc_u32 s27, s27, 0
	s_add_u32 s52, s52, 0x100
	s_addc_u32 s53, s53, 0
	s_waitcnt vmcnt(8)
	s_waitcnt lgkmcnt(0)
	s_setprio 1
	s_barrier
	v_mfma_f32_16x16x32_bf16 v[60:63], v[144:147], v[176:179], v[60:63]
	v_mfma_f32_16x16x32_bf16 v[56:59], v[152:155], v[176:179], v[56:59]
	v_mfma_f32_16x16x32_bf16 v[44:47], v[144:147], v[184:187], v[44:47]
	v_mfma_f32_16x16x32_bf16 v[40:43], v[152:155], v[184:187], v[40:43]
	v_mfma_f32_16x16x32_bf16 v[28:31], v[144:147], v[192:195], v[28:31]
	v_mfma_f32_16x16x32_bf16 v[24:27], v[152:155], v[192:195], v[24:27]
	v_mfma_f32_16x16x32_bf16 v[12:15], v[144:147], v[200:203], v[12:15]
	v_mfma_f32_16x16x32_bf16 v[8:11], v[152:155], v[200:203], v[8:11]
	v_mfma_f32_16x16x32_bf16 v[60:63], v[148:151], v[180:183], v[60:63]
	v_mfma_f32_16x16x32_bf16 v[56:59], v[156:159], v[180:183], v[56:59]
	v_mfma_f32_16x16x32_bf16 v[44:47], v[148:151], v[188:191], v[44:47]
	v_mfma_f32_16x16x32_bf16 v[40:43], v[156:159], v[188:191], v[40:43]
	v_mfma_f32_16x16x32_bf16 v[28:31], v[148:151], v[196:199], v[28:31]
	v_mfma_f32_16x16x32_bf16 v[24:27], v[156:159], v[196:199], v[24:27]
	v_mfma_f32_16x16x32_bf16 v[12:15], v[148:151], v[206:209], v[12:15]
	v_mfma_f32_16x16x32_bf16 v[8:11], v[156:159], v[206:209], v[8:11]
	s_setprio 0
	s_setprio 1
	v_mfma_f32_16x16x32_bf16 v[52:55], v[160:163], v[176:179], v[52:55]
	v_mfma_f32_16x16x32_bf16 v[48:51], v[168:171], v[176:179], v[48:51]
	v_mfma_f32_16x16x32_bf16 v[36:39], v[160:163], v[184:187], v[36:39]
	v_mfma_f32_16x16x32_bf16 v[32:35], v[168:171], v[184:187], v[32:35]
	v_mfma_f32_16x16x32_bf16 v[20:23], v[160:163], v[192:195], v[20:23]
	v_mfma_f32_16x16x32_bf16 v[16:19], v[168:171], v[192:195], v[16:19]
	v_mfma_f32_16x16x32_bf16 v[4:7], v[160:163], v[200:203], v[4:7]
	v_mfma_f32_16x16x32_bf16 v[0:3], v[168:171], v[200:203], v[0:3]
	v_mfma_f32_16x16x32_bf16 v[52:55], v[164:167], v[180:183], v[52:55]
	v_mfma_f32_16x16x32_bf16 v[48:51], v[172:175], v[180:183], v[48:51]
	v_mfma_f32_16x16x32_bf16 v[36:39], v[164:167], v[188:191], v[36:39]
	v_mfma_f32_16x16x32_bf16 v[32:35], v[172:175], v[188:191], v[32:35]
	v_mfma_f32_16x16x32_bf16 v[20:23], v[164:167], v[196:199], v[20:23]
	v_mfma_f32_16x16x32_bf16 v[16:19], v[172:175], v[196:199], v[16:19]
	v_mfma_f32_16x16x32_bf16 v[4:7], v[164:167], v[206:209], v[4:7]
	v_mfma_f32_16x16x32_bf16 v[0:3], v[172:175], v[206:209], v[0:3]
	s_barrier
	s_setprio 0
	s_cmp_gt_u32 s54, 29
	s_cbranch_scc0 .LBB0_1088
	s_and_b64 vcc, exec, s[14:15]
	s_cbranch_vccz .LBB0_1091
	s_barrier

; #define PG8_STAGE(bufoff, gbase, voff) do { _Pragma("unroll") for (int _i = 0; _i < 2; ++_i) \
;         __builtin_amdgcn_global_load_lds((const unsigned*)((const char*)(gbase) + (voff)[_i]), (PG8_LAS unsigned*)(lds + (bufoff) + ldsw + _i * 8192), 16, 0, 0); } while (0)
; #define PG8_LDA(dst, b, h) do { _Pragma("unroll") for (int m = 0; m < 4; ++m) _Pragma("unroll") for (int k = 0; k < 2; ++k) dst[m][k] = *(const PG8_LAS bf16x8*)(lds + PG8_SA(b, h) + aoff + m * 2048 + k * 1024); } while (0)
; #define PG8_LDB(dst, b, h) do { _Pragma("unroll") for (int n = 0; n < 2; ++n) _Pragma("unroll") for (int k = 0; k < 2; ++k) dst[n][k] = *(const PG8_LAS bf16x8*)(lds + PG8_SB(b, h) + boff + n * 2048 + k * 1024); } while (0)
; #define PG8_MMA(ai, bj, At, Bt) do { __builtin_amdgcn_s_setprio(1); _Pragma("unroll") for (int m = 0; m < 4; ++m) _Pragma("unroll") for (int n = 0; n < 2; ++n) _Pragma("unroll") for (int k = 0; k < 2; ++k) \
;         acc[ai][bj][m][n] = __builtin_amdgcn_mfma_f32_16x16x32_bf16(Bt[n][k], At[m][k], acc[ai][bj][m][n], 0, 0, 0); __builtin_amdgcn_s_setprio(0); } while (0)
; #define PG8_WAIT_V(n) asm volatile("s_waitcnt vmcnt(" #n ")" ::: "memory")
; #define PG8_BAR __builtin_amdgcn_s_barrier()
; template <class Epi, class Sched, bool ALIGN_EPI = false, bool SP2 = false>
; __device__ __forceinline__ void gemm_phase(PG8_LAS unsigned char* lds, const Gemm g, const Sched& S, const Epi& E, const int tid) {
;     ...
;         for (int t = 0; t < nt; t += 2) {
;             const bool last = (t == nt - 2);
;             const char* a1 = cA + (size_t)(t + 1) * kstep;
;             const char* a2 = last ? nA : cA + (size_t)(t + 2) * kstep; const char* b2 = last ? nB : cB + (size_t)(t + 2) * kstep;
;             const char* a3 = a2 + kstep; const char* b3 = b2 + kstep;
;             if (last && has_next) S.a_ready(nxt);
;             if constexpr (SP2) {
;             PG8_LDB(B0, 0, 0); PG8_LDB(B1, 0, 1); PG8_SCHED; PG8_LDA(At, 0, 0); PG8_STAGE(PG8_SA(1, 1), a1 + hstep, voffA);
;             PG8_WAIT_V(8); PG8_WAIT_L(0); PG8_BAR; PG8_MMA(0, 0, At, B0); PG8_MMA(0, 1, At, B1); PG8_BAR; PG8_SCHED;
;             PG8_LDA(At, 0, 1); PG8_STAGE(PG8_SB(0, 0), b2, voffB); PG8_STAGE(PG8_SB(0, 1), b2 + hstep, voffB); PG8_STAGE(PG8_SA(0, 0), a2, voffA);
;             PG8_WAIT_V(8); PG8_WAIT_L(0); PG8_BAR; PG8_MMA(1, 0, At, B0); PG8_MMA(1, 1, At, B1); PG8_BAR; PG8_SCHED;
.LBB0_1198:
	s_add_i32 s65, 0, 0x10000
	s_add_i32 s75, 0, 0x14000
	v_add_u32_e32 v140, s65, v216
	v_add_u32_e32 v156, s75, v216
	ds_read_b128 v[128:131], v140
	ds_read_b128 v[132:135], v140 offset:1024
	ds_read_b128 v[136:139], v140 offset:2048
	ds_read_b128 v[140:143], v140 offset:3072
	ds_read_b128 v[144:147], v156
	ds_read_b128 v[148:151], v156 offset:1024
	ds_read_b128 v[152:155], v156 offset:2048
	ds_read_b128 v[156:159], v156 offset:3072
	v_lshl_add_u64 v[202:203], s[30:31], 0, v[198:199]
	s_add_i32 m0, s44, 0xc000
	ds_read_b128 v[160:163], v217
	ds_read_b128 v[164:167], v217 offset:1024
	ds_read_b128 v[168:171], v217 offset:2048
	ds_read_b128 v[172:175], v217 offset:3072
	ds_read_b128 v[176:179], v217 offset:4096
	ds_read_b128 v[180:183], v217 offset:5120
	ds_read_b128 v[184:187], v217 offset:6144
	ds_read_b128 v[188:191], v217 offset:7168
	s_add_u32 s28, s30, 0xffe00080
	s_addc_u32 s29, s31, -1
	s_cmpk_eq_i32 s64, 0x7c
	s_cselect_b32 s35, s19, s29
	s_cselect_b32 s34, s40, s28
	s_cselect_b32 s29, s17, s62
	s_cselect_b32 s28, s54, s55
	global_load_lds_dwordx4 v[202:203], off
	v_lshl_add_u64 v[202:203], s[30:31], 0, v[200:201]
	s_add_i32 m0, s44, 0xe000
	s_nop 0
	global_load_lds_dwordx4 v[202:203], off
	s_waitcnt vmcnt(8)
	s_waitcnt lgkmcnt(0)
	s_setprio 1
	s_barrier
	v_mfma_f32_16x16x32_bf16 v[120:123], v[128:131], v[160:163], v[120:123]
	v_mfma_f32_16x16x32_bf16 v[124:127], v[136:139], v[160:163], v[124:127]
	v_mfma_f32_16x16x32_bf16 v[104:107], v[128:131], v[168:171], v[104:107]
	v_mfma_f32_16x16x32_bf16 v[108:111], v[136:139], v[168:171], v[108:111]
	v_mfma_f32_16x16x32_bf16 v[88:91], v[128:131], v[176:179], v[88:91]
	v_mfma_f32_16x16x32_bf16 v[92:95], v[136:139], v[176:179], v[92:95]
	v_mfma_f32_16x16x32_bf16 v[72:75], v[128:131], v[184:187], v[72:75]
	v_mfma_f32_16x16x32_bf16 v[76:79], v[136:139], v[184:187], v[76:79]
	v_mfma_f32_16x16x32_bf16 v[120:123], v[132:135], v[164:167], v[120:123]
	v_mfma_f32_16x16x32_bf16 v[124:127], v[140:143], v[164:167], v[124:127]
	v_mfma_f32_16x16x32_bf16 v[104:107], v[132:135], v[172:175], v[104:107]
	v_mfma_f32_16x16x32_bf16 v[108:111], v[140:143], v[172:175], v[108:111]
	v_mfma_f32_16x16x32_bf16 v[88:91], v[132:135], v[180:183], v[88:91]
	v_mfma_f32_16x16x32_bf16 v[92:95], v[140:143], v[180:183], v[92:95]
	v_mfma_f32_16x16x32_bf16 v[72:75], v[132:135], v[188:191], v[72:75]
	v_mfma_f32_16x16x32_bf16 v[76:79], v[140:143], v[188:191], v[76:79]
	s_setprio 0
	s_setprio 1
	v_mfma_f32_16x16x32_bf16 v[112:115], v[144:147], v[160:163], v[112:115]
	v_mfma_f32_16x16x32_bf16 v[116:119], v[152:155], v[160:163], v[116:119]
	v_mfma_f32_16x16x32_bf16 v[96:99], v[144:147], v[168:171], v[96:99]
	v_mfma_f32_16x16x32_bf16 v[100:103], v[152:155], v[168:171], v[100:103]
	v_mfma_f32_16x16x32_bf16 v[80:83], v[144:147], v[176:179], v[80:83]
	v_mfma_f32_16x16x32_bf16 v[84:87], v[152:155], v[176:179], v[84:87]
	v_mfma_f32_16x16x32_bf16 v[64:67], v[144:147], v[184:187], v[64:67]
	v_mfma_f32_16x16x32_bf16 v[68:71], v[152:155], v[184:187], v[68:71]
	v_mfma_f32_16x16x32_bf16 v[112:115], v[148:151], v[164:167], v[112:115]
	v_mfma_f32_16x16x32_bf16 v[116:119], v[156:159], v[164:167], v[116:119]
	v_mfma_f32_16x16x32_bf16 v[96:99], v[148:151], v[172:175], v[96:99]
	v_mfma_f32_16x16x32_bf16 v[100:103], v[156:159], v[172:175], v[100:103]
	v_mfma_f32_16x16x32_bf16 v[80:83], v[148:151], v[180:183], v[80:83]
	v_mfma_f32_16x16x32_bf16 v[84:87], v[156:159], v[180:183], v[84:87]
	v_mfma_f32_16x16x32_bf16 v[64:67], v[148:151], v[188:191], v[64:67]
	v_mfma_f32_16x16x32_bf16 v[68:71], v[156:159], v[188:191], v[68:71]
	s_barrier
	s_setprio 0
	s_add_i32 s65, s65, s38
	v_lshl_add_u64 v[202:203], s[28:29], 0, v[204:205]
	s_mov_b32 m0, s65
	ds_read_b128 v[160:163], v217 offset:16384
	ds_read_b128 v[164:167], v217 offset:17408
	ds_read_b128 v[168:171], v217 offset:18432
	ds_read_b128 v[172:175], v217 offset:19456
	ds_read_b128 v[176:179], v217 offset:20480
	ds_read_b128 v[180:183], v217 offset:21504
	ds_read_b128 v[184:187], v217 offset:22528
	ds_read_b128 v[188:191], v217 offset:23552
	global_load_lds_dwordx4 v[202:203], off
	s_add_i32 m0, s65, 0x2000
	s_add_u32 s68, s28, 0x200000
	v_lshl_add_u64 v[206:207], s[28:29], 0, v[196:197]
	s_addc_u32 s69, s29, 0
	s_add_i32 s65, s75, s38
	global_load_lds_dwordx4 v[206:207], off
	v_lshl_add_u64 v[208:209], s[68:69], 0, v[204:205]
	s_mov_b32 m0, s65
	v_lshl_add_u64 v[210:211], s[34:35], 0, v[194:195]
	global_load_lds_dwordx4 v[208:209], off
	v_lshl_add_u64 v[208:209], s[68:69], 0, v[196:197]
	s_add_i32 m0, s65, 0x2000
	s_nop 0
	global_load_lds_dwordx4 v[208:209], off
	v_lshl_add_u64 v[208:209], s[34:35], 0, v[192:193]
	s_mov_b32 m0, s44
	s_nop 0
	global_load_lds_dwordx4 v[208:209], off
	s_mov_b32 m0, s45
	s_nop 0
	global_load_lds_dwordx4 v[210:211], off
	s_waitcnt vmcnt(8)
	s_waitcnt lgkmcnt(0)
	s_setprio 1
	s_barrier
; #define PG8_STAGE(bufoff, gbase, voff) do { _Pragma("unroll") for (int _i = 0; _i < 2; ++_i) \
;         __builtin_amdgcn_global_load_lds((const unsigned*)((const char*)(gbase) + (voff)[_i]), (PG8_LAS unsigned*)(lds + (bufoff) + ldsw + _i * 8192), 16, 0, 0); } while (0)
; #define PG8_LDA(dst, b, h) do { _Pragma("unroll") for (int m = 0; m < 4; ++m) _Pragma("unroll") for (int k = 0; k < 2; ++k) dst[m][k] = *(const PG8_LAS bf16x8*)(lds + PG8_SA(b, h) + aoff + m * 2048 + k * 1024); } while (0)
; #define PG8_LDB(dst, b, h) do { _Pragma("unroll") for (int n = 0; n < 2; ++n) _Pragma("unroll") for (int k = 0; k < 2; ++k) dst[n][k] = *(const PG8_LAS bf16x8*)(lds + PG8_SB(b, h) + boff + n * 2048 + k * 1024); } while (0)
; #define PG8_MMA(ai, bj, At, Bt) do { __builtin_amdgcn_s_setprio(1); _Pragma("unroll") for (int m = 0; m < 4; ++m) _Pragma("unroll") for (int n = 0; n < 2; ++n) _Pragma("unroll") for (int k = 0; k < 2; ++k) \
;         acc[ai][bj][m][n] = __builtin_amdgcn_mfma_f32_16x16x32_bf16(Bt[n][k], At[m][k], acc[ai][bj][m][n], 0, 0, 0); __builtin_amdgcn_s_setprio(0); } while (0)
; #define PG8_WAIT_V(n) asm volatile("s_waitcnt vmcnt(" #n ")" ::: "memory")
; #define PG8_WAIT_L(n) asm volatile("s_waitcnt lgkmcnt(" #n ")" ::: "memory")
; #define PG8_BAR __builtin_amdgcn_s_barrier()
; #define PG8_SCHED __builtin_amdgcn_sched_barrier(0)
; template <class Epi, class Sched, bool ALIGN_EPI = false, bool SP2 = false>
; __device__ __forceinline__ void gemm_phase(PG8_LAS unsigned char* lds, const Gemm g, const Sched& S, const Epi& E, const int tid) {
;     ...
;             PG8_WAIT_V(8); PG8_WAIT_L(0); PG8_BAR; PG8_MMA(1, 0, At, B0); PG8_MMA(1, 1, At, B1); PG8_BAR; PG8_SCHED;
;             PG8_LDB(B0, 1, 0); PG8_LDB(B1, 1, 1); PG8_SCHED; PG8_LDA(At, 1, 0); PG8_STAGE(PG8_SA(0, 1), a2 + hstep, voffA);
;             PG8_WAIT_V(8); PG8_WAIT_L(0); PG8_BAR; PG8_MMA(0, 0, At, B0); PG8_MMA(0, 1, At, B1); PG8_BAR; PG8_SCHED;
	v_mfma_f32_16x16x32_bf16 v[52:55], v[128:131], v[160:163], v[52:55]
	v_mfma_f32_16x16x32_bf16 v[56:59], v[136:139], v[160:163], v[56:59]
	v_mfma_f32_16x16x32_bf16 v[24:27], v[128:131], v[168:171], v[24:27]
	v_mfma_f32_16x16x32_bf16 v[60:63], v[136:139], v[168:171], v[60:63]
	v_mfma_f32_16x16x32_bf16 v[28:31], v[128:131], v[176:179], v[28:31]
	v_mfma_f32_16x16x32_bf16 v[32:35], v[136:139], v[176:179], v[32:35]
	v_mfma_f32_16x16x32_bf16 v[8:11], v[128:131], v[184:187], v[8:11]
	v_mfma_f32_16x16x32_bf16 v[12:15], v[136:139], v[184:187], v[12:15]
	v_mfma_f32_16x16x32_bf16 v[52:55], v[132:135], v[164:167], v[52:55]
	v_mfma_f32_16x16x32_bf16 v[56:59], v[140:143], v[164:167], v[56:59]
	v_mfma_f32_16x16x32_bf16 v[24:27], v[132:135], v[172:175], v[24:27]
	v_mfma_f32_16x16x32_bf16 v[60:63], v[140:143], v[172:175], v[60:63]
	v_mfma_f32_16x16x32_bf16 v[28:31], v[132:135], v[180:183], v[28:31]
	v_mfma_f32_16x16x32_bf16 v[32:35], v[140:143], v[180:183], v[32:35]
	v_mfma_f32_16x16x32_bf16 v[8:11], v[132:135], v[188:191], v[8:11]
	v_mfma_f32_16x16x32_bf16 v[12:15], v[140:143], v[188:191], v[12:15]
	s_setprio 0
	s_setprio 1
	v_mfma_f32_16x16x32_bf16 v[36:39], v[144:147], v[160:163], v[36:39]
	v_mfma_f32_16x16x32_bf16 v[40:43], v[152:155], v[160:163], v[40:43]
	v_mfma_f32_16x16x32_bf16 v[44:47], v[144:147], v[168:171], v[44:47]
	v_mfma_f32_16x16x32_bf16 v[48:51], v[152:155], v[168:171], v[48:51]
	v_mfma_f32_16x16x32_bf16 v[16:19], v[144:147], v[176:179], v[16:19]
	v_mfma_f32_16x16x32_bf16 v[20:23], v[152:155], v[176:179], v[20:23]
	v_mfma_f32_16x16x32_bf16 v[0:3], v[144:147], v[184:187], v[0:3]
	v_mfma_f32_16x16x32_bf16 v[4:7], v[152:155], v[184:187], v[4:7]
	v_mfma_f32_16x16x32_bf16 v[36:39], v[148:151], v[164:167], v[36:39]
	v_mfma_f32_16x16x32_bf16 v[40:43], v[156:159], v[164:167], v[40:43]
	v_mfma_f32_16x16x32_bf16 v[44:47], v[148:151], v[172:175], v[44:47]
	v_mfma_f32_16x16x32_bf16 v[48:51], v[156:159], v[172:175], v[48:51]
	v_mfma_f32_16x16x32_bf16 v[16:19], v[148:151], v[180:183], v[16:19]
	v_mfma_f32_16x16x32_bf16 v[20:23], v[156:159], v[180:183], v[20:23]
	v_mfma_f32_16x16x32_bf16 v[0:3], v[148:151], v[188:191], v[0:3]
	v_mfma_f32_16x16x32_bf16 v[4:7], v[156:159], v[188:191], v[4:7]
	s_barrier
	s_setprio 0
	s_add_i32 s65, 0, 0x18000
	s_add_i32 s68, 0, 0x1c000
	v_add_u32_e32 v140, s65, v216
	v_add_u32_e32 v156, s68, v216
	ds_read_b128 v[128:131], v140
	ds_read_b128 v[132:135], v140 offset:1024
	ds_read_b128 v[136:139], v140 offset:2048
	ds_read_b128 v[140:143], v140 offset:3072
	ds_read_b128 v[144:147], v156
	ds_read_b128 v[148:151], v156 offset:1024
	ds_read_b128 v[152:155], v156 offset:2048
	ds_read_b128 v[156:159], v156 offset:3072
	s_add_u32 s34, s34, 0x200000
	s_addc_u32 s35, s35, 0
	s_mov_b32 m0, s46
	v_lshl_add_u64 v[212:213], s[34:35], 0, v[192:193]
	ds_read_b128 v[160:163], v217 offset:32768
	ds_read_b128 v[164:167], v217 offset:33792
	ds_read_b128 v[168:171], v217 offset:34816
	ds_read_b128 v[172:175], v217 offset:35840
	ds_read_b128 v[176:179], v217 offset:36864
	ds_read_b128 v[180:183], v217 offset:37888
	ds_read_b128 v[184:187], v217 offset:38912
	ds_read_b128 v[188:191], v217 offset:39936
	global_load_lds_dwordx4 v[212:213], off
	v_lshl_add_u64 v[212:213], s[34:35], 0, v[194:195]
	s_mov_b32 m0, s47
	s_nop 0
	global_load_lds_dwordx4 v[212:213], off
	s_waitcnt vmcnt(8)
	s_waitcnt lgkmcnt(0)
	s_setprio 1
	s_barrier
	v_mfma_f32_16x16x32_bf16 v[120:123], v[128:131], v[160:163], v[120:123]
	v_mfma_f32_16x16x32_bf16 v[124:127], v[136:139], v[160:163], v[124:127]
	v_mfma_f32_16x16x32_bf16 v[104:107], v[128:131], v[168:171], v[104:107]
	v_mfma_f32_16x16x32_bf16 v[108:111], v[136:139], v[168:171], v[108:111]
	v_mfma_f32_16x16x32_bf16 v[88:91], v[128:131], v[176:179], v[88:91]
	v_mfma_f32_16x16x32_bf16 v[92:95], v[136:139], v[176:179], v[92:95]
	v_mfma_f32_16x16x32_bf16 v[72:75], v[128:131], v[184:187], v[72:75]
	v_mfma_f32_16x16x32_bf16 v[76:79], v[136:139], v[184:187], v[76:79]
	v_mfma_f32_16x16x32_bf16 v[120:123], v[132:135], v[164:167], v[120:123]
	v_mfma_f32_16x16x32_bf16 v[124:127], v[140:143], v[164:167], v[124:127]
	v_mfma_f32_16x16x32_bf16 v[104:107], v[132:135], v[172:175], v[104:107]
	v_mfma_f32_16x16x32_bf16 v[108:111], v[140:143], v[172:175], v[108:111]
	v_mfma_f32_16x16x32_bf16 v[88:91], v[132:135], v[180:183], v[88:91]
	v_mfma_f32_16x16x32_bf16 v[92:95], v[140:143], v[180:183], v[92:95]
	v_mfma_f32_16x16x32_bf16 v[72:75], v[132:135], v[188:191], v[72:75]
	v_mfma_f32_16x16x32_bf16 v[76:79], v[140:143], v[188:191], v[76:79]
	s_setprio 0
	s_setprio 1
	v_mfma_f32_16x16x32_bf16 v[112:115], v[144:147], v[160:163], v[112:115]
	v_mfma_f32_16x16x32_bf16 v[116:119], v[152:155], v[160:163], v[116:119]
	v_mfma_f32_16x16x32_bf16 v[96:99], v[144:147], v[168:171], v[96:99]
	v_mfma_f32_16x16x32_bf16 v[100:103], v[152:155], v[168:171], v[100:103]
	v_mfma_f32_16x16x32_bf16 v[80:83], v[144:147], v[176:179], v[80:83]
	v_mfma_f32_16x16x32_bf16 v[84:87], v[152:155], v[176:179], v[84:87]
	v_mfma_f32_16x16x32_bf16 v[64:67], v[144:147], v[184:187], v[64:67]
	v_mfma_f32_16x16x32_bf16 v[68:71], v[152:155], v[184:187], v[68:71]
	v_mfma_f32_16x16x32_bf16 v[112:115], v[148:151], v[164:167], v[112:115]
	v_mfma_f32_16x16x32_bf16 v[116:119], v[156:159], v[164:167], v[116:119]
	v_mfma_f32_16x16x32_bf16 v[96:99], v[148:151], v[172:175], v[96:99]
	v_mfma_f32_16x16x32_bf16 v[100:103], v[156:159], v[172:175], v[100:103]
	v_mfma_f32_16x16x32_bf16 v[80:83], v[148:151], v[180:183], v[80:83]
	v_mfma_f32_16x16x32_bf16 v[84:87], v[156:159], v[180:183], v[84:87]
	v_mfma_f32_16x16x32_bf16 v[64:67], v[148:151], v[188:191], v[64:67]
	v_mfma_f32_16x16x32_bf16 v[68:71], v[156:159], v[188:191], v[68:71]
	s_barrier
; #define PG8_STAGE(bufoff, gbase, voff) do { _Pragma("unroll") for (int _i = 0; _i < 2; ++_i) \
;         __builtin_amdgcn_global_load_lds((const unsigned*)((const char*)(gbase) + (voff)[_i]), (PG8_LAS unsigned*)(lds + (bufoff) + ldsw + _i * 8192), 16, 0, 0); } while (0)
; #define PG8_LDA(dst, b, h) do { _Pragma("unroll") for (int m = 0; m < 4; ++m) _Pragma("unroll") for (int k = 0; k < 2; ++k) dst[m][k] = *(const PG8_LAS bf16x8*)(lds + PG8_SA(b, h) + aoff + m * 2048 + k * 1024); } while (0)
; #define PG8_MMA(ai, bj, At, Bt) do { __builtin_amdgcn_s_setprio(1); _Pragma("unroll") for (int m = 0; m < 4; ++m) _Pragma("unroll") for (int n = 0; n < 2; ++n) _Pragma("unroll") for (int k = 0; k < 2; ++k) \
;         acc[ai][bj][m][n] = __builtin_amdgcn_mfma_f32_16x16x32_bf16(Bt[n][k], At[m][k], acc[ai][bj][m][n], 0, 0, 0); __builtin_amdgcn_s_setprio(0); } while (0)
; #define PG8_WAIT_V(n) asm volatile("s_waitcnt vmcnt(" #n ")" ::: "memory")
; #define PG8_WAIT_L(n) asm volatile("s_waitcnt lgkmcnt(" #n ")" ::: "memory")
; #define PG8_BAR __builtin_amdgcn_s_barrier()
; #define PG8_SCHED __builtin_amdgcn_sched_barrier(0)
; template <class Epi, class Sched, bool ALIGN_EPI = false, bool SP2 = false>
; __device__ __forceinline__ void gemm_phase(PG8_LAS unsigned char* lds, const Gemm g, const Sched& S, const Epi& E, const int tid) {
;     ...
;         for (int t = 0; t < nt; t += 2) {
;             const bool last = (t == nt - 2);
;             const char* a1 = cA + (size_t)(t + 1) * kstep;
;             const char* a2 = last ? nA : cA + (size_t)(t + 2) * kstep; const char* b2 = last ? nB : cB + (size_t)(t + 2) * kstep;
;     ...
;             PG8_LDA(At, 1, 1); PG8_STAGE(PG8_SB(1, 0), b3, voffB); PG8_STAGE(PG8_SB(1, 1), b3 + hstep, voffB); PG8_STAGE(PG8_SA(1, 0), a3, voffA);
;             PG8_WAIT_V(8); PG8_WAIT_L(0); PG8_BAR; PG8_MMA(1, 0, At, B0); PG8_MMA(1, 1, At, B1); PG8_BAR; PG8_SCHED;
	s_setprio 0
	s_add_i32 s34, s65, s38
	v_lshl_add_u64 v[202:203], v[202:203], 0, s[70:71]
	s_mov_b32 m0, s34
	ds_read_b128 v[160:163], v217 offset:49152
	ds_read_b128 v[164:167], v217 offset:50176
	ds_read_b128 v[168:171], v217 offset:51200
	ds_read_b128 v[172:175], v217 offset:52224
	ds_read_b128 v[176:179], v217 offset:53248
	ds_read_b128 v[180:183], v217 offset:54272
	ds_read_b128 v[184:187], v217 offset:55296
	ds_read_b128 v[188:191], v217 offset:56320
	global_load_lds_dwordx4 v[202:203], off
	s_add_i32 m0, s34, 0x2000
	s_add_u32 s28, s28, 0x200080
	v_lshl_add_u64 v[202:203], v[206:207], 0, s[70:71]
	s_addc_u32 s29, s29, 0
	s_add_i32 s34, s68, s38
	global_load_lds_dwordx4 v[202:203], off
	v_lshl_add_u64 v[202:203], s[28:29], 0, v[204:205]
	s_mov_b32 m0, s34
	s_nop 0
	global_load_lds_dwordx4 v[202:203], off
	v_lshl_add_u64 v[202:203], s[28:29], 0, v[196:197]
	s_add_i32 m0, s34, 0x2000
	s_nop 0
	global_load_lds_dwordx4 v[202:203], off
	v_lshl_add_u64 v[202:203], v[208:209], 0, s[70:71]
	s_mov_b32 m0, s49
	s_nop 0
	global_load_lds_dwordx4 v[202:203], off
	v_lshl_add_u64 v[202:203], v[210:211], 0, s[70:71]
	s_mov_b32 m0, s50
	s_nop 0
	global_load_lds_dwordx4 v[202:203], off
	s_add_i32 s64, s64, 2
	s_add_u32 s30, s30, 0x100
	s_addc_u32 s31, s31, 0
	s_add_u32 s55, s55, 0x100
	s_addc_u32 s62, s62, 0
	s_waitcnt vmcnt(8)
	s_waitcnt lgkmcnt(0)
	s_setprio 1
	s_barrier
	v_mfma_f32_16x16x32_bf16 v[52:55], v[128:131], v[160:163], v[52:55]
	v_mfma_f32_16x16x32_bf16 v[56:59], v[136:139], v[160:163], v[56:59]
	v_mfma_f32_16x16x32_bf16 v[24:27], v[128:131], v[168:171], v[24:27]
	v_mfma_f32_16x16x32_bf16 v[60:63], v[136:139], v[168:171], v[60:63]
	v_mfma_f32_16x16x32_bf16 v[28:31], v[128:131], v[176:179], v[28:31]
	v_mfma_f32_16x16x32_bf16 v[32:35], v[136:139], v[176:179], v[32:35]
	v_mfma_f32_16x16x32_bf16 v[8:11], v[128:131], v[184:187], v[8:11]
	v_mfma_f32_16x16x32_bf16 v[12:15], v[136:139], v[184:187], v[12:15]
	v_mfma_f32_16x16x32_bf16 v[52:55], v[132:135], v[164:167], v[52:55]
	v_mfma_f32_16x16x32_bf16 v[56:59], v[140:143], v[164:167], v[56:59]
	v_mfma_f32_16x16x32_bf16 v[24:27], v[132:135], v[172:175], v[24:27]
	v_mfma_f32_16x16x32_bf16 v[60:63], v[140:143], v[172:175], v[60:63]
	v_mfma_f32_16x16x32_bf16 v[28:31], v[132:135], v[180:183], v[28:31]
	v_mfma_f32_16x16x32_bf16 v[32:35], v[140:143], v[180:183], v[32:35]
	v_mfma_f32_16x16x32_bf16 v[8:11], v[132:135], v[188:191], v[8:11]
	v_mfma_f32_16x16x32_bf16 v[12:15], v[140:143], v[188:191], v[12:15]
	s_setprio 0
	s_setprio 1
	v_mfma_f32_16x16x32_bf16 v[36:39], v[144:147], v[160:163], v[36:39]
	v_mfma_f32_16x16x32_bf16 v[40:43], v[152:155], v[160:163], v[40:43]
	v_mfma_f32_16x16x32_bf16 v[44:47], v[144:147], v[168:171], v[44:47]
	v_mfma_f32_16x16x32_bf16 v[48:51], v[152:155], v[168:171], v[48:51]
	v_mfma_f32_16x16x32_bf16 v[16:19], v[144:147], v[176:179], v[16:19]
	v_mfma_f32_16x16x32_bf16 v[20:23], v[152:155], v[176:179], v[20:23]
	v_mfma_f32_16x16x32_bf16 v[0:3], v[144:147], v[184:187], v[0:3]
	v_mfma_f32_16x16x32_bf16 v[4:7], v[152:155], v[184:187], v[4:7]
	v_mfma_f32_16x16x32_bf16 v[36:39], v[148:151], v[164:167], v[36:39]
	v_mfma_f32_16x16x32_bf16 v[40:43], v[156:159], v[164:167], v[40:43]
	v_mfma_f32_16x16x32_bf16 v[44:47], v[148:151], v[172:175], v[44:47]
	v_mfma_f32_16x16x32_bf16 v[48:51], v[156:159], v[172:175], v[48:51]
	v_mfma_f32_16x16x32_bf16 v[16:19], v[148:151], v[180:183], v[16:19]
	v_mfma_f32_16x16x32_bf16 v[20:23], v[156:159], v[180:183], v[20:23]
	v_mfma_f32_16x16x32_bf16 v[0:3], v[148:151], v[188:191], v[0:3]
	v_mfma_f32_16x16x32_bf16 v[4:7], v[156:159], v[188:191], v[4:7]
	s_barrier
	s_setprio 0
	s_cmpk_gt_u32 s64, 0x7d
	s_cbranch_scc0 .LBB0_1198
	s_and_b64 vcc, exec, s[14:15]
	s_cbranch_vccz .LBB0_1201
	s_barrier

; #define PG8_STAGE(bufoff, gbase, voff) do { _Pragma("unroll") for (int _i = 0; _i < 2; ++_i) \
;         __builtin_amdgcn_global_load_lds((const unsigned*)((const char*)(gbase) + (voff)[_i]), (PG8_LAS unsigned*)(lds + (bufoff) + ldsw + _i * 8192), 16, 0, 0); } while (0)
; #define PG8_LDA(dst, b, h) do { _Pragma("unroll") for (int m = 0; m < 4; ++m) _Pragma("unroll") for (int k = 0; k < 2; ++k) dst[m][k] = *(const PG8_LAS bf16x8*)(lds + PG8_SA(b, h) + aoff + m * 2048 + k * 1024); } while (0)
; #define PG8_LDB(dst, b, h) do { _Pragma("unroll") for (int n = 0; n < 2; ++n) _Pragma("unroll") for (int k = 0; k < 2; ++k) dst[n][k] = *(const PG8_LAS bf16x8*)(lds + PG8_SB(b, h) + boff + n * 2048 + k * 1024); } while (0)
; #define PG8_WAIT_V(n) asm volatile("s_waitcnt vmcnt(" #n ")" ::: "memory")
; #define PG8_WAIT_L(n) asm volatile("s_waitcnt lgkmcnt(" #n ")" ::: "memory")
; #define PG8_BAR __builtin_amdgcn_s_barrier()
; #define PG8_SCHED __builtin_amdgcn_sched_barrier(0)
; template <class Epi, class Sched, bool ALIGN_EPI = false, bool SP2 = false>
; __device__ __forceinline__ void gemm_phase(PG8_LAS unsigned char* lds, const Gemm g, const Sched& S, const Epi& E, const int tid) {
;     ...
;         const bool has_next = S.next(ui + 1, nxt);
;         const char* nA = has_next ? (const char*)g.A + (size_t)nxt.pm * tstep : cA; const char* nB = has_next ? (const char*)g.Bt + (size_t)nxt.pn * tstep : cB;
;         for (int t = 0; t < nt; t += 2) {
;             const bool last = (t == nt - 2);
;             const char* a1 = cA + (size_t)(t + 1) * kstep;
;             const char* a2 = last ? nA : cA + (size_t)(t + 2) * kstep; const char* b2 = last ? nB : cB + (size_t)(t + 2) * kstep;
;             const char* a3 = a2 + kstep; const char* b3 = b2 + kstep;
;             if (last && has_next) S.a_ready(nxt);
;             if constexpr (SP2) {
;             PG8_LDB(B0, 0, 0); PG8_LDB(B1, 0, 1); PG8_SCHED; PG8_LDA(At, 0, 0); PG8_STAGE(PG8_SA(1, 1), a1 + hstep, voffA);
;             PG8_WAIT_V(8); PG8_WAIT_L(0); PG8_BAR; PG8_MMA(0, 0, At, B0); PG8_MMA(0, 1, At, B1); PG8_BAR; PG8_SCHED;
;             PG8_LDA(At, 0, 1); PG8_STAGE(PG8_SB(0, 0), b2, voffB); PG8_STAGE(PG8_SB(0, 1), b2 + hstep, voffB); PG8_STAGE(PG8_SA(0, 0), a2, voffA);
;             PG8_WAIT_V(8); PG8_WAIT_L(0); PG8_BAR; PG8_MMA(1, 0, At, B0); PG8_MMA(1, 1, At, B1); PG8_BAR; PG8_SCHED;
.LBB0_1383:
	s_ashr_i32 s27, s26, 31
	s_lshl_b64 s[28:29], s[26:27], 20
	s_add_u32 s28, s6, s28
	s_addc_u32 s29, s7, s29
	s_and_b64 s[30:31], s[4:5], exec
	s_cselect_b32 s27, s29, s43
	s_cselect_b32 s35, s28, s42
	s_ashr_i32 s25, s24, 31
	s_lshl_b64 s[30:31], s[24:25], 20
	s_add_u32 s30, s49, s30
	s_addc_u32 s31, s50, s31
	s_and_b64 s[46:47], s[4:5], exec
	s_cselect_b32 s25, s31, s45
	s_cselect_b32 s37, s30, s44
	s_add_u32 s42, s42, 0x80080
	s_addc_u32 s43, s43, 0
	s_add_u32 s40, s44, 0x100
	s_addc_u32 s69, s45, 0
	s_mov_b32 s75, -2
	s_waitcnt lgkmcnt(0)
	s_add_i32 s76, 0, 0x10000
	s_add_i32 s78, 0, 0x14000
	v_add_u32_e32 v68, s76, v175
	v_add_u32_e32 v156, s78, v175
	ds_read_b128 v[48:51], v68
	ds_read_b128 v[52:55], v68 offset:1024
	ds_read_b128 v[64:67], v68 offset:2048
	ds_read_b128 v[68:71], v68 offset:3072
	ds_read_b128 v[144:147], v156
	ds_read_b128 v[148:151], v156 offset:1024
	ds_read_b128 v[152:155], v156 offset:2048
	ds_read_b128 v[156:159], v156 offset:3072
	v_lshl_add_u64 v[176:177], s[42:43], 0, v[166:167]
	s_add_i32 m0, s52, 0xc000
	ds_read_b128 v[170:173], v179
	ds_read_b128 v[180:183], v179 offset:1024
	ds_read_b128 v[184:187], v179 offset:2048
	ds_read_b128 v[188:191], v179 offset:3072
	ds_read_b128 v[192:195], v179 offset:4096
	ds_read_b128 v[196:199], v179 offset:5120
	ds_read_b128 v[200:203], v179 offset:6144
	ds_read_b128 v[206:209], v179 offset:7168
	s_add_u32 s44, s42, 0xfff80080
	s_addc_u32 s45, s43, -1
	s_cmp_eq_u32 s75, 28
	s_cselect_b32 s47, s27, s45
	s_cselect_b32 s46, s35, s44
	s_cselect_b32 s45, s25, s69
	s_cselect_b32 s44, s37, s40
	global_load_lds_dwordx4 v[176:177], off
	v_lshl_add_u64 v[176:177], s[42:43], 0, v[168:169]
	s_add_i32 m0, s52, 0xe000
	s_nop 0
	global_load_lds_dwordx4 v[176:177], off
	s_waitcnt vmcnt(24)
	s_waitcnt lgkmcnt(0)
	s_setprio 1
	s_barrier
	v_mfma_f32_16x16x32_bf16 v[140:143], v[48:51], v[170:173], 0
	v_mfma_f32_16x16x32_bf16 v[136:139], v[64:67], v[170:173], 0
	v_mfma_f32_16x16x32_bf16 v[124:127], v[48:51], v[184:187], 0
	v_mfma_f32_16x16x32_bf16 v[120:123], v[64:67], v[184:187], 0
	v_mfma_f32_16x16x32_bf16 v[108:111], v[48:51], v[192:195], 0
	v_mfma_f32_16x16x32_bf16 v[104:107], v[64:67], v[192:195], 0
	v_mfma_f32_16x16x32_bf16 v[92:95], v[48:51], v[200:203], 0
	v_mfma_f32_16x16x32_bf16 v[88:91], v[64:67], v[200:203], 0
	v_mfma_f32_16x16x32_bf16 v[140:143], v[52:55], v[180:183], v[140:143]
	v_mfma_f32_16x16x32_bf16 v[136:139], v[68:71], v[180:183], v[136:139]
	v_mfma_f32_16x16x32_bf16 v[124:127], v[52:55], v[188:191], v[124:127]
	v_mfma_f32_16x16x32_bf16 v[120:123], v[68:71], v[188:191], v[120:123]
	v_mfma_f32_16x16x32_bf16 v[108:111], v[52:55], v[196:199], v[108:111]
	v_mfma_f32_16x16x32_bf16 v[104:107], v[68:71], v[196:199], v[104:107]
	v_mfma_f32_16x16x32_bf16 v[92:95], v[52:55], v[206:209], v[92:95]
	v_mfma_f32_16x16x32_bf16 v[88:91], v[68:71], v[206:209], v[88:91]
	s_setprio 0
	s_setprio 1
	v_mfma_f32_16x16x32_bf16 v[132:135], v[144:147], v[170:173], 0
	v_mfma_f32_16x16x32_bf16 v[128:131], v[152:155], v[170:173], 0
	v_mfma_f32_16x16x32_bf16 v[116:119], v[144:147], v[184:187], 0
	v_mfma_f32_16x16x32_bf16 v[112:115], v[152:155], v[184:187], 0
	v_mfma_f32_16x16x32_bf16 v[100:103], v[144:147], v[192:195], 0
	v_mfma_f32_16x16x32_bf16 v[96:99], v[152:155], v[192:195], 0
	v_mfma_f32_16x16x32_bf16 v[84:87], v[144:147], v[200:203], 0
	v_mfma_f32_16x16x32_bf16 v[80:83], v[152:155], v[200:203], 0
	v_mfma_f32_16x16x32_bf16 v[132:135], v[148:151], v[180:183], v[132:135]
	v_mfma_f32_16x16x32_bf16 v[128:131], v[156:159], v[180:183], v[128:131]
	v_mfma_f32_16x16x32_bf16 v[116:119], v[148:151], v[188:191], v[116:119]
	v_mfma_f32_16x16x32_bf16 v[112:115], v[156:159], v[188:191], v[112:115]
	v_mfma_f32_16x16x32_bf16 v[100:103], v[148:151], v[196:199], v[100:103]
	v_mfma_f32_16x16x32_bf16 v[96:99], v[156:159], v[196:199], v[96:99]
	v_mfma_f32_16x16x32_bf16 v[84:87], v[148:151], v[206:209], v[84:87]
	v_mfma_f32_16x16x32_bf16 v[80:83], v[156:159], v[206:209], v[80:83]
	s_barrier
	s_setprio 0
	s_add_i32 s76, s76, s51
	v_lshl_add_u64 v[176:177], s[44:45], 0, v[204:205]
	s_mov_b32 m0, s76
	ds_read_b128 v[170:173], v179 offset:16384
	ds_read_b128 v[180:183], v179 offset:17408
	ds_read_b128 v[184:187], v179 offset:18432
	ds_read_b128 v[188:191], v179 offset:19456
	ds_read_b128 v[192:195], v179 offset:20480
	ds_read_b128 v[196:199], v179 offset:21504
	ds_read_b128 v[200:203], v179 offset:22528
	ds_read_b128 v[206:209], v179 offset:23552
	global_load_lds_dwordx4 v[176:177], off
	s_add_i32 m0, s76, 0x2000
	s_add_u32 s76, s44, 0x80000
	v_lshl_add_u64 v[210:211], s[44:45], 0, v[164:165]
	s_addc_u32 s77, s45, 0
	s_add_i32 s78, s78, s51
	global_load_lds_dwordx4 v[210:211], off
	v_lshl_add_u64 v[212:213], s[76:77], 0, v[204:205]
	s_mov_b32 m0, s78
	v_lshl_add_u64 v[214:215], s[46:47], 0, v[162:163]
	global_load_lds_dwordx4 v[212:213], off
	v_lshl_add_u64 v[212:213], s[76:77], 0, v[164:165]
	s_add_i32 m0, s78, 0x2000
	s_nop 0
	global_load_lds_dwordx4 v[212:213], off
	v_lshl_add_u64 v[212:213], s[46:47], 0, v[160:161]
	s_mov_b32 m0, s52
	s_nop 0
	global_load_lds_dwordx4 v[212:213], off
	s_mov_b32 m0, s0
	s_nop 0
	global_load_lds_dwordx4 v[214:215], off
	s_waitcnt vmcnt(8)
	s_waitcnt lgkmcnt(0)
	s_setprio 1
	s_barrier
; #define PG8_STAGE(bufoff, gbase, voff) do { _Pragma("unroll") for (int _i = 0; _i < 2; ++_i) \
;         __builtin_amdgcn_global_load_lds((const unsigned*)((const char*)(gbase) + (voff)[_i]), (PG8_LAS unsigned*)(lds + (bufoff) + ldsw + _i * 8192), 16, 0, 0); } while (0)
; #define PG8_LDA(dst, b, h) do { _Pragma("unroll") for (int m = 0; m < 4; ++m) _Pragma("unroll") for (int k = 0; k < 2; ++k) dst[m][k] = *(const PG8_LAS bf16x8*)(lds + PG8_SA(b, h) + aoff + m * 2048 + k * 1024); } while (0)
; #define PG8_LDB(dst, b, h) do { _Pragma("unroll") for (int n = 0; n < 2; ++n) _Pragma("unroll") for (int k = 0; k < 2; ++k) dst[n][k] = *(const PG8_LAS bf16x8*)(lds + PG8_SB(b, h) + boff + n * 2048 + k * 1024); } while (0)
; #define PG8_MMA(ai, bj, At, Bt) do { __builtin_amdgcn_s_setprio(1); _Pragma("unroll") for (int m = 0; m < 4; ++m) _Pragma("unroll") for (int n = 0; n < 2; ++n) _Pragma("unroll") for (int k = 0; k < 2; ++k) \
;         acc[ai][bj][m][n] = __builtin_amdgcn_mfma_f32_16x16x32_bf16(Bt[n][k], At[m][k], acc[ai][bj][m][n], 0, 0, 0); __builtin_amdgcn_s_setprio(0); } while (0)
; #define PG8_WAIT_V(n) asm volatile("s_waitcnt vmcnt(" #n ")" ::: "memory")
; #define PG8_WAIT_L(n) asm volatile("s_waitcnt lgkmcnt(" #n ")" ::: "memory")
; #define PG8_BAR __builtin_amdgcn_s_barrier()
; #define PG8_SCHED __builtin_amdgcn_sched_barrier(0)
; template <class Epi, class Sched, bool ALIGN_EPI = false, bool SP2 = false>
; __device__ __forceinline__ void gemm_phase(PG8_LAS unsigned char* lds, const Gemm g, const Sched& S, const Epi& E, const int tid) {
;     ...
;             PG8_WAIT_V(8); PG8_WAIT_L(0); PG8_BAR; PG8_MMA(1, 0, At, B0); PG8_MMA(1, 1, At, B1); PG8_BAR; PG8_SCHED;
;             PG8_LDB(B0, 1, 0); PG8_LDB(B1, 1, 1); PG8_SCHED; PG8_LDA(At, 1, 0); PG8_STAGE(PG8_SA(0, 1), a2 + hstep, voffA);
;             PG8_WAIT_V(8); PG8_WAIT_L(0); PG8_BAR; PG8_MMA(0, 0, At, B0); PG8_MMA(0, 1, At, B1); PG8_BAR; PG8_SCHED;
	v_mfma_f32_16x16x32_bf16 v[76:79], v[48:51], v[170:173], 0
	v_mfma_f32_16x16x32_bf16 v[72:75], v[64:67], v[170:173], 0
	v_mfma_f32_16x16x32_bf16 v[44:47], v[48:51], v[184:187], 0
	v_mfma_f32_16x16x32_bf16 v[40:43], v[64:67], v[184:187], 0
	v_mfma_f32_16x16x32_bf16 v[28:31], v[48:51], v[192:195], 0
	v_mfma_f32_16x16x32_bf16 v[24:27], v[64:67], v[192:195], 0
	v_mfma_f32_16x16x32_bf16 v[12:15], v[48:51], v[200:203], 0
	v_mfma_f32_16x16x32_bf16 v[8:11], v[64:67], v[200:203], 0
	v_mfma_f32_16x16x32_bf16 v[76:79], v[52:55], v[180:183], v[76:79]
	v_mfma_f32_16x16x32_bf16 v[72:75], v[68:71], v[180:183], v[72:75]
	v_mfma_f32_16x16x32_bf16 v[44:47], v[52:55], v[188:191], v[44:47]
	v_mfma_f32_16x16x32_bf16 v[40:43], v[68:71], v[188:191], v[40:43]
	v_mfma_f32_16x16x32_bf16 v[28:31], v[52:55], v[196:199], v[28:31]
	v_mfma_f32_16x16x32_bf16 v[24:27], v[68:71], v[196:199], v[24:27]
	v_mfma_f32_16x16x32_bf16 v[12:15], v[52:55], v[206:209], v[12:15]
	v_mfma_f32_16x16x32_bf16 v[8:11], v[68:71], v[206:209], v[8:11]
	s_setprio 0
	s_setprio 1
	v_mfma_f32_16x16x32_bf16 v[36:39], v[144:147], v[184:187], 0
	v_mfma_f32_16x16x32_bf16 v[32:35], v[152:155], v[184:187], 0
	v_mfma_f32_16x16x32_bf16 v[20:23], v[144:147], v[192:195], 0
	v_mfma_f32_16x16x32_bf16 v[16:19], v[152:155], v[192:195], 0
	v_mfma_f32_16x16x32_bf16 v[4:7], v[144:147], v[200:203], 0
	v_mfma_f32_16x16x32_bf16 v[0:3], v[152:155], v[200:203], 0
	v_mfma_f32_16x16x32_bf16 v[48:51], v[144:147], v[170:173], 0
	v_mfma_f32_16x16x32_bf16 v[52:55], v[152:155], v[170:173], 0
	v_mfma_f32_16x16x32_bf16 v[36:39], v[148:151], v[188:191], v[36:39]
	v_mfma_f32_16x16x32_bf16 v[32:35], v[156:159], v[188:191], v[32:35]
	v_mfma_f32_16x16x32_bf16 v[20:23], v[148:151], v[196:199], v[20:23]
	v_mfma_f32_16x16x32_bf16 v[16:19], v[156:159], v[196:199], v[16:19]
	v_mfma_f32_16x16x32_bf16 v[4:7], v[148:151], v[206:209], v[4:7]
	v_mfma_f32_16x16x32_bf16 v[0:3], v[156:159], v[206:209], v[0:3]
	v_mfma_f32_16x16x32_bf16 v[48:51], v[148:151], v[180:183], v[48:51]
	v_mfma_f32_16x16x32_bf16 v[52:55], v[156:159], v[180:183], v[52:55]
	s_barrier
	s_setprio 0
	s_add_i32 s76, 0, 0x18000
	s_add_i32 s77, 0, 0x1c000
	v_add_u32_e32 v68, s76, v175
	v_add_u32_e32 v156, s77, v175
	ds_read_b128 v[56:59], v68
	ds_read_b128 v[60:63], v68 offset:1024
	ds_read_b128 v[64:67], v68 offset:2048
	ds_read_b128 v[68:71], v68 offset:3072
	ds_read_b128 v[144:147], v156
	ds_read_b128 v[148:151], v156 offset:1024
	ds_read_b128 v[152:155], v156 offset:2048
	ds_read_b128 v[156:159], v156 offset:3072
	s_add_u32 s46, s46, 0x80000
	s_addc_u32 s47, s47, 0
	s_mov_b32 m0, s33
	v_lshl_add_u64 v[216:217], s[46:47], 0, v[160:161]
	ds_read_b128 v[170:173], v179 offset:32768
	ds_read_b128 v[180:183], v179 offset:33792
	ds_read_b128 v[184:187], v179 offset:34816
	ds_read_b128 v[188:191], v179 offset:35840
	ds_read_b128 v[192:195], v179 offset:36864
	ds_read_b128 v[196:199], v179 offset:37888
	ds_read_b128 v[200:203], v179 offset:38912
	ds_read_b128 v[206:209], v179 offset:39936
	global_load_lds_dwordx4 v[216:217], off
	v_lshl_add_u64 v[216:217], s[46:47], 0, v[162:163]
	s_mov_b32 m0, s53
	s_nop 0
	global_load_lds_dwordx4 v[216:217], off
	s_waitcnt vmcnt(8)
	s_waitcnt lgkmcnt(0)
	s_setprio 1
	s_barrier
	v_mfma_f32_16x16x32_bf16 v[140:143], v[56:59], v[170:173], v[140:143]
	v_mfma_f32_16x16x32_bf16 v[136:139], v[64:67], v[170:173], v[136:139]
	v_mfma_f32_16x16x32_bf16 v[124:127], v[56:59], v[184:187], v[124:127]
	v_mfma_f32_16x16x32_bf16 v[120:123], v[64:67], v[184:187], v[120:123]
	v_mfma_f32_16x16x32_bf16 v[108:111], v[56:59], v[192:195], v[108:111]
	v_mfma_f32_16x16x32_bf16 v[104:107], v[64:67], v[192:195], v[104:107]
	v_mfma_f32_16x16x32_bf16 v[92:95], v[56:59], v[200:203], v[92:95]
	v_mfma_f32_16x16x32_bf16 v[88:91], v[64:67], v[200:203], v[88:91]
	v_mfma_f32_16x16x32_bf16 v[140:143], v[60:63], v[180:183], v[140:143]
	v_mfma_f32_16x16x32_bf16 v[136:139], v[68:71], v[180:183], v[136:139]
	v_mfma_f32_16x16x32_bf16 v[124:127], v[60:63], v[188:191], v[124:127]
	v_mfma_f32_16x16x32_bf16 v[120:123], v[68:71], v[188:191], v[120:123]
	v_mfma_f32_16x16x32_bf16 v[108:111], v[60:63], v[196:199], v[108:111]
	v_mfma_f32_16x16x32_bf16 v[104:107], v[68:71], v[196:199], v[104:107]
	v_mfma_f32_16x16x32_bf16 v[92:95], v[60:63], v[206:209], v[92:95]
	v_mfma_f32_16x16x32_bf16 v[88:91], v[68:71], v[206:209], v[88:91]
	s_setprio 0
	s_setprio 1
	v_mfma_f32_16x16x32_bf16 v[132:135], v[144:147], v[170:173], v[132:135]
	v_mfma_f32_16x16x32_bf16 v[128:131], v[152:155], v[170:173], v[128:131]
	v_mfma_f32_16x16x32_bf16 v[116:119], v[144:147], v[184:187], v[116:119]
	v_mfma_f32_16x16x32_bf16 v[112:115], v[152:155], v[184:187], v[112:115]
	v_mfma_f32_16x16x32_bf16 v[100:103], v[144:147], v[192:195], v[100:103]
	v_mfma_f32_16x16x32_bf16 v[96:99], v[152:155], v[192:195], v[96:99]
	v_mfma_f32_16x16x32_bf16 v[84:87], v[144:147], v[200:203], v[84:87]
	v_mfma_f32_16x16x32_bf16 v[80:83], v[152:155], v[200:203], v[80:83]
	v_mfma_f32_16x16x32_bf16 v[132:135], v[148:151], v[180:183], v[132:135]
	v_mfma_f32_16x16x32_bf16 v[128:131], v[156:159], v[180:183], v[128:131]
	v_mfma_f32_16x16x32_bf16 v[116:119], v[148:151], v[188:191], v[116:119]
	v_mfma_f32_16x16x32_bf16 v[112:115], v[156:159], v[188:191], v[112:115]
	v_mfma_f32_16x16x32_bf16 v[100:103], v[148:151], v[196:199], v[100:103]
	v_mfma_f32_16x16x32_bf16 v[96:99], v[156:159], v[196:199], v[96:99]
	v_mfma_f32_16x16x32_bf16 v[84:87], v[148:151], v[206:209], v[84:87]
	v_mfma_f32_16x16x32_bf16 v[80:83], v[156:159], v[206:209], v[80:83]
	s_barrier
; #define PG8_STAGE(bufoff, gbase, voff) do { _Pragma("unroll") for (int _i = 0; _i < 2; ++_i) \
;         __builtin_amdgcn_global_load_lds((const unsigned*)((const char*)(gbase) + (voff)[_i]), (PG8_LAS unsigned*)(lds + (bufoff) + ldsw + _i * 8192), 16, 0, 0); } while (0)
; #define PG8_LDA(dst, b, h) do { _Pragma("unroll") for (int m = 0; m < 4; ++m) _Pragma("unroll") for (int k = 0; k < 2; ++k) dst[m][k] = *(const PG8_LAS bf16x8*)(lds + PG8_SA(b, h) + aoff + m * 2048 + k * 1024); } while (0)
; #define PG8_WAIT_V(n) asm volatile("s_waitcnt vmcnt(" #n ")" ::: "memory")
; #define PG8_WAIT_L(n) asm volatile("s_waitcnt lgkmcnt(" #n ")" ::: "memory")
; #define PG8_BAR __builtin_amdgcn_s_barrier()
; template <class Epi, class Sched, bool ALIGN_EPI = false, bool SP2 = false>
; __device__ __forceinline__ void gemm_phase(PG8_LAS unsigned char* lds, const Gemm g, const Sched& S, const Epi& E, const int tid) {
;     ...
;         for (int t = 0; t < nt; t += 2) {
;             const bool last = (t == nt - 2);
;             const char* a1 = cA + (size_t)(t + 1) * kstep;
;             const char* a2 = last ? nA : cA + (size_t)(t + 2) * kstep; const char* b2 = last ? nB : cB + (size_t)(t + 2) * kstep;
;             const char* a3 = a2 + kstep; const char* b3 = b2 + kstep;
;             if (last && has_next) S.a_ready(nxt);
;             if constexpr (SP2) {
;             PG8_LDB(B0, 0, 0); PG8_LDB(B1, 0, 1); PG8_SCHED; PG8_LDA(At, 0, 0); PG8_STAGE(PG8_SA(1, 1), a1 + hstep, voffA);
;             PG8_WAIT_V(8); PG8_WAIT_L(0); PG8_BAR; PG8_MMA(0, 0, At, B0); PG8_MMA(0, 1, At, B1); PG8_BAR; PG8_SCHED;
;             PG8_LDA(At, 0, 1); PG8_STAGE(PG8_SB(0, 0), b2, voffB); PG8_STAGE(PG8_SB(0, 1), b2 + hstep, voffB); PG8_STAGE(PG8_SA(0, 0), a2, voffA);
;             PG8_WAIT_V(8); PG8_WAIT_L(0); PG8_BAR; PG8_MMA(1, 0, At, B0); PG8_MMA(1, 1, At, B1); PG8_BAR; PG8_SCHED;
;             PG8_LDB(B0, 1, 0); PG8_LDB(B1, 1, 1); PG8_SCHED; PG8_LDA(At, 1, 0); PG8_STAGE(PG8_SA(0, 1), a2 + hstep, voffA);
;             PG8_WAIT_V(8); PG8_WAIT_L(0); PG8_BAR; PG8_MMA(0, 0, At, B0); PG8_MMA(0, 1, At, B1); PG8_BAR; PG8_SCHED;
;             PG8_LDA(At, 1, 1); PG8_STAGE(PG8_SB(1, 0), b3, voffB); PG8_STAGE(PG8_SB(1, 1), b3 + hstep, voffB); PG8_STAGE(PG8_SA(1, 0), a3, voffA);
;             PG8_WAIT_V(8); PG8_WAIT_L(0); PG8_BAR; PG8_MMA(1, 0, At, B0); PG8_MMA(1, 1, At, B1); PG8_BAR; PG8_SCHED;
	s_setprio 0
	s_add_i32 s46, s76, s51
	v_lshl_add_u64 v[176:177], v[176:177], 0, s[70:71]
	s_mov_b32 m0, s46
	ds_read_b128 v[170:173], v179 offset:49152
	ds_read_b128 v[180:183], v179 offset:50176
	ds_read_b128 v[184:187], v179 offset:51200
	ds_read_b128 v[188:191], v179 offset:52224
	ds_read_b128 v[192:195], v179 offset:53248
	ds_read_b128 v[196:199], v179 offset:54272
	ds_read_b128 v[200:203], v179 offset:55296
	ds_read_b128 v[206:209], v179 offset:56320
	global_load_lds_dwordx4 v[176:177], off
	s_add_i32 m0, s46, 0x2000
	s_add_u32 s44, s44, 0x80080
	v_lshl_add_u64 v[176:177], v[210:211], 0, s[70:71]
	s_addc_u32 s45, s45, 0
	s_add_i32 s46, s77, s51
	global_load_lds_dwordx4 v[176:177], off
	v_lshl_add_u64 v[176:177], s[44:45], 0, v[204:205]
	s_mov_b32 m0, s46
	s_nop 0
	global_load_lds_dwordx4 v[176:177], off
	v_lshl_add_u64 v[176:177], s[44:45], 0, v[164:165]
	s_add_i32 m0, s46, 0x2000
	s_nop 0
	global_load_lds_dwordx4 v[176:177], off
	v_lshl_add_u64 v[176:177], v[212:213], 0, s[70:71]
	s_mov_b32 m0, s55
	s_nop 0
	global_load_lds_dwordx4 v[176:177], off
	v_lshl_add_u64 v[176:177], v[214:215], 0, s[70:71]
	s_mov_b32 m0, s62
	s_nop 0
	global_load_lds_dwordx4 v[176:177], off
	s_add_i32 s75, s75, 2
	s_add_u32 s42, s42, 0x100
	s_addc_u32 s43, s43, 0
	s_add_u32 s40, s40, 0x100
	s_addc_u32 s69, s69, 0
	s_waitcnt vmcnt(8)
	s_waitcnt lgkmcnt(0)
	s_setprio 1
	s_barrier
	v_mfma_f32_16x16x32_bf16 v[76:79], v[56:59], v[170:173], v[76:79]
	v_mfma_f32_16x16x32_bf16 v[72:75], v[64:67], v[170:173], v[72:75]
	v_mfma_f32_16x16x32_bf16 v[44:47], v[56:59], v[184:187], v[44:47]
	v_mfma_f32_16x16x32_bf16 v[40:43], v[64:67], v[184:187], v[40:43]
	v_mfma_f32_16x16x32_bf16 v[28:31], v[56:59], v[192:195], v[28:31]
	v_mfma_f32_16x16x32_bf16 v[24:27], v[64:67], v[192:195], v[24:27]
	v_mfma_f32_16x16x32_bf16 v[12:15], v[56:59], v[200:203], v[12:15]
	v_mfma_f32_16x16x32_bf16 v[8:11], v[64:67], v[200:203], v[8:11]
	v_mfma_f32_16x16x32_bf16 v[76:79], v[60:63], v[180:183], v[76:79]
	v_mfma_f32_16x16x32_bf16 v[72:75], v[68:71], v[180:183], v[72:75]
	v_mfma_f32_16x16x32_bf16 v[44:47], v[60:63], v[188:191], v[44:47]
	v_mfma_f32_16x16x32_bf16 v[40:43], v[68:71], v[188:191], v[40:43]
	v_mfma_f32_16x16x32_bf16 v[28:31], v[60:63], v[196:199], v[28:31]
	v_mfma_f32_16x16x32_bf16 v[24:27], v[68:71], v[196:199], v[24:27]
	v_mfma_f32_16x16x32_bf16 v[12:15], v[60:63], v[206:209], v[12:15]
	v_mfma_f32_16x16x32_bf16 v[8:11], v[68:71], v[206:209], v[8:11]
	s_setprio 0
	s_setprio 1
	v_mfma_f32_16x16x32_bf16 v[48:51], v[144:147], v[170:173], v[48:51]
	v_mfma_f32_16x16x32_bf16 v[60:63], v[148:151], v[180:183], v[48:51]
	v_mfma_f32_16x16x32_bf16 v[48:51], v[152:155], v[170:173], v[52:55]
	v_mfma_f32_16x16x32_bf16 v[36:39], v[144:147], v[184:187], v[36:39]
	v_mfma_f32_16x16x32_bf16 v[32:35], v[152:155], v[184:187], v[32:35]
	v_mfma_f32_16x16x32_bf16 v[20:23], v[144:147], v[192:195], v[20:23]
	v_mfma_f32_16x16x32_bf16 v[16:19], v[152:155], v[192:195], v[16:19]
	v_mfma_f32_16x16x32_bf16 v[4:7], v[144:147], v[200:203], v[4:7]
	v_mfma_f32_16x16x32_bf16 v[0:3], v[152:155], v[200:203], v[0:3]
	v_mfma_f32_16x16x32_bf16 v[56:59], v[156:159], v[180:183], v[48:51]
	v_mfma_f32_16x16x32_bf16 v[36:39], v[148:151], v[188:191], v[36:39]
	v_mfma_f32_16x16x32_bf16 v[32:35], v[156:159], v[188:191], v[32:35]
	v_mfma_f32_16x16x32_bf16 v[20:23], v[148:151], v[196:199], v[20:23]
	v_mfma_f32_16x16x32_bf16 v[16:19], v[156:159], v[196:199], v[16:19]
	v_mfma_f32_16x16x32_bf16 v[4:7], v[148:151], v[206:209], v[4:7]
	v_mfma_f32_16x16x32_bf16 v[0:3], v[156:159], v[206:209], v[0:3]
	s_barrier
	s_setprio 0
.LBB0_1384:
	s_add_i32 s76, 0, 0x10000
	s_add_i32 s78, 0, 0x14000
	v_add_u32_e32 v68, s76, v175
	v_add_u32_e32 v156, s78, v175
	ds_read_b128 v[48:51], v68
	ds_read_b128 v[52:55], v68 offset:1024
	ds_read_b128 v[64:67], v68 offset:2048
	ds_read_b128 v[68:71], v68 offset:3072
	ds_read_b128 v[144:147], v156
	ds_read_b128 v[148:151], v156 offset:1024
	ds_read_b128 v[152:155], v156 offset:2048
	ds_read_b128 v[156:159], v156 offset:3072
	v_lshl_add_u64 v[176:177], s[42:43], 0, v[166:167]
	s_add_i32 m0, s52, 0xc000
	ds_read_b128 v[170:173], v179
	ds_read_b128 v[180:183], v179 offset:1024
	ds_read_b128 v[184:187], v179 offset:2048
	ds_read_b128 v[188:191], v179 offset:3072
	ds_read_b128 v[192:195], v179 offset:4096
	ds_read_b128 v[196:199], v179 offset:5120
	ds_read_b128 v[200:203], v179 offset:6144
	ds_read_b128 v[206:209], v179 offset:7168
	s_add_u32 s44, s42, 0xfff80080
	s_addc_u32 s45, s43, -1
	s_cmp_eq_u32 s75, 28
	s_cselect_b32 s47, s27, s45
	s_cselect_b32 s46, s35, s44
	s_cselect_b32 s45, s25, s69
	s_cselect_b32 s44, s37, s40
	global_load_lds_dwordx4 v[176:177], off
	v_lshl_add_u64 v[176:177], s[42:43], 0, v[168:169]
	s_add_i32 m0, s52, 0xe000
	s_nop 0
	global_load_lds_dwordx4 v[176:177], off
	s_waitcnt vmcnt(8)
	s_waitcnt lgkmcnt(0)
	s_setprio 1
	s_barrier
; #define PG8_STAGE(bufoff, gbase, voff) do { _Pragma("unroll") for (int _i = 0; _i < 2; ++_i) \
;         __builtin_amdgcn_global_load_lds((const unsigned*)((const char*)(gbase) + (voff)[_i]), (PG8_LAS unsigned*)(lds + (bufoff) + ldsw + _i * 8192), 16, 0, 0); } while (0)
; #define PG8_LDA(dst, b, h) do { _Pragma("unroll") for (int m = 0; m < 4; ++m) _Pragma("unroll") for (int k = 0; k < 2; ++k) dst[m][k] = *(const PG8_LAS bf16x8*)(lds + PG8_SA(b, h) + aoff + m * 2048 + k * 1024); } while (0)
; #define PG8_MMA(ai, bj, At, Bt) do { __builtin_amdgcn_s_setprio(1); _Pragma("unroll") for (int m = 0; m < 4; ++m) _Pragma("unroll") for (int n = 0; n < 2; ++n) _Pragma("unroll") for (int k = 0; k < 2; ++k) \
;         acc[ai][bj][m][n] = __builtin_amdgcn_mfma_f32_16x16x32_bf16(Bt[n][k], At[m][k], acc[ai][bj][m][n], 0, 0, 0); __builtin_amdgcn_s_setprio(0); } while (0)
; #define PG8_WAIT_V(n) asm volatile("s_waitcnt vmcnt(" #n ")" ::: "memory")
; #define PG8_WAIT_L(n) asm volatile("s_waitcnt lgkmcnt(" #n ")" ::: "memory")
; #define PG8_BAR __builtin_amdgcn_s_barrier()
; #define PG8_SCHED __builtin_amdgcn_sched_barrier(0)
; template <class Epi, class Sched, bool ALIGN_EPI = false, bool SP2 = false>
; __device__ __forceinline__ void gemm_phase(PG8_LAS unsigned char* lds, const Gemm g, const Sched& S, const Epi& E, const int tid) {
;     ...
;             PG8_WAIT_V(8); PG8_WAIT_L(0); PG8_BAR; PG8_MMA(0, 0, At, B0); PG8_MMA(0, 1, At, B1); PG8_BAR; PG8_SCHED;
;             PG8_LDA(At, 0, 1); PG8_STAGE(PG8_SB(0, 0), b2, voffB); PG8_STAGE(PG8_SB(0, 1), b2 + hstep, voffB); PG8_STAGE(PG8_SA(0, 0), a2, voffA);
;             PG8_WAIT_V(8); PG8_WAIT_L(0); PG8_BAR; PG8_MMA(1, 0, At, B0); PG8_MMA(1, 1, At, B1); PG8_BAR; PG8_SCHED;
	v_mfma_f32_16x16x32_bf16 v[140:143], v[48:51], v[170:173], v[140:143]
	v_mfma_f32_16x16x32_bf16 v[136:139], v[64:67], v[170:173], v[136:139]
	v_mfma_f32_16x16x32_bf16 v[124:127], v[48:51], v[184:187], v[124:127]
	v_mfma_f32_16x16x32_bf16 v[120:123], v[64:67], v[184:187], v[120:123]
	v_mfma_f32_16x16x32_bf16 v[108:111], v[48:51], v[192:195], v[108:111]
	v_mfma_f32_16x16x32_bf16 v[104:107], v[64:67], v[192:195], v[104:107]
	v_mfma_f32_16x16x32_bf16 v[92:95], v[48:51], v[200:203], v[92:95]
	v_mfma_f32_16x16x32_bf16 v[88:91], v[64:67], v[200:203], v[88:91]
	v_mfma_f32_16x16x32_bf16 v[140:143], v[52:55], v[180:183], v[140:143]
	v_mfma_f32_16x16x32_bf16 v[136:139], v[68:71], v[180:183], v[136:139]
	v_mfma_f32_16x16x32_bf16 v[124:127], v[52:55], v[188:191], v[124:127]
	v_mfma_f32_16x16x32_bf16 v[120:123], v[68:71], v[188:191], v[120:123]
	v_mfma_f32_16x16x32_bf16 v[108:111], v[52:55], v[196:199], v[108:111]
	v_mfma_f32_16x16x32_bf16 v[104:107], v[68:71], v[196:199], v[104:107]
	v_mfma_f32_16x16x32_bf16 v[92:95], v[52:55], v[206:209], v[92:95]
	v_mfma_f32_16x16x32_bf16 v[88:91], v[68:71], v[206:209], v[88:91]
	s_setprio 0
	s_setprio 1
	v_mfma_f32_16x16x32_bf16 v[132:135], v[144:147], v[170:173], v[132:135]
	v_mfma_f32_16x16x32_bf16 v[128:131], v[152:155], v[170:173], v[128:131]
	v_mfma_f32_16x16x32_bf16 v[116:119], v[144:147], v[184:187], v[116:119]
	v_mfma_f32_16x16x32_bf16 v[112:115], v[152:155], v[184:187], v[112:115]
	v_mfma_f32_16x16x32_bf16 v[100:103], v[144:147], v[192:195], v[100:103]
	v_mfma_f32_16x16x32_bf16 v[96:99], v[152:155], v[192:195], v[96:99]
	v_mfma_f32_16x16x32_bf16 v[84:87], v[144:147], v[200:203], v[84:87]
	v_mfma_f32_16x16x32_bf16 v[80:83], v[152:155], v[200:203], v[80:83]
	v_mfma_f32_16x16x32_bf16 v[132:135], v[148:151], v[180:183], v[132:135]
	v_mfma_f32_16x16x32_bf16 v[128:131], v[156:159], v[180:183], v[128:131]
	v_mfma_f32_16x16x32_bf16 v[116:119], v[148:151], v[188:191], v[116:119]
	v_mfma_f32_16x16x32_bf16 v[112:115], v[156:159], v[188:191], v[112:115]
	v_mfma_f32_16x16x32_bf16 v[100:103], v[148:151], v[196:199], v[100:103]
	v_mfma_f32_16x16x32_bf16 v[96:99], v[156:159], v[196:199], v[96:99]
	v_mfma_f32_16x16x32_bf16 v[84:87], v[148:151], v[206:209], v[84:87]
	v_mfma_f32_16x16x32_bf16 v[80:83], v[156:159], v[206:209], v[80:83]
	s_barrier
	s_setprio 0
	s_add_i32 s76, s76, s51
	v_lshl_add_u64 v[176:177], s[44:45], 0, v[204:205]
	s_mov_b32 m0, s76
	ds_read_b128 v[170:173], v179 offset:16384
	ds_read_b128 v[180:183], v179 offset:17408
	ds_read_b128 v[184:187], v179 offset:18432
	ds_read_b128 v[188:191], v179 offset:19456
	ds_read_b128 v[192:195], v179 offset:20480
	ds_read_b128 v[196:199], v179 offset:21504
	ds_read_b128 v[200:203], v179 offset:22528
	ds_read_b128 v[206:209], v179 offset:23552
	global_load_lds_dwordx4 v[176:177], off
	s_add_i32 m0, s76, 0x2000
	s_add_u32 s76, s44, 0x80000
	v_lshl_add_u64 v[210:211], s[44:45], 0, v[164:165]
	s_addc_u32 s77, s45, 0
	s_add_i32 s78, s78, s51
	global_load_lds_dwordx4 v[210:211], off
	v_lshl_add_u64 v[212:213], s[76:77], 0, v[204:205]
	s_mov_b32 m0, s78
	v_lshl_add_u64 v[214:215], s[46:47], 0, v[162:163]
	global_load_lds_dwordx4 v[212:213], off
	v_lshl_add_u64 v[212:213], s[76:77], 0, v[164:165]
	s_add_i32 m0, s78, 0x2000
	s_nop 0
	global_load_lds_dwordx4 v[212:213], off
	v_lshl_add_u64 v[212:213], s[46:47], 0, v[160:161]
	s_mov_b32 m0, s52
	s_nop 0
	global_load_lds_dwordx4 v[212:213], off
	s_mov_b32 m0, s0
	s_nop 0
	global_load_lds_dwordx4 v[214:215], off
	s_waitcnt vmcnt(8)
	s_waitcnt lgkmcnt(0)
	s_setprio 1
	s_barrier
	v_mfma_f32_16x16x32_bf16 v[76:79], v[48:51], v[170:173], v[76:79]
	v_mfma_f32_16x16x32_bf16 v[72:75], v[64:67], v[170:173], v[72:75]
	v_mfma_f32_16x16x32_bf16 v[44:47], v[48:51], v[184:187], v[44:47]
	v_mfma_f32_16x16x32_bf16 v[40:43], v[64:67], v[184:187], v[40:43]
	v_mfma_f32_16x16x32_bf16 v[28:31], v[48:51], v[192:195], v[28:31]
	v_mfma_f32_16x16x32_bf16 v[24:27], v[64:67], v[192:195], v[24:27]
	v_mfma_f32_16x16x32_bf16 v[12:15], v[48:51], v[200:203], v[12:15]
	v_mfma_f32_16x16x32_bf16 v[8:11], v[64:67], v[200:203], v[8:11]
	v_mfma_f32_16x16x32_bf16 v[76:79], v[52:55], v[180:183], v[76:79]
	v_mfma_f32_16x16x32_bf16 v[72:75], v[68:71], v[180:183], v[72:75]
	v_mfma_f32_16x16x32_bf16 v[44:47], v[52:55], v[188:191], v[44:47]
	v_mfma_f32_16x16x32_bf16 v[40:43], v[68:71], v[188:191], v[40:43]
	v_mfma_f32_16x16x32_bf16 v[28:31], v[52:55], v[196:199], v[28:31]
	v_mfma_f32_16x16x32_bf16 v[24:27], v[68:71], v[196:199], v[24:27]
	v_mfma_f32_16x16x32_bf16 v[12:15], v[52:55], v[206:209], v[12:15]
	v_mfma_f32_16x16x32_bf16 v[8:11], v[68:71], v[206:209], v[8:11]
	s_setprio 0
	s_setprio 1
	v_mfma_f32_16x16x32_bf16 v[36:39], v[144:147], v[184:187], v[36:39]
	v_mfma_f32_16x16x32_bf16 v[32:35], v[152:155], v[184:187], v[32:35]
	v_mfma_f32_16x16x32_bf16 v[20:23], v[144:147], v[192:195], v[20:23]
	v_mfma_f32_16x16x32_bf16 v[16:19], v[152:155], v[192:195], v[16:19]
	v_mfma_f32_16x16x32_bf16 v[4:7], v[144:147], v[200:203], v[4:7]
	v_mfma_f32_16x16x32_bf16 v[0:3], v[152:155], v[200:203], v[0:3]
	v_mfma_f32_16x16x32_bf16 v[48:51], v[144:147], v[170:173], v[60:63]
	v_mfma_f32_16x16x32_bf16 v[52:55], v[152:155], v[170:173], v[56:59]
	v_mfma_f32_16x16x32_bf16 v[36:39], v[148:151], v[188:191], v[36:39]
	v_mfma_f32_16x16x32_bf16 v[32:35], v[156:159], v[188:191], v[32:35]
	v_mfma_f32_16x16x32_bf16 v[20:23], v[148:151], v[196:199], v[20:23]
	v_mfma_f32_16x16x32_bf16 v[16:19], v[156:159], v[196:199], v[16:19]
	v_mfma_f32_16x16x32_bf16 v[4:7], v[148:151], v[206:209], v[4:7]
	v_mfma_f32_16x16x32_bf16 v[0:3], v[156:159], v[206:209], v[0:3]
	v_mfma_f32_16x16x32_bf16 v[48:51], v[148:151], v[180:183], v[48:51]
	v_mfma_f32_16x16x32_bf16 v[52:55], v[156:159], v[180:183], v[52:55]
	s_barrier
; #define PG8_STAGE(bufoff, gbase, voff) do { _Pragma("unroll") for (int _i = 0; _i < 2; ++_i) \
;         __builtin_amdgcn_global_load_lds((const unsigned*)((const char*)(gbase) + (voff)[_i]), (PG8_LAS unsigned*)(lds + (bufoff) + ldsw + _i * 8192), 16, 0, 0); } while (0)
; #define PG8_LDA(dst, b, h) do { _Pragma("unroll") for (int m = 0; m < 4; ++m) _Pragma("unroll") for (int k = 0; k < 2; ++k) dst[m][k] = *(const PG8_LAS bf16x8*)(lds + PG8_SA(b, h) + aoff + m * 2048 + k * 1024); } while (0)
; #define PG8_LDB(dst, b, h) do { _Pragma("unroll") for (int n = 0; n < 2; ++n) _Pragma("unroll") for (int k = 0; k < 2; ++k) dst[n][k] = *(const PG8_LAS bf16x8*)(lds + PG8_SB(b, h) + boff + n * 2048 + k * 1024); } while (0)
; #define PG8_MMA(ai, bj, At, Bt) do { __builtin_amdgcn_s_setprio(1); _Pragma("unroll") for (int m = 0; m < 4; ++m) _Pragma("unroll") for (int n = 0; n < 2; ++n) _Pragma("unroll") for (int k = 0; k < 2; ++k) \
;         acc[ai][bj][m][n] = __builtin_amdgcn_mfma_f32_16x16x32_bf16(Bt[n][k], At[m][k], acc[ai][bj][m][n], 0, 0, 0); __builtin_amdgcn_s_setprio(0); } while (0)
; #define PG8_WAIT_V(n) asm volatile("s_waitcnt vmcnt(" #n ")" ::: "memory")
; #define PG8_WAIT_L(n) asm volatile("s_waitcnt lgkmcnt(" #n ")" ::: "memory")
; #define PG8_BAR __builtin_amdgcn_s_barrier()
; #define PG8_SCHED __builtin_amdgcn_sched_barrier(0)
; template <class Epi, class Sched, bool ALIGN_EPI = false, bool SP2 = false>
; __device__ __forceinline__ void gemm_phase(PG8_LAS unsigned char* lds, const Gemm g, const Sched& S, const Epi& E, const int tid) {
;     ...
;             PG8_LDB(B0, 1, 0); PG8_LDB(B1, 1, 1); PG8_SCHED; PG8_LDA(At, 1, 0); PG8_STAGE(PG8_SA(0, 1), a2 + hstep, voffA);
;             PG8_WAIT_V(8); PG8_WAIT_L(0); PG8_BAR; PG8_MMA(0, 0, At, B0); PG8_MMA(0, 1, At, B1); PG8_BAR; PG8_SCHED;
	s_setprio 0
	s_add_i32 s76, 0, 0x18000
	s_add_i32 s77, 0, 0x1c000
	v_add_u32_e32 v68, s76, v175
	v_add_u32_e32 v156, s77, v175
	ds_read_b128 v[56:59], v68
	ds_read_b128 v[60:63], v68 offset:1024
	ds_read_b128 v[64:67], v68 offset:2048
	ds_read_b128 v[68:71], v68 offset:3072
	ds_read_b128 v[144:147], v156
	ds_read_b128 v[148:151], v156 offset:1024
	ds_read_b128 v[152:155], v156 offset:2048
	ds_read_b128 v[156:159], v156 offset:3072
	s_add_u32 s46, s46, 0x80000
	s_addc_u32 s47, s47, 0
	s_mov_b32 m0, s33
	v_lshl_add_u64 v[216:217], s[46:47], 0, v[160:161]
	ds_read_b128 v[170:173], v179 offset:32768
	ds_read_b128 v[180:183], v179 offset:33792
	ds_read_b128 v[184:187], v179 offset:34816
	ds_read_b128 v[188:191], v179 offset:35840
	ds_read_b128 v[192:195], v179 offset:36864
	ds_read_b128 v[196:199], v179 offset:37888
	ds_read_b128 v[200:203], v179 offset:38912
	ds_read_b128 v[206:209], v179 offset:39936
	global_load_lds_dwordx4 v[216:217], off
	v_lshl_add_u64 v[216:217], s[46:47], 0, v[162:163]
	s_mov_b32 m0, s53
	s_nop 0
	global_load_lds_dwordx4 v[216:217], off
	s_waitcnt vmcnt(8)
	s_waitcnt lgkmcnt(0)
	s_setprio 1
	s_barrier
	v_mfma_f32_16x16x32_bf16 v[140:143], v[56:59], v[170:173], v[140:143]
	v_mfma_f32_16x16x32_bf16 v[136:139], v[64:67], v[170:173], v[136:139]
	v_mfma_f32_16x16x32_bf16 v[124:127], v[56:59], v[184:187], v[124:127]
	v_mfma_f32_16x16x32_bf16 v[120:123], v[64:67], v[184:187], v[120:123]
	v_mfma_f32_16x16x32_bf16 v[108:111], v[56:59], v[192:195], v[108:111]
	v_mfma_f32_16x16x32_bf16 v[104:107], v[64:67], v[192:195], v[104:107]
	v_mfma_f32_16x16x32_bf16 v[92:95], v[56:59], v[200:203], v[92:95]
	v_mfma_f32_16x16x32_bf16 v[88:91], v[64:67], v[200:203], v[88:91]
	v_mfma_f32_16x16x32_bf16 v[140:143], v[60:63], v[180:183], v[140:143]
	v_mfma_f32_16x16x32_bf16 v[136:139], v[68:71], v[180:183], v[136:139]
	v_mfma_f32_16x16x32_bf16 v[124:127], v[60:63], v[188:191], v[124:127]
	v_mfma_f32_16x16x32_bf16 v[120:123], v[68:71], v[188:191], v[120:123]
	v_mfma_f32_16x16x32_bf16 v[108:111], v[60:63], v[196:199], v[108:111]
	v_mfma_f32_16x16x32_bf16 v[104:107], v[68:71], v[196:199], v[104:107]
	v_mfma_f32_16x16x32_bf16 v[92:95], v[60:63], v[206:209], v[92:95]
	v_mfma_f32_16x16x32_bf16 v[88:91], v[68:71], v[206:209], v[88:91]
	s_setprio 0
	s_setprio 1
	v_mfma_f32_16x16x32_bf16 v[132:135], v[144:147], v[170:173], v[132:135]
	v_mfma_f32_16x16x32_bf16 v[128:131], v[152:155], v[170:173], v[128:131]
	v_mfma_f32_16x16x32_bf16 v[116:119], v[144:147], v[184:187], v[116:119]
	v_mfma_f32_16x16x32_bf16 v[112:115], v[152:155], v[184:187], v[112:115]
	v_mfma_f32_16x16x32_bf16 v[100:103], v[144:147], v[192:195], v[100:103]
	v_mfma_f32_16x16x32_bf16 v[96:99], v[152:155], v[192:195], v[96:99]
	v_mfma_f32_16x16x32_bf16 v[84:87], v[144:147], v[200:203], v[84:87]
	v_mfma_f32_16x16x32_bf16 v[80:83], v[152:155], v[200:203], v[80:83]
	v_mfma_f32_16x16x32_bf16 v[132:135], v[148:151], v[180:183], v[132:135]
	v_mfma_f32_16x16x32_bf16 v[128:131], v[156:159], v[180:183], v[128:131]
	v_mfma_f32_16x16x32_bf16 v[116:119], v[148:151], v[188:191], v[116:119]
	v_mfma_f32_16x16x32_bf16 v[112:115], v[156:159], v[188:191], v[112:115]
	v_mfma_f32_16x16x32_bf16 v[100:103], v[148:151], v[196:199], v[100:103]
	v_mfma_f32_16x16x32_bf16 v[96:99], v[156:159], v[196:199], v[96:99]
	v_mfma_f32_16x16x32_bf16 v[84:87], v[148:151], v[206:209], v[84:87]
	v_mfma_f32_16x16x32_bf16 v[80:83], v[156:159], v[206:209], v[80:83]
	s_barrier
; #define PG8_STAGE(bufoff, gbase, voff) do { _Pragma("unroll") for (int _i = 0; _i < 2; ++_i) \
;         __builtin_amdgcn_global_load_lds((const unsigned*)((const char*)(gbase) + (voff)[_i]), (PG8_LAS unsigned*)(lds + (bufoff) + ldsw + _i * 8192), 16, 0, 0); } while (0)
; #define PG8_LDA(dst, b, h) do { _Pragma("unroll") for (int m = 0; m < 4; ++m) _Pragma("unroll") for (int k = 0; k < 2; ++k) dst[m][k] = *(const PG8_LAS bf16x8*)(lds + PG8_SA(b, h) + aoff + m * 2048 + k * 1024); } while (0)
; #define PG8_MMA(ai, bj, At, Bt) do { __builtin_amdgcn_s_setprio(1); _Pragma("unroll") for (int m = 0; m < 4; ++m) _Pragma("unroll") for (int n = 0; n < 2; ++n) _Pragma("unroll") for (int k = 0; k < 2; ++k) \
;         acc[ai][bj][m][n] = __builtin_amdgcn_mfma_f32_16x16x32_bf16(Bt[n][k], At[m][k], acc[ai][bj][m][n], 0, 0, 0); __builtin_amdgcn_s_setprio(0); } while (0)
; #define PG8_WAIT_V(n) asm volatile("s_waitcnt vmcnt(" #n ")" ::: "memory")
; #define PG8_WAIT_L(n) asm volatile("s_waitcnt lgkmcnt(" #n ")" ::: "memory")
; #define PG8_BAR __builtin_amdgcn_s_barrier()
; #define PG8_SCHED __builtin_amdgcn_sched_barrier(0)
; template <class Epi, class Sched, bool ALIGN_EPI = false, bool SP2 = false>
; __device__ __forceinline__ void gemm_phase(PG8_LAS unsigned char* lds, const Gemm g, const Sched& S, const Epi& E, const int tid) {
;     ...
;             PG8_LDA(At, 1, 1); PG8_STAGE(PG8_SB(1, 0), b3, voffB); PG8_STAGE(PG8_SB(1, 1), b3 + hstep, voffB); PG8_STAGE(PG8_SA(1, 0), a3, voffA);
;             PG8_WAIT_V(8); PG8_WAIT_L(0); PG8_BAR; PG8_MMA(1, 0, At, B0); PG8_MMA(1, 1, At, B1); PG8_BAR; PG8_SCHED;
	s_setprio 0
	s_add_i32 s46, s76, s51
	v_lshl_add_u64 v[176:177], v[176:177], 0, s[70:71]
	s_mov_b32 m0, s46
	ds_read_b128 v[170:173], v179 offset:49152
	ds_read_b128 v[180:183], v179 offset:50176
	ds_read_b128 v[184:187], v179 offset:51200
	ds_read_b128 v[188:191], v179 offset:52224
	ds_read_b128 v[192:195], v179 offset:53248
	ds_read_b128 v[196:199], v179 offset:54272
	ds_read_b128 v[200:203], v179 offset:55296
	ds_read_b128 v[206:209], v179 offset:56320
	global_load_lds_dwordx4 v[176:177], off
	s_add_i32 m0, s46, 0x2000
	s_add_u32 s44, s44, 0x80080
	v_lshl_add_u64 v[176:177], v[210:211], 0, s[70:71]
	s_addc_u32 s45, s45, 0
	s_add_i32 s46, s77, s51
	global_load_lds_dwordx4 v[176:177], off
	v_lshl_add_u64 v[176:177], s[44:45], 0, v[204:205]
	s_mov_b32 m0, s46
	s_nop 0
	global_load_lds_dwordx4 v[176:177], off
	v_lshl_add_u64 v[176:177], s[44:45], 0, v[164:165]
	s_add_i32 m0, s46, 0x2000
	s_nop 0
	global_load_lds_dwordx4 v[176:177], off
	v_lshl_add_u64 v[176:177], v[212:213], 0, s[70:71]
	s_mov_b32 m0, s55
	s_nop 0
	global_load_lds_dwordx4 v[176:177], off
	v_lshl_add_u64 v[176:177], v[214:215], 0, s[70:71]
	s_mov_b32 m0, s62
	s_nop 0
	global_load_lds_dwordx4 v[176:177], off
	s_add_i32 s75, s75, 2
	s_add_u32 s42, s42, 0x100
	s_addc_u32 s43, s43, 0
	s_add_u32 s40, s40, 0x100
	s_addc_u32 s69, s69, 0
	s_waitcnt vmcnt(8)
	s_waitcnt lgkmcnt(0)
	s_setprio 1
	s_barrier
	v_mfma_f32_16x16x32_bf16 v[76:79], v[56:59], v[170:173], v[76:79]
	v_mfma_f32_16x16x32_bf16 v[72:75], v[64:67], v[170:173], v[72:75]
	v_mfma_f32_16x16x32_bf16 v[44:47], v[56:59], v[184:187], v[44:47]
	v_mfma_f32_16x16x32_bf16 v[40:43], v[64:67], v[184:187], v[40:43]
	v_mfma_f32_16x16x32_bf16 v[28:31], v[56:59], v[192:195], v[28:31]
	v_mfma_f32_16x16x32_bf16 v[24:27], v[64:67], v[192:195], v[24:27]
	v_mfma_f32_16x16x32_bf16 v[12:15], v[56:59], v[200:203], v[12:15]
	v_mfma_f32_16x16x32_bf16 v[8:11], v[64:67], v[200:203], v[8:11]
	v_mfma_f32_16x16x32_bf16 v[76:79], v[60:63], v[180:183], v[76:79]
	v_mfma_f32_16x16x32_bf16 v[72:75], v[68:71], v[180:183], v[72:75]
	v_mfma_f32_16x16x32_bf16 v[44:47], v[60:63], v[188:191], v[44:47]
	v_mfma_f32_16x16x32_bf16 v[40:43], v[68:71], v[188:191], v[40:43]
	v_mfma_f32_16x16x32_bf16 v[28:31], v[60:63], v[196:199], v[28:31]
	v_mfma_f32_16x16x32_bf16 v[24:27], v[68:71], v[196:199], v[24:27]
	v_mfma_f32_16x16x32_bf16 v[12:15], v[60:63], v[206:209], v[12:15]
	v_mfma_f32_16x16x32_bf16 v[8:11], v[68:71], v[206:209], v[8:11]
	s_setprio 0
	s_setprio 1
	v_mfma_f32_16x16x32_bf16 v[48:51], v[144:147], v[170:173], v[48:51]
	v_mfma_f32_16x16x32_bf16 v[60:63], v[148:151], v[180:183], v[48:51]
	v_mfma_f32_16x16x32_bf16 v[48:51], v[152:155], v[170:173], v[52:55]
	v_mfma_f32_16x16x32_bf16 v[36:39], v[144:147], v[184:187], v[36:39]
	v_mfma_f32_16x16x32_bf16 v[32:35], v[152:155], v[184:187], v[32:35]
	v_mfma_f32_16x16x32_bf16 v[20:23], v[144:147], v[192:195], v[20:23]
	v_mfma_f32_16x16x32_bf16 v[16:19], v[152:155], v[192:195], v[16:19]
	v_mfma_f32_16x16x32_bf16 v[4:7], v[144:147], v[200:203], v[4:7]
	v_mfma_f32_16x16x32_bf16 v[0:3], v[152:155], v[200:203], v[0:3]
	v_mfma_f32_16x16x32_bf16 v[56:59], v[156:159], v[180:183], v[48:51]
	v_mfma_f32_16x16x32_bf16 v[36:39], v[148:151], v[188:191], v[36:39]
	v_mfma_f32_16x16x32_bf16 v[32:35], v[156:159], v[188:191], v[32:35]
	v_mfma_f32_16x16x32_bf16 v[20:23], v[148:151], v[196:199], v[20:23]
	v_mfma_f32_16x16x32_bf16 v[16:19], v[156:159], v[196:199], v[16:19]
	v_mfma_f32_16x16x32_bf16 v[4:7], v[148:151], v[206:209], v[4:7]
	v_mfma_f32_16x16x32_bf16 v[0:3], v[156:159], v[206:209], v[0:3]
	s_barrier
	s_setprio 0
	s_cmp_gt_u32 s75, 29
	s_cbranch_scc0 .LBB0_1384
	s_and_b64 vcc, exec, s[22:23]
	s_cbranch_vccz .LBB0_1387
	s_barrier

; #define PG8_STAGE(bufoff, gbase, voff) do { _Pragma("unroll") for (int _i = 0; _i < 2; ++_i) \
;         __builtin_amdgcn_global_load_lds((const unsigned*)((const char*)(gbase) + (voff)[_i]), (PG8_LAS unsigned*)(lds + (bufoff) + ldsw + _i * 8192), 16, 0, 0); } while (0)
; #define PG8_LDA(dst, b, h) do { _Pragma("unroll") for (int m = 0; m < 4; ++m) _Pragma("unroll") for (int k = 0; k < 2; ++k) dst[m][k] = *(const PG8_LAS bf16x8*)(lds + PG8_SA(b, h) + aoff + m * 2048 + k * 1024); } while (0)
; #define PG8_LDB(dst, b, h) do { _Pragma("unroll") for (int n = 0; n < 2; ++n) _Pragma("unroll") for (int k = 0; k < 2; ++k) dst[n][k] = *(const PG8_LAS bf16x8*)(lds + PG8_SB(b, h) + boff + n * 2048 + k * 1024); } while (0)
; #define PG8_WAIT_V(n) asm volatile("s_waitcnt vmcnt(" #n ")" ::: "memory")
; #define PG8_WAIT_L(n) asm volatile("s_waitcnt lgkmcnt(" #n ")" ::: "memory")
; #define PG8_BAR __builtin_amdgcn_s_barrier()
; #define PG8_SCHED __builtin_amdgcn_sched_barrier(0)
; template <class Epi, class Sched, bool ALIGN_EPI = false, bool SP2 = false>
; __device__ __forceinline__ void gemm_phase(PG8_LAS unsigned char* lds, const Gemm g, const Sched& S, const Epi& E, const int tid) {
;     ...
;         const bool has_next = S.next(ui + 1, nxt);
;         const char* nA = has_next ? (const char*)g.A + (size_t)nxt.pm * tstep : cA; const char* nB = has_next ? (const char*)g.Bt + (size_t)nxt.pn * tstep : cB;
;         for (int t = 0; t < nt; t += 2) {
;             const bool last = (t == nt - 2);
;             const char* a1 = cA + (size_t)(t + 1) * kstep;
;             const char* a2 = last ? nA : cA + (size_t)(t + 2) * kstep; const char* b2 = last ? nB : cB + (size_t)(t + 2) * kstep;
;             const char* a3 = a2 + kstep; const char* b3 = b2 + kstep;
;             if (last && has_next) S.a_ready(nxt);
;             if constexpr (SP2) {
;             PG8_LDB(B0, 0, 0); PG8_LDB(B1, 0, 1); PG8_SCHED; PG8_LDA(At, 0, 0); PG8_STAGE(PG8_SA(1, 1), a1 + hstep, voffA);
;             PG8_WAIT_V(8); PG8_WAIT_L(0); PG8_BAR; PG8_MMA(0, 0, At, B0); PG8_MMA(0, 1, At, B1); PG8_BAR; PG8_SCHED;
;             PG8_LDA(At, 0, 1); PG8_STAGE(PG8_SB(0, 0), b2, voffB); PG8_STAGE(PG8_SB(0, 1), b2 + hstep, voffB); PG8_STAGE(PG8_SA(0, 0), a2, voffA);
;             PG8_WAIT_V(8); PG8_WAIT_L(0); PG8_BAR; PG8_MMA(1, 0, At, B0); PG8_MMA(1, 1, At, B1); PG8_BAR; PG8_SCHED;
.LBB0_1425:
	s_ashr_i32 s27, s26, 31
	s_lshl_b64 s[28:29], s[26:27], 20
	s_add_u32 s28, s6, s28
	s_addc_u32 s29, s7, s29
	s_and_b64 s[30:31], s[4:5], exec
	s_cselect_b32 s27, s29, s37
	s_cselect_b32 s62, s28, s36
	s_ashr_i32 s25, s24, 31
	s_lshl_b64 s[30:31], s[24:25], 20
	s_add_u32 s30, s11, s30
	s_addc_u32 s31, s33, s31
	s_and_b64 s[44:45], s[4:5], exec
	s_cselect_b32 s25, s31, s43
	s_cselect_b32 s64, s30, s42
	s_add_u32 s36, s36, 0x80080
	s_addc_u32 s37, s37, 0
	s_add_u32 s65, s42, 0x100
	s_addc_u32 s68, s43, 0
	s_mov_b32 s69, -2
	s_add_i32 s75, 0, 0x10000
	s_add_i32 s78, 0, 0x14000
	v_add_u32_e32 v84, s75, v167
	v_add_u32_e32 v166, s78, v167
	ds_read_b128 v[64:67], v84
	ds_read_b128 v[68:71], v84 offset:1024
	ds_read_b128 v[80:83], v84 offset:2048
	ds_read_b128 v[84:87], v84 offset:3072
	ds_read_b128 v[144:147], v166
	ds_read_b128 v[148:151], v166 offset:1024
	ds_read_b128 v[152:155], v166 offset:2048
	ds_read_b128 v[170:173], v166 offset:3072
	v_lshl_add_u64 v[202:203], s[36:37], 0, v[162:163]
	s_add_i32 m0, s35, 0xc000
	ds_read_b128 v[174:177], v169
	ds_read_b128 v[178:181], v169 offset:1024
	ds_read_b128 v[182:185], v169 offset:2048
	ds_read_b128 v[186:189], v169 offset:3072
	ds_read_b128 v[190:193], v169 offset:4096
	ds_read_b128 v[194:197], v169 offset:5120
	ds_read_b128 v[198:201], v169 offset:6144
	ds_read_b128 v[206:209], v169 offset:7168
	s_add_u32 s42, s36, 0xfff80080
	s_addc_u32 s43, s37, -1
	s_cmp_eq_u32 s69, 28
	s_cselect_b32 s45, s27, s43
	s_cselect_b32 s44, s62, s42
	s_cselect_b32 s43, s25, s68
	s_cselect_b32 s42, s64, s65
	global_load_lds_dwordx4 v[202:203], off
	v_lshl_add_u64 v[202:203], s[36:37], 0, v[164:165]
	s_add_i32 m0, s35, 0xe000
	s_nop 0
	global_load_lds_dwordx4 v[202:203], off
	s_waitcnt vmcnt(24)
	s_waitcnt lgkmcnt(0)
	s_setprio 1
	s_barrier
	v_mfma_f32_16x16x32_bf16 v[140:143], v[64:67], v[174:177], 0
	v_mfma_f32_16x16x32_bf16 v[136:139], v[80:83], v[174:177], 0
	v_mfma_f32_16x16x32_bf16 v[124:127], v[64:67], v[182:185], 0
	v_mfma_f32_16x16x32_bf16 v[120:123], v[80:83], v[182:185], 0
	v_mfma_f32_16x16x32_bf16 v[108:111], v[64:67], v[190:193], 0
	v_mfma_f32_16x16x32_bf16 v[104:107], v[80:83], v[190:193], 0
	v_mfma_f32_16x16x32_bf16 v[92:95], v[64:67], v[198:201], 0
	v_mfma_f32_16x16x32_bf16 v[88:91], v[80:83], v[198:201], 0
	v_mfma_f32_16x16x32_bf16 v[140:143], v[68:71], v[178:181], v[140:143]
	v_mfma_f32_16x16x32_bf16 v[136:139], v[84:87], v[178:181], v[136:139]
	v_mfma_f32_16x16x32_bf16 v[124:127], v[68:71], v[186:189], v[124:127]
	v_mfma_f32_16x16x32_bf16 v[120:123], v[84:87], v[186:189], v[120:123]
	v_mfma_f32_16x16x32_bf16 v[108:111], v[68:71], v[194:197], v[108:111]
	v_mfma_f32_16x16x32_bf16 v[104:107], v[84:87], v[194:197], v[104:107]
	v_mfma_f32_16x16x32_bf16 v[92:95], v[68:71], v[206:209], v[92:95]
	v_mfma_f32_16x16x32_bf16 v[88:91], v[84:87], v[206:209], v[88:91]
	s_setprio 0
	s_setprio 1
	v_mfma_f32_16x16x32_bf16 v[132:135], v[144:147], v[174:177], 0
	v_mfma_f32_16x16x32_bf16 v[128:131], v[152:155], v[174:177], 0
	v_mfma_f32_16x16x32_bf16 v[116:119], v[144:147], v[182:185], 0
	v_mfma_f32_16x16x32_bf16 v[112:115], v[152:155], v[182:185], 0
	v_mfma_f32_16x16x32_bf16 v[100:103], v[144:147], v[190:193], 0
	v_mfma_f32_16x16x32_bf16 v[96:99], v[152:155], v[190:193], 0
	v_mfma_f32_16x16x32_bf16 v[76:79], v[144:147], v[198:201], 0
	v_mfma_f32_16x16x32_bf16 v[72:75], v[152:155], v[198:201], 0
	v_mfma_f32_16x16x32_bf16 v[132:135], v[148:151], v[178:181], v[132:135]
	v_mfma_f32_16x16x32_bf16 v[128:131], v[170:173], v[178:181], v[128:131]
	v_mfma_f32_16x16x32_bf16 v[116:119], v[148:151], v[186:189], v[116:119]
	v_mfma_f32_16x16x32_bf16 v[112:115], v[170:173], v[186:189], v[112:115]
	v_mfma_f32_16x16x32_bf16 v[100:103], v[148:151], v[194:197], v[100:103]
	v_mfma_f32_16x16x32_bf16 v[96:99], v[170:173], v[194:197], v[96:99]
	v_mfma_f32_16x16x32_bf16 v[76:79], v[148:151], v[206:209], v[76:79]
	v_mfma_f32_16x16x32_bf16 v[72:75], v[170:173], v[206:209], v[72:75]
	s_barrier
	s_setprio 0
	s_add_i32 s75, s75, s38
	v_lshl_add_u64 v[202:203], s[42:43], 0, v[204:205]
	s_mov_b32 m0, s75
	ds_read_b128 v[174:177], v169 offset:16384
	ds_read_b128 v[178:181], v169 offset:17408
	ds_read_b128 v[182:185], v169 offset:18432
	ds_read_b128 v[186:189], v169 offset:19456
	ds_read_b128 v[190:193], v169 offset:20480
	ds_read_b128 v[194:197], v169 offset:21504
	ds_read_b128 v[198:201], v169 offset:22528
	ds_read_b128 v[206:209], v169 offset:23552
	global_load_lds_dwordx4 v[202:203], off
	s_add_i32 m0, s75, 0x2000
	s_add_u32 s76, s42, 0x80000
	v_lshl_add_u64 v[210:211], s[42:43], 0, v[160:161]
	s_addc_u32 s77, s43, 0
	s_add_i32 s75, s78, s38
	global_load_lds_dwordx4 v[210:211], off
	v_lshl_add_u64 v[212:213], s[76:77], 0, v[204:205]
	s_mov_b32 m0, s75
	v_lshl_add_u64 v[214:215], s[44:45], 0, v[158:159]
	global_load_lds_dwordx4 v[212:213], off
	v_lshl_add_u64 v[212:213], s[76:77], 0, v[160:161]
	s_add_i32 m0, s75, 0x2000
	s_nop 0
	global_load_lds_dwordx4 v[212:213], off
	v_lshl_add_u64 v[212:213], s[44:45], 0, v[156:157]
	s_mov_b32 m0, s35
	s_nop 0
	global_load_lds_dwordx4 v[212:213], off
	s_mov_b32 m0, s40
	s_nop 0
	global_load_lds_dwordx4 v[214:215], off
	s_waitcnt vmcnt(8)
	s_waitcnt lgkmcnt(0)
	s_setprio 1
	s_barrier
; #define PG8_STAGE(bufoff, gbase, voff) do { _Pragma("unroll") for (int _i = 0; _i < 2; ++_i) \
;         __builtin_amdgcn_global_load_lds((const unsigned*)((const char*)(gbase) + (voff)[_i]), (PG8_LAS unsigned*)(lds + (bufoff) + ldsw + _i * 8192), 16, 0, 0); } while (0)
; #define PG8_LDA(dst, b, h) do { _Pragma("unroll") for (int m = 0; m < 4; ++m) _Pragma("unroll") for (int k = 0; k < 2; ++k) dst[m][k] = *(const PG8_LAS bf16x8*)(lds + PG8_SA(b, h) + aoff + m * 2048 + k * 1024); } while (0)
; #define PG8_LDB(dst, b, h) do { _Pragma("unroll") for (int n = 0; n < 2; ++n) _Pragma("unroll") for (int k = 0; k < 2; ++k) dst[n][k] = *(const PG8_LAS bf16x8*)(lds + PG8_SB(b, h) + boff + n * 2048 + k * 1024); } while (0)
; #define PG8_MMA(ai, bj, At, Bt) do { __builtin_amdgcn_s_setprio(1); _Pragma("unroll") for (int m = 0; m < 4; ++m) _Pragma("unroll") for (int n = 0; n < 2; ++n) _Pragma("unroll") for (int k = 0; k < 2; ++k) \
;         acc[ai][bj][m][n] = __builtin_amdgcn_mfma_f32_16x16x32_bf16(Bt[n][k], At[m][k], acc[ai][bj][m][n], 0, 0, 0); __builtin_amdgcn_s_setprio(0); } while (0)
; #define PG8_WAIT_V(n) asm volatile("s_waitcnt vmcnt(" #n ")" ::: "memory")
; #define PG8_WAIT_L(n) asm volatile("s_waitcnt lgkmcnt(" #n ")" ::: "memory")
; #define PG8_BAR __builtin_amdgcn_s_barrier()
; #define PG8_SCHED __builtin_amdgcn_sched_barrier(0)
; template <class Epi, class Sched, bool ALIGN_EPI = false, bool SP2 = false>
; __device__ __forceinline__ void gemm_phase(PG8_LAS unsigned char* lds, const Gemm g, const Sched& S, const Epi& E, const int tid) {
;     ...
;             PG8_WAIT_V(8); PG8_WAIT_L(0); PG8_BAR; PG8_MMA(1, 0, At, B0); PG8_MMA(1, 1, At, B1); PG8_BAR; PG8_SCHED;
;             PG8_LDB(B0, 1, 0); PG8_LDB(B1, 1, 1); PG8_SCHED; PG8_LDA(At, 1, 0); PG8_STAGE(PG8_SA(0, 1), a2 + hstep, voffA);
;             PG8_WAIT_V(8); PG8_WAIT_L(0); PG8_BAR; PG8_MMA(0, 0, At, B0); PG8_MMA(0, 1, At, B1); PG8_BAR; PG8_SCHED;
	v_mfma_f32_16x16x32_bf16 v[60:63], v[64:67], v[174:177], 0
	v_mfma_f32_16x16x32_bf16 v[56:59], v[80:83], v[174:177], 0
	v_mfma_f32_16x16x32_bf16 v[44:47], v[64:67], v[182:185], 0
	v_mfma_f32_16x16x32_bf16 v[40:43], v[80:83], v[182:185], 0
	v_mfma_f32_16x16x32_bf16 v[28:31], v[64:67], v[190:193], 0
	v_mfma_f32_16x16x32_bf16 v[24:27], v[80:83], v[190:193], 0
	v_mfma_f32_16x16x32_bf16 v[12:15], v[64:67], v[198:201], 0
	v_mfma_f32_16x16x32_bf16 v[8:11], v[80:83], v[198:201], 0
	v_mfma_f32_16x16x32_bf16 v[60:63], v[68:71], v[178:181], v[60:63]
	v_mfma_f32_16x16x32_bf16 v[56:59], v[84:87], v[178:181], v[56:59]
	v_mfma_f32_16x16x32_bf16 v[44:47], v[68:71], v[186:189], v[44:47]
	v_mfma_f32_16x16x32_bf16 v[40:43], v[84:87], v[186:189], v[40:43]
	v_mfma_f32_16x16x32_bf16 v[28:31], v[68:71], v[194:197], v[28:31]
	v_mfma_f32_16x16x32_bf16 v[24:27], v[84:87], v[194:197], v[24:27]
	v_mfma_f32_16x16x32_bf16 v[12:15], v[68:71], v[206:209], v[12:15]
	v_mfma_f32_16x16x32_bf16 v[8:11], v[84:87], v[206:209], v[8:11]
	s_setprio 0
	s_setprio 1
	v_mfma_f32_16x16x32_bf16 v[52:55], v[144:147], v[174:177], 0
	v_mfma_f32_16x16x32_bf16 v[48:51], v[152:155], v[174:177], 0
	v_mfma_f32_16x16x32_bf16 v[36:39], v[144:147], v[182:185], 0
	v_mfma_f32_16x16x32_bf16 v[32:35], v[152:155], v[182:185], 0
	v_mfma_f32_16x16x32_bf16 v[20:23], v[144:147], v[190:193], 0
	v_mfma_f32_16x16x32_bf16 v[16:19], v[152:155], v[190:193], 0
	v_mfma_f32_16x16x32_bf16 v[4:7], v[144:147], v[198:201], 0
	v_mfma_f32_16x16x32_bf16 v[0:3], v[152:155], v[198:201], 0
	v_mfma_f32_16x16x32_bf16 v[52:55], v[148:151], v[178:181], v[52:55]
	v_mfma_f32_16x16x32_bf16 v[48:51], v[170:173], v[178:181], v[48:51]
	v_mfma_f32_16x16x32_bf16 v[36:39], v[148:151], v[186:189], v[36:39]
	v_mfma_f32_16x16x32_bf16 v[32:35], v[170:173], v[186:189], v[32:35]
	v_mfma_f32_16x16x32_bf16 v[20:23], v[148:151], v[194:197], v[20:23]
	v_mfma_f32_16x16x32_bf16 v[16:19], v[170:173], v[194:197], v[16:19]
	v_mfma_f32_16x16x32_bf16 v[4:7], v[148:151], v[206:209], v[4:7]
	v_mfma_f32_16x16x32_bf16 v[0:3], v[170:173], v[206:209], v[0:3]
	s_barrier
	s_setprio 0
	s_add_i32 s75, 0, 0x18000
	s_add_i32 s76, 0, 0x1c000
	v_add_u32_e32 v84, s75, v167
	v_add_u32_e32 v166, s76, v167
	ds_read_b128 v[64:67], v84
	ds_read_b128 v[68:71], v84 offset:1024
	ds_read_b128 v[80:83], v84 offset:2048
	ds_read_b128 v[84:87], v84 offset:3072
	ds_read_b128 v[144:147], v166
	ds_read_b128 v[148:151], v166 offset:1024
	ds_read_b128 v[152:155], v166 offset:2048
	ds_read_b128 v[170:173], v166 offset:3072
	s_add_u32 s44, s44, 0x80000
	s_addc_u32 s45, s45, 0
	s_mov_b32 m0, s46
	v_lshl_add_u64 v[216:217], s[44:45], 0, v[156:157]
	ds_read_b128 v[174:177], v169 offset:32768
	ds_read_b128 v[178:181], v169 offset:33792
	ds_read_b128 v[182:185], v169 offset:34816
	ds_read_b128 v[186:189], v169 offset:35840
	ds_read_b128 v[190:193], v169 offset:36864
	ds_read_b128 v[194:197], v169 offset:37888
	ds_read_b128 v[198:201], v169 offset:38912
	ds_read_b128 v[206:209], v169 offset:39936
	global_load_lds_dwordx4 v[216:217], off
	v_lshl_add_u64 v[216:217], s[44:45], 0, v[158:159]
	s_mov_b32 m0, s47
	s_nop 0
	global_load_lds_dwordx4 v[216:217], off
	s_waitcnt vmcnt(8)
	s_waitcnt lgkmcnt(0)
	s_setprio 1
	s_barrier
	v_mfma_f32_16x16x32_bf16 v[140:143], v[64:67], v[174:177], v[140:143]
	v_mfma_f32_16x16x32_bf16 v[136:139], v[80:83], v[174:177], v[136:139]
	v_mfma_f32_16x16x32_bf16 v[124:127], v[64:67], v[182:185], v[124:127]
	v_mfma_f32_16x16x32_bf16 v[120:123], v[80:83], v[182:185], v[120:123]
	v_mfma_f32_16x16x32_bf16 v[108:111], v[64:67], v[190:193], v[108:111]
	v_mfma_f32_16x16x32_bf16 v[104:107], v[80:83], v[190:193], v[104:107]
	v_mfma_f32_16x16x32_bf16 v[92:95], v[64:67], v[198:201], v[92:95]
	v_mfma_f32_16x16x32_bf16 v[88:91], v[80:83], v[198:201], v[88:91]
	v_mfma_f32_16x16x32_bf16 v[140:143], v[68:71], v[178:181], v[140:143]
	v_mfma_f32_16x16x32_bf16 v[136:139], v[84:87], v[178:181], v[136:139]
	v_mfma_f32_16x16x32_bf16 v[124:127], v[68:71], v[186:189], v[124:127]
	v_mfma_f32_16x16x32_bf16 v[120:123], v[84:87], v[186:189], v[120:123]
	v_mfma_f32_16x16x32_bf16 v[108:111], v[68:71], v[194:197], v[108:111]
	v_mfma_f32_16x16x32_bf16 v[104:107], v[84:87], v[194:197], v[104:107]
	v_mfma_f32_16x16x32_bf16 v[92:95], v[68:71], v[206:209], v[92:95]
	v_mfma_f32_16x16x32_bf16 v[88:91], v[84:87], v[206:209], v[88:91]
	s_setprio 0
	s_setprio 1
	v_mfma_f32_16x16x32_bf16 v[132:135], v[144:147], v[174:177], v[132:135]
	v_mfma_f32_16x16x32_bf16 v[128:131], v[152:155], v[174:177], v[128:131]
	v_mfma_f32_16x16x32_bf16 v[116:119], v[144:147], v[182:185], v[116:119]
	v_mfma_f32_16x16x32_bf16 v[112:115], v[152:155], v[182:185], v[112:115]
	v_mfma_f32_16x16x32_bf16 v[100:103], v[144:147], v[190:193], v[100:103]
	v_mfma_f32_16x16x32_bf16 v[96:99], v[152:155], v[190:193], v[96:99]
	v_mfma_f32_16x16x32_bf16 v[76:79], v[144:147], v[198:201], v[76:79]
	v_mfma_f32_16x16x32_bf16 v[72:75], v[152:155], v[198:201], v[72:75]
	v_mfma_f32_16x16x32_bf16 v[132:135], v[148:151], v[178:181], v[132:135]
	v_mfma_f32_16x16x32_bf16 v[128:131], v[170:173], v[178:181], v[128:131]
	v_mfma_f32_16x16x32_bf16 v[116:119], v[148:151], v[186:189], v[116:119]
	v_mfma_f32_16x16x32_bf16 v[112:115], v[170:173], v[186:189], v[112:115]
	v_mfma_f32_16x16x32_bf16 v[100:103], v[148:151], v[194:197], v[100:103]
	v_mfma_f32_16x16x32_bf16 v[96:99], v[170:173], v[194:197], v[96:99]
	v_mfma_f32_16x16x32_bf16 v[76:79], v[148:151], v[206:209], v[76:79]
	v_mfma_f32_16x16x32_bf16 v[72:75], v[170:173], v[206:209], v[72:75]
	s_barrier
; #define PG8_STAGE(bufoff, gbase, voff) do { _Pragma("unroll") for (int _i = 0; _i < 2; ++_i) \
;         __builtin_amdgcn_global_load_lds((const unsigned*)((const char*)(gbase) + (voff)[_i]), (PG8_LAS unsigned*)(lds + (bufoff) + ldsw + _i * 8192), 16, 0, 0); } while (0)
; #define PG8_LDA(dst, b, h) do { _Pragma("unroll") for (int m = 0; m < 4; ++m) _Pragma("unroll") for (int k = 0; k < 2; ++k) dst[m][k] = *(const PG8_LAS bf16x8*)(lds + PG8_SA(b, h) + aoff + m * 2048 + k * 1024); } while (0)
; #define PG8_WAIT_V(n) asm volatile("s_waitcnt vmcnt(" #n ")" ::: "memory")
; #define PG8_WAIT_L(n) asm volatile("s_waitcnt lgkmcnt(" #n ")" ::: "memory")
; #define PG8_BAR __builtin_amdgcn_s_barrier()
; template <class Epi, class Sched, bool ALIGN_EPI = false, bool SP2 = false>
; __device__ __forceinline__ void gemm_phase(PG8_LAS unsigned char* lds, const Gemm g, const Sched& S, const Epi& E, const int tid) {
;     ...
;         for (int t = 0; t < nt; t += 2) {
;             const bool last = (t == nt - 2);
;             const char* a1 = cA + (size_t)(t + 1) * kstep;
;             const char* a2 = last ? nA : cA + (size_t)(t + 2) * kstep; const char* b2 = last ? nB : cB + (size_t)(t + 2) * kstep;
;             const char* a3 = a2 + kstep; const char* b3 = b2 + kstep;
;             if (last && has_next) S.a_ready(nxt);
;             if constexpr (SP2) {
;             PG8_LDB(B0, 0, 0); PG8_LDB(B1, 0, 1); PG8_SCHED; PG8_LDA(At, 0, 0); PG8_STAGE(PG8_SA(1, 1), a1 + hstep, voffA);
;             PG8_WAIT_V(8); PG8_WAIT_L(0); PG8_BAR; PG8_MMA(0, 0, At, B0); PG8_MMA(0, 1, At, B1); PG8_BAR; PG8_SCHED;
;             PG8_LDA(At, 0, 1); PG8_STAGE(PG8_SB(0, 0), b2, voffB); PG8_STAGE(PG8_SB(0, 1), b2 + hstep, voffB); PG8_STAGE(PG8_SA(0, 0), a2, voffA);
;             PG8_WAIT_V(8); PG8_WAIT_L(0); PG8_BAR; PG8_MMA(1, 0, At, B0); PG8_MMA(1, 1, At, B1); PG8_BAR; PG8_SCHED;
;             PG8_LDB(B0, 1, 0); PG8_LDB(B1, 1, 1); PG8_SCHED; PG8_LDA(At, 1, 0); PG8_STAGE(PG8_SA(0, 1), a2 + hstep, voffA);
;             PG8_WAIT_V(8); PG8_WAIT_L(0); PG8_BAR; PG8_MMA(0, 0, At, B0); PG8_MMA(0, 1, At, B1); PG8_BAR; PG8_SCHED;
;             PG8_LDA(At, 1, 1); PG8_STAGE(PG8_SB(1, 0), b3, voffB); PG8_STAGE(PG8_SB(1, 1), b3 + hstep, voffB); PG8_STAGE(PG8_SA(1, 0), a3, voffA);
;             PG8_WAIT_V(8); PG8_WAIT_L(0); PG8_BAR; PG8_MMA(1, 0, At, B0); PG8_MMA(1, 1, At, B1); PG8_BAR; PG8_SCHED;
	s_setprio 0
	s_add_i32 s44, s75, s38
	v_lshl_add_u64 v[202:203], v[202:203], 0, s[70:71]
	s_mov_b32 m0, s44
	ds_read_b128 v[174:177], v169 offset:49152
	ds_read_b128 v[178:181], v169 offset:50176
	ds_read_b128 v[182:185], v169 offset:51200
	ds_read_b128 v[186:189], v169 offset:52224
	ds_read_b128 v[190:193], v169 offset:53248
	ds_read_b128 v[194:197], v169 offset:54272
	ds_read_b128 v[198:201], v169 offset:55296
	ds_read_b128 v[206:209], v169 offset:56320
	global_load_lds_dwordx4 v[202:203], off
	s_add_i32 m0, s44, 0x2000
	s_add_u32 s42, s42, 0x80080
	v_lshl_add_u64 v[202:203], v[210:211], 0, s[70:71]
	s_addc_u32 s43, s43, 0
	s_add_i32 s44, s76, s38
	global_load_lds_dwordx4 v[202:203], off
	v_lshl_add_u64 v[202:203], s[42:43], 0, v[204:205]
	s_mov_b32 m0, s44
	s_nop 0
	global_load_lds_dwordx4 v[202:203], off
	v_lshl_add_u64 v[202:203], s[42:43], 0, v[160:161]
	s_add_i32 m0, s44, 0x2000
	s_nop 0
	global_load_lds_dwordx4 v[202:203], off
	v_lshl_add_u64 v[202:203], v[212:213], 0, s[70:71]
	s_mov_b32 m0, s51
	s_nop 0
	global_load_lds_dwordx4 v[202:203], off
	v_lshl_add_u64 v[202:203], v[214:215], 0, s[70:71]
	s_mov_b32 m0, s52
	s_nop 0
	global_load_lds_dwordx4 v[202:203], off
	s_add_i32 s69, s69, 2
	s_add_u32 s36, s36, 0x100
	s_addc_u32 s37, s37, 0
	s_add_u32 s65, s65, 0x100
	s_addc_u32 s68, s68, 0
	s_waitcnt vmcnt(8)
	s_waitcnt lgkmcnt(0)
	s_setprio 1
	s_barrier
	v_mfma_f32_16x16x32_bf16 v[60:63], v[64:67], v[174:177], v[60:63]
	v_mfma_f32_16x16x32_bf16 v[56:59], v[80:83], v[174:177], v[56:59]
	v_mfma_f32_16x16x32_bf16 v[44:47], v[64:67], v[182:185], v[44:47]
	v_mfma_f32_16x16x32_bf16 v[40:43], v[80:83], v[182:185], v[40:43]
	v_mfma_f32_16x16x32_bf16 v[28:31], v[64:67], v[190:193], v[28:31]
	v_mfma_f32_16x16x32_bf16 v[24:27], v[80:83], v[190:193], v[24:27]
	v_mfma_f32_16x16x32_bf16 v[12:15], v[64:67], v[198:201], v[12:15]
	v_mfma_f32_16x16x32_bf16 v[8:11], v[80:83], v[198:201], v[8:11]
	v_mfma_f32_16x16x32_bf16 v[60:63], v[68:71], v[178:181], v[60:63]
	v_mfma_f32_16x16x32_bf16 v[56:59], v[84:87], v[178:181], v[56:59]
	v_mfma_f32_16x16x32_bf16 v[44:47], v[68:71], v[186:189], v[44:47]
	v_mfma_f32_16x16x32_bf16 v[40:43], v[84:87], v[186:189], v[40:43]
	v_mfma_f32_16x16x32_bf16 v[28:31], v[68:71], v[194:197], v[28:31]
	v_mfma_f32_16x16x32_bf16 v[24:27], v[84:87], v[194:197], v[24:27]
	v_mfma_f32_16x16x32_bf16 v[12:15], v[68:71], v[206:209], v[12:15]
	v_mfma_f32_16x16x32_bf16 v[8:11], v[84:87], v[206:209], v[8:11]
	s_setprio 0
	s_setprio 1
	v_mfma_f32_16x16x32_bf16 v[52:55], v[144:147], v[174:177], v[52:55]
	v_mfma_f32_16x16x32_bf16 v[48:51], v[152:155], v[174:177], v[48:51]
	v_mfma_f32_16x16x32_bf16 v[36:39], v[144:147], v[182:185], v[36:39]
	v_mfma_f32_16x16x32_bf16 v[32:35], v[152:155], v[182:185], v[32:35]
	v_mfma_f32_16x16x32_bf16 v[20:23], v[144:147], v[190:193], v[20:23]
	v_mfma_f32_16x16x32_bf16 v[16:19], v[152:155], v[190:193], v[16:19]
	v_mfma_f32_16x16x32_bf16 v[4:7], v[144:147], v[198:201], v[4:7]
	v_mfma_f32_16x16x32_bf16 v[0:3], v[152:155], v[198:201], v[0:3]
	v_mfma_f32_16x16x32_bf16 v[52:55], v[148:151], v[178:181], v[52:55]
	v_mfma_f32_16x16x32_bf16 v[48:51], v[170:173], v[178:181], v[48:51]
	v_mfma_f32_16x16x32_bf16 v[36:39], v[148:151], v[186:189], v[36:39]
	v_mfma_f32_16x16x32_bf16 v[32:35], v[170:173], v[186:189], v[32:35]
	v_mfma_f32_16x16x32_bf16 v[20:23], v[148:151], v[194:197], v[20:23]
	v_mfma_f32_16x16x32_bf16 v[16:19], v[170:173], v[194:197], v[16:19]
	v_mfma_f32_16x16x32_bf16 v[4:7], v[148:151], v[206:209], v[4:7]
	v_mfma_f32_16x16x32_bf16 v[0:3], v[170:173], v[206:209], v[0:3]
	s_barrier
	s_setprio 0
.LBB0_1426:
	s_add_i32 s75, 0, 0x10000
	s_add_i32 s78, 0, 0x14000
	v_add_u32_e32 v84, s75, v167
	v_add_u32_e32 v166, s78, v167
	ds_read_b128 v[64:67], v84
	ds_read_b128 v[68:71], v84 offset:1024
	ds_read_b128 v[80:83], v84 offset:2048
	ds_read_b128 v[84:87], v84 offset:3072
	ds_read_b128 v[144:147], v166
	ds_read_b128 v[148:151], v166 offset:1024
	ds_read_b128 v[152:155], v166 offset:2048
	ds_read_b128 v[170:173], v166 offset:3072
	v_lshl_add_u64 v[202:203], s[36:37], 0, v[162:163]
	s_add_i32 m0, s35, 0xc000
	ds_read_b128 v[174:177], v169
	ds_read_b128 v[178:181], v169 offset:1024
	ds_read_b128 v[182:185], v169 offset:2048
	ds_read_b128 v[186:189], v169 offset:3072
	ds_read_b128 v[190:193], v169 offset:4096
	ds_read_b128 v[194:197], v169 offset:5120
	ds_read_b128 v[198:201], v169 offset:6144
	ds_read_b128 v[206:209], v169 offset:7168
	s_add_u32 s42, s36, 0xfff80080
	s_addc_u32 s43, s37, -1
	s_cmp_eq_u32 s69, 28
	s_cselect_b32 s45, s27, s43
	s_cselect_b32 s44, s62, s42
	s_cselect_b32 s43, s25, s68
	s_cselect_b32 s42, s64, s65
	global_load_lds_dwordx4 v[202:203], off
	v_lshl_add_u64 v[202:203], s[36:37], 0, v[164:165]
	s_add_i32 m0, s35, 0xe000
	s_nop 0
	global_load_lds_dwordx4 v[202:203], off
	s_waitcnt vmcnt(8)
	s_waitcnt lgkmcnt(0)
	s_setprio 1
	s_barrier
; #define PG8_STAGE(bufoff, gbase, voff) do { _Pragma("unroll") for (int _i = 0; _i < 2; ++_i) \
;         __builtin_amdgcn_global_load_lds((const unsigned*)((const char*)(gbase) + (voff)[_i]), (PG8_LAS unsigned*)(lds + (bufoff) + ldsw + _i * 8192), 16, 0, 0); } while (0)
; #define PG8_LDA(dst, b, h) do { _Pragma("unroll") for (int m = 0; m < 4; ++m) _Pragma("unroll") for (int k = 0; k < 2; ++k) dst[m][k] = *(const PG8_LAS bf16x8*)(lds + PG8_SA(b, h) + aoff + m * 2048 + k * 1024); } while (0)
; #define PG8_MMA(ai, bj, At, Bt) do { __builtin_amdgcn_s_setprio(1); _Pragma("unroll") for (int m = 0; m < 4; ++m) _Pragma("unroll") for (int n = 0; n < 2; ++n) _Pragma("unroll") for (int k = 0; k < 2; ++k) \
;         acc[ai][bj][m][n] = __builtin_amdgcn_mfma_f32_16x16x32_bf16(Bt[n][k], At[m][k], acc[ai][bj][m][n], 0, 0, 0); __builtin_amdgcn_s_setprio(0); } while (0)
; #define PG8_WAIT_V(n) asm volatile("s_waitcnt vmcnt(" #n ")" ::: "memory")
; #define PG8_WAIT_L(n) asm volatile("s_waitcnt lgkmcnt(" #n ")" ::: "memory")
; #define PG8_BAR __builtin_amdgcn_s_barrier()
; #define PG8_SCHED __builtin_amdgcn_sched_barrier(0)
; template <class Epi, class Sched, bool ALIGN_EPI = false, bool SP2 = false>
; __device__ __forceinline__ void gemm_phase(PG8_LAS unsigned char* lds, const Gemm g, const Sched& S, const Epi& E, const int tid) {
;     ...
;             PG8_WAIT_V(8); PG8_WAIT_L(0); PG8_BAR; PG8_MMA(0, 0, At, B0); PG8_MMA(0, 1, At, B1); PG8_BAR; PG8_SCHED;
;             PG8_LDA(At, 0, 1); PG8_STAGE(PG8_SB(0, 0), b2, voffB); PG8_STAGE(PG8_SB(0, 1), b2 + hstep, voffB); PG8_STAGE(PG8_SA(0, 0), a2, voffA);
;             PG8_WAIT_V(8); PG8_WAIT_L(0); PG8_BAR; PG8_MMA(1, 0, At, B0); PG8_MMA(1, 1, At, B1); PG8_BAR; PG8_SCHED;
	v_mfma_f32_16x16x32_bf16 v[140:143], v[64:67], v[174:177], v[140:143]
	v_mfma_f32_16x16x32_bf16 v[136:139], v[80:83], v[174:177], v[136:139]
	v_mfma_f32_16x16x32_bf16 v[124:127], v[64:67], v[182:185], v[124:127]
	v_mfma_f32_16x16x32_bf16 v[120:123], v[80:83], v[182:185], v[120:123]
	v_mfma_f32_16x16x32_bf16 v[108:111], v[64:67], v[190:193], v[108:111]
	v_mfma_f32_16x16x32_bf16 v[104:107], v[80:83], v[190:193], v[104:107]
	v_mfma_f32_16x16x32_bf16 v[92:95], v[64:67], v[198:201], v[92:95]
	v_mfma_f32_16x16x32_bf16 v[88:91], v[80:83], v[198:201], v[88:91]
	v_mfma_f32_16x16x32_bf16 v[140:143], v[68:71], v[178:181], v[140:143]
	v_mfma_f32_16x16x32_bf16 v[136:139], v[84:87], v[178:181], v[136:139]
	v_mfma_f32_16x16x32_bf16 v[124:127], v[68:71], v[186:189], v[124:127]
	v_mfma_f32_16x16x32_bf16 v[120:123], v[84:87], v[186:189], v[120:123]
	v_mfma_f32_16x16x32_bf16 v[108:111], v[68:71], v[194:197], v[108:111]
	v_mfma_f32_16x16x32_bf16 v[104:107], v[84:87], v[194:197], v[104:107]
	v_mfma_f32_16x16x32_bf16 v[92:95], v[68:71], v[206:209], v[92:95]
	v_mfma_f32_16x16x32_bf16 v[88:91], v[84:87], v[206:209], v[88:91]
	s_setprio 0
	s_setprio 1
	v_mfma_f32_16x16x32_bf16 v[132:135], v[144:147], v[174:177], v[132:135]
	v_mfma_f32_16x16x32_bf16 v[128:131], v[152:155], v[174:177], v[128:131]
	v_mfma_f32_16x16x32_bf16 v[116:119], v[144:147], v[182:185], v[116:119]
	v_mfma_f32_16x16x32_bf16 v[112:115], v[152:155], v[182:185], v[112:115]
	v_mfma_f32_16x16x32_bf16 v[100:103], v[144:147], v[190:193], v[100:103]
	v_mfma_f32_16x16x32_bf16 v[96:99], v[152:155], v[190:193], v[96:99]
	v_mfma_f32_16x16x32_bf16 v[76:79], v[144:147], v[198:201], v[76:79]
	v_mfma_f32_16x16x32_bf16 v[72:75], v[152:155], v[198:201], v[72:75]
	v_mfma_f32_16x16x32_bf16 v[132:135], v[148:151], v[178:181], v[132:135]
	v_mfma_f32_16x16x32_bf16 v[128:131], v[170:173], v[178:181], v[128:131]
	v_mfma_f32_16x16x32_bf16 v[116:119], v[148:151], v[186:189], v[116:119]
	v_mfma_f32_16x16x32_bf16 v[112:115], v[170:173], v[186:189], v[112:115]
	v_mfma_f32_16x16x32_bf16 v[100:103], v[148:151], v[194:197], v[100:103]
	v_mfma_f32_16x16x32_bf16 v[96:99], v[170:173], v[194:197], v[96:99]
	v_mfma_f32_16x16x32_bf16 v[76:79], v[148:151], v[206:209], v[76:79]
	v_mfma_f32_16x16x32_bf16 v[72:75], v[170:173], v[206:209], v[72:75]
	s_barrier
	s_setprio 0
	s_add_i32 s75, s75, s38
	v_lshl_add_u64 v[202:203], s[42:43], 0, v[204:205]
	s_mov_b32 m0, s75
	ds_read_b128 v[174:177], v169 offset:16384
	ds_read_b128 v[178:181], v169 offset:17408
	ds_read_b128 v[182:185], v169 offset:18432
	ds_read_b128 v[186:189], v169 offset:19456
	ds_read_b128 v[190:193], v169 offset:20480
	ds_read_b128 v[194:197], v169 offset:21504
	ds_read_b128 v[198:201], v169 offset:22528
	ds_read_b128 v[206:209], v169 offset:23552
	global_load_lds_dwordx4 v[202:203], off
	s_add_i32 m0, s75, 0x2000
	s_add_u32 s76, s42, 0x80000
	v_lshl_add_u64 v[210:211], s[42:43], 0, v[160:161]
	s_addc_u32 s77, s43, 0
	s_add_i32 s75, s78, s38
	global_load_lds_dwordx4 v[210:211], off
	v_lshl_add_u64 v[212:213], s[76:77], 0, v[204:205]
	s_mov_b32 m0, s75
	v_lshl_add_u64 v[214:215], s[44:45], 0, v[158:159]
	global_load_lds_dwordx4 v[212:213], off
	v_lshl_add_u64 v[212:213], s[76:77], 0, v[160:161]
	s_add_i32 m0, s75, 0x2000
	s_nop 0
	global_load_lds_dwordx4 v[212:213], off
	v_lshl_add_u64 v[212:213], s[44:45], 0, v[156:157]
	s_mov_b32 m0, s35
	s_nop 0
	global_load_lds_dwordx4 v[212:213], off
	s_mov_b32 m0, s40
	s_nop 0
	global_load_lds_dwordx4 v[214:215], off
	s_waitcnt vmcnt(8)
	s_waitcnt lgkmcnt(0)
	s_setprio 1
	s_barrier
	v_mfma_f32_16x16x32_bf16 v[60:63], v[64:67], v[174:177], v[60:63]
	v_mfma_f32_16x16x32_bf16 v[56:59], v[80:83], v[174:177], v[56:59]
	v_mfma_f32_16x16x32_bf16 v[44:47], v[64:67], v[182:185], v[44:47]
	v_mfma_f32_16x16x32_bf16 v[40:43], v[80:83], v[182:185], v[40:43]
	v_mfma_f32_16x16x32_bf16 v[28:31], v[64:67], v[190:193], v[28:31]
	v_mfma_f32_16x16x32_bf16 v[24:27], v[80:83], v[190:193], v[24:27]
	v_mfma_f32_16x16x32_bf16 v[12:15], v[64:67], v[198:201], v[12:15]
	v_mfma_f32_16x16x32_bf16 v[8:11], v[80:83], v[198:201], v[8:11]
	v_mfma_f32_16x16x32_bf16 v[60:63], v[68:71], v[178:181], v[60:63]
	v_mfma_f32_16x16x32_bf16 v[56:59], v[84:87], v[178:181], v[56:59]
	v_mfma_f32_16x16x32_bf16 v[44:47], v[68:71], v[186:189], v[44:47]
	v_mfma_f32_16x16x32_bf16 v[40:43], v[84:87], v[186:189], v[40:43]
	v_mfma_f32_16x16x32_bf16 v[28:31], v[68:71], v[194:197], v[28:31]
	v_mfma_f32_16x16x32_bf16 v[24:27], v[84:87], v[194:197], v[24:27]
	v_mfma_f32_16x16x32_bf16 v[12:15], v[68:71], v[206:209], v[12:15]
	v_mfma_f32_16x16x32_bf16 v[8:11], v[84:87], v[206:209], v[8:11]
	s_setprio 0
	s_setprio 1
	v_mfma_f32_16x16x32_bf16 v[52:55], v[144:147], v[174:177], v[52:55]
	v_mfma_f32_16x16x32_bf16 v[48:51], v[152:155], v[174:177], v[48:51]
	v_mfma_f32_16x16x32_bf16 v[36:39], v[144:147], v[182:185], v[36:39]
	v_mfma_f32_16x16x32_bf16 v[32:35], v[152:155], v[182:185], v[32:35]
	v_mfma_f32_16x16x32_bf16 v[20:23], v[144:147], v[190:193], v[20:23]
	v_mfma_f32_16x16x32_bf16 v[16:19], v[152:155], v[190:193], v[16:19]
	v_mfma_f32_16x16x32_bf16 v[4:7], v[144:147], v[198:201], v[4:7]
	v_mfma_f32_16x16x32_bf16 v[0:3], v[152:155], v[198:201], v[0:3]
	v_mfma_f32_16x16x32_bf16 v[52:55], v[148:151], v[178:181], v[52:55]
	v_mfma_f32_16x16x32_bf16 v[48:51], v[170:173], v[178:181], v[48:51]
	v_mfma_f32_16x16x32_bf16 v[36:39], v[148:151], v[186:189], v[36:39]
	v_mfma_f32_16x16x32_bf16 v[32:35], v[170:173], v[186:189], v[32:35]
	v_mfma_f32_16x16x32_bf16 v[20:23], v[148:151], v[194:197], v[20:23]
	v_mfma_f32_16x16x32_bf16 v[16:19], v[170:173], v[194:197], v[16:19]
	v_mfma_f32_16x16x32_bf16 v[4:7], v[148:151], v[206:209], v[4:7]
	v_mfma_f32_16x16x32_bf16 v[0:3], v[170:173], v[206:209], v[0:3]
	s_barrier
; #define PG8_STAGE(bufoff, gbase, voff) do { _Pragma("unroll") for (int _i = 0; _i < 2; ++_i) \
;         __builtin_amdgcn_global_load_lds((const unsigned*)((const char*)(gbase) + (voff)[_i]), (PG8_LAS unsigned*)(lds + (bufoff) + ldsw + _i * 8192), 16, 0, 0); } while (0)
; #define PG8_LDA(dst, b, h) do { _Pragma("unroll") for (int m = 0; m < 4; ++m) _Pragma("unroll") for (int k = 0; k < 2; ++k) dst[m][k] = *(const PG8_LAS bf16x8*)(lds + PG8_SA(b, h) + aoff + m * 2048 + k * 1024); } while (0)
; #define PG8_LDB(dst, b, h) do { _Pragma("unroll") for (int n = 0; n < 2; ++n) _Pragma("unroll") for (int k = 0; k < 2; ++k) dst[n][k] = *(const PG8_LAS bf16x8*)(lds + PG8_SB(b, h) + boff + n * 2048 + k * 1024); } while (0)
; #define PG8_MMA(ai, bj, At, Bt) do { __builtin_amdgcn_s_setprio(1); _Pragma("unroll") for (int m = 0; m < 4; ++m) _Pragma("unroll") for (int n = 0; n < 2; ++n) _Pragma("unroll") for (int k = 0; k < 2; ++k) \
;         acc[ai][bj][m][n] = __builtin_amdgcn_mfma_f32_16x16x32_bf16(Bt[n][k], At[m][k], acc[ai][bj][m][n], 0, 0, 0); __builtin_amdgcn_s_setprio(0); } while (0)
; #define PG8_WAIT_V(n) asm volatile("s_waitcnt vmcnt(" #n ")" ::: "memory")
; #define PG8_WAIT_L(n) asm volatile("s_waitcnt lgkmcnt(" #n ")" ::: "memory")
; #define PG8_BAR __builtin_amdgcn_s_barrier()
; #define PG8_SCHED __builtin_amdgcn_sched_barrier(0)
; template <class Epi, class Sched, bool ALIGN_EPI = false, bool SP2 = false>
; __device__ __forceinline__ void gemm_phase(PG8_LAS unsigned char* lds, const Gemm g, const Sched& S, const Epi& E, const int tid) {
;     ...
;             PG8_LDB(B0, 1, 0); PG8_LDB(B1, 1, 1); PG8_SCHED; PG8_LDA(At, 1, 0); PG8_STAGE(PG8_SA(0, 1), a2 + hstep, voffA);
;             PG8_WAIT_V(8); PG8_WAIT_L(0); PG8_BAR; PG8_MMA(0, 0, At, B0); PG8_MMA(0, 1, At, B1); PG8_BAR; PG8_SCHED;
	s_setprio 0
	s_add_i32 s75, 0, 0x18000
	s_add_i32 s76, 0, 0x1c000
	v_add_u32_e32 v84, s75, v167
	v_add_u32_e32 v166, s76, v167
	ds_read_b128 v[64:67], v84
	ds_read_b128 v[68:71], v84 offset:1024
	ds_read_b128 v[80:83], v84 offset:2048
	ds_read_b128 v[84:87], v84 offset:3072
	ds_read_b128 v[144:147], v166
	ds_read_b128 v[148:151], v166 offset:1024
	ds_read_b128 v[152:155], v166 offset:2048
	ds_read_b128 v[170:173], v166 offset:3072
	s_add_u32 s44, s44, 0x80000
	s_addc_u32 s45, s45, 0
	s_mov_b32 m0, s46
	v_lshl_add_u64 v[216:217], s[44:45], 0, v[156:157]
	ds_read_b128 v[174:177], v169 offset:32768
	ds_read_b128 v[178:181], v169 offset:33792
	ds_read_b128 v[182:185], v169 offset:34816
	ds_read_b128 v[186:189], v169 offset:35840
	ds_read_b128 v[190:193], v169 offset:36864
	ds_read_b128 v[194:197], v169 offset:37888
	ds_read_b128 v[198:201], v169 offset:38912
	ds_read_b128 v[206:209], v169 offset:39936
	global_load_lds_dwordx4 v[216:217], off
	v_lshl_add_u64 v[216:217], s[44:45], 0, v[158:159]
	s_mov_b32 m0, s47
	s_nop 0
	global_load_lds_dwordx4 v[216:217], off
	s_waitcnt vmcnt(8)
	s_waitcnt lgkmcnt(0)
	s_setprio 1
	s_barrier
	v_mfma_f32_16x16x32_bf16 v[140:143], v[64:67], v[174:177], v[140:143]
	v_mfma_f32_16x16x32_bf16 v[136:139], v[80:83], v[174:177], v[136:139]
	v_mfma_f32_16x16x32_bf16 v[124:127], v[64:67], v[182:185], v[124:127]
	v_mfma_f32_16x16x32_bf16 v[120:123], v[80:83], v[182:185], v[120:123]
	v_mfma_f32_16x16x32_bf16 v[108:111], v[64:67], v[190:193], v[108:111]
	v_mfma_f32_16x16x32_bf16 v[104:107], v[80:83], v[190:193], v[104:107]
	v_mfma_f32_16x16x32_bf16 v[92:95], v[64:67], v[198:201], v[92:95]
	v_mfma_f32_16x16x32_bf16 v[88:91], v[80:83], v[198:201], v[88:91]
	v_mfma_f32_16x16x32_bf16 v[140:143], v[68:71], v[178:181], v[140:143]
	v_mfma_f32_16x16x32_bf16 v[136:139], v[84:87], v[178:181], v[136:139]
	v_mfma_f32_16x16x32_bf16 v[124:127], v[68:71], v[186:189], v[124:127]
	v_mfma_f32_16x16x32_bf16 v[120:123], v[84:87], v[186:189], v[120:123]
	v_mfma_f32_16x16x32_bf16 v[108:111], v[68:71], v[194:197], v[108:111]
	v_mfma_f32_16x16x32_bf16 v[104:107], v[84:87], v[194:197], v[104:107]
	v_mfma_f32_16x16x32_bf16 v[92:95], v[68:71], v[206:209], v[92:95]
	v_mfma_f32_16x16x32_bf16 v[88:91], v[84:87], v[206:209], v[88:91]
	s_setprio 0
	s_setprio 1
	v_mfma_f32_16x16x32_bf16 v[132:135], v[144:147], v[174:177], v[132:135]
	v_mfma_f32_16x16x32_bf16 v[128:131], v[152:155], v[174:177], v[128:131]
	v_mfma_f32_16x16x32_bf16 v[116:119], v[144:147], v[182:185], v[116:119]
	v_mfma_f32_16x16x32_bf16 v[112:115], v[152:155], v[182:185], v[112:115]
	v_mfma_f32_16x16x32_bf16 v[100:103], v[144:147], v[190:193], v[100:103]
	v_mfma_f32_16x16x32_bf16 v[96:99], v[152:155], v[190:193], v[96:99]
	v_mfma_f32_16x16x32_bf16 v[76:79], v[144:147], v[198:201], v[76:79]
	v_mfma_f32_16x16x32_bf16 v[72:75], v[152:155], v[198:201], v[72:75]
	v_mfma_f32_16x16x32_bf16 v[132:135], v[148:151], v[178:181], v[132:135]
	v_mfma_f32_16x16x32_bf16 v[128:131], v[170:173], v[178:181], v[128:131]
	v_mfma_f32_16x16x32_bf16 v[116:119], v[148:151], v[186:189], v[116:119]
	v_mfma_f32_16x16x32_bf16 v[112:115], v[170:173], v[186:189], v[112:115]
	v_mfma_f32_16x16x32_bf16 v[100:103], v[148:151], v[194:197], v[100:103]
	v_mfma_f32_16x16x32_bf16 v[96:99], v[170:173], v[194:197], v[96:99]
	v_mfma_f32_16x16x32_bf16 v[76:79], v[148:151], v[206:209], v[76:79]
	v_mfma_f32_16x16x32_bf16 v[72:75], v[170:173], v[206:209], v[72:75]
	s_barrier
; #define PG8_STAGE(bufoff, gbase, voff) do { _Pragma("unroll") for (int _i = 0; _i < 2; ++_i) \
;         __builtin_amdgcn_global_load_lds((const unsigned*)((const char*)(gbase) + (voff)[_i]), (PG8_LAS unsigned*)(lds + (bufoff) + ldsw + _i * 8192), 16, 0, 0); } while (0)
; #define PG8_LDA(dst, b, h) do { _Pragma("unroll") for (int m = 0; m < 4; ++m) _Pragma("unroll") for (int k = 0; k < 2; ++k) dst[m][k] = *(const PG8_LAS bf16x8*)(lds + PG8_SA(b, h) + aoff + m * 2048 + k * 1024); } while (0)
; #define PG8_MMA(ai, bj, At, Bt) do { __builtin_amdgcn_s_setprio(1); _Pragma("unroll") for (int m = 0; m < 4; ++m) _Pragma("unroll") for (int n = 0; n < 2; ++n) _Pragma("unroll") for (int k = 0; k < 2; ++k) \
;         acc[ai][bj][m][n] = __builtin_amdgcn_mfma_f32_16x16x32_bf16(Bt[n][k], At[m][k], acc[ai][bj][m][n], 0, 0, 0); __builtin_amdgcn_s_setprio(0); } while (0)
; #define PG8_WAIT_V(n) asm volatile("s_waitcnt vmcnt(" #n ")" ::: "memory")
; #define PG8_WAIT_L(n) asm volatile("s_waitcnt lgkmcnt(" #n ")" ::: "memory")
; #define PG8_BAR __builtin_amdgcn_s_barrier()
; #define PG8_SCHED __builtin_amdgcn_sched_barrier(0)
; template <class Epi, class Sched, bool ALIGN_EPI = false, bool SP2 = false>
; __device__ __forceinline__ void gemm_phase(PG8_LAS unsigned char* lds, const Gemm g, const Sched& S, const Epi& E, const int tid) {
;     ...
;             PG8_LDA(At, 1, 1); PG8_STAGE(PG8_SB(1, 0), b3, voffB); PG8_STAGE(PG8_SB(1, 1), b3 + hstep, voffB); PG8_STAGE(PG8_SA(1, 0), a3, voffA);
;             PG8_WAIT_V(8); PG8_WAIT_L(0); PG8_BAR; PG8_MMA(1, 0, At, B0); PG8_MMA(1, 1, At, B1); PG8_BAR; PG8_SCHED;
	s_setprio 0
	s_add_i32 s44, s75, s38
	v_lshl_add_u64 v[202:203], v[202:203], 0, s[70:71]
	s_mov_b32 m0, s44
	ds_read_b128 v[174:177], v169 offset:49152
	ds_read_b128 v[178:181], v169 offset:50176
	ds_read_b128 v[182:185], v169 offset:51200
	ds_read_b128 v[186:189], v169 offset:52224
	ds_read_b128 v[190:193], v169 offset:53248
	ds_read_b128 v[194:197], v169 offset:54272
	ds_read_b128 v[198:201], v169 offset:55296
	ds_read_b128 v[206:209], v169 offset:56320
	global_load_lds_dwordx4 v[202:203], off
	s_add_i32 m0, s44, 0x2000
	s_add_u32 s42, s42, 0x80080
	v_lshl_add_u64 v[202:203], v[210:211], 0, s[70:71]
	s_addc_u32 s43, s43, 0
	s_add_i32 s44, s76, s38
	global_load_lds_dwordx4 v[202:203], off
	v_lshl_add_u64 v[202:203], s[42:43], 0, v[204:205]
	s_mov_b32 m0, s44
	s_nop 0
	global_load_lds_dwordx4 v[202:203], off
	v_lshl_add_u64 v[202:203], s[42:43], 0, v[160:161]
	s_add_i32 m0, s44, 0x2000
	s_nop 0
	global_load_lds_dwordx4 v[202:203], off
	v_lshl_add_u64 v[202:203], v[212:213], 0, s[70:71]
	s_mov_b32 m0, s51
	s_nop 0
	global_load_lds_dwordx4 v[202:203], off
	v_lshl_add_u64 v[202:203], v[214:215], 0, s[70:71]
	s_mov_b32 m0, s52
	s_nop 0
	global_load_lds_dwordx4 v[202:203], off
	s_add_i32 s69, s69, 2
	s_add_u32 s36, s36, 0x100
	s_addc_u32 s37, s37, 0
	s_add_u32 s65, s65, 0x100
	s_addc_u32 s68, s68, 0
	s_waitcnt vmcnt(8)
	s_waitcnt lgkmcnt(0)
	s_setprio 1
	s_barrier
	v_mfma_f32_16x16x32_bf16 v[60:63], v[64:67], v[174:177], v[60:63]
	v_mfma_f32_16x16x32_bf16 v[56:59], v[80:83], v[174:177], v[56:59]
	v_mfma_f32_16x16x32_bf16 v[44:47], v[64:67], v[182:185], v[44:47]
	v_mfma_f32_16x16x32_bf16 v[40:43], v[80:83], v[182:185], v[40:43]
	v_mfma_f32_16x16x32_bf16 v[28:31], v[64:67], v[190:193], v[28:31]
	v_mfma_f32_16x16x32_bf16 v[24:27], v[80:83], v[190:193], v[24:27]
	v_mfma_f32_16x16x32_bf16 v[12:15], v[64:67], v[198:201], v[12:15]
	v_mfma_f32_16x16x32_bf16 v[8:11], v[80:83], v[198:201], v[8:11]
	v_mfma_f32_16x16x32_bf16 v[60:63], v[68:71], v[178:181], v[60:63]
	v_mfma_f32_16x16x32_bf16 v[56:59], v[84:87], v[178:181], v[56:59]
	v_mfma_f32_16x16x32_bf16 v[44:47], v[68:71], v[186:189], v[44:47]
	v_mfma_f32_16x16x32_bf16 v[40:43], v[84:87], v[186:189], v[40:43]
	v_mfma_f32_16x16x32_bf16 v[28:31], v[68:71], v[194:197], v[28:31]
	v_mfma_f32_16x16x32_bf16 v[24:27], v[84:87], v[194:197], v[24:27]
	v_mfma_f32_16x16x32_bf16 v[12:15], v[68:71], v[206:209], v[12:15]
	v_mfma_f32_16x16x32_bf16 v[8:11], v[84:87], v[206:209], v[8:11]
	s_setprio 0
	s_setprio 1
	v_mfma_f32_16x16x32_bf16 v[52:55], v[144:147], v[174:177], v[52:55]
	v_mfma_f32_16x16x32_bf16 v[48:51], v[152:155], v[174:177], v[48:51]
	v_mfma_f32_16x16x32_bf16 v[36:39], v[144:147], v[182:185], v[36:39]
	v_mfma_f32_16x16x32_bf16 v[32:35], v[152:155], v[182:185], v[32:35]
	v_mfma_f32_16x16x32_bf16 v[20:23], v[144:147], v[190:193], v[20:23]
	v_mfma_f32_16x16x32_bf16 v[16:19], v[152:155], v[190:193], v[16:19]
	v_mfma_f32_16x16x32_bf16 v[4:7], v[144:147], v[198:201], v[4:7]
	v_mfma_f32_16x16x32_bf16 v[0:3], v[152:155], v[198:201], v[0:3]
	v_mfma_f32_16x16x32_bf16 v[52:55], v[148:151], v[178:181], v[52:55]
	v_mfma_f32_16x16x32_bf16 v[48:51], v[170:173], v[178:181], v[48:51]
	v_mfma_f32_16x16x32_bf16 v[36:39], v[148:151], v[186:189], v[36:39]
	v_mfma_f32_16x16x32_bf16 v[32:35], v[170:173], v[186:189], v[32:35]
	v_mfma_f32_16x16x32_bf16 v[20:23], v[148:151], v[194:197], v[20:23]
	v_mfma_f32_16x16x32_bf16 v[16:19], v[170:173], v[194:197], v[16:19]
	v_mfma_f32_16x16x32_bf16 v[4:7], v[148:151], v[206:209], v[4:7]
	v_mfma_f32_16x16x32_bf16 v[0:3], v[170:173], v[206:209], v[0:3]
	s_barrier
	s_setprio 0
	s_cmp_gt_u32 s69, 29
	s_cbranch_scc0 .LBB0_1426
	s_and_b64 vcc, exec, s[22:23]
	s_cbranch_vccz .LBB0_1429
	s_barrier

; #define PG8_STAGE(bufoff, gbase, voff) do { _Pragma("unroll") for (int _i = 0; _i < 2; ++_i) \
;         __builtin_amdgcn_global_load_lds((const unsigned*)((const char*)(gbase) + (voff)[_i]), (PG8_LAS unsigned*)(lds + (bufoff) + ldsw + _i * 8192), 16, 0, 0); } while (0)
; #define PG8_LDA(dst, b, h) do { _Pragma("unroll") for (int m = 0; m < 4; ++m) _Pragma("unroll") for (int k = 0; k < 2; ++k) dst[m][k] = *(const PG8_LAS bf16x8*)(lds + PG8_SA(b, h) + aoff + m * 2048 + k * 1024); } while (0)
; #define PG8_LDB(dst, b, h) do { _Pragma("unroll") for (int n = 0; n < 2; ++n) _Pragma("unroll") for (int k = 0; k < 2; ++k) dst[n][k] = *(const PG8_LAS bf16x8*)(lds + PG8_SB(b, h) + boff + n * 2048 + k * 1024); } while (0)
; #define PG8_WAIT_V(n) asm volatile("s_waitcnt vmcnt(" #n ")" ::: "memory")
; #define PG8_WAIT_L(n) asm volatile("s_waitcnt lgkmcnt(" #n ")" ::: "memory")
; #define PG8_BAR __builtin_amdgcn_s_barrier()
; #define PG8_SCHED __builtin_amdgcn_sched_barrier(0)
; template <class Epi, class Sched, bool ALIGN_EPI = false, bool SP2 = false>
; __device__ __forceinline__ void gemm_phase(PG8_LAS unsigned char* lds, const Gemm g, const Sched& S, const Epi& E, const int tid) {
;     ...
;         const bool has_next = S.next(ui + 1, nxt);
;         const char* nA = has_next ? (const char*)g.A + (size_t)nxt.pm * tstep : cA; const char* nB = has_next ? (const char*)g.Bt + (size_t)nxt.pn * tstep : cB;
;         for (int t = 0; t < nt; t += 2) {
;             const bool last = (t == nt - 2);
;             const char* a1 = cA + (size_t)(t + 1) * kstep;
;             const char* a2 = last ? nA : cA + (size_t)(t + 2) * kstep; const char* b2 = last ? nB : cB + (size_t)(t + 2) * kstep;
;             const char* a3 = a2 + kstep; const char* b3 = b2 + kstep;
;             if (last && has_next) S.a_ready(nxt);
;             if constexpr (SP2) {
;             PG8_LDB(B0, 0, 0); PG8_LDB(B1, 0, 1); PG8_SCHED; PG8_LDA(At, 0, 0); PG8_STAGE(PG8_SA(1, 1), a1 + hstep, voffA);
;             PG8_WAIT_V(8); PG8_WAIT_L(0); PG8_BAR; PG8_MMA(0, 0, At, B0); PG8_MMA(0, 1, At, B1); PG8_BAR; PG8_SCHED;
;             PG8_LDA(At, 0, 1); PG8_STAGE(PG8_SB(0, 0), b2, voffB); PG8_STAGE(PG8_SB(0, 1), b2 + hstep, voffB); PG8_STAGE(PG8_SA(0, 0), a2, voffA);
;             PG8_WAIT_V(8); PG8_WAIT_L(0); PG8_BAR; PG8_MMA(1, 0, At, B0); PG8_MMA(1, 1, At, B1); PG8_BAR; PG8_SCHED;
.LBB0_1548:
	s_ashr_i32 s17, s16, 31
	s_lshl_b64 s[18:19], s[16:17], 18
	s_add_u32 s18, s10, s18
	s_addc_u32 s19, s11, s19
	s_and_b64 s[20:21], s[4:5], exec
	s_cselect_b32 s17, s19, s25
	s_cselect_b32 s48, s18, s24
	s_ashr_i32 s15, s14, 31
	s_lshl_b64 s[20:21], s[14:15], 18
	s_add_u32 s20, s30, s20
	s_addc_u32 s21, s31, s21
	s_and_b64 s[28:29], s[4:5], exec
	s_cselect_b32 s15, s21, s27
	s_cselect_b32 s49, s20, s26
	s_add_u32 s24, s24, 0x20080
	s_addc_u32 s25, s25, 0
	s_add_u32 s50, s26, 0x100
	s_addc_u32 s51, s27, 0
	s_mov_b32 s52, -2
	s_add_i32 s53, 0, 0x10000
	s_add_i32 s62, 0, 0x14000
	v_add_u32_e32 v152, s53, v142
	v_add_u32_e32 v168, s62, v142
	ds_read_b128 v[138:141], v152
	ds_read_b128 v[144:147], v152 offset:1024
	ds_read_b128 v[148:151], v152 offset:2048
	ds_read_b128 v[152:155], v152 offset:3072
	ds_read_b128 v[156:159], v168
	ds_read_b128 v[160:163], v168 offset:1024
	ds_read_b128 v[164:167], v168 offset:2048
	ds_read_b128 v[168:171], v168 offset:3072
	v_lshl_add_u64 v[206:207], s[24:25], 0, v[134:135]
	s_add_i32 m0, s23, 0xc000
	ds_read_b128 v[172:175], v143
	ds_read_b128 v[176:179], v143 offset:1024
	ds_read_b128 v[180:183], v143 offset:2048
	ds_read_b128 v[184:187], v143 offset:3072
	ds_read_b128 v[188:191], v143 offset:4096
	ds_read_b128 v[192:195], v143 offset:5120
	ds_read_b128 v[196:199], v143 offset:6144
	ds_read_b128 v[200:203], v143 offset:7168
	s_add_u32 s26, s24, 0xfffe0080
	s_addc_u32 s27, s25, -1
	s_cmp_eq_u32 s52, 4
	s_cselect_b32 s29, s17, s27
	s_cselect_b32 s28, s48, s26
	s_cselect_b32 s27, s15, s51
	s_cselect_b32 s26, s49, s50
	global_load_lds_dwordx4 v[206:207], off
	v_lshl_add_u64 v[206:207], s[24:25], 0, v[136:137]
	s_add_i32 m0, s23, 0xe000
	s_nop 0
	global_load_lds_dwordx4 v[206:207], off
	s_waitcnt vmcnt(24)
	s_waitcnt lgkmcnt(0)
	s_setprio 1
	s_barrier
	v_mfma_f32_16x16x32_bf16 v[124:127], v[138:141], v[172:175], 0
	v_mfma_f32_16x16x32_bf16 v[120:123], v[148:151], v[172:175], 0
	v_mfma_f32_16x16x32_bf16 v[116:119], v[138:141], v[180:183], 0
	v_mfma_f32_16x16x32_bf16 v[108:111], v[148:151], v[180:183], 0
	v_mfma_f32_16x16x32_bf16 v[100:103], v[138:141], v[188:191], 0
	v_mfma_f32_16x16x32_bf16 v[92:95], v[148:151], v[188:191], 0
	v_mfma_f32_16x16x32_bf16 v[84:87], v[138:141], v[196:199], 0
	v_mfma_f32_16x16x32_bf16 v[76:79], v[148:151], v[196:199], 0
	v_mfma_f32_16x16x32_bf16 v[124:127], v[144:147], v[176:179], v[124:127]
	v_mfma_f32_16x16x32_bf16 v[120:123], v[152:155], v[176:179], v[120:123]
	v_mfma_f32_16x16x32_bf16 v[116:119], v[144:147], v[184:187], v[116:119]
	v_mfma_f32_16x16x32_bf16 v[108:111], v[152:155], v[184:187], v[108:111]
	v_mfma_f32_16x16x32_bf16 v[100:103], v[144:147], v[192:195], v[100:103]
	v_mfma_f32_16x16x32_bf16 v[92:95], v[152:155], v[192:195], v[92:95]
	v_mfma_f32_16x16x32_bf16 v[84:87], v[144:147], v[200:203], v[84:87]
	v_mfma_f32_16x16x32_bf16 v[76:79], v[152:155], v[200:203], v[76:79]
	s_setprio 0
	s_setprio 1
	v_mfma_f32_16x16x32_bf16 v[112:115], v[156:159], v[172:175], 0
	v_mfma_f32_16x16x32_bf16 v[104:107], v[164:167], v[172:175], 0
	v_mfma_f32_16x16x32_bf16 v[96:99], v[156:159], v[180:183], 0
	v_mfma_f32_16x16x32_bf16 v[88:91], v[164:167], v[180:183], 0
	v_mfma_f32_16x16x32_bf16 v[80:83], v[156:159], v[188:191], 0
	v_mfma_f32_16x16x32_bf16 v[72:75], v[164:167], v[188:191], 0
	v_mfma_f32_16x16x32_bf16 v[68:71], v[156:159], v[196:199], 0
	v_mfma_f32_16x16x32_bf16 v[64:67], v[164:167], v[196:199], 0
	v_mfma_f32_16x16x32_bf16 v[112:115], v[160:163], v[176:179], v[112:115]
	v_mfma_f32_16x16x32_bf16 v[104:107], v[168:171], v[176:179], v[104:107]
	v_mfma_f32_16x16x32_bf16 v[96:99], v[160:163], v[184:187], v[96:99]
	v_mfma_f32_16x16x32_bf16 v[88:91], v[168:171], v[184:187], v[88:91]
	v_mfma_f32_16x16x32_bf16 v[80:83], v[160:163], v[192:195], v[80:83]
	v_mfma_f32_16x16x32_bf16 v[72:75], v[168:171], v[192:195], v[72:75]
	v_mfma_f32_16x16x32_bf16 v[68:71], v[160:163], v[200:203], v[68:71]
	v_mfma_f32_16x16x32_bf16 v[64:67], v[168:171], v[200:203], v[64:67]
	s_barrier
	s_setprio 0
	s_add_i32 s53, s53, s33
	v_lshl_add_u64 v[206:207], s[26:27], 0, v[204:205]
	s_mov_b32 m0, s53
	ds_read_b128 v[172:175], v143 offset:16384
	ds_read_b128 v[176:179], v143 offset:17408
	ds_read_b128 v[180:183], v143 offset:18432
	ds_read_b128 v[184:187], v143 offset:19456
	ds_read_b128 v[188:191], v143 offset:20480
	ds_read_b128 v[192:195], v143 offset:21504
	ds_read_b128 v[196:199], v143 offset:22528
	ds_read_b128 v[200:203], v143 offset:23552
	global_load_lds_dwordx4 v[206:207], off
	s_add_i32 m0, s53, 0x2000
	s_add_u32 s54, s26, 0x20000
	v_lshl_add_u64 v[208:209], s[26:27], 0, v[128:129]
	s_addc_u32 s55, s27, 0
	s_add_i32 s53, s62, s33
	global_load_lds_dwordx4 v[208:209], off
	v_lshl_add_u64 v[210:211], s[54:55], 0, v[204:205]
	s_mov_b32 m0, s53
	v_lshl_add_u64 v[212:213], s[28:29], 0, v[130:131]
	global_load_lds_dwordx4 v[210:211], off
	v_lshl_add_u64 v[210:211], s[54:55], 0, v[128:129]
	s_add_i32 m0, s53, 0x2000
	s_nop 0
	global_load_lds_dwordx4 v[210:211], off
	v_lshl_add_u64 v[210:211], s[28:29], 0, v[132:133]
	s_mov_b32 m0, s23
	s_nop 0
	global_load_lds_dwordx4 v[210:211], off
	s_mov_b32 m0, s35
	s_nop 0
	global_load_lds_dwordx4 v[212:213], off
	s_waitcnt vmcnt(8)
	s_waitcnt lgkmcnt(0)
	s_setprio 1
	s_barrier
; #define PG8_STAGE(bufoff, gbase, voff) do { _Pragma("unroll") for (int _i = 0; _i < 2; ++_i) \
;         __builtin_amdgcn_global_load_lds((const unsigned*)((const char*)(gbase) + (voff)[_i]), (PG8_LAS unsigned*)(lds + (bufoff) + ldsw + _i * 8192), 16, 0, 0); } while (0)
; #define PG8_LDA(dst, b, h) do { _Pragma("unroll") for (int m = 0; m < 4; ++m) _Pragma("unroll") for (int k = 0; k < 2; ++k) dst[m][k] = *(const PG8_LAS bf16x8*)(lds + PG8_SA(b, h) + aoff + m * 2048 + k * 1024); } while (0)
; #define PG8_LDB(dst, b, h) do { _Pragma("unroll") for (int n = 0; n < 2; ++n) _Pragma("unroll") for (int k = 0; k < 2; ++k) dst[n][k] = *(const PG8_LAS bf16x8*)(lds + PG8_SB(b, h) + boff + n * 2048 + k * 1024); } while (0)
; #define PG8_MMA(ai, bj, At, Bt) do { __builtin_amdgcn_s_setprio(1); _Pragma("unroll") for (int m = 0; m < 4; ++m) _Pragma("unroll") for (int n = 0; n < 2; ++n) _Pragma("unroll") for (int k = 0; k < 2; ++k) \
;         acc[ai][bj][m][n] = __builtin_amdgcn_mfma_f32_16x16x32_bf16(Bt[n][k], At[m][k], acc[ai][bj][m][n], 0, 0, 0); __builtin_amdgcn_s_setprio(0); } while (0)
; #define PG8_WAIT_V(n) asm volatile("s_waitcnt vmcnt(" #n ")" ::: "memory")
; #define PG8_WAIT_L(n) asm volatile("s_waitcnt lgkmcnt(" #n ")" ::: "memory")
; #define PG8_BAR __builtin_amdgcn_s_barrier()
; #define PG8_SCHED __builtin_amdgcn_sched_barrier(0)
; template <class Epi, class Sched, bool ALIGN_EPI = false, bool SP2 = false>
; __device__ __forceinline__ void gemm_phase(PG8_LAS unsigned char* lds, const Gemm g, const Sched& S, const Epi& E, const int tid) {
;     ...
;             PG8_WAIT_V(8); PG8_WAIT_L(0); PG8_BAR; PG8_MMA(1, 0, At, B0); PG8_MMA(1, 1, At, B1); PG8_BAR; PG8_SCHED;
;             PG8_LDB(B0, 1, 0); PG8_LDB(B1, 1, 1); PG8_SCHED; PG8_LDA(At, 1, 0); PG8_STAGE(PG8_SA(0, 1), a2 + hstep, voffA);
;             PG8_WAIT_V(8); PG8_WAIT_L(0); PG8_BAR; PG8_MMA(0, 0, At, B0); PG8_MMA(0, 1, At, B1); PG8_BAR; PG8_SCHED;
	v_mfma_f32_16x16x32_bf16 v[60:63], v[138:141], v[172:175], 0
	v_mfma_f32_16x16x32_bf16 v[56:59], v[148:151], v[172:175], 0
	v_mfma_f32_16x16x32_bf16 v[52:55], v[138:141], v[180:183], 0
	v_mfma_f32_16x16x32_bf16 v[44:47], v[148:151], v[180:183], 0
	v_mfma_f32_16x16x32_bf16 v[36:39], v[138:141], v[188:191], 0
	v_mfma_f32_16x16x32_bf16 v[28:31], v[148:151], v[188:191], 0
	v_mfma_f32_16x16x32_bf16 v[20:23], v[138:141], v[196:199], 0
	v_mfma_f32_16x16x32_bf16 v[12:15], v[148:151], v[196:199], 0
	v_mfma_f32_16x16x32_bf16 v[60:63], v[144:147], v[176:179], v[60:63]
	v_mfma_f32_16x16x32_bf16 v[56:59], v[152:155], v[176:179], v[56:59]
	v_mfma_f32_16x16x32_bf16 v[52:55], v[144:147], v[184:187], v[52:55]
	v_mfma_f32_16x16x32_bf16 v[44:47], v[152:155], v[184:187], v[44:47]
	v_mfma_f32_16x16x32_bf16 v[36:39], v[144:147], v[192:195], v[36:39]
	v_mfma_f32_16x16x32_bf16 v[28:31], v[152:155], v[192:195], v[28:31]
	v_mfma_f32_16x16x32_bf16 v[20:23], v[144:147], v[200:203], v[20:23]
	v_mfma_f32_16x16x32_bf16 v[12:15], v[152:155], v[200:203], v[12:15]
	s_setprio 0
	s_setprio 1
	v_mfma_f32_16x16x32_bf16 v[48:51], v[156:159], v[172:175], 0
	v_mfma_f32_16x16x32_bf16 v[40:43], v[164:167], v[172:175], 0
	v_mfma_f32_16x16x32_bf16 v[32:35], v[156:159], v[180:183], 0
	v_mfma_f32_16x16x32_bf16 v[24:27], v[164:167], v[180:183], 0
	v_mfma_f32_16x16x32_bf16 v[16:19], v[156:159], v[188:191], 0
	v_mfma_f32_16x16x32_bf16 v[8:11], v[164:167], v[188:191], 0
	v_mfma_f32_16x16x32_bf16 v[4:7], v[156:159], v[196:199], 0
	v_mfma_f32_16x16x32_bf16 v[0:3], v[164:167], v[196:199], 0
	v_mfma_f32_16x16x32_bf16 v[48:51], v[160:163], v[176:179], v[48:51]
	v_mfma_f32_16x16x32_bf16 v[40:43], v[168:171], v[176:179], v[40:43]
	v_mfma_f32_16x16x32_bf16 v[32:35], v[160:163], v[184:187], v[32:35]
	v_mfma_f32_16x16x32_bf16 v[24:27], v[168:171], v[184:187], v[24:27]
	v_mfma_f32_16x16x32_bf16 v[16:19], v[160:163], v[192:195], v[16:19]
	v_mfma_f32_16x16x32_bf16 v[8:11], v[168:171], v[192:195], v[8:11]
	v_mfma_f32_16x16x32_bf16 v[4:7], v[160:163], v[200:203], v[4:7]
	v_mfma_f32_16x16x32_bf16 v[0:3], v[168:171], v[200:203], v[0:3]
	s_barrier
	s_setprio 0
	s_add_i32 s53, 0, 0x18000
	s_add_i32 s54, 0, 0x1c000
	v_add_u32_e32 v152, s53, v142
	v_add_u32_e32 v168, s54, v142
	ds_read_b128 v[138:141], v152
	ds_read_b128 v[144:147], v152 offset:1024
	ds_read_b128 v[148:151], v152 offset:2048
	ds_read_b128 v[152:155], v152 offset:3072
	ds_read_b128 v[156:159], v168
	ds_read_b128 v[160:163], v168 offset:1024
	ds_read_b128 v[164:167], v168 offset:2048
	ds_read_b128 v[168:171], v168 offset:3072
	s_add_u32 s28, s28, 0x20000
	s_addc_u32 s29, s29, 0
	s_mov_b32 m0, s36
	v_lshl_add_u64 v[214:215], s[28:29], 0, v[132:133]
	ds_read_b128 v[172:175], v143 offset:32768
	ds_read_b128 v[176:179], v143 offset:33792
	ds_read_b128 v[180:183], v143 offset:34816
	ds_read_b128 v[184:187], v143 offset:35840
	ds_read_b128 v[188:191], v143 offset:36864
	ds_read_b128 v[192:195], v143 offset:37888
	ds_read_b128 v[196:199], v143 offset:38912
	ds_read_b128 v[200:203], v143 offset:39936
	global_load_lds_dwordx4 v[214:215], off
	v_lshl_add_u64 v[214:215], s[28:29], 0, v[130:131]
	s_mov_b32 m0, s37
	s_nop 0
	global_load_lds_dwordx4 v[214:215], off
	s_waitcnt vmcnt(8)
	s_waitcnt lgkmcnt(0)
	s_setprio 1
	s_barrier
	v_mfma_f32_16x16x32_bf16 v[124:127], v[138:141], v[172:175], v[124:127]
	v_mfma_f32_16x16x32_bf16 v[120:123], v[148:151], v[172:175], v[120:123]
	v_mfma_f32_16x16x32_bf16 v[116:119], v[138:141], v[180:183], v[116:119]
	v_mfma_f32_16x16x32_bf16 v[108:111], v[148:151], v[180:183], v[108:111]
	v_mfma_f32_16x16x32_bf16 v[100:103], v[138:141], v[188:191], v[100:103]
	v_mfma_f32_16x16x32_bf16 v[92:95], v[148:151], v[188:191], v[92:95]
	v_mfma_f32_16x16x32_bf16 v[84:87], v[138:141], v[196:199], v[84:87]
	v_mfma_f32_16x16x32_bf16 v[76:79], v[148:151], v[196:199], v[76:79]
	v_mfma_f32_16x16x32_bf16 v[124:127], v[144:147], v[176:179], v[124:127]
	v_mfma_f32_16x16x32_bf16 v[120:123], v[152:155], v[176:179], v[120:123]
	v_mfma_f32_16x16x32_bf16 v[116:119], v[144:147], v[184:187], v[116:119]
	v_mfma_f32_16x16x32_bf16 v[108:111], v[152:155], v[184:187], v[108:111]
	v_mfma_f32_16x16x32_bf16 v[100:103], v[144:147], v[192:195], v[100:103]
	v_mfma_f32_16x16x32_bf16 v[92:95], v[152:155], v[192:195], v[92:95]
	v_mfma_f32_16x16x32_bf16 v[84:87], v[144:147], v[200:203], v[84:87]
	v_mfma_f32_16x16x32_bf16 v[76:79], v[152:155], v[200:203], v[76:79]
	s_setprio 0
	s_setprio 1
	v_mfma_f32_16x16x32_bf16 v[112:115], v[156:159], v[172:175], v[112:115]
	v_mfma_f32_16x16x32_bf16 v[104:107], v[164:167], v[172:175], v[104:107]
	v_mfma_f32_16x16x32_bf16 v[96:99], v[156:159], v[180:183], v[96:99]
	v_mfma_f32_16x16x32_bf16 v[88:91], v[164:167], v[180:183], v[88:91]
	v_mfma_f32_16x16x32_bf16 v[80:83], v[156:159], v[188:191], v[80:83]
	v_mfma_f32_16x16x32_bf16 v[72:75], v[164:167], v[188:191], v[72:75]
	v_mfma_f32_16x16x32_bf16 v[68:71], v[156:159], v[196:199], v[68:71]
	v_mfma_f32_16x16x32_bf16 v[64:67], v[164:167], v[196:199], v[64:67]
	v_mfma_f32_16x16x32_bf16 v[112:115], v[160:163], v[176:179], v[112:115]
	v_mfma_f32_16x16x32_bf16 v[104:107], v[168:171], v[176:179], v[104:107]
	v_mfma_f32_16x16x32_bf16 v[96:99], v[160:163], v[184:187], v[96:99]
	v_mfma_f32_16x16x32_bf16 v[88:91], v[168:171], v[184:187], v[88:91]
	v_mfma_f32_16x16x32_bf16 v[80:83], v[160:163], v[192:195], v[80:83]
	v_mfma_f32_16x16x32_bf16 v[72:75], v[168:171], v[192:195], v[72:75]
	v_mfma_f32_16x16x32_bf16 v[68:71], v[160:163], v[200:203], v[68:71]
	v_mfma_f32_16x16x32_bf16 v[64:67], v[168:171], v[200:203], v[64:67]
	s_barrier
; #define PG8_STAGE(bufoff, gbase, voff) do { _Pragma("unroll") for (int _i = 0; _i < 2; ++_i) \
;         __builtin_amdgcn_global_load_lds((const unsigned*)((const char*)(gbase) + (voff)[_i]), (PG8_LAS unsigned*)(lds + (bufoff) + ldsw + _i * 8192), 16, 0, 0); } while (0)
; #define PG8_LDA(dst, b, h) do { _Pragma("unroll") for (int m = 0; m < 4; ++m) _Pragma("unroll") for (int k = 0; k < 2; ++k) dst[m][k] = *(const PG8_LAS bf16x8*)(lds + PG8_SA(b, h) + aoff + m * 2048 + k * 1024); } while (0)
; #define PG8_WAIT_V(n) asm volatile("s_waitcnt vmcnt(" #n ")" ::: "memory")
; #define PG8_WAIT_L(n) asm volatile("s_waitcnt lgkmcnt(" #n ")" ::: "memory")
; #define PG8_BAR __builtin_amdgcn_s_barrier()
; template <class Epi, class Sched, bool ALIGN_EPI = false, bool SP2 = false>
; __device__ __forceinline__ void gemm_phase(PG8_LAS unsigned char* lds, const Gemm g, const Sched& S, const Epi& E, const int tid) {
;     ...
;         for (int t = 0; t < nt; t += 2) {
;             const bool last = (t == nt - 2);
;             const char* a1 = cA + (size_t)(t + 1) * kstep;
;             const char* a2 = last ? nA : cA + (size_t)(t + 2) * kstep; const char* b2 = last ? nB : cB + (size_t)(t + 2) * kstep;
;             const char* a3 = a2 + kstep; const char* b3 = b2 + kstep;
;             if (last && has_next) S.a_ready(nxt);
;             if constexpr (SP2) {
;             PG8_LDB(B0, 0, 0); PG8_LDB(B1, 0, 1); PG8_SCHED; PG8_LDA(At, 0, 0); PG8_STAGE(PG8_SA(1, 1), a1 + hstep, voffA);
;             PG8_WAIT_V(8); PG8_WAIT_L(0); PG8_BAR; PG8_MMA(0, 0, At, B0); PG8_MMA(0, 1, At, B1); PG8_BAR; PG8_SCHED;
;             PG8_LDA(At, 0, 1); PG8_STAGE(PG8_SB(0, 0), b2, voffB); PG8_STAGE(PG8_SB(0, 1), b2 + hstep, voffB); PG8_STAGE(PG8_SA(0, 0), a2, voffA);
;             PG8_WAIT_V(8); PG8_WAIT_L(0); PG8_BAR; PG8_MMA(1, 0, At, B0); PG8_MMA(1, 1, At, B1); PG8_BAR; PG8_SCHED;
;             PG8_LDB(B0, 1, 0); PG8_LDB(B1, 1, 1); PG8_SCHED; PG8_LDA(At, 1, 0); PG8_STAGE(PG8_SA(0, 1), a2 + hstep, voffA);
;             PG8_WAIT_V(8); PG8_WAIT_L(0); PG8_BAR; PG8_MMA(0, 0, At, B0); PG8_MMA(0, 1, At, B1); PG8_BAR; PG8_SCHED;
;             PG8_LDA(At, 1, 1); PG8_STAGE(PG8_SB(1, 0), b3, voffB); PG8_STAGE(PG8_SB(1, 1), b3 + hstep, voffB); PG8_STAGE(PG8_SA(1, 0), a3, voffA);
;             PG8_WAIT_V(8); PG8_WAIT_L(0); PG8_BAR; PG8_MMA(1, 0, At, B0); PG8_MMA(1, 1, At, B1); PG8_BAR; PG8_SCHED;
	s_setprio 0
	s_add_i32 s28, s53, s33
	v_lshl_add_u64 v[206:207], v[206:207], 0, s[70:71]
	s_mov_b32 m0, s28
	ds_read_b128 v[172:175], v143 offset:49152
	ds_read_b128 v[176:179], v143 offset:50176
	ds_read_b128 v[180:183], v143 offset:51200
	ds_read_b128 v[184:187], v143 offset:52224
	ds_read_b128 v[188:191], v143 offset:53248
	ds_read_b128 v[192:195], v143 offset:54272
	ds_read_b128 v[196:199], v143 offset:55296
	ds_read_b128 v[200:203], v143 offset:56320
	global_load_lds_dwordx4 v[206:207], off
	s_add_i32 m0, s28, 0x2000
	s_add_u32 s26, s26, 0x20080
	v_lshl_add_u64 v[206:207], v[208:209], 0, s[70:71]
	s_addc_u32 s27, s27, 0
	s_add_i32 s28, s54, s33
	global_load_lds_dwordx4 v[206:207], off
	v_lshl_add_u64 v[206:207], s[26:27], 0, v[204:205]
	s_mov_b32 m0, s28
	s_nop 0
	global_load_lds_dwordx4 v[206:207], off
	v_lshl_add_u64 v[206:207], s[26:27], 0, v[128:129]
	s_add_i32 m0, s28, 0x2000
	s_nop 0
	global_load_lds_dwordx4 v[206:207], off
	v_lshl_add_u64 v[206:207], v[210:211], 0, s[70:71]
	s_mov_b32 m0, s43
	s_nop 0
	global_load_lds_dwordx4 v[206:207], off
	v_lshl_add_u64 v[206:207], v[212:213], 0, s[70:71]
	s_mov_b32 m0, s44
	s_nop 0
	global_load_lds_dwordx4 v[206:207], off
	s_add_i32 s52, s52, 2
	s_add_u32 s24, s24, 0x100
	s_addc_u32 s25, s25, 0
	s_add_u32 s50, s50, 0x100
	s_addc_u32 s51, s51, 0
	s_waitcnt vmcnt(8)
	s_waitcnt lgkmcnt(0)
	s_setprio 1
	s_barrier
	v_mfma_f32_16x16x32_bf16 v[60:63], v[138:141], v[172:175], v[60:63]
	v_mfma_f32_16x16x32_bf16 v[56:59], v[148:151], v[172:175], v[56:59]
	v_mfma_f32_16x16x32_bf16 v[52:55], v[138:141], v[180:183], v[52:55]
	v_mfma_f32_16x16x32_bf16 v[44:47], v[148:151], v[180:183], v[44:47]
	v_mfma_f32_16x16x32_bf16 v[36:39], v[138:141], v[188:191], v[36:39]
	v_mfma_f32_16x16x32_bf16 v[28:31], v[148:151], v[188:191], v[28:31]
	v_mfma_f32_16x16x32_bf16 v[20:23], v[138:141], v[196:199], v[20:23]
	v_mfma_f32_16x16x32_bf16 v[12:15], v[148:151], v[196:199], v[12:15]
	v_mfma_f32_16x16x32_bf16 v[60:63], v[144:147], v[176:179], v[60:63]
	v_mfma_f32_16x16x32_bf16 v[56:59], v[152:155], v[176:179], v[56:59]
	v_mfma_f32_16x16x32_bf16 v[52:55], v[144:147], v[184:187], v[52:55]
	v_mfma_f32_16x16x32_bf16 v[44:47], v[152:155], v[184:187], v[44:47]
	v_mfma_f32_16x16x32_bf16 v[36:39], v[144:147], v[192:195], v[36:39]
	v_mfma_f32_16x16x32_bf16 v[28:31], v[152:155], v[192:195], v[28:31]
	v_mfma_f32_16x16x32_bf16 v[20:23], v[144:147], v[200:203], v[20:23]
	v_mfma_f32_16x16x32_bf16 v[12:15], v[152:155], v[200:203], v[12:15]
	s_setprio 0
	s_setprio 1
	v_mfma_f32_16x16x32_bf16 v[48:51], v[156:159], v[172:175], v[48:51]
	v_mfma_f32_16x16x32_bf16 v[40:43], v[164:167], v[172:175], v[40:43]
	v_mfma_f32_16x16x32_bf16 v[32:35], v[156:159], v[180:183], v[32:35]
	v_mfma_f32_16x16x32_bf16 v[24:27], v[164:167], v[180:183], v[24:27]
	v_mfma_f32_16x16x32_bf16 v[16:19], v[156:159], v[188:191], v[16:19]
	v_mfma_f32_16x16x32_bf16 v[8:11], v[164:167], v[188:191], v[8:11]
	v_mfma_f32_16x16x32_bf16 v[4:7], v[156:159], v[196:199], v[4:7]
	v_mfma_f32_16x16x32_bf16 v[0:3], v[164:167], v[196:199], v[0:3]
	v_mfma_f32_16x16x32_bf16 v[48:51], v[160:163], v[176:179], v[48:51]
	v_mfma_f32_16x16x32_bf16 v[40:43], v[168:171], v[176:179], v[40:43]
	v_mfma_f32_16x16x32_bf16 v[32:35], v[160:163], v[184:187], v[32:35]
	v_mfma_f32_16x16x32_bf16 v[24:27], v[168:171], v[184:187], v[24:27]
	v_mfma_f32_16x16x32_bf16 v[16:19], v[160:163], v[192:195], v[16:19]
	v_mfma_f32_16x16x32_bf16 v[8:11], v[168:171], v[192:195], v[8:11]
	v_mfma_f32_16x16x32_bf16 v[4:7], v[160:163], v[200:203], v[4:7]
	v_mfma_f32_16x16x32_bf16 v[0:3], v[168:171], v[200:203], v[0:3]
	s_barrier
	s_setprio 0
.LBB0_1549:
	s_add_i32 s53, 0, 0x10000
	s_add_i32 s62, 0, 0x14000
	v_add_u32_e32 v152, s53, v142
	v_add_u32_e32 v168, s62, v142
	ds_read_b128 v[138:141], v152
	ds_read_b128 v[144:147], v152 offset:1024
	ds_read_b128 v[148:151], v152 offset:2048
	ds_read_b128 v[152:155], v152 offset:3072
	ds_read_b128 v[156:159], v168
	ds_read_b128 v[160:163], v168 offset:1024
	ds_read_b128 v[164:167], v168 offset:2048
	ds_read_b128 v[168:171], v168 offset:3072
	v_lshl_add_u64 v[206:207], s[24:25], 0, v[134:135]
	s_add_i32 m0, s23, 0xc000
	ds_read_b128 v[172:175], v143
	ds_read_b128 v[176:179], v143 offset:1024
	ds_read_b128 v[180:183], v143 offset:2048
	ds_read_b128 v[184:187], v143 offset:3072
	ds_read_b128 v[188:191], v143 offset:4096
	ds_read_b128 v[192:195], v143 offset:5120
	ds_read_b128 v[196:199], v143 offset:6144
	ds_read_b128 v[200:203], v143 offset:7168
	s_add_u32 s26, s24, 0xfffe0080
	s_addc_u32 s27, s25, -1
	s_cmp_eq_u32 s52, 4
	s_cselect_b32 s29, s17, s27
	s_cselect_b32 s28, s48, s26
	s_cselect_b32 s27, s15, s51
	s_cselect_b32 s26, s49, s50
	global_load_lds_dwordx4 v[206:207], off
	v_lshl_add_u64 v[206:207], s[24:25], 0, v[136:137]
	s_add_i32 m0, s23, 0xe000
	s_nop 0
	global_load_lds_dwordx4 v[206:207], off
	s_waitcnt vmcnt(8)
	s_waitcnt lgkmcnt(0)
	s_setprio 1
	s_barrier
; #define PG8_STAGE(bufoff, gbase, voff) do { _Pragma("unroll") for (int _i = 0; _i < 2; ++_i) \
;         __builtin_amdgcn_global_load_lds((const unsigned*)((const char*)(gbase) + (voff)[_i]), (PG8_LAS unsigned*)(lds + (bufoff) + ldsw + _i * 8192), 16, 0, 0); } while (0)
; #define PG8_LDA(dst, b, h) do { _Pragma("unroll") for (int m = 0; m < 4; ++m) _Pragma("unroll") for (int k = 0; k < 2; ++k) dst[m][k] = *(const PG8_LAS bf16x8*)(lds + PG8_SA(b, h) + aoff + m * 2048 + k * 1024); } while (0)
; #define PG8_MMA(ai, bj, At, Bt) do { __builtin_amdgcn_s_setprio(1); _Pragma("unroll") for (int m = 0; m < 4; ++m) _Pragma("unroll") for (int n = 0; n < 2; ++n) _Pragma("unroll") for (int k = 0; k < 2; ++k) \
;         acc[ai][bj][m][n] = __builtin_amdgcn_mfma_f32_16x16x32_bf16(Bt[n][k], At[m][k], acc[ai][bj][m][n], 0, 0, 0); __builtin_amdgcn_s_setprio(0); } while (0)
; #define PG8_WAIT_V(n) asm volatile("s_waitcnt vmcnt(" #n ")" ::: "memory")
; #define PG8_WAIT_L(n) asm volatile("s_waitcnt lgkmcnt(" #n ")" ::: "memory")
; #define PG8_BAR __builtin_amdgcn_s_barrier()
; #define PG8_SCHED __builtin_amdgcn_sched_barrier(0)
; template <class Epi, class Sched, bool ALIGN_EPI = false, bool SP2 = false>
; __device__ __forceinline__ void gemm_phase(PG8_LAS unsigned char* lds, const Gemm g, const Sched& S, const Epi& E, const int tid) {
;     ...
;             PG8_WAIT_V(8); PG8_WAIT_L(0); PG8_BAR; PG8_MMA(0, 0, At, B0); PG8_MMA(0, 1, At, B1); PG8_BAR; PG8_SCHED;
;             PG8_LDA(At, 0, 1); PG8_STAGE(PG8_SB(0, 0), b2, voffB); PG8_STAGE(PG8_SB(0, 1), b2 + hstep, voffB); PG8_STAGE(PG8_SA(0, 0), a2, voffA);
;             PG8_WAIT_V(8); PG8_WAIT_L(0); PG8_BAR; PG8_MMA(1, 0, At, B0); PG8_MMA(1, 1, At, B1); PG8_BAR; PG8_SCHED;
	v_mfma_f32_16x16x32_bf16 v[124:127], v[138:141], v[172:175], v[124:127]
	v_mfma_f32_16x16x32_bf16 v[120:123], v[148:151], v[172:175], v[120:123]
	v_mfma_f32_16x16x32_bf16 v[116:119], v[138:141], v[180:183], v[116:119]
	v_mfma_f32_16x16x32_bf16 v[108:111], v[148:151], v[180:183], v[108:111]
	v_mfma_f32_16x16x32_bf16 v[100:103], v[138:141], v[188:191], v[100:103]
	v_mfma_f32_16x16x32_bf16 v[92:95], v[148:151], v[188:191], v[92:95]
	v_mfma_f32_16x16x32_bf16 v[84:87], v[138:141], v[196:199], v[84:87]
	v_mfma_f32_16x16x32_bf16 v[76:79], v[148:151], v[196:199], v[76:79]
	v_mfma_f32_16x16x32_bf16 v[124:127], v[144:147], v[176:179], v[124:127]
	v_mfma_f32_16x16x32_bf16 v[120:123], v[152:155], v[176:179], v[120:123]
	v_mfma_f32_16x16x32_bf16 v[116:119], v[144:147], v[184:187], v[116:119]
	v_mfma_f32_16x16x32_bf16 v[108:111], v[152:155], v[184:187], v[108:111]
	v_mfma_f32_16x16x32_bf16 v[100:103], v[144:147], v[192:195], v[100:103]
	v_mfma_f32_16x16x32_bf16 v[92:95], v[152:155], v[192:195], v[92:95]
	v_mfma_f32_16x16x32_bf16 v[84:87], v[144:147], v[200:203], v[84:87]
	v_mfma_f32_16x16x32_bf16 v[76:79], v[152:155], v[200:203], v[76:79]
	s_setprio 0
	s_setprio 1
	v_mfma_f32_16x16x32_bf16 v[112:115], v[156:159], v[172:175], v[112:115]
	v_mfma_f32_16x16x32_bf16 v[104:107], v[164:167], v[172:175], v[104:107]
	v_mfma_f32_16x16x32_bf16 v[96:99], v[156:159], v[180:183], v[96:99]
	v_mfma_f32_16x16x32_bf16 v[88:91], v[164:167], v[180:183], v[88:91]
	v_mfma_f32_16x16x32_bf16 v[80:83], v[156:159], v[188:191], v[80:83]
	v_mfma_f32_16x16x32_bf16 v[72:75], v[164:167], v[188:191], v[72:75]
	v_mfma_f32_16x16x32_bf16 v[68:71], v[156:159], v[196:199], v[68:71]
	v_mfma_f32_16x16x32_bf16 v[64:67], v[164:167], v[196:199], v[64:67]
	v_mfma_f32_16x16x32_bf16 v[112:115], v[160:163], v[176:179], v[112:115]
	v_mfma_f32_16x16x32_bf16 v[104:107], v[168:171], v[176:179], v[104:107]
	v_mfma_f32_16x16x32_bf16 v[96:99], v[160:163], v[184:187], v[96:99]
	v_mfma_f32_16x16x32_bf16 v[88:91], v[168:171], v[184:187], v[88:91]
	v_mfma_f32_16x16x32_bf16 v[80:83], v[160:163], v[192:195], v[80:83]
	v_mfma_f32_16x16x32_bf16 v[72:75], v[168:171], v[192:195], v[72:75]
	v_mfma_f32_16x16x32_bf16 v[68:71], v[160:163], v[200:203], v[68:71]
	v_mfma_f32_16x16x32_bf16 v[64:67], v[168:171], v[200:203], v[64:67]
	s_barrier
	s_setprio 0
	s_add_i32 s53, s53, s33
	v_lshl_add_u64 v[206:207], s[26:27], 0, v[204:205]
	s_mov_b32 m0, s53
	ds_read_b128 v[172:175], v143 offset:16384
	ds_read_b128 v[176:179], v143 offset:17408
	ds_read_b128 v[180:183], v143 offset:18432
	ds_read_b128 v[184:187], v143 offset:19456
	ds_read_b128 v[188:191], v143 offset:20480
	ds_read_b128 v[192:195], v143 offset:21504
	ds_read_b128 v[196:199], v143 offset:22528
	ds_read_b128 v[200:203], v143 offset:23552
	global_load_lds_dwordx4 v[206:207], off
	s_add_i32 m0, s53, 0x2000
	s_add_u32 s54, s26, 0x20000
	v_lshl_add_u64 v[208:209], s[26:27], 0, v[128:129]
	s_addc_u32 s55, s27, 0
	s_add_i32 s53, s62, s33
	global_load_lds_dwordx4 v[208:209], off
	v_lshl_add_u64 v[210:211], s[54:55], 0, v[204:205]
	s_mov_b32 m0, s53
	v_lshl_add_u64 v[212:213], s[28:29], 0, v[130:131]
	global_load_lds_dwordx4 v[210:211], off
	v_lshl_add_u64 v[210:211], s[54:55], 0, v[128:129]
	s_add_i32 m0, s53, 0x2000
	s_nop 0
	global_load_lds_dwordx4 v[210:211], off
	v_lshl_add_u64 v[210:211], s[28:29], 0, v[132:133]
	s_mov_b32 m0, s23
	s_nop 0
	global_load_lds_dwordx4 v[210:211], off
	s_mov_b32 m0, s35
	s_nop 0
	global_load_lds_dwordx4 v[212:213], off
	s_waitcnt vmcnt(8)
	s_waitcnt lgkmcnt(0)
	s_setprio 1
	s_barrier
	v_mfma_f32_16x16x32_bf16 v[60:63], v[138:141], v[172:175], v[60:63]
	v_mfma_f32_16x16x32_bf16 v[56:59], v[148:151], v[172:175], v[56:59]
	v_mfma_f32_16x16x32_bf16 v[52:55], v[138:141], v[180:183], v[52:55]
	v_mfma_f32_16x16x32_bf16 v[44:47], v[148:151], v[180:183], v[44:47]
	v_mfma_f32_16x16x32_bf16 v[36:39], v[138:141], v[188:191], v[36:39]
	v_mfma_f32_16x16x32_bf16 v[28:31], v[148:151], v[188:191], v[28:31]
	v_mfma_f32_16x16x32_bf16 v[20:23], v[138:141], v[196:199], v[20:23]
	v_mfma_f32_16x16x32_bf16 v[12:15], v[148:151], v[196:199], v[12:15]
	v_mfma_f32_16x16x32_bf16 v[60:63], v[144:147], v[176:179], v[60:63]
	v_mfma_f32_16x16x32_bf16 v[56:59], v[152:155], v[176:179], v[56:59]
	v_mfma_f32_16x16x32_bf16 v[52:55], v[144:147], v[184:187], v[52:55]
	v_mfma_f32_16x16x32_bf16 v[44:47], v[152:155], v[184:187], v[44:47]
	v_mfma_f32_16x16x32_bf16 v[36:39], v[144:147], v[192:195], v[36:39]
	v_mfma_f32_16x16x32_bf16 v[28:31], v[152:155], v[192:195], v[28:31]
	v_mfma_f32_16x16x32_bf16 v[20:23], v[144:147], v[200:203], v[20:23]
	v_mfma_f32_16x16x32_bf16 v[12:15], v[152:155], v[200:203], v[12:15]
	s_setprio 0
	s_setprio 1
	v_mfma_f32_16x16x32_bf16 v[48:51], v[156:159], v[172:175], v[48:51]
	v_mfma_f32_16x16x32_bf16 v[40:43], v[164:167], v[172:175], v[40:43]
	v_mfma_f32_16x16x32_bf16 v[32:35], v[156:159], v[180:183], v[32:35]
	v_mfma_f32_16x16x32_bf16 v[24:27], v[164:167], v[180:183], v[24:27]
	v_mfma_f32_16x16x32_bf16 v[16:19], v[156:159], v[188:191], v[16:19]
	v_mfma_f32_16x16x32_bf16 v[8:11], v[164:167], v[188:191], v[8:11]
	v_mfma_f32_16x16x32_bf16 v[4:7], v[156:159], v[196:199], v[4:7]
	v_mfma_f32_16x16x32_bf16 v[0:3], v[164:167], v[196:199], v[0:3]
	v_mfma_f32_16x16x32_bf16 v[48:51], v[160:163], v[176:179], v[48:51]
	v_mfma_f32_16x16x32_bf16 v[40:43], v[168:171], v[176:179], v[40:43]
	v_mfma_f32_16x16x32_bf16 v[32:35], v[160:163], v[184:187], v[32:35]
	v_mfma_f32_16x16x32_bf16 v[24:27], v[168:171], v[184:187], v[24:27]
	v_mfma_f32_16x16x32_bf16 v[16:19], v[160:163], v[192:195], v[16:19]
	v_mfma_f32_16x16x32_bf16 v[8:11], v[168:171], v[192:195], v[8:11]
	v_mfma_f32_16x16x32_bf16 v[4:7], v[160:163], v[200:203], v[4:7]
	v_mfma_f32_16x16x32_bf16 v[0:3], v[168:171], v[200:203], v[0:3]
	s_barrier
; #define PG8_STAGE(bufoff, gbase, voff) do { _Pragma("unroll") for (int _i = 0; _i < 2; ++_i) \
;         __builtin_amdgcn_global_load_lds((const unsigned*)((const char*)(gbase) + (voff)[_i]), (PG8_LAS unsigned*)(lds + (bufoff) + ldsw + _i * 8192), 16, 0, 0); } while (0)
; #define PG8_LDA(dst, b, h) do { _Pragma("unroll") for (int m = 0; m < 4; ++m) _Pragma("unroll") for (int k = 0; k < 2; ++k) dst[m][k] = *(const PG8_LAS bf16x8*)(lds + PG8_SA(b, h) + aoff + m * 2048 + k * 1024); } while (0)
; #define PG8_LDB(dst, b, h) do { _Pragma("unroll") for (int n = 0; n < 2; ++n) _Pragma("unroll") for (int k = 0; k < 2; ++k) dst[n][k] = *(const PG8_LAS bf16x8*)(lds + PG8_SB(b, h) + boff + n * 2048 + k * 1024); } while (0)
; #define PG8_MMA(ai, bj, At, Bt) do { __builtin_amdgcn_s_setprio(1); _Pragma("unroll") for (int m = 0; m < 4; ++m) _Pragma("unroll") for (int n = 0; n < 2; ++n) _Pragma("unroll") for (int k = 0; k < 2; ++k) \
;         acc[ai][bj][m][n] = __builtin_amdgcn_mfma_f32_16x16x32_bf16(Bt[n][k], At[m][k], acc[ai][bj][m][n], 0, 0, 0); __builtin_amdgcn_s_setprio(0); } while (0)
; #define PG8_WAIT_V(n) asm volatile("s_waitcnt vmcnt(" #n ")" ::: "memory")
; #define PG8_WAIT_L(n) asm volatile("s_waitcnt lgkmcnt(" #n ")" ::: "memory")
; #define PG8_BAR __builtin_amdgcn_s_barrier()
; #define PG8_SCHED __builtin_amdgcn_sched_barrier(0)
; template <class Epi, class Sched, bool ALIGN_EPI = false, bool SP2 = false>
; __device__ __forceinline__ void gemm_phase(PG8_LAS unsigned char* lds, const Gemm g, const Sched& S, const Epi& E, const int tid) {
;     ...
;             PG8_LDB(B0, 1, 0); PG8_LDB(B1, 1, 1); PG8_SCHED; PG8_LDA(At, 1, 0); PG8_STAGE(PG8_SA(0, 1), a2 + hstep, voffA);
;             PG8_WAIT_V(8); PG8_WAIT_L(0); PG8_BAR; PG8_MMA(0, 0, At, B0); PG8_MMA(0, 1, At, B1); PG8_BAR; PG8_SCHED;
	s_setprio 0
	s_add_i32 s53, 0, 0x18000
	s_add_i32 s54, 0, 0x1c000
	v_add_u32_e32 v152, s53, v142
	v_add_u32_e32 v168, s54, v142
	ds_read_b128 v[138:141], v152
	ds_read_b128 v[144:147], v152 offset:1024
	ds_read_b128 v[148:151], v152 offset:2048
	ds_read_b128 v[152:155], v152 offset:3072
	ds_read_b128 v[156:159], v168
	ds_read_b128 v[160:163], v168 offset:1024
	ds_read_b128 v[164:167], v168 offset:2048
	ds_read_b128 v[168:171], v168 offset:3072
	s_add_u32 s28, s28, 0x20000
	s_addc_u32 s29, s29, 0
	s_mov_b32 m0, s36
	v_lshl_add_u64 v[214:215], s[28:29], 0, v[132:133]
	ds_read_b128 v[172:175], v143 offset:32768
	ds_read_b128 v[176:179], v143 offset:33792
	ds_read_b128 v[180:183], v143 offset:34816
	ds_read_b128 v[184:187], v143 offset:35840
	ds_read_b128 v[188:191], v143 offset:36864
	ds_read_b128 v[192:195], v143 offset:37888
	ds_read_b128 v[196:199], v143 offset:38912
	ds_read_b128 v[200:203], v143 offset:39936
	global_load_lds_dwordx4 v[214:215], off
	v_lshl_add_u64 v[214:215], s[28:29], 0, v[130:131]
	s_mov_b32 m0, s37
	s_nop 0
	global_load_lds_dwordx4 v[214:215], off
	s_waitcnt vmcnt(8)
	s_waitcnt lgkmcnt(0)
	s_setprio 1
	s_barrier
	v_mfma_f32_16x16x32_bf16 v[124:127], v[138:141], v[172:175], v[124:127]
	v_mfma_f32_16x16x32_bf16 v[120:123], v[148:151], v[172:175], v[120:123]
	v_mfma_f32_16x16x32_bf16 v[116:119], v[138:141], v[180:183], v[116:119]
	v_mfma_f32_16x16x32_bf16 v[108:111], v[148:151], v[180:183], v[108:111]
	v_mfma_f32_16x16x32_bf16 v[100:103], v[138:141], v[188:191], v[100:103]
	v_mfma_f32_16x16x32_bf16 v[92:95], v[148:151], v[188:191], v[92:95]
	v_mfma_f32_16x16x32_bf16 v[84:87], v[138:141], v[196:199], v[84:87]
	v_mfma_f32_16x16x32_bf16 v[76:79], v[148:151], v[196:199], v[76:79]
	v_mfma_f32_16x16x32_bf16 v[124:127], v[144:147], v[176:179], v[124:127]
	v_mfma_f32_16x16x32_bf16 v[120:123], v[152:155], v[176:179], v[120:123]
	v_mfma_f32_16x16x32_bf16 v[116:119], v[144:147], v[184:187], v[116:119]
	v_mfma_f32_16x16x32_bf16 v[108:111], v[152:155], v[184:187], v[108:111]
	v_mfma_f32_16x16x32_bf16 v[100:103], v[144:147], v[192:195], v[100:103]
	v_mfma_f32_16x16x32_bf16 v[92:95], v[152:155], v[192:195], v[92:95]
	v_mfma_f32_16x16x32_bf16 v[84:87], v[144:147], v[200:203], v[84:87]
	v_mfma_f32_16x16x32_bf16 v[76:79], v[152:155], v[200:203], v[76:79]
	s_setprio 0
	s_setprio 1
	v_mfma_f32_16x16x32_bf16 v[112:115], v[156:159], v[172:175], v[112:115]
	v_mfma_f32_16x16x32_bf16 v[104:107], v[164:167], v[172:175], v[104:107]
	v_mfma_f32_16x16x32_bf16 v[96:99], v[156:159], v[180:183], v[96:99]
	v_mfma_f32_16x16x32_bf16 v[88:91], v[164:167], v[180:183], v[88:91]
	v_mfma_f32_16x16x32_bf16 v[80:83], v[156:159], v[188:191], v[80:83]
	v_mfma_f32_16x16x32_bf16 v[72:75], v[164:167], v[188:191], v[72:75]
	v_mfma_f32_16x16x32_bf16 v[68:71], v[156:159], v[196:199], v[68:71]
	v_mfma_f32_16x16x32_bf16 v[64:67], v[164:167], v[196:199], v[64:67]
	v_mfma_f32_16x16x32_bf16 v[112:115], v[160:163], v[176:179], v[112:115]
	v_mfma_f32_16x16x32_bf16 v[104:107], v[168:171], v[176:179], v[104:107]
	v_mfma_f32_16x16x32_bf16 v[96:99], v[160:163], v[184:187], v[96:99]
	v_mfma_f32_16x16x32_bf16 v[88:91], v[168:171], v[184:187], v[88:91]
	v_mfma_f32_16x16x32_bf16 v[80:83], v[160:163], v[192:195], v[80:83]
	v_mfma_f32_16x16x32_bf16 v[72:75], v[168:171], v[192:195], v[72:75]
	v_mfma_f32_16x16x32_bf16 v[68:71], v[160:163], v[200:203], v[68:71]
	v_mfma_f32_16x16x32_bf16 v[64:67], v[168:171], v[200:203], v[64:67]
	s_barrier
; #define PG8_STAGE(bufoff, gbase, voff) do { _Pragma("unroll") for (int _i = 0; _i < 2; ++_i) \
;         __builtin_amdgcn_global_load_lds((const unsigned*)((const char*)(gbase) + (voff)[_i]), (PG8_LAS unsigned*)(lds + (bufoff) + ldsw + _i * 8192), 16, 0, 0); } while (0)
; #define PG8_LDA(dst, b, h) do { _Pragma("unroll") for (int m = 0; m < 4; ++m) _Pragma("unroll") for (int k = 0; k < 2; ++k) dst[m][k] = *(const PG8_LAS bf16x8*)(lds + PG8_SA(b, h) + aoff + m * 2048 + k * 1024); } while (0)
; #define PG8_MMA(ai, bj, At, Bt) do { __builtin_amdgcn_s_setprio(1); _Pragma("unroll") for (int m = 0; m < 4; ++m) _Pragma("unroll") for (int n = 0; n < 2; ++n) _Pragma("unroll") for (int k = 0; k < 2; ++k) \
;         acc[ai][bj][m][n] = __builtin_amdgcn_mfma_f32_16x16x32_bf16(Bt[n][k], At[m][k], acc[ai][bj][m][n], 0, 0, 0); __builtin_amdgcn_s_setprio(0); } while (0)
; #define PG8_WAIT_V(n) asm volatile("s_waitcnt vmcnt(" #n ")" ::: "memory")
; #define PG8_WAIT_L(n) asm volatile("s_waitcnt lgkmcnt(" #n ")" ::: "memory")
; #define PG8_BAR __builtin_amdgcn_s_barrier()
; #define PG8_SCHED __builtin_amdgcn_sched_barrier(0)
; template <class Epi, class Sched, bool ALIGN_EPI = false, bool SP2 = false>
; __device__ __forceinline__ void gemm_phase(PG8_LAS unsigned char* lds, const Gemm g, const Sched& S, const Epi& E, const int tid) {
;     ...
;             PG8_LDA(At, 1, 1); PG8_STAGE(PG8_SB(1, 0), b3, voffB); PG8_STAGE(PG8_SB(1, 1), b3 + hstep, voffB); PG8_STAGE(PG8_SA(1, 0), a3, voffA);
;             PG8_WAIT_V(8); PG8_WAIT_L(0); PG8_BAR; PG8_MMA(1, 0, At, B0); PG8_MMA(1, 1, At, B1); PG8_BAR; PG8_SCHED;
	s_setprio 0
	s_add_i32 s28, s53, s33
	v_lshl_add_u64 v[206:207], v[206:207], 0, s[70:71]
	s_mov_b32 m0, s28
	ds_read_b128 v[172:175], v143 offset:49152
	ds_read_b128 v[176:179], v143 offset:50176
	ds_read_b128 v[180:183], v143 offset:51200
	ds_read_b128 v[184:187], v143 offset:52224
	ds_read_b128 v[188:191], v143 offset:53248
	ds_read_b128 v[192:195], v143 offset:54272
	ds_read_b128 v[196:199], v143 offset:55296
	ds_read_b128 v[200:203], v143 offset:56320
	global_load_lds_dwordx4 v[206:207], off
	s_add_i32 m0, s28, 0x2000
	s_add_u32 s26, s26, 0x20080
	v_lshl_add_u64 v[206:207], v[208:209], 0, s[70:71]
	s_addc_u32 s27, s27, 0
	s_add_i32 s28, s54, s33
	global_load_lds_dwordx4 v[206:207], off
	v_lshl_add_u64 v[206:207], s[26:27], 0, v[204:205]
	s_mov_b32 m0, s28
	s_nop 0
	global_load_lds_dwordx4 v[206:207], off
	v_lshl_add_u64 v[206:207], s[26:27], 0, v[128:129]
	s_add_i32 m0, s28, 0x2000
	s_nop 0
	global_load_lds_dwordx4 v[206:207], off
	v_lshl_add_u64 v[206:207], v[210:211], 0, s[70:71]
	s_mov_b32 m0, s43
	s_nop 0
	global_load_lds_dwordx4 v[206:207], off
	v_lshl_add_u64 v[206:207], v[212:213], 0, s[70:71]
	s_mov_b32 m0, s44
	s_nop 0
	global_load_lds_dwordx4 v[206:207], off
	s_add_i32 s52, s52, 2
	s_add_u32 s24, s24, 0x100
	s_addc_u32 s25, s25, 0
	s_add_u32 s50, s50, 0x100
	s_addc_u32 s51, s51, 0
	s_waitcnt vmcnt(8)
	s_waitcnt lgkmcnt(0)
	s_setprio 1
	s_barrier
	v_mfma_f32_16x16x32_bf16 v[60:63], v[138:141], v[172:175], v[60:63]
	v_mfma_f32_16x16x32_bf16 v[56:59], v[148:151], v[172:175], v[56:59]
	v_mfma_f32_16x16x32_bf16 v[52:55], v[138:141], v[180:183], v[52:55]
	v_mfma_f32_16x16x32_bf16 v[44:47], v[148:151], v[180:183], v[44:47]
	v_mfma_f32_16x16x32_bf16 v[36:39], v[138:141], v[188:191], v[36:39]
	v_mfma_f32_16x16x32_bf16 v[28:31], v[148:151], v[188:191], v[28:31]
	v_mfma_f32_16x16x32_bf16 v[20:23], v[138:141], v[196:199], v[20:23]
	v_mfma_f32_16x16x32_bf16 v[12:15], v[148:151], v[196:199], v[12:15]
	v_mfma_f32_16x16x32_bf16 v[60:63], v[144:147], v[176:179], v[60:63]
	v_mfma_f32_16x16x32_bf16 v[56:59], v[152:155], v[176:179], v[56:59]
	v_mfma_f32_16x16x32_bf16 v[52:55], v[144:147], v[184:187], v[52:55]
	v_mfma_f32_16x16x32_bf16 v[44:47], v[152:155], v[184:187], v[44:47]
	v_mfma_f32_16x16x32_bf16 v[36:39], v[144:147], v[192:195], v[36:39]
	v_mfma_f32_16x16x32_bf16 v[28:31], v[152:155], v[192:195], v[28:31]
	v_mfma_f32_16x16x32_bf16 v[20:23], v[144:147], v[200:203], v[20:23]
	v_mfma_f32_16x16x32_bf16 v[12:15], v[152:155], v[200:203], v[12:15]
	s_setprio 0
	s_setprio 1
	v_mfma_f32_16x16x32_bf16 v[48:51], v[156:159], v[172:175], v[48:51]
	v_mfma_f32_16x16x32_bf16 v[40:43], v[164:167], v[172:175], v[40:43]
	v_mfma_f32_16x16x32_bf16 v[32:35], v[156:159], v[180:183], v[32:35]
	v_mfma_f32_16x16x32_bf16 v[24:27], v[164:167], v[180:183], v[24:27]
	v_mfma_f32_16x16x32_bf16 v[16:19], v[156:159], v[188:191], v[16:19]
	v_mfma_f32_16x16x32_bf16 v[8:11], v[164:167], v[188:191], v[8:11]
	v_mfma_f32_16x16x32_bf16 v[4:7], v[156:159], v[196:199], v[4:7]
	v_mfma_f32_16x16x32_bf16 v[0:3], v[164:167], v[196:199], v[0:3]
	v_mfma_f32_16x16x32_bf16 v[48:51], v[160:163], v[176:179], v[48:51]
	v_mfma_f32_16x16x32_bf16 v[40:43], v[168:171], v[176:179], v[40:43]
	v_mfma_f32_16x16x32_bf16 v[32:35], v[160:163], v[184:187], v[32:35]
	v_mfma_f32_16x16x32_bf16 v[24:27], v[168:171], v[184:187], v[24:27]
	v_mfma_f32_16x16x32_bf16 v[16:19], v[160:163], v[192:195], v[16:19]
	v_mfma_f32_16x16x32_bf16 v[8:11], v[168:171], v[192:195], v[8:11]
	v_mfma_f32_16x16x32_bf16 v[4:7], v[160:163], v[200:203], v[4:7]
	v_mfma_f32_16x16x32_bf16 v[0:3], v[168:171], v[200:203], v[0:3]
	s_barrier
	s_setprio 0
	s_cmp_gt_u32 s52, 5
	s_cbranch_scc0 .LBB0_1549
	s_and_b64 vcc, exec, s[12:13]
	s_cbranch_vccz .LBB0_1552
	s_barrier

; #define PG8_STAGE(bufoff, gbase, voff) do { _Pragma("unroll") for (int _i = 0; _i < 2; ++_i) \
;         __builtin_amdgcn_global_load_lds((const unsigned*)((const char*)(gbase) + (voff)[_i]), (PG8_LAS unsigned*)(lds + (bufoff) + ldsw + _i * 8192), 16, 0, 0); } while (0)
; #define PG8_LDA(dst, b, h) do { _Pragma("unroll") for (int m = 0; m < 4; ++m) _Pragma("unroll") for (int k = 0; k < 2; ++k) dst[m][k] = *(const PG8_LAS bf16x8*)(lds + PG8_SA(b, h) + aoff + m * 2048 + k * 1024); } while (0)
; #define PG8_LDB(dst, b, h) do { _Pragma("unroll") for (int n = 0; n < 2; ++n) _Pragma("unroll") for (int k = 0; k < 2; ++k) dst[n][k] = *(const PG8_LAS bf16x8*)(lds + PG8_SB(b, h) + boff + n * 2048 + k * 1024); } while (0)
; #define PG8_WAIT_V(n) asm volatile("s_waitcnt vmcnt(" #n ")" ::: "memory")
; #define PG8_WAIT_L(n) asm volatile("s_waitcnt lgkmcnt(" #n ")" ::: "memory")
; #define PG8_BAR __builtin_amdgcn_s_barrier()
; #define PG8_SCHED __builtin_amdgcn_sched_barrier(0)
; template <class Epi, class Sched, bool ALIGN_EPI = false, bool SP2 = false>
; __device__ __forceinline__ void gemm_phase(PG8_LAS unsigned char* lds, const Gemm g, const Sched& S, const Epi& E, const int tid) {
;     ...
;         const bool has_next = S.next(ui + 1, nxt);
;         const char* nA = has_next ? (const char*)g.A + (size_t)nxt.pm * tstep : cA; const char* nB = has_next ? (const char*)g.Bt + (size_t)nxt.pn * tstep : cB;
;         for (int t = 0; t < nt; t += 2) {
;             const bool last = (t == nt - 2);
;             const char* a1 = cA + (size_t)(t + 1) * kstep;
;             const char* a2 = last ? nA : cA + (size_t)(t + 2) * kstep; const char* b2 = last ? nB : cB + (size_t)(t + 2) * kstep;
;             const char* a3 = a2 + kstep; const char* b3 = b2 + kstep;
;             if (last && has_next) S.a_ready(nxt);
;             if constexpr (SP2) {
;             PG8_LDB(B0, 0, 0); PG8_LDB(B1, 0, 1); PG8_SCHED; PG8_LDA(At, 0, 0); PG8_STAGE(PG8_SA(1, 1), a1 + hstep, voffA);
;             PG8_WAIT_V(8); PG8_WAIT_L(0); PG8_BAR; PG8_MMA(0, 0, At, B0); PG8_MMA(0, 1, At, B1); PG8_BAR; PG8_SCHED;
;             PG8_LDA(At, 0, 1); PG8_STAGE(PG8_SB(0, 0), b2, voffB); PG8_STAGE(PG8_SB(0, 1), b2 + hstep, voffB); PG8_STAGE(PG8_SA(0, 0), a2, voffA);
;             PG8_WAIT_V(8); PG8_WAIT_L(0); PG8_BAR; PG8_MMA(1, 0, At, B0); PG8_MMA(1, 1, At, B1); PG8_BAR; PG8_SCHED;
.LBB0_1572:
	s_ashr_i32 s17, s16, 31
	s_lshl_b64 s[18:19], s[16:17], 18
	s_add_u32 s18, s11, s18
	s_addc_u32 s19, s30, s19
	s_and_b64 s[20:21], s[4:5], exec
	s_cselect_b32 s17, s19, s25
	s_cselect_b32 s48, s18, s24
	s_ashr_i32 s15, s14, 31
	s_lshl_b64 s[20:21], s[14:15], 18
	s_add_u32 s20, s31, s20
	s_addc_u32 s21, s33, s21
	s_and_b64 s[28:29], s[4:5], exec
	s_cselect_b32 s15, s21, s27
	s_cselect_b32 s49, s20, s26
	s_add_u32 s24, s24, 0x20080
	s_addc_u32 s25, s25, 0
	s_add_u32 s50, s26, 0x100
	s_addc_u32 s51, s27, 0
	s_mov_b32 s52, -2
	s_add_i32 s53, 0, 0x10000
	v_add_u32_e32 v138, s53, v140
	s_add_i32 s62, 0, 0x14000
	ds_read_b128 v[142:145], v138
	ds_read_b128 v[146:149], v138 offset:1024
	ds_read_b128 v[150:153], v138 offset:2048
	ds_read_b128 v[154:157], v138 offset:3072
	v_add_u32_e32 v138, s62, v140
	ds_read_b128 v[158:161], v138
	ds_read_b128 v[162:165], v138 offset:1024
	ds_read_b128 v[166:169], v138 offset:2048
	ds_read_b128 v[170:173], v138 offset:3072
	v_lshl_add_u64 v[138:139], s[24:25], 0, v[134:135]
	s_add_i32 m0, s23, 0xc000
	ds_read_b128 v[174:177], v141
	ds_read_b128 v[178:181], v141 offset:1024
	ds_read_b128 v[182:185], v141 offset:2048
	ds_read_b128 v[186:189], v141 offset:3072
	ds_read_b128 v[190:193], v141 offset:4096
	ds_read_b128 v[194:197], v141 offset:5120
	ds_read_b128 v[198:201], v141 offset:6144
	ds_read_b128 v[206:209], v141 offset:7168
	s_add_u32 s26, s24, 0xfffe0080
	s_addc_u32 s27, s25, -1
	s_cmp_eq_u32 s52, 4
	s_cselect_b32 s29, s17, s27
	s_cselect_b32 s28, s48, s26
	s_cselect_b32 s27, s15, s51
	s_cselect_b32 s26, s49, s50
	global_load_lds_dwordx4 v[138:139], off
	v_lshl_add_u64 v[138:139], s[24:25], 0, v[136:137]
	s_add_i32 m0, s23, 0xe000
	s_nop 0
	global_load_lds_dwordx4 v[138:139], off
	s_waitcnt vmcnt(24)
	s_waitcnt lgkmcnt(0)
	s_setprio 1
	s_barrier
	v_mfma_f32_16x16x32_bf16 v[124:127], v[142:145], v[174:177], 0
	v_mfma_f32_16x16x32_bf16 v[120:123], v[150:153], v[174:177], 0
	v_mfma_f32_16x16x32_bf16 v[116:119], v[142:145], v[182:185], 0
	v_mfma_f32_16x16x32_bf16 v[108:111], v[150:153], v[182:185], 0
	v_mfma_f32_16x16x32_bf16 v[100:103], v[142:145], v[190:193], 0
	v_mfma_f32_16x16x32_bf16 v[92:95], v[150:153], v[190:193], 0
	v_mfma_f32_16x16x32_bf16 v[84:87], v[142:145], v[198:201], 0
	v_mfma_f32_16x16x32_bf16 v[76:79], v[150:153], v[198:201], 0
	v_mfma_f32_16x16x32_bf16 v[124:127], v[146:149], v[178:181], v[124:127]
	v_mfma_f32_16x16x32_bf16 v[120:123], v[154:157], v[178:181], v[120:123]
	v_mfma_f32_16x16x32_bf16 v[116:119], v[146:149], v[186:189], v[116:119]
	v_mfma_f32_16x16x32_bf16 v[108:111], v[154:157], v[186:189], v[108:111]
	v_mfma_f32_16x16x32_bf16 v[100:103], v[146:149], v[194:197], v[100:103]
	v_mfma_f32_16x16x32_bf16 v[92:95], v[154:157], v[194:197], v[92:95]
	v_mfma_f32_16x16x32_bf16 v[84:87], v[146:149], v[206:209], v[84:87]
	v_mfma_f32_16x16x32_bf16 v[76:79], v[154:157], v[206:209], v[76:79]
	s_setprio 0
	s_setprio 1
	v_mfma_f32_16x16x32_bf16 v[112:115], v[158:161], v[174:177], 0
	v_mfma_f32_16x16x32_bf16 v[104:107], v[166:169], v[174:177], 0
	v_mfma_f32_16x16x32_bf16 v[96:99], v[158:161], v[182:185], 0
	v_mfma_f32_16x16x32_bf16 v[88:91], v[166:169], v[182:185], 0
	v_mfma_f32_16x16x32_bf16 v[80:83], v[158:161], v[190:193], 0
	v_mfma_f32_16x16x32_bf16 v[72:75], v[166:169], v[190:193], 0
	v_mfma_f32_16x16x32_bf16 v[68:71], v[158:161], v[198:201], 0
	v_mfma_f32_16x16x32_bf16 v[64:67], v[166:169], v[198:201], 0
	v_mfma_f32_16x16x32_bf16 v[112:115], v[162:165], v[178:181], v[112:115]
	v_mfma_f32_16x16x32_bf16 v[104:107], v[170:173], v[178:181], v[104:107]
	v_mfma_f32_16x16x32_bf16 v[96:99], v[162:165], v[186:189], v[96:99]
	v_mfma_f32_16x16x32_bf16 v[88:91], v[170:173], v[186:189], v[88:91]
	v_mfma_f32_16x16x32_bf16 v[80:83], v[162:165], v[194:197], v[80:83]
	v_mfma_f32_16x16x32_bf16 v[72:75], v[170:173], v[194:197], v[72:75]
	v_mfma_f32_16x16x32_bf16 v[68:71], v[162:165], v[206:209], v[68:71]
	v_mfma_f32_16x16x32_bf16 v[64:67], v[170:173], v[206:209], v[64:67]
	s_barrier
	s_setprio 0
	s_add_i32 s53, s53, s34
	v_lshl_add_u64 v[138:139], s[26:27], 0, v[204:205]
	s_mov_b32 m0, s53
	ds_read_b128 v[174:177], v141 offset:16384
	ds_read_b128 v[178:181], v141 offset:17408
	ds_read_b128 v[182:185], v141 offset:18432
	ds_read_b128 v[186:189], v141 offset:19456
	ds_read_b128 v[190:193], v141 offset:20480
	ds_read_b128 v[194:197], v141 offset:21504
	ds_read_b128 v[198:201], v141 offset:22528
	ds_read_b128 v[206:209], v141 offset:23552
	global_load_lds_dwordx4 v[138:139], off
	s_add_i32 m0, s53, 0x2000
	s_add_u32 s54, s26, 0x20000
	v_lshl_add_u64 v[202:203], s[26:27], 0, v[132:133]
	s_addc_u32 s55, s27, 0
	s_add_i32 s53, s62, s34
	global_load_lds_dwordx4 v[202:203], off
	v_lshl_add_u64 v[210:211], s[54:55], 0, v[204:205]
	s_mov_b32 m0, s53
	v_lshl_add_u64 v[212:213], s[28:29], 0, v[130:131]
	global_load_lds_dwordx4 v[210:211], off
	v_lshl_add_u64 v[210:211], s[54:55], 0, v[132:133]
	s_add_i32 m0, s53, 0x2000
	s_nop 0
	global_load_lds_dwordx4 v[210:211], off
	v_lshl_add_u64 v[210:211], s[28:29], 0, v[128:129]
	s_mov_b32 m0, s23
	s_nop 0
	global_load_lds_dwordx4 v[210:211], off
	s_mov_b32 m0, s35
	s_nop 0
	global_load_lds_dwordx4 v[212:213], off
	s_waitcnt vmcnt(8)
	s_waitcnt lgkmcnt(0)
	s_setprio 1
	s_barrier
; #define PG8_STAGE(bufoff, gbase, voff) do { _Pragma("unroll") for (int _i = 0; _i < 2; ++_i) \
;         __builtin_amdgcn_global_load_lds((const unsigned*)((const char*)(gbase) + (voff)[_i]), (PG8_LAS unsigned*)(lds + (bufoff) + ldsw + _i * 8192), 16, 0, 0); } while (0)
; #define PG8_LDA(dst, b, h) do { _Pragma("unroll") for (int m = 0; m < 4; ++m) _Pragma("unroll") for (int k = 0; k < 2; ++k) dst[m][k] = *(const PG8_LAS bf16x8*)(lds + PG8_SA(b, h) + aoff + m * 2048 + k * 1024); } while (0)
; #define PG8_LDB(dst, b, h) do { _Pragma("unroll") for (int n = 0; n < 2; ++n) _Pragma("unroll") for (int k = 0; k < 2; ++k) dst[n][k] = *(const PG8_LAS bf16x8*)(lds + PG8_SB(b, h) + boff + n * 2048 + k * 1024); } while (0)
; #define PG8_MMA(ai, bj, At, Bt) do { __builtin_amdgcn_s_setprio(1); _Pragma("unroll") for (int m = 0; m < 4; ++m) _Pragma("unroll") for (int n = 0; n < 2; ++n) _Pragma("unroll") for (int k = 0; k < 2; ++k) \
;         acc[ai][bj][m][n] = __builtin_amdgcn_mfma_f32_16x16x32_bf16(Bt[n][k], At[m][k], acc[ai][bj][m][n], 0, 0, 0); __builtin_amdgcn_s_setprio(0); } while (0)
; #define PG8_WAIT_V(n) asm volatile("s_waitcnt vmcnt(" #n ")" ::: "memory")
; #define PG8_WAIT_L(n) asm volatile("s_waitcnt lgkmcnt(" #n ")" ::: "memory")
; #define PG8_BAR __builtin_amdgcn_s_barrier()
; #define PG8_SCHED __builtin_amdgcn_sched_barrier(0)
; template <class Epi, class Sched, bool ALIGN_EPI = false, bool SP2 = false>
; __device__ __forceinline__ void gemm_phase(PG8_LAS unsigned char* lds, const Gemm g, const Sched& S, const Epi& E, const int tid) {
;     ...
;             PG8_WAIT_V(8); PG8_WAIT_L(0); PG8_BAR; PG8_MMA(1, 0, At, B0); PG8_MMA(1, 1, At, B1); PG8_BAR; PG8_SCHED;
;             PG8_LDB(B0, 1, 0); PG8_LDB(B1, 1, 1); PG8_SCHED; PG8_LDA(At, 1, 0); PG8_STAGE(PG8_SA(0, 1), a2 + hstep, voffA);
;             PG8_WAIT_V(8); PG8_WAIT_L(0); PG8_BAR; PG8_MMA(0, 0, At, B0); PG8_MMA(0, 1, At, B1); PG8_BAR; PG8_SCHED;
	v_mfma_f32_16x16x32_bf16 v[60:63], v[142:145], v[174:177], 0
	v_mfma_f32_16x16x32_bf16 v[56:59], v[150:153], v[174:177], 0
	v_mfma_f32_16x16x32_bf16 v[52:55], v[142:145], v[182:185], 0
	v_mfma_f32_16x16x32_bf16 v[44:47], v[150:153], v[182:185], 0
	v_mfma_f32_16x16x32_bf16 v[36:39], v[142:145], v[190:193], 0
	v_mfma_f32_16x16x32_bf16 v[28:31], v[150:153], v[190:193], 0
	v_mfma_f32_16x16x32_bf16 v[20:23], v[142:145], v[198:201], 0
	v_mfma_f32_16x16x32_bf16 v[12:15], v[150:153], v[198:201], 0
	v_mfma_f32_16x16x32_bf16 v[60:63], v[146:149], v[178:181], v[60:63]
	v_mfma_f32_16x16x32_bf16 v[56:59], v[154:157], v[178:181], v[56:59]
	v_mfma_f32_16x16x32_bf16 v[52:55], v[146:149], v[186:189], v[52:55]
	v_mfma_f32_16x16x32_bf16 v[44:47], v[154:157], v[186:189], v[44:47]
	v_mfma_f32_16x16x32_bf16 v[36:39], v[146:149], v[194:197], v[36:39]
	v_mfma_f32_16x16x32_bf16 v[28:31], v[154:157], v[194:197], v[28:31]
	v_mfma_f32_16x16x32_bf16 v[20:23], v[146:149], v[206:209], v[20:23]
	v_mfma_f32_16x16x32_bf16 v[12:15], v[154:157], v[206:209], v[12:15]
	s_setprio 0
	s_setprio 1
	v_mfma_f32_16x16x32_bf16 v[48:51], v[158:161], v[174:177], 0
	v_mfma_f32_16x16x32_bf16 v[40:43], v[166:169], v[174:177], 0
	v_mfma_f32_16x16x32_bf16 v[32:35], v[158:161], v[182:185], 0
	v_mfma_f32_16x16x32_bf16 v[24:27], v[166:169], v[182:185], 0
	v_mfma_f32_16x16x32_bf16 v[16:19], v[158:161], v[190:193], 0
	v_mfma_f32_16x16x32_bf16 v[8:11], v[166:169], v[190:193], 0
	v_mfma_f32_16x16x32_bf16 v[4:7], v[158:161], v[198:201], 0
	v_mfma_f32_16x16x32_bf16 v[0:3], v[166:169], v[198:201], 0
	v_mfma_f32_16x16x32_bf16 v[48:51], v[162:165], v[178:181], v[48:51]
	v_mfma_f32_16x16x32_bf16 v[40:43], v[170:173], v[178:181], v[40:43]
	v_mfma_f32_16x16x32_bf16 v[32:35], v[162:165], v[186:189], v[32:35]
	v_mfma_f32_16x16x32_bf16 v[24:27], v[170:173], v[186:189], v[24:27]
	v_mfma_f32_16x16x32_bf16 v[16:19], v[162:165], v[194:197], v[16:19]
	v_mfma_f32_16x16x32_bf16 v[8:11], v[170:173], v[194:197], v[8:11]
	v_mfma_f32_16x16x32_bf16 v[4:7], v[162:165], v[206:209], v[4:7]
	v_mfma_f32_16x16x32_bf16 v[0:3], v[170:173], v[206:209], v[0:3]
	s_barrier
	s_setprio 0
	s_add_i32 s53, 0, 0x18000
	s_add_i32 s54, 0, 0x1c000
	v_add_u32_e32 v154, s53, v140
	v_add_u32_e32 v170, s54, v140
	ds_read_b128 v[142:145], v154
	ds_read_b128 v[146:149], v154 offset:1024
	ds_read_b128 v[150:153], v154 offset:2048
	ds_read_b128 v[154:157], v154 offset:3072
	ds_read_b128 v[158:161], v170
	ds_read_b128 v[162:165], v170 offset:1024
	ds_read_b128 v[166:169], v170 offset:2048
	ds_read_b128 v[170:173], v170 offset:3072
	s_add_u32 s28, s28, 0x20000
	s_addc_u32 s29, s29, 0
	s_mov_b32 m0, s36
	v_lshl_add_u64 v[214:215], s[28:29], 0, v[128:129]
	ds_read_b128 v[174:177], v141 offset:32768
	ds_read_b128 v[178:181], v141 offset:33792
	ds_read_b128 v[182:185], v141 offset:34816
	ds_read_b128 v[186:189], v141 offset:35840
	ds_read_b128 v[190:193], v141 offset:36864
	ds_read_b128 v[194:197], v141 offset:37888
	ds_read_b128 v[198:201], v141 offset:38912
	ds_read_b128 v[206:209], v141 offset:39936
	global_load_lds_dwordx4 v[214:215], off
	v_lshl_add_u64 v[214:215], s[28:29], 0, v[130:131]
	s_mov_b32 m0, s37
	s_nop 0
	global_load_lds_dwordx4 v[214:215], off
	s_waitcnt vmcnt(8)
	s_waitcnt lgkmcnt(0)
	s_setprio 1
	s_barrier
	v_mfma_f32_16x16x32_bf16 v[124:127], v[142:145], v[174:177], v[124:127]
	v_mfma_f32_16x16x32_bf16 v[120:123], v[150:153], v[174:177], v[120:123]
	v_mfma_f32_16x16x32_bf16 v[116:119], v[142:145], v[182:185], v[116:119]
	v_mfma_f32_16x16x32_bf16 v[108:111], v[150:153], v[182:185], v[108:111]
	v_mfma_f32_16x16x32_bf16 v[100:103], v[142:145], v[190:193], v[100:103]
	v_mfma_f32_16x16x32_bf16 v[92:95], v[150:153], v[190:193], v[92:95]
	v_mfma_f32_16x16x32_bf16 v[84:87], v[142:145], v[198:201], v[84:87]
	v_mfma_f32_16x16x32_bf16 v[76:79], v[150:153], v[198:201], v[76:79]
	v_mfma_f32_16x16x32_bf16 v[124:127], v[146:149], v[178:181], v[124:127]
	v_mfma_f32_16x16x32_bf16 v[120:123], v[154:157], v[178:181], v[120:123]
	v_mfma_f32_16x16x32_bf16 v[116:119], v[146:149], v[186:189], v[116:119]
	v_mfma_f32_16x16x32_bf16 v[108:111], v[154:157], v[186:189], v[108:111]
	v_mfma_f32_16x16x32_bf16 v[100:103], v[146:149], v[194:197], v[100:103]
	v_mfma_f32_16x16x32_bf16 v[92:95], v[154:157], v[194:197], v[92:95]
	v_mfma_f32_16x16x32_bf16 v[84:87], v[146:149], v[206:209], v[84:87]
	v_mfma_f32_16x16x32_bf16 v[76:79], v[154:157], v[206:209], v[76:79]
	s_setprio 0
	s_setprio 1
	v_mfma_f32_16x16x32_bf16 v[112:115], v[158:161], v[174:177], v[112:115]
	v_mfma_f32_16x16x32_bf16 v[104:107], v[166:169], v[174:177], v[104:107]
	v_mfma_f32_16x16x32_bf16 v[96:99], v[158:161], v[182:185], v[96:99]
	v_mfma_f32_16x16x32_bf16 v[88:91], v[166:169], v[182:185], v[88:91]
	v_mfma_f32_16x16x32_bf16 v[80:83], v[158:161], v[190:193], v[80:83]
	v_mfma_f32_16x16x32_bf16 v[72:75], v[166:169], v[190:193], v[72:75]
	v_mfma_f32_16x16x32_bf16 v[68:71], v[158:161], v[198:201], v[68:71]
	v_mfma_f32_16x16x32_bf16 v[64:67], v[166:169], v[198:201], v[64:67]
	v_mfma_f32_16x16x32_bf16 v[112:115], v[162:165], v[178:181], v[112:115]
	v_mfma_f32_16x16x32_bf16 v[104:107], v[170:173], v[178:181], v[104:107]
	v_mfma_f32_16x16x32_bf16 v[96:99], v[162:165], v[186:189], v[96:99]
	v_mfma_f32_16x16x32_bf16 v[88:91], v[170:173], v[186:189], v[88:91]
	v_mfma_f32_16x16x32_bf16 v[80:83], v[162:165], v[194:197], v[80:83]
	v_mfma_f32_16x16x32_bf16 v[72:75], v[170:173], v[194:197], v[72:75]
	v_mfma_f32_16x16x32_bf16 v[68:71], v[162:165], v[206:209], v[68:71]
	v_mfma_f32_16x16x32_bf16 v[64:67], v[170:173], v[206:209], v[64:67]
	s_barrier
; #define PG8_STAGE(bufoff, gbase, voff) do { _Pragma("unroll") for (int _i = 0; _i < 2; ++_i) \
;         __builtin_amdgcn_global_load_lds((const unsigned*)((const char*)(gbase) + (voff)[_i]), (PG8_LAS unsigned*)(lds + (bufoff) + ldsw + _i * 8192), 16, 0, 0); } while (0)
; #define PG8_LDA(dst, b, h) do { _Pragma("unroll") for (int m = 0; m < 4; ++m) _Pragma("unroll") for (int k = 0; k < 2; ++k) dst[m][k] = *(const PG8_LAS bf16x8*)(lds + PG8_SA(b, h) + aoff + m * 2048 + k * 1024); } while (0)
; #define PG8_WAIT_V(n) asm volatile("s_waitcnt vmcnt(" #n ")" ::: "memory")
; #define PG8_WAIT_L(n) asm volatile("s_waitcnt lgkmcnt(" #n ")" ::: "memory")
; #define PG8_BAR __builtin_amdgcn_s_barrier()
; template <class Epi, class Sched, bool ALIGN_EPI = false, bool SP2 = false>
; __device__ __forceinline__ void gemm_phase(PG8_LAS unsigned char* lds, const Gemm g, const Sched& S, const Epi& E, const int tid) {
;     ...
;         for (int t = 0; t < nt; t += 2) {
;             const bool last = (t == nt - 2);
;             const char* a1 = cA + (size_t)(t + 1) * kstep;
;             const char* a2 = last ? nA : cA + (size_t)(t + 2) * kstep; const char* b2 = last ? nB : cB + (size_t)(t + 2) * kstep;
;             const char* a3 = a2 + kstep; const char* b3 = b2 + kstep;
;             if (last && has_next) S.a_ready(nxt);
;             if constexpr (SP2) {
;             PG8_LDB(B0, 0, 0); PG8_LDB(B1, 0, 1); PG8_SCHED; PG8_LDA(At, 0, 0); PG8_STAGE(PG8_SA(1, 1), a1 + hstep, voffA);
;             PG8_WAIT_V(8); PG8_WAIT_L(0); PG8_BAR; PG8_MMA(0, 0, At, B0); PG8_MMA(0, 1, At, B1); PG8_BAR; PG8_SCHED;
;             PG8_LDA(At, 0, 1); PG8_STAGE(PG8_SB(0, 0), b2, voffB); PG8_STAGE(PG8_SB(0, 1), b2 + hstep, voffB); PG8_STAGE(PG8_SA(0, 0), a2, voffA);
;             PG8_WAIT_V(8); PG8_WAIT_L(0); PG8_BAR; PG8_MMA(1, 0, At, B0); PG8_MMA(1, 1, At, B1); PG8_BAR; PG8_SCHED;
;             PG8_LDB(B0, 1, 0); PG8_LDB(B1, 1, 1); PG8_SCHED; PG8_LDA(At, 1, 0); PG8_STAGE(PG8_SA(0, 1), a2 + hstep, voffA);
;             PG8_WAIT_V(8); PG8_WAIT_L(0); PG8_BAR; PG8_MMA(0, 0, At, B0); PG8_MMA(0, 1, At, B1); PG8_BAR; PG8_SCHED;
;             PG8_LDA(At, 1, 1); PG8_STAGE(PG8_SB(1, 0), b3, voffB); PG8_STAGE(PG8_SB(1, 1), b3 + hstep, voffB); PG8_STAGE(PG8_SA(1, 0), a3, voffA);
;             PG8_WAIT_V(8); PG8_WAIT_L(0); PG8_BAR; PG8_MMA(1, 0, At, B0); PG8_MMA(1, 1, At, B1); PG8_BAR; PG8_SCHED;
	s_setprio 0
	s_add_i32 s28, s53, s34
	v_lshl_add_u64 v[138:139], v[138:139], 0, s[70:71]
	s_mov_b32 m0, s28
	ds_read_b128 v[174:177], v141 offset:49152
	ds_read_b128 v[178:181], v141 offset:50176
	ds_read_b128 v[182:185], v141 offset:51200
	ds_read_b128 v[186:189], v141 offset:52224
	ds_read_b128 v[190:193], v141 offset:53248
	ds_read_b128 v[194:197], v141 offset:54272
	ds_read_b128 v[198:201], v141 offset:55296
	ds_read_b128 v[206:209], v141 offset:56320
	global_load_lds_dwordx4 v[138:139], off
	s_add_i32 m0, s28, 0x2000
	s_add_u32 s26, s26, 0x20080
	v_lshl_add_u64 v[138:139], v[202:203], 0, s[70:71]
	s_addc_u32 s27, s27, 0
	s_add_i32 s28, s54, s34
	global_load_lds_dwordx4 v[138:139], off
	v_lshl_add_u64 v[138:139], s[26:27], 0, v[204:205]
	s_mov_b32 m0, s28
	s_nop 0
	global_load_lds_dwordx4 v[138:139], off
	v_lshl_add_u64 v[138:139], s[26:27], 0, v[132:133]
	s_add_i32 m0, s28, 0x2000
	s_nop 0
	global_load_lds_dwordx4 v[138:139], off
	v_lshl_add_u64 v[138:139], v[210:211], 0, s[70:71]
	s_mov_b32 m0, s43
	s_nop 0
	global_load_lds_dwordx4 v[138:139], off
	v_lshl_add_u64 v[138:139], v[212:213], 0, s[70:71]
	s_mov_b32 m0, s44
	s_nop 0
	global_load_lds_dwordx4 v[138:139], off
	s_add_i32 s52, s52, 2
	s_add_u32 s24, s24, 0x100
	s_addc_u32 s25, s25, 0
	s_add_u32 s50, s50, 0x100
	s_addc_u32 s51, s51, 0
	s_waitcnt vmcnt(8)
	s_waitcnt lgkmcnt(0)
	s_setprio 1
	s_barrier
	v_mfma_f32_16x16x32_bf16 v[60:63], v[142:145], v[174:177], v[60:63]
	v_mfma_f32_16x16x32_bf16 v[56:59], v[150:153], v[174:177], v[56:59]
	v_mfma_f32_16x16x32_bf16 v[52:55], v[142:145], v[182:185], v[52:55]
	v_mfma_f32_16x16x32_bf16 v[44:47], v[150:153], v[182:185], v[44:47]
	v_mfma_f32_16x16x32_bf16 v[36:39], v[142:145], v[190:193], v[36:39]
	v_mfma_f32_16x16x32_bf16 v[28:31], v[150:153], v[190:193], v[28:31]
	v_mfma_f32_16x16x32_bf16 v[20:23], v[142:145], v[198:201], v[20:23]
	v_mfma_f32_16x16x32_bf16 v[12:15], v[150:153], v[198:201], v[12:15]
	v_mfma_f32_16x16x32_bf16 v[60:63], v[146:149], v[178:181], v[60:63]
	v_mfma_f32_16x16x32_bf16 v[56:59], v[154:157], v[178:181], v[56:59]
	v_mfma_f32_16x16x32_bf16 v[52:55], v[146:149], v[186:189], v[52:55]
	v_mfma_f32_16x16x32_bf16 v[44:47], v[154:157], v[186:189], v[44:47]
	v_mfma_f32_16x16x32_bf16 v[36:39], v[146:149], v[194:197], v[36:39]
	v_mfma_f32_16x16x32_bf16 v[28:31], v[154:157], v[194:197], v[28:31]
	v_mfma_f32_16x16x32_bf16 v[20:23], v[146:149], v[206:209], v[20:23]
	v_mfma_f32_16x16x32_bf16 v[12:15], v[154:157], v[206:209], v[12:15]
	s_setprio 0
	s_setprio 1
	v_mfma_f32_16x16x32_bf16 v[48:51], v[158:161], v[174:177], v[48:51]
	v_mfma_f32_16x16x32_bf16 v[40:43], v[166:169], v[174:177], v[40:43]
	v_mfma_f32_16x16x32_bf16 v[32:35], v[158:161], v[182:185], v[32:35]
	v_mfma_f32_16x16x32_bf16 v[24:27], v[166:169], v[182:185], v[24:27]
	v_mfma_f32_16x16x32_bf16 v[16:19], v[158:161], v[190:193], v[16:19]
	v_mfma_f32_16x16x32_bf16 v[8:11], v[166:169], v[190:193], v[8:11]
	v_mfma_f32_16x16x32_bf16 v[4:7], v[158:161], v[198:201], v[4:7]
	v_mfma_f32_16x16x32_bf16 v[0:3], v[166:169], v[198:201], v[0:3]
	v_mfma_f32_16x16x32_bf16 v[48:51], v[162:165], v[178:181], v[48:51]
	v_mfma_f32_16x16x32_bf16 v[40:43], v[170:173], v[178:181], v[40:43]
	v_mfma_f32_16x16x32_bf16 v[32:35], v[162:165], v[186:189], v[32:35]
	v_mfma_f32_16x16x32_bf16 v[24:27], v[170:173], v[186:189], v[24:27]
	v_mfma_f32_16x16x32_bf16 v[16:19], v[162:165], v[194:197], v[16:19]
	v_mfma_f32_16x16x32_bf16 v[8:11], v[170:173], v[194:197], v[8:11]
	v_mfma_f32_16x16x32_bf16 v[4:7], v[162:165], v[206:209], v[4:7]
	v_mfma_f32_16x16x32_bf16 v[0:3], v[170:173], v[206:209], v[0:3]
	s_barrier
	s_setprio 0
.LBB0_1573:
	s_add_i32 s53, 0, 0x10000
	v_add_u32_e32 v138, s53, v140
	s_add_i32 s62, 0, 0x14000
	ds_read_b128 v[142:145], v138
	ds_read_b128 v[146:149], v138 offset:1024
	ds_read_b128 v[150:153], v138 offset:2048
	ds_read_b128 v[154:157], v138 offset:3072
	v_add_u32_e32 v138, s62, v140
	ds_read_b128 v[158:161], v138
	ds_read_b128 v[162:165], v138 offset:1024
	ds_read_b128 v[166:169], v138 offset:2048
	ds_read_b128 v[170:173], v138 offset:3072
	v_lshl_add_u64 v[138:139], s[24:25], 0, v[134:135]
	s_add_i32 m0, s23, 0xc000
	ds_read_b128 v[174:177], v141
	ds_read_b128 v[178:181], v141 offset:1024
	ds_read_b128 v[182:185], v141 offset:2048
	ds_read_b128 v[186:189], v141 offset:3072
	ds_read_b128 v[190:193], v141 offset:4096
	ds_read_b128 v[194:197], v141 offset:5120
	ds_read_b128 v[198:201], v141 offset:6144
	ds_read_b128 v[206:209], v141 offset:7168
	s_add_u32 s26, s24, 0xfffe0080
	s_addc_u32 s27, s25, -1
	s_cmp_eq_u32 s52, 4
	s_cselect_b32 s29, s17, s27
	s_cselect_b32 s28, s48, s26
	s_cselect_b32 s27, s15, s51
	s_cselect_b32 s26, s49, s50
	global_load_lds_dwordx4 v[138:139], off
	v_lshl_add_u64 v[138:139], s[24:25], 0, v[136:137]
	s_add_i32 m0, s23, 0xe000
	s_nop 0
	global_load_lds_dwordx4 v[138:139], off
	s_waitcnt vmcnt(8)
	s_waitcnt lgkmcnt(0)
	s_setprio 1
	s_barrier
; #define PG8_STAGE(bufoff, gbase, voff) do { _Pragma("unroll") for (int _i = 0; _i < 2; ++_i) \
;         __builtin_amdgcn_global_load_lds((const unsigned*)((const char*)(gbase) + (voff)[_i]), (PG8_LAS unsigned*)(lds + (bufoff) + ldsw + _i * 8192), 16, 0, 0); } while (0)
; #define PG8_LDA(dst, b, h) do { _Pragma("unroll") for (int m = 0; m < 4; ++m) _Pragma("unroll") for (int k = 0; k < 2; ++k) dst[m][k] = *(const PG8_LAS bf16x8*)(lds + PG8_SA(b, h) + aoff + m * 2048 + k * 1024); } while (0)
; #define PG8_MMA(ai, bj, At, Bt) do { __builtin_amdgcn_s_setprio(1); _Pragma("unroll") for (int m = 0; m < 4; ++m) _Pragma("unroll") for (int n = 0; n < 2; ++n) _Pragma("unroll") for (int k = 0; k < 2; ++k) \
;         acc[ai][bj][m][n] = __builtin_amdgcn_mfma_f32_16x16x32_bf16(Bt[n][k], At[m][k], acc[ai][bj][m][n], 0, 0, 0); __builtin_amdgcn_s_setprio(0); } while (0)
; #define PG8_WAIT_V(n) asm volatile("s_waitcnt vmcnt(" #n ")" ::: "memory")
; #define PG8_WAIT_L(n) asm volatile("s_waitcnt lgkmcnt(" #n ")" ::: "memory")
; #define PG8_BAR __builtin_amdgcn_s_barrier()
; #define PG8_SCHED __builtin_amdgcn_sched_barrier(0)
; template <class Epi, class Sched, bool ALIGN_EPI = false, bool SP2 = false>
; __device__ __forceinline__ void gemm_phase(PG8_LAS unsigned char* lds, const Gemm g, const Sched& S, const Epi& E, const int tid) {
;     ...
;             PG8_WAIT_V(8); PG8_WAIT_L(0); PG8_BAR; PG8_MMA(0, 0, At, B0); PG8_MMA(0, 1, At, B1); PG8_BAR; PG8_SCHED;
;             PG8_LDA(At, 0, 1); PG8_STAGE(PG8_SB(0, 0), b2, voffB); PG8_STAGE(PG8_SB(0, 1), b2 + hstep, voffB); PG8_STAGE(PG8_SA(0, 0), a2, voffA);
;             PG8_WAIT_V(8); PG8_WAIT_L(0); PG8_BAR; PG8_MMA(1, 0, At, B0); PG8_MMA(1, 1, At, B1); PG8_BAR; PG8_SCHED;
	v_mfma_f32_16x16x32_bf16 v[124:127], v[142:145], v[174:177], v[124:127]
	v_mfma_f32_16x16x32_bf16 v[120:123], v[150:153], v[174:177], v[120:123]
	v_mfma_f32_16x16x32_bf16 v[116:119], v[142:145], v[182:185], v[116:119]
	v_mfma_f32_16x16x32_bf16 v[108:111], v[150:153], v[182:185], v[108:111]
	v_mfma_f32_16x16x32_bf16 v[100:103], v[142:145], v[190:193], v[100:103]
	v_mfma_f32_16x16x32_bf16 v[92:95], v[150:153], v[190:193], v[92:95]
	v_mfma_f32_16x16x32_bf16 v[84:87], v[142:145], v[198:201], v[84:87]
	v_mfma_f32_16x16x32_bf16 v[76:79], v[150:153], v[198:201], v[76:79]
	v_mfma_f32_16x16x32_bf16 v[124:127], v[146:149], v[178:181], v[124:127]
	v_mfma_f32_16x16x32_bf16 v[120:123], v[154:157], v[178:181], v[120:123]
	v_mfma_f32_16x16x32_bf16 v[116:119], v[146:149], v[186:189], v[116:119]
	v_mfma_f32_16x16x32_bf16 v[108:111], v[154:157], v[186:189], v[108:111]
	v_mfma_f32_16x16x32_bf16 v[100:103], v[146:149], v[194:197], v[100:103]
	v_mfma_f32_16x16x32_bf16 v[92:95], v[154:157], v[194:197], v[92:95]
	v_mfma_f32_16x16x32_bf16 v[84:87], v[146:149], v[206:209], v[84:87]
	v_mfma_f32_16x16x32_bf16 v[76:79], v[154:157], v[206:209], v[76:79]
	s_setprio 0
	s_setprio 1
	v_mfma_f32_16x16x32_bf16 v[112:115], v[158:161], v[174:177], v[112:115]
	v_mfma_f32_16x16x32_bf16 v[104:107], v[166:169], v[174:177], v[104:107]
	v_mfma_f32_16x16x32_bf16 v[96:99], v[158:161], v[182:185], v[96:99]
	v_mfma_f32_16x16x32_bf16 v[88:91], v[166:169], v[182:185], v[88:91]
	v_mfma_f32_16x16x32_bf16 v[80:83], v[158:161], v[190:193], v[80:83]
	v_mfma_f32_16x16x32_bf16 v[72:75], v[166:169], v[190:193], v[72:75]
	v_mfma_f32_16x16x32_bf16 v[68:71], v[158:161], v[198:201], v[68:71]
	v_mfma_f32_16x16x32_bf16 v[64:67], v[166:169], v[198:201], v[64:67]
	v_mfma_f32_16x16x32_bf16 v[112:115], v[162:165], v[178:181], v[112:115]
	v_mfma_f32_16x16x32_bf16 v[104:107], v[170:173], v[178:181], v[104:107]
	v_mfma_f32_16x16x32_bf16 v[96:99], v[162:165], v[186:189], v[96:99]
	v_mfma_f32_16x16x32_bf16 v[88:91], v[170:173], v[186:189], v[88:91]
	v_mfma_f32_16x16x32_bf16 v[80:83], v[162:165], v[194:197], v[80:83]
	v_mfma_f32_16x16x32_bf16 v[72:75], v[170:173], v[194:197], v[72:75]
	v_mfma_f32_16x16x32_bf16 v[68:71], v[162:165], v[206:209], v[68:71]
	v_mfma_f32_16x16x32_bf16 v[64:67], v[170:173], v[206:209], v[64:67]
	s_barrier
	s_setprio 0
	s_add_i32 s53, s53, s34
	v_lshl_add_u64 v[138:139], s[26:27], 0, v[204:205]
	s_mov_b32 m0, s53
	ds_read_b128 v[174:177], v141 offset:16384
	ds_read_b128 v[178:181], v141 offset:17408
	ds_read_b128 v[182:185], v141 offset:18432
	ds_read_b128 v[186:189], v141 offset:19456
	ds_read_b128 v[190:193], v141 offset:20480
	ds_read_b128 v[194:197], v141 offset:21504
	ds_read_b128 v[198:201], v141 offset:22528
	ds_read_b128 v[206:209], v141 offset:23552
	global_load_lds_dwordx4 v[138:139], off
	s_add_i32 m0, s53, 0x2000
	s_add_u32 s54, s26, 0x20000
	v_lshl_add_u64 v[202:203], s[26:27], 0, v[132:133]
	s_addc_u32 s55, s27, 0
	s_add_i32 s53, s62, s34
	global_load_lds_dwordx4 v[202:203], off
	v_lshl_add_u64 v[210:211], s[54:55], 0, v[204:205]
	s_mov_b32 m0, s53
	v_lshl_add_u64 v[212:213], s[28:29], 0, v[130:131]
	global_load_lds_dwordx4 v[210:211], off
	v_lshl_add_u64 v[210:211], s[54:55], 0, v[132:133]
	s_add_i32 m0, s53, 0x2000
	s_nop 0
	global_load_lds_dwordx4 v[210:211], off
	v_lshl_add_u64 v[210:211], s[28:29], 0, v[128:129]
	s_mov_b32 m0, s23
	s_nop 0
	global_load_lds_dwordx4 v[210:211], off
	s_mov_b32 m0, s35
	s_nop 0
	global_load_lds_dwordx4 v[212:213], off
	s_waitcnt vmcnt(8)
	s_waitcnt lgkmcnt(0)
	s_setprio 1
	s_barrier
	v_mfma_f32_16x16x32_bf16 v[60:63], v[142:145], v[174:177], v[60:63]
	v_mfma_f32_16x16x32_bf16 v[56:59], v[150:153], v[174:177], v[56:59]
	v_mfma_f32_16x16x32_bf16 v[52:55], v[142:145], v[182:185], v[52:55]
	v_mfma_f32_16x16x32_bf16 v[44:47], v[150:153], v[182:185], v[44:47]
	v_mfma_f32_16x16x32_bf16 v[36:39], v[142:145], v[190:193], v[36:39]
	v_mfma_f32_16x16x32_bf16 v[28:31], v[150:153], v[190:193], v[28:31]
	v_mfma_f32_16x16x32_bf16 v[20:23], v[142:145], v[198:201], v[20:23]
	v_mfma_f32_16x16x32_bf16 v[12:15], v[150:153], v[198:201], v[12:15]
	v_mfma_f32_16x16x32_bf16 v[60:63], v[146:149], v[178:181], v[60:63]
	v_mfma_f32_16x16x32_bf16 v[56:59], v[154:157], v[178:181], v[56:59]
	v_mfma_f32_16x16x32_bf16 v[52:55], v[146:149], v[186:189], v[52:55]
	v_mfma_f32_16x16x32_bf16 v[44:47], v[154:157], v[186:189], v[44:47]
	v_mfma_f32_16x16x32_bf16 v[36:39], v[146:149], v[194:197], v[36:39]
	v_mfma_f32_16x16x32_bf16 v[28:31], v[154:157], v[194:197], v[28:31]
	v_mfma_f32_16x16x32_bf16 v[20:23], v[146:149], v[206:209], v[20:23]
	v_mfma_f32_16x16x32_bf16 v[12:15], v[154:157], v[206:209], v[12:15]
	s_setprio 0
	s_setprio 1
	v_mfma_f32_16x16x32_bf16 v[48:51], v[158:161], v[174:177], v[48:51]
	v_mfma_f32_16x16x32_bf16 v[40:43], v[166:169], v[174:177], v[40:43]
	v_mfma_f32_16x16x32_bf16 v[32:35], v[158:161], v[182:185], v[32:35]
	v_mfma_f32_16x16x32_bf16 v[24:27], v[166:169], v[182:185], v[24:27]
	v_mfma_f32_16x16x32_bf16 v[16:19], v[158:161], v[190:193], v[16:19]
	v_mfma_f32_16x16x32_bf16 v[8:11], v[166:169], v[190:193], v[8:11]
	v_mfma_f32_16x16x32_bf16 v[4:7], v[158:161], v[198:201], v[4:7]
	v_mfma_f32_16x16x32_bf16 v[0:3], v[166:169], v[198:201], v[0:3]
	v_mfma_f32_16x16x32_bf16 v[48:51], v[162:165], v[178:181], v[48:51]
	v_mfma_f32_16x16x32_bf16 v[40:43], v[170:173], v[178:181], v[40:43]
	v_mfma_f32_16x16x32_bf16 v[32:35], v[162:165], v[186:189], v[32:35]
	v_mfma_f32_16x16x32_bf16 v[24:27], v[170:173], v[186:189], v[24:27]
	v_mfma_f32_16x16x32_bf16 v[16:19], v[162:165], v[194:197], v[16:19]
	v_mfma_f32_16x16x32_bf16 v[8:11], v[170:173], v[194:197], v[8:11]
	v_mfma_f32_16x16x32_bf16 v[4:7], v[162:165], v[206:209], v[4:7]
	v_mfma_f32_16x16x32_bf16 v[0:3], v[170:173], v[206:209], v[0:3]
	s_barrier
; #define PG8_STAGE(bufoff, gbase, voff) do { _Pragma("unroll") for (int _i = 0; _i < 2; ++_i) \
;         __builtin_amdgcn_global_load_lds((const unsigned*)((const char*)(gbase) + (voff)[_i]), (PG8_LAS unsigned*)(lds + (bufoff) + ldsw + _i * 8192), 16, 0, 0); } while (0)
; #define PG8_LDA(dst, b, h) do { _Pragma("unroll") for (int m = 0; m < 4; ++m) _Pragma("unroll") for (int k = 0; k < 2; ++k) dst[m][k] = *(const PG8_LAS bf16x8*)(lds + PG8_SA(b, h) + aoff + m * 2048 + k * 1024); } while (0)
; #define PG8_LDB(dst, b, h) do { _Pragma("unroll") for (int n = 0; n < 2; ++n) _Pragma("unroll") for (int k = 0; k < 2; ++k) dst[n][k] = *(const PG8_LAS bf16x8*)(lds + PG8_SB(b, h) + boff + n * 2048 + k * 1024); } while (0)
; #define PG8_MMA(ai, bj, At, Bt) do { __builtin_amdgcn_s_setprio(1); _Pragma("unroll") for (int m = 0; m < 4; ++m) _Pragma("unroll") for (int n = 0; n < 2; ++n) _Pragma("unroll") for (int k = 0; k < 2; ++k) \
;         acc[ai][bj][m][n] = __builtin_amdgcn_mfma_f32_16x16x32_bf16(Bt[n][k], At[m][k], acc[ai][bj][m][n], 0, 0, 0); __builtin_amdgcn_s_setprio(0); } while (0)
; #define PG8_WAIT_V(n) asm volatile("s_waitcnt vmcnt(" #n ")" ::: "memory")
; #define PG8_WAIT_L(n) asm volatile("s_waitcnt lgkmcnt(" #n ")" ::: "memory")
; #define PG8_BAR __builtin_amdgcn_s_barrier()
; #define PG8_SCHED __builtin_amdgcn_sched_barrier(0)
; template <class Epi, class Sched, bool ALIGN_EPI = false, bool SP2 = false>
; __device__ __forceinline__ void gemm_phase(PG8_LAS unsigned char* lds, const Gemm g, const Sched& S, const Epi& E, const int tid) {
;     ...
;             PG8_LDB(B0, 1, 0); PG8_LDB(B1, 1, 1); PG8_SCHED; PG8_LDA(At, 1, 0); PG8_STAGE(PG8_SA(0, 1), a2 + hstep, voffA);
;             PG8_WAIT_V(8); PG8_WAIT_L(0); PG8_BAR; PG8_MMA(0, 0, At, B0); PG8_MMA(0, 1, At, B1); PG8_BAR; PG8_SCHED;
	s_setprio 0
	s_add_i32 s53, 0, 0x18000
	s_add_i32 s54, 0, 0x1c000
	v_add_u32_e32 v154, s53, v140
	v_add_u32_e32 v170, s54, v140
	ds_read_b128 v[142:145], v154
	ds_read_b128 v[146:149], v154 offset:1024
	ds_read_b128 v[150:153], v154 offset:2048
	ds_read_b128 v[154:157], v154 offset:3072
	ds_read_b128 v[158:161], v170
	ds_read_b128 v[162:165], v170 offset:1024
	ds_read_b128 v[166:169], v170 offset:2048
	ds_read_b128 v[170:173], v170 offset:3072
	s_add_u32 s28, s28, 0x20000
	s_addc_u32 s29, s29, 0
	s_mov_b32 m0, s36
	v_lshl_add_u64 v[214:215], s[28:29], 0, v[128:129]
	ds_read_b128 v[174:177], v141 offset:32768
	ds_read_b128 v[178:181], v141 offset:33792
	ds_read_b128 v[182:185], v141 offset:34816
	ds_read_b128 v[186:189], v141 offset:35840
	ds_read_b128 v[190:193], v141 offset:36864
	ds_read_b128 v[194:197], v141 offset:37888
	ds_read_b128 v[198:201], v141 offset:38912
	ds_read_b128 v[206:209], v141 offset:39936
	global_load_lds_dwordx4 v[214:215], off
	v_lshl_add_u64 v[214:215], s[28:29], 0, v[130:131]
	s_mov_b32 m0, s37
	s_nop 0
	global_load_lds_dwordx4 v[214:215], off
	s_waitcnt vmcnt(8)
	s_waitcnt lgkmcnt(0)
	s_setprio 1
	s_barrier
	v_mfma_f32_16x16x32_bf16 v[124:127], v[142:145], v[174:177], v[124:127]
	v_mfma_f32_16x16x32_bf16 v[120:123], v[150:153], v[174:177], v[120:123]
	v_mfma_f32_16x16x32_bf16 v[116:119], v[142:145], v[182:185], v[116:119]
	v_mfma_f32_16x16x32_bf16 v[108:111], v[150:153], v[182:185], v[108:111]
	v_mfma_f32_16x16x32_bf16 v[100:103], v[142:145], v[190:193], v[100:103]
	v_mfma_f32_16x16x32_bf16 v[92:95], v[150:153], v[190:193], v[92:95]
	v_mfma_f32_16x16x32_bf16 v[84:87], v[142:145], v[198:201], v[84:87]
	v_mfma_f32_16x16x32_bf16 v[76:79], v[150:153], v[198:201], v[76:79]
	v_mfma_f32_16x16x32_bf16 v[124:127], v[146:149], v[178:181], v[124:127]
	v_mfma_f32_16x16x32_bf16 v[120:123], v[154:157], v[178:181], v[120:123]
	v_mfma_f32_16x16x32_bf16 v[116:119], v[146:149], v[186:189], v[116:119]
	v_mfma_f32_16x16x32_bf16 v[108:111], v[154:157], v[186:189], v[108:111]
	v_mfma_f32_16x16x32_bf16 v[100:103], v[146:149], v[194:197], v[100:103]
	v_mfma_f32_16x16x32_bf16 v[92:95], v[154:157], v[194:197], v[92:95]
	v_mfma_f32_16x16x32_bf16 v[84:87], v[146:149], v[206:209], v[84:87]
	v_mfma_f32_16x16x32_bf16 v[76:79], v[154:157], v[206:209], v[76:79]
	s_setprio 0
	s_setprio 1
	v_mfma_f32_16x16x32_bf16 v[112:115], v[158:161], v[174:177], v[112:115]
	v_mfma_f32_16x16x32_bf16 v[104:107], v[166:169], v[174:177], v[104:107]
	v_mfma_f32_16x16x32_bf16 v[96:99], v[158:161], v[182:185], v[96:99]
	v_mfma_f32_16x16x32_bf16 v[88:91], v[166:169], v[182:185], v[88:91]
	v_mfma_f32_16x16x32_bf16 v[80:83], v[158:161], v[190:193], v[80:83]
	v_mfma_f32_16x16x32_bf16 v[72:75], v[166:169], v[190:193], v[72:75]
	v_mfma_f32_16x16x32_bf16 v[68:71], v[158:161], v[198:201], v[68:71]
	v_mfma_f32_16x16x32_bf16 v[64:67], v[166:169], v[198:201], v[64:67]
	v_mfma_f32_16x16x32_bf16 v[112:115], v[162:165], v[178:181], v[112:115]
	v_mfma_f32_16x16x32_bf16 v[104:107], v[170:173], v[178:181], v[104:107]
	v_mfma_f32_16x16x32_bf16 v[96:99], v[162:165], v[186:189], v[96:99]
	v_mfma_f32_16x16x32_bf16 v[88:91], v[170:173], v[186:189], v[88:91]
	v_mfma_f32_16x16x32_bf16 v[80:83], v[162:165], v[194:197], v[80:83]
	v_mfma_f32_16x16x32_bf16 v[72:75], v[170:173], v[194:197], v[72:75]
	v_mfma_f32_16x16x32_bf16 v[68:71], v[162:165], v[206:209], v[68:71]
	v_mfma_f32_16x16x32_bf16 v[64:67], v[170:173], v[206:209], v[64:67]
	s_barrier
; #define PG8_STAGE(bufoff, gbase, voff) do { _Pragma("unroll") for (int _i = 0; _i < 2; ++_i) \
;         __builtin_amdgcn_global_load_lds((const unsigned*)((const char*)(gbase) + (voff)[_i]), (PG8_LAS unsigned*)(lds + (bufoff) + ldsw + _i * 8192), 16, 0, 0); } while (0)
; #define PG8_LDA(dst, b, h) do { _Pragma("unroll") for (int m = 0; m < 4; ++m) _Pragma("unroll") for (int k = 0; k < 2; ++k) dst[m][k] = *(const PG8_LAS bf16x8*)(lds + PG8_SA(b, h) + aoff + m * 2048 + k * 1024); } while (0)
; #define PG8_MMA(ai, bj, At, Bt) do { __builtin_amdgcn_s_setprio(1); _Pragma("unroll") for (int m = 0; m < 4; ++m) _Pragma("unroll") for (int n = 0; n < 2; ++n) _Pragma("unroll") for (int k = 0; k < 2; ++k) \
;         acc[ai][bj][m][n] = __builtin_amdgcn_mfma_f32_16x16x32_bf16(Bt[n][k], At[m][k], acc[ai][bj][m][n], 0, 0, 0); __builtin_amdgcn_s_setprio(0); } while (0)
; #define PG8_WAIT_V(n) asm volatile("s_waitcnt vmcnt(" #n ")" ::: "memory")
; #define PG8_WAIT_L(n) asm volatile("s_waitcnt lgkmcnt(" #n ")" ::: "memory")
; #define PG8_BAR __builtin_amdgcn_s_barrier()
; #define PG8_SCHED __builtin_amdgcn_sched_barrier(0)
; template <class Epi, class Sched, bool ALIGN_EPI = false, bool SP2 = false>
; __device__ __forceinline__ void gemm_phase(PG8_LAS unsigned char* lds, const Gemm g, const Sched& S, const Epi& E, const int tid) {
;     ...
;             PG8_LDA(At, 1, 1); PG8_STAGE(PG8_SB(1, 0), b3, voffB); PG8_STAGE(PG8_SB(1, 1), b3 + hstep, voffB); PG8_STAGE(PG8_SA(1, 0), a3, voffA);
;             PG8_WAIT_V(8); PG8_WAIT_L(0); PG8_BAR; PG8_MMA(1, 0, At, B0); PG8_MMA(1, 1, At, B1); PG8_BAR; PG8_SCHED;
	s_setprio 0
	s_add_i32 s28, s53, s34
	v_lshl_add_u64 v[138:139], v[138:139], 0, s[70:71]
	s_mov_b32 m0, s28
	ds_read_b128 v[174:177], v141 offset:49152
	ds_read_b128 v[178:181], v141 offset:50176
	ds_read_b128 v[182:185], v141 offset:51200
	ds_read_b128 v[186:189], v141 offset:52224
	ds_read_b128 v[190:193], v141 offset:53248
	ds_read_b128 v[194:197], v141 offset:54272
	ds_read_b128 v[198:201], v141 offset:55296
	ds_read_b128 v[206:209], v141 offset:56320
	global_load_lds_dwordx4 v[138:139], off
	s_add_i32 m0, s28, 0x2000
	s_add_u32 s26, s26, 0x20080
	v_lshl_add_u64 v[138:139], v[202:203], 0, s[70:71]
	s_addc_u32 s27, s27, 0
	s_add_i32 s28, s54, s34
	global_load_lds_dwordx4 v[138:139], off
	v_lshl_add_u64 v[138:139], s[26:27], 0, v[204:205]
	s_mov_b32 m0, s28
	s_nop 0
	global_load_lds_dwordx4 v[138:139], off
	v_lshl_add_u64 v[138:139], s[26:27], 0, v[132:133]
	s_add_i32 m0, s28, 0x2000
	s_nop 0
	global_load_lds_dwordx4 v[138:139], off
	v_lshl_add_u64 v[138:139], v[210:211], 0, s[70:71]
	s_mov_b32 m0, s43
	s_nop 0
	global_load_lds_dwordx4 v[138:139], off
	v_lshl_add_u64 v[138:139], v[212:213], 0, s[70:71]
	s_mov_b32 m0, s44
	s_nop 0
	global_load_lds_dwordx4 v[138:139], off
	s_add_i32 s52, s52, 2
	s_add_u32 s24, s24, 0x100
	s_addc_u32 s25, s25, 0
	s_add_u32 s50, s50, 0x100
	s_addc_u32 s51, s51, 0
	s_waitcnt vmcnt(8)
	s_waitcnt lgkmcnt(0)
	s_setprio 1
	s_barrier
	v_mfma_f32_16x16x32_bf16 v[60:63], v[142:145], v[174:177], v[60:63]
	v_mfma_f32_16x16x32_bf16 v[56:59], v[150:153], v[174:177], v[56:59]
	v_mfma_f32_16x16x32_bf16 v[52:55], v[142:145], v[182:185], v[52:55]
	v_mfma_f32_16x16x32_bf16 v[44:47], v[150:153], v[182:185], v[44:47]
	v_mfma_f32_16x16x32_bf16 v[36:39], v[142:145], v[190:193], v[36:39]
	v_mfma_f32_16x16x32_bf16 v[28:31], v[150:153], v[190:193], v[28:31]
	v_mfma_f32_16x16x32_bf16 v[20:23], v[142:145], v[198:201], v[20:23]
	v_mfma_f32_16x16x32_bf16 v[12:15], v[150:153], v[198:201], v[12:15]
	v_mfma_f32_16x16x32_bf16 v[60:63], v[146:149], v[178:181], v[60:63]
	v_mfma_f32_16x16x32_bf16 v[56:59], v[154:157], v[178:181], v[56:59]
	v_mfma_f32_16x16x32_bf16 v[52:55], v[146:149], v[186:189], v[52:55]
	v_mfma_f32_16x16x32_bf16 v[44:47], v[154:157], v[186:189], v[44:47]
	v_mfma_f32_16x16x32_bf16 v[36:39], v[146:149], v[194:197], v[36:39]
	v_mfma_f32_16x16x32_bf16 v[28:31], v[154:157], v[194:197], v[28:31]
	v_mfma_f32_16x16x32_bf16 v[20:23], v[146:149], v[206:209], v[20:23]
	v_mfma_f32_16x16x32_bf16 v[12:15], v[154:157], v[206:209], v[12:15]
	s_setprio 0
	s_setprio 1
	v_mfma_f32_16x16x32_bf16 v[48:51], v[158:161], v[174:177], v[48:51]
	v_mfma_f32_16x16x32_bf16 v[40:43], v[166:169], v[174:177], v[40:43]
	v_mfma_f32_16x16x32_bf16 v[32:35], v[158:161], v[182:185], v[32:35]
	v_mfma_f32_16x16x32_bf16 v[24:27], v[166:169], v[182:185], v[24:27]
	v_mfma_f32_16x16x32_bf16 v[16:19], v[158:161], v[190:193], v[16:19]
	v_mfma_f32_16x16x32_bf16 v[8:11], v[166:169], v[190:193], v[8:11]
	v_mfma_f32_16x16x32_bf16 v[4:7], v[158:161], v[198:201], v[4:7]
	v_mfma_f32_16x16x32_bf16 v[0:3], v[166:169], v[198:201], v[0:3]
	v_mfma_f32_16x16x32_bf16 v[48:51], v[162:165], v[178:181], v[48:51]
	v_mfma_f32_16x16x32_bf16 v[40:43], v[170:173], v[178:181], v[40:43]
	v_mfma_f32_16x16x32_bf16 v[32:35], v[162:165], v[186:189], v[32:35]
	v_mfma_f32_16x16x32_bf16 v[24:27], v[170:173], v[186:189], v[24:27]
	v_mfma_f32_16x16x32_bf16 v[16:19], v[162:165], v[194:197], v[16:19]
	v_mfma_f32_16x16x32_bf16 v[8:11], v[170:173], v[194:197], v[8:11]
	v_mfma_f32_16x16x32_bf16 v[4:7], v[162:165], v[206:209], v[4:7]
	v_mfma_f32_16x16x32_bf16 v[0:3], v[170:173], v[206:209], v[0:3]
	s_barrier
	s_setprio 0
	s_cmp_gt_u32 s52, 5
	s_cbranch_scc0 .LBB0_1573
	s_and_b64 vcc, exec, s[12:13]
	s_cbranch_vccz .LBB0_1576
	s_barrier
